# v25 + GEMM K-loops: 8 of 16 stage loads per iteration use the saddr form (SGPR base + 32-bit VGPR offset) instead of v_lshl_add_u64 + 64-bit address
# speedup vs baseline: 1.0021x; 1.0013x over previous
; #define PG8_STAGE(bufoff, gbase, voff) do { _Pragma("unroll") for (int _i = 0; _i < 2; ++_i) \
;         __builtin_amdgcn_global_load_lds((const unsigned*)((const char*)(gbase) + (voff)[_i]), (LAS unsigned*)(lds + (bufoff) + ldsw + _i * 8192), 16, 0, 0); } while (0)
; #define PG8_LDA(dst, b, h) do { _Pragma("unroll") for (int m = 0; m < 4; ++m) _Pragma("unroll") for (int k = 0; k < 2; ++k) dst[m][k] = *(const LAS bf16x8*)(lds + PG8_SA(b, h) + aoff + m * 2048 + k * 1024); } while (0)
; #define PG8_LDB(dst, b, h) do { _Pragma("unroll") for (int n = 0; n < 2; ++n) _Pragma("unroll") for (int k = 0; k < 2; ++k) dst[n][k] = *(const LAS bf16x8*)(lds + PG8_SB(b, h) + boff + n * 2048 + k * 1024); } while (0)
; #define PG8_MMA(ai, bj, At, Bt) do { __builtin_amdgcn_s_setprio(1); _Pragma("unroll") for (int m = 0; m < 4; ++m) _Pragma("unroll") for (int n = 0; n < 2; ++n) _Pragma("unroll") for (int k = 0; k < 2; ++k) \
;         acc[ai][bj][m][n] = __builtin_amdgcn_mfma_f32_16x16x32_bf16(Bt[n][k], At[m][k], acc[ai][bj][m][n], 0, 0, 0); __builtin_amdgcn_s_setprio(0); } while (0)
; #define PG8_WAIT_V(n) asm volatile("s_waitcnt vmcnt(" #n ")" ::: "memory")
; #define PG8_WAIT_L(n) asm volatile("s_waitcnt lgkmcnt(" #n ")" ::: "memory")
; #define PG8_BAR __builtin_amdgcn_s_barrier()
; #define PG8_SCHED __builtin_amdgcn_sched_barrier(0)
; template <class Epi, class Sched, bool ALIGN_EPI = false, bool SP2 = false>
; __device__ __forceinline__ void gemm_phase(LAS unsigned char* lds, const Gemm g, const Sched& S, const Epi& E) {
;     ...
;             if constexpr (SP2) {
;             PG8_LDB(B0, 0, 0); PG8_LDB(B1, 0, 1); PG8_SCHED; PG8_LDA(At, 0, 0); PG8_STAGE(PG8_SA(1, 1), a1 + hstep, voffA);
;             PG8_WAIT_V(8); PG8_WAIT_L(0); PG8_BAR; PG8_MMA(0, 0, At, B0); PG8_MMA(0, 1, At, B1); PG8_BAR; PG8_SCHED;
;             PG8_LDA(At, 0, 1); PG8_STAGE(PG8_SB(0, 0), b2, voffB); PG8_STAGE(PG8_SB(0, 1), b2 + hstepB, voffB); PG8_STAGE(PG8_SA(0, 0), a2, voffA);
;             PG8_WAIT_V(8); PG8_WAIT_L(0); PG8_BAR; PG8_MMA(1, 0, At, B0); PG8_MMA(1, 1, At, B1); PG8_BAR; PG8_SCHED;
.Lprio_188:
	ds_read_b128 v[66:69], v174
	ds_read_b128 v[70:73], v174 offset:1024
	ds_read_b128 v[74:77], v174 offset:2048
	ds_read_b128 v[78:81], v174 offset:3072
	ds_read_b128 v[162:165], v175
	ds_read_b128 v[182:185], v175 offset:1024
	ds_read_b128 v[186:189], v175 offset:2048
	ds_read_b128 v[190:193], v175 offset:3072
	s_add_u32 s20, s16, 0xfff80080
	s_addc_u32 s21, s17, -1
	s_cmp_eq_u32 s19, 28
	s_cselect_b32 s53, s3, s21
	s_cselect_b32 s52, s12, s20
	s_cselect_b32 s51, s13, s18
	s_cselect_b32 s50, s14, s15
	s_add_i32 m0, s33, 0xc000
	ds_read_b128 v[194:197], v176
	ds_read_b128 v[198:201], v176 offset:1024
	ds_read_b128 v[202:205], v176 offset:2048
	ds_read_b128 v[206:209], v176 offset:3072
	ds_read_b128 v[210:213], v176 offset:4096
	ds_read_b128 v[214:217], v176 offset:5120
	ds_read_b128 v[218:221], v176 offset:6144
	ds_read_b128 v[222:225], v176 offset:7168
	global_load_lds_dwordx4 v154, s[16:17]
	s_add_i32 m0, s33, 0xe000
	s_nop 0
	global_load_lds_dwordx4 v156, s[16:17]
	s_waitcnt lgkmcnt(0)
	s_barrier
	s_waitcnt lgkmcnt(0)
	v_mfma_f32_16x16x32_bf16 v[142:145], v[66:69], v[194:197], 0
	v_mfma_f32_16x16x32_bf16 v[138:141], v[74:77], v[194:197], 0
	v_mfma_f32_16x16x32_bf16 v[126:129], v[66:69], v[202:205], 0
	v_mfma_f32_16x16x32_bf16 v[122:125], v[74:77], v[202:205], 0
	v_mfma_f32_16x16x32_bf16 v[110:113], v[66:69], v[210:213], 0
	v_mfma_f32_16x16x32_bf16 v[106:109], v[74:77], v[210:213], 0
	v_mfma_f32_16x16x32_bf16 v[94:97], v[66:69], v[218:221], 0
	v_mfma_f32_16x16x32_bf16 v[90:93], v[74:77], v[218:221], 0
	v_mfma_f32_16x16x32_bf16 v[142:145], v[70:73], v[198:201], v[142:145]
	v_mfma_f32_16x16x32_bf16 v[138:141], v[78:81], v[198:201], v[138:141]
	v_mfma_f32_16x16x32_bf16 v[126:129], v[70:73], v[206:209], v[126:129]
	v_mfma_f32_16x16x32_bf16 v[122:125], v[78:81], v[206:209], v[122:125]
	v_mfma_f32_16x16x32_bf16 v[110:113], v[70:73], v[214:217], v[110:113]
	v_mfma_f32_16x16x32_bf16 v[106:109], v[78:81], v[214:217], v[106:109]
	v_mfma_f32_16x16x32_bf16 v[94:97], v[70:73], v[222:225], v[94:97]
	v_mfma_f32_16x16x32_bf16 v[90:93], v[78:81], v[222:225], v[90:93]
	v_mfma_f32_16x16x32_bf16 v[134:137], v[162:165], v[194:197], 0
	v_mfma_f32_16x16x32_bf16 v[130:133], v[186:189], v[194:197], 0
	v_mfma_f32_16x16x32_bf16 v[118:121], v[162:165], v[202:205], 0
	v_mfma_f32_16x16x32_bf16 v[114:117], v[186:189], v[202:205], 0
	v_mfma_f32_16x16x32_bf16 v[102:105], v[162:165], v[210:213], 0
	v_mfma_f32_16x16x32_bf16 v[98:101], v[186:189], v[210:213], 0
	v_mfma_f32_16x16x32_bf16 v[86:89], v[162:165], v[218:221], 0
	v_mfma_f32_16x16x32_bf16 v[82:85], v[186:189], v[218:221], 0
	v_mfma_f32_16x16x32_bf16 v[134:137], v[182:185], v[198:201], v[134:137]
	v_mfma_f32_16x16x32_bf16 v[130:133], v[190:193], v[198:201], v[130:133]
	v_mfma_f32_16x16x32_bf16 v[118:121], v[182:185], v[206:209], v[118:121]
	v_mfma_f32_16x16x32_bf16 v[114:117], v[190:193], v[206:209], v[114:117]
	v_mfma_f32_16x16x32_bf16 v[102:105], v[182:185], v[214:217], v[102:105]
	v_mfma_f32_16x16x32_bf16 v[98:101], v[190:193], v[214:217], v[98:101]
	v_mfma_f32_16x16x32_bf16 v[86:89], v[182:185], v[222:225], v[86:89]
	v_mfma_f32_16x16x32_bf16 v[82:85], v[190:193], v[222:225], v[82:85]
	s_barrier
	s_add_i32 s20, s57, s27
	v_lshl_add_u64 v[166:167], s[50:51], 0, v[150:151]
	s_mov_b32 m0, s20
	ds_read_b128 v[194:197], v176 offset:16384
	ds_read_b128 v[198:201], v176 offset:17408
	ds_read_b128 v[202:205], v176 offset:18432
	ds_read_b128 v[206:209], v176 offset:19456
	ds_read_b128 v[210:213], v176 offset:20480
	ds_read_b128 v[214:217], v176 offset:21504
	ds_read_b128 v[218:221], v176 offset:22528
	ds_read_b128 v[222:225], v176 offset:23552
	global_load_lds_dwordx4 v[166:167], off
	s_add_i32 m0, s20, 0x2000
	s_add_u32 s20, s50, 0x80000
	v_lshl_add_u64 v[226:227], s[50:51], 0, v[146:147]
	s_addc_u32 s21, s51, 0
	s_add_i32 s22, s58, s27
	global_load_lds_dwordx4 v[226:227], off
	s_mov_b32 m0, s22
	v_lshl_add_u64 v[230:231], s[52:53], 0, v[148:149]
	global_load_lds_dwordx4 v150, s[20:21]
	s_add_i32 m0, s22, 0x2000
	s_nop 0
	global_load_lds_dwordx4 v146, s[20:21]
	v_lshl_add_u64 v[228:229], s[52:53], 0, v[152:153]
	s_mov_b32 m0, s33
	s_nop 0
	global_load_lds_dwordx4 v[228:229], off
	s_mov_b32 m0, s34
	s_nop 0
	global_load_lds_dwordx4 v[230:231], off
	s_waitcnt lgkmcnt(0)
	s_barrier
	s_waitcnt lgkmcnt(0)
	v_mfma_f32_16x16x32_bf16 v[62:65], v[66:69], v[194:197], 0
	v_mfma_f32_16x16x32_bf16 v[58:61], v[74:77], v[194:197], 0
	v_mfma_f32_16x16x32_bf16 v[46:49], v[66:69], v[202:205], 0
	v_mfma_f32_16x16x32_bf16 v[42:45], v[74:77], v[202:205], 0
	v_mfma_f32_16x16x32_bf16 v[30:33], v[66:69], v[210:213], 0
	v_mfma_f32_16x16x32_bf16 v[26:29], v[74:77], v[210:213], 0
	v_mfma_f32_16x16x32_bf16 v[14:17], v[66:69], v[218:221], 0
	v_mfma_f32_16x16x32_bf16 v[10:13], v[74:77], v[218:221], 0
	v_mfma_f32_16x16x32_bf16 v[62:65], v[70:73], v[198:201], v[62:65]
	v_mfma_f32_16x16x32_bf16 v[58:61], v[78:81], v[198:201], v[58:61]
	v_mfma_f32_16x16x32_bf16 v[46:49], v[70:73], v[206:209], v[46:49]
	v_mfma_f32_16x16x32_bf16 v[42:45], v[78:81], v[206:209], v[42:45]
	v_mfma_f32_16x16x32_bf16 v[30:33], v[70:73], v[214:217], v[30:33]
	v_mfma_f32_16x16x32_bf16 v[26:29], v[78:81], v[214:217], v[26:29]
	v_mfma_f32_16x16x32_bf16 v[14:17], v[70:73], v[222:225], v[14:17]
	v_mfma_f32_16x16x32_bf16 v[10:13], v[78:81], v[222:225], v[10:13]
	v_mfma_f32_16x16x32_bf16 v[54:57], v[162:165], v[194:197], 0
	v_mfma_f32_16x16x32_bf16 v[50:53], v[186:189], v[194:197], 0
	v_mfma_f32_16x16x32_bf16 v[38:41], v[162:165], v[202:205], 0
	v_mfma_f32_16x16x32_bf16 v[34:37], v[186:189], v[202:205], 0
	v_mfma_f32_16x16x32_bf16 v[22:25], v[162:165], v[210:213], 0
	v_mfma_f32_16x16x32_bf16 v[18:21], v[186:189], v[210:213], 0
	v_mfma_f32_16x16x32_bf16 v[6:9], v[162:165], v[218:221], 0
	v_mfma_f32_16x16x32_bf16 v[2:5], v[186:189], v[218:221], 0
	v_mfma_f32_16x16x32_bf16 v[54:57], v[182:185], v[198:201], v[54:57]
	v_mfma_f32_16x16x32_bf16 v[50:53], v[190:193], v[198:201], v[50:53]
	v_mfma_f32_16x16x32_bf16 v[38:41], v[182:185], v[206:209], v[38:41]
	v_mfma_f32_16x16x32_bf16 v[34:37], v[190:193], v[206:209], v[34:37]
	v_mfma_f32_16x16x32_bf16 v[22:25], v[182:185], v[214:217], v[22:25]
	v_mfma_f32_16x16x32_bf16 v[18:21], v[190:193], v[214:217], v[18:21]
	v_mfma_f32_16x16x32_bf16 v[6:9], v[182:185], v[222:225], v[6:9]
	v_mfma_f32_16x16x32_bf16 v[2:5], v[190:193], v[222:225], v[2:5]
	s_barrier
; #define PG8_STAGE(bufoff, gbase, voff) do { _Pragma("unroll") for (int _i = 0; _i < 2; ++_i) \
;         __builtin_amdgcn_global_load_lds((const unsigned*)((const char*)(gbase) + (voff)[_i]), (LAS unsigned*)(lds + (bufoff) + ldsw + _i * 8192), 16, 0, 0); } while (0)
; #define PG8_LDA(dst, b, h) do { _Pragma("unroll") for (int m = 0; m < 4; ++m) _Pragma("unroll") for (int k = 0; k < 2; ++k) dst[m][k] = *(const LAS bf16x8*)(lds + PG8_SA(b, h) + aoff + m * 2048 + k * 1024); } while (0)
; #define PG8_LDB(dst, b, h) do { _Pragma("unroll") for (int n = 0; n < 2; ++n) _Pragma("unroll") for (int k = 0; k < 2; ++k) dst[n][k] = *(const LAS bf16x8*)(lds + PG8_SB(b, h) + boff + n * 2048 + k * 1024); } while (0)
; #define PG8_MMA(ai, bj, At, Bt) do { __builtin_amdgcn_s_setprio(1); _Pragma("unroll") for (int m = 0; m < 4; ++m) _Pragma("unroll") for (int n = 0; n < 2; ++n) _Pragma("unroll") for (int k = 0; k < 2; ++k) \
;         acc[ai][bj][m][n] = __builtin_amdgcn_mfma_f32_16x16x32_bf16(Bt[n][k], At[m][k], acc[ai][bj][m][n], 0, 0, 0); __builtin_amdgcn_s_setprio(0); } while (0)
; #define PG8_WAIT_V(n) asm volatile("s_waitcnt vmcnt(" #n ")" ::: "memory")
; #define PG8_WAIT_L(n) asm volatile("s_waitcnt lgkmcnt(" #n ")" ::: "memory")
; #define PG8_BAR __builtin_amdgcn_s_barrier()
; #define PG8_SCHED __builtin_amdgcn_sched_barrier(0)
; template <class Epi, class Sched, bool ALIGN_EPI = false, bool SP2 = false>
; __device__ __forceinline__ void gemm_phase(LAS unsigned char* lds, const Gemm g, const Sched& S, const Epi& E) {
;     ...
;             PG8_LDB(B0, 1, 0); PG8_LDB(B1, 1, 1); PG8_SCHED; PG8_LDA(At, 1, 0); PG8_STAGE(PG8_SA(0, 1), a2 + hstep, voffA);
;             PG8_WAIT_V(8); PG8_WAIT_L(0); PG8_BAR; PG8_MMA(0, 0, At, B0); PG8_MMA(0, 1, At, B1); PG8_BAR; PG8_SCHED;
;             PG8_LDA(At, 1, 1); PG8_STAGE(PG8_SB(1, 0), b3, voffB); PG8_STAGE(PG8_SB(1, 1), b3 + hstepB, voffB); PG8_STAGE(PG8_SA(1, 0), a3, voffA);
;             PG8_WAIT_V(8); PG8_WAIT_L(0); PG8_BAR; PG8_MMA(1, 0, At, B0); PG8_MMA(1, 1, At, B1); PG8_BAR; PG8_SCHED;
	s_add_i32 s22, 0, 0x18000
	s_add_i32 s23, 0, 0x1c000
	v_add_u32_e32 v78, s22, v170
	v_add_u32_e32 v168, s23, v170
	ds_read_b128 v[66:69], v78
	ds_read_b128 v[70:73], v78 offset:1024
	ds_read_b128 v[74:77], v78 offset:2048
	ds_read_b128 v[78:81], v78 offset:3072
	ds_read_b128 v[162:165], v168
	ds_read_b128 v[182:185], v168 offset:1024
	ds_read_b128 v[186:189], v168 offset:2048
	ds_read_b128 v[190:193], v168 offset:3072
	s_add_u32 s20, s52, 0x80000
	s_addc_u32 s21, s53, 0
	s_mov_b32 m0, s35
	ds_read_b128 v[194:197], v176 offset:32768
	ds_read_b128 v[198:201], v176 offset:33792
	ds_read_b128 v[202:205], v176 offset:34816
	ds_read_b128 v[206:209], v176 offset:35840
	ds_read_b128 v[210:213], v176 offset:36864
	ds_read_b128 v[214:217], v176 offset:37888
	ds_read_b128 v[218:221], v176 offset:38912
	ds_read_b128 v[222:225], v176 offset:39936
	global_load_lds_dwordx4 v152, s[20:21]
	s_mov_b32 m0, s36
	s_nop 0
	global_load_lds_dwordx4 v148, s[20:21]
	s_waitcnt vmcnt(8)
	s_waitcnt lgkmcnt(0)
	s_barrier
	s_waitcnt lgkmcnt(0)
	v_mfma_f32_16x16x32_bf16 v[142:145], v[66:69], v[194:197], v[142:145]
	v_mfma_f32_16x16x32_bf16 v[138:141], v[74:77], v[194:197], v[138:141]
	v_mfma_f32_16x16x32_bf16 v[126:129], v[66:69], v[202:205], v[126:129]
	v_mfma_f32_16x16x32_bf16 v[122:125], v[74:77], v[202:205], v[122:125]
	v_mfma_f32_16x16x32_bf16 v[110:113], v[66:69], v[210:213], v[110:113]
	v_mfma_f32_16x16x32_bf16 v[106:109], v[74:77], v[210:213], v[106:109]
	v_mfma_f32_16x16x32_bf16 v[94:97], v[66:69], v[218:221], v[94:97]
	v_mfma_f32_16x16x32_bf16 v[90:93], v[74:77], v[218:221], v[90:93]
	v_mfma_f32_16x16x32_bf16 v[142:145], v[70:73], v[198:201], v[142:145]
	v_mfma_f32_16x16x32_bf16 v[138:141], v[78:81], v[198:201], v[138:141]
	v_mfma_f32_16x16x32_bf16 v[126:129], v[70:73], v[206:209], v[126:129]
	v_mfma_f32_16x16x32_bf16 v[122:125], v[78:81], v[206:209], v[122:125]
	v_mfma_f32_16x16x32_bf16 v[110:113], v[70:73], v[214:217], v[110:113]
	v_mfma_f32_16x16x32_bf16 v[106:109], v[78:81], v[214:217], v[106:109]
	v_mfma_f32_16x16x32_bf16 v[94:97], v[70:73], v[222:225], v[94:97]
	v_mfma_f32_16x16x32_bf16 v[90:93], v[78:81], v[222:225], v[90:93]
	v_mfma_f32_16x16x32_bf16 v[134:137], v[162:165], v[194:197], v[134:137]
	v_mfma_f32_16x16x32_bf16 v[130:133], v[186:189], v[194:197], v[130:133]
	v_mfma_f32_16x16x32_bf16 v[118:121], v[162:165], v[202:205], v[118:121]
	v_mfma_f32_16x16x32_bf16 v[114:117], v[186:189], v[202:205], v[114:117]
	v_mfma_f32_16x16x32_bf16 v[102:105], v[162:165], v[210:213], v[102:105]
	v_mfma_f32_16x16x32_bf16 v[98:101], v[186:189], v[210:213], v[98:101]
	v_mfma_f32_16x16x32_bf16 v[86:89], v[162:165], v[218:221], v[86:89]
	v_mfma_f32_16x16x32_bf16 v[82:85], v[186:189], v[218:221], v[82:85]
	v_mfma_f32_16x16x32_bf16 v[134:137], v[182:185], v[198:201], v[134:137]
	v_mfma_f32_16x16x32_bf16 v[130:133], v[190:193], v[198:201], v[130:133]
	v_mfma_f32_16x16x32_bf16 v[118:121], v[182:185], v[206:209], v[118:121]
	v_mfma_f32_16x16x32_bf16 v[114:117], v[190:193], v[206:209], v[114:117]
	v_mfma_f32_16x16x32_bf16 v[102:105], v[182:185], v[214:217], v[102:105]
	v_mfma_f32_16x16x32_bf16 v[98:101], v[190:193], v[214:217], v[98:101]
	v_mfma_f32_16x16x32_bf16 v[86:89], v[182:185], v[222:225], v[86:89]
	v_mfma_f32_16x16x32_bf16 v[82:85], v[190:193], v[222:225], v[82:85]
	s_barrier
	s_add_i32 s20, s22, s27
	v_lshl_add_u64 v[166:167], v[166:167], 0, s[10:11]
	s_mov_b32 m0, s20
	ds_read_b128 v[194:197], v176 offset:49152
	ds_read_b128 v[198:201], v176 offset:50176
	ds_read_b128 v[202:205], v176 offset:51200
	ds_read_b128 v[206:209], v176 offset:52224
	ds_read_b128 v[210:213], v176 offset:53248
	ds_read_b128 v[214:217], v176 offset:54272
	ds_read_b128 v[218:221], v176 offset:55296
	ds_read_b128 v[222:225], v176 offset:56320
	global_load_lds_dwordx4 v[166:167], off
	s_add_i32 m0, s20, 0x2000
	s_add_u32 s20, s50, 0x80080
	v_lshl_add_u64 v[166:167], v[226:227], 0, s[10:11]
	s_addc_u32 s21, s51, 0
	s_add_i32 s22, s23, s27
	global_load_lds_dwordx4 v[166:167], off
	s_mov_b32 m0, s22
	s_nop 0
	global_load_lds_dwordx4 v150, s[20:21]
	s_add_i32 m0, s22, 0x2000
	s_nop 0
	global_load_lds_dwordx4 v146, s[20:21]
	v_lshl_add_u64 v[166:167], v[228:229], 0, s[10:11]
	s_mov_b32 m0, s55
	s_nop 0
	global_load_lds_dwordx4 v[166:167], off
	v_lshl_add_u64 v[166:167], v[230:231], 0, s[10:11]
	s_mov_b32 m0, s56
	s_nop 0
	global_load_lds_dwordx4 v[166:167], off
	s_waitcnt vmcnt(8)
	s_waitcnt lgkmcnt(0)
	s_barrier
	s_waitcnt lgkmcnt(0)
	v_mfma_f32_16x16x32_bf16 v[62:65], v[66:69], v[194:197], v[62:65]
	v_mfma_f32_16x16x32_bf16 v[58:61], v[74:77], v[194:197], v[58:61]
	v_mfma_f32_16x16x32_bf16 v[46:49], v[66:69], v[202:205], v[46:49]
	v_mfma_f32_16x16x32_bf16 v[42:45], v[74:77], v[202:205], v[42:45]
	v_mfma_f32_16x16x32_bf16 v[30:33], v[66:69], v[210:213], v[30:33]
	v_mfma_f32_16x16x32_bf16 v[26:29], v[74:77], v[210:213], v[26:29]
	v_mfma_f32_16x16x32_bf16 v[14:17], v[66:69], v[218:221], v[14:17]
	v_mfma_f32_16x16x32_bf16 v[10:13], v[74:77], v[218:221], v[10:13]
	v_mfma_f32_16x16x32_bf16 v[62:65], v[70:73], v[198:201], v[62:65]
	v_mfma_f32_16x16x32_bf16 v[58:61], v[78:81], v[198:201], v[58:61]
	v_mfma_f32_16x16x32_bf16 v[46:49], v[70:73], v[206:209], v[46:49]
	v_mfma_f32_16x16x32_bf16 v[42:45], v[78:81], v[206:209], v[42:45]
	v_mfma_f32_16x16x32_bf16 v[30:33], v[70:73], v[214:217], v[30:33]
	v_mfma_f32_16x16x32_bf16 v[26:29], v[78:81], v[214:217], v[26:29]
	v_mfma_f32_16x16x32_bf16 v[14:17], v[70:73], v[222:225], v[14:17]
	v_mfma_f32_16x16x32_bf16 v[10:13], v[78:81], v[222:225], v[10:13]
	v_mfma_f32_16x16x32_bf16 v[54:57], v[162:165], v[194:197], v[54:57]
	v_mfma_f32_16x16x32_bf16 v[50:53], v[186:189], v[194:197], v[50:53]
	v_mfma_f32_16x16x32_bf16 v[38:41], v[162:165], v[202:205], v[38:41]
	v_mfma_f32_16x16x32_bf16 v[34:37], v[186:189], v[202:205], v[34:37]
	v_mfma_f32_16x16x32_bf16 v[22:25], v[162:165], v[210:213], v[22:25]
	v_mfma_f32_16x16x32_bf16 v[18:21], v[186:189], v[210:213], v[18:21]
	v_mfma_f32_16x16x32_bf16 v[6:9], v[162:165], v[218:221], v[6:9]
	v_mfma_f32_16x16x32_bf16 v[2:5], v[186:189], v[218:221], v[2:5]
	v_mfma_f32_16x16x32_bf16 v[54:57], v[182:185], v[198:201], v[54:57]
	v_mfma_f32_16x16x32_bf16 v[50:53], v[190:193], v[198:201], v[50:53]
	v_mfma_f32_16x16x32_bf16 v[38:41], v[182:185], v[206:209], v[38:41]
	v_mfma_f32_16x16x32_bf16 v[34:37], v[190:193], v[206:209], v[34:37]
	v_mfma_f32_16x16x32_bf16 v[22:25], v[182:185], v[214:217], v[22:25]
	v_mfma_f32_16x16x32_bf16 v[18:21], v[190:193], v[214:217], v[18:21]
	v_mfma_f32_16x16x32_bf16 v[6:9], v[182:185], v[222:225], v[6:9]
	v_mfma_f32_16x16x32_bf16 v[2:5], v[190:193], v[222:225], v[2:5]
	s_barrier
	s_add_i32 s19, s19, 2
	s_add_u32 s16, s16, 0x100
	s_addc_u32 s17, s17, 0
	s_add_u32 s15, s15, 0x100
	s_addc_u32 s18, s18, 0
	s_cmp_gt_u32 s19, 29
; #define PG8_STAGE(bufoff, gbase, voff) do { _Pragma("unroll") for (int _i = 0; _i < 2; ++_i) \
;         __builtin_amdgcn_global_load_lds((const unsigned*)((const char*)(gbase) + (voff)[_i]), (LAS unsigned*)(lds + (bufoff) + ldsw + _i * 8192), 16, 0, 0); } while (0)
; #define PG8_LDA(dst, b, h) do { _Pragma("unroll") for (int m = 0; m < 4; ++m) _Pragma("unroll") for (int k = 0; k < 2; ++k) dst[m][k] = *(const LAS bf16x8*)(lds + PG8_SA(b, h) + aoff + m * 2048 + k * 1024); } while (0)
; #define PG8_LDB(dst, b, h) do { _Pragma("unroll") for (int n = 0; n < 2; ++n) _Pragma("unroll") for (int k = 0; k < 2; ++k) dst[n][k] = *(const LAS bf16x8*)(lds + PG8_SB(b, h) + boff + n * 2048 + k * 1024); } while (0)
; #define PG8_MMA(ai, bj, At, Bt) do { __builtin_amdgcn_s_setprio(1); _Pragma("unroll") for (int m = 0; m < 4; ++m) _Pragma("unroll") for (int n = 0; n < 2; ++n) _Pragma("unroll") for (int k = 0; k < 2; ++k) \
;         acc[ai][bj][m][n] = __builtin_amdgcn_mfma_f32_16x16x32_bf16(Bt[n][k], At[m][k], acc[ai][bj][m][n], 0, 0, 0); __builtin_amdgcn_s_setprio(0); } while (0)
; #define PG8_WAIT_V(n) asm volatile("s_waitcnt vmcnt(" #n ")" ::: "memory")
; #define PG8_WAIT_L(n) asm volatile("s_waitcnt lgkmcnt(" #n ")" ::: "memory")
; #define PG8_BAR __builtin_amdgcn_s_barrier()
; #define PG8_SCHED __builtin_amdgcn_sched_barrier(0)
; template <class Epi, class Sched, bool ALIGN_EPI = false, bool SP2 = false>
; __device__ __forceinline__ void gemm_phase(LAS unsigned char* lds, const Gemm g, const Sched& S, const Epi& E) {
;     ...
;         for (int t = 0; t < nt; t += 2) {
;             const bool last = (t == nt - 2);
;             const char* a1 = cA + (size_t)(t + 1) * kstep;
;             const char* a2 = last ? nA : cA + (size_t)(t + 2) * kstep; const char* b2 = last ? nB : cB + (size_t)(t + 2) * kstep;
;             const char* a3 = a2 + kstep; const char* b3 = b2 + kstep;
;             if (last && has_next) S.a_ready(nxt);
;             if constexpr (SP2) {
;             PG8_LDB(B0, 0, 0); PG8_LDB(B1, 0, 1); PG8_SCHED; PG8_LDA(At, 0, 0); PG8_STAGE(PG8_SA(1, 1), a1 + hstep, voffA);
;             PG8_WAIT_V(8); PG8_WAIT_L(0); PG8_BAR; PG8_MMA(0, 0, At, B0); PG8_MMA(0, 1, At, B1); PG8_BAR; PG8_SCHED;
;             PG8_LDA(At, 0, 1); PG8_STAGE(PG8_SB(0, 0), b2, voffB); PG8_STAGE(PG8_SB(0, 1), b2 + hstepB, voffB); PG8_STAGE(PG8_SA(0, 0), a2, voffA);
.LBB0_188:
	ds_read_b128 v[66:69], v174
	ds_read_b128 v[70:73], v174 offset:1024
	ds_read_b128 v[74:77], v174 offset:2048
	ds_read_b128 v[78:81], v174 offset:3072
	ds_read_b128 v[162:165], v175
	ds_read_b128 v[182:185], v175 offset:1024
	ds_read_b128 v[186:189], v175 offset:2048
	ds_read_b128 v[190:193], v175 offset:3072
	s_add_u32 s20, s16, 0xfff80080
	s_addc_u32 s21, s17, -1
	s_cmp_eq_u32 s19, 28
	s_cselect_b32 s53, s3, s21
	s_cselect_b32 s52, s12, s20
	s_cselect_b32 s51, s13, s18
	s_cselect_b32 s50, s14, s15
	s_add_i32 m0, s33, 0xc000
	ds_read_b128 v[194:197], v176
	ds_read_b128 v[198:201], v176 offset:1024
	ds_read_b128 v[202:205], v176 offset:2048
	ds_read_b128 v[206:209], v176 offset:3072
	ds_read_b128 v[210:213], v176 offset:4096
	ds_read_b128 v[214:217], v176 offset:5120
	ds_read_b128 v[218:221], v176 offset:6144
	ds_read_b128 v[222:225], v176 offset:7168
	global_load_lds_dwordx4 v154, s[16:17]
	s_add_i32 m0, s33, 0xe000
	s_nop 0
	global_load_lds_dwordx4 v156, s[16:17]
	s_waitcnt vmcnt(8)
	s_waitcnt lgkmcnt(0)
	s_barrier
	s_waitcnt lgkmcnt(0)
	v_mfma_f32_16x16x32_bf16 v[142:145], v[66:69], v[194:197], v[142:145]
	v_mfma_f32_16x16x32_bf16 v[138:141], v[74:77], v[194:197], v[138:141]
	v_mfma_f32_16x16x32_bf16 v[126:129], v[66:69], v[202:205], v[126:129]
	v_mfma_f32_16x16x32_bf16 v[122:125], v[74:77], v[202:205], v[122:125]
	v_mfma_f32_16x16x32_bf16 v[110:113], v[66:69], v[210:213], v[110:113]
	v_mfma_f32_16x16x32_bf16 v[106:109], v[74:77], v[210:213], v[106:109]
	v_mfma_f32_16x16x32_bf16 v[94:97], v[66:69], v[218:221], v[94:97]
	v_mfma_f32_16x16x32_bf16 v[90:93], v[74:77], v[218:221], v[90:93]
	v_mfma_f32_16x16x32_bf16 v[142:145], v[70:73], v[198:201], v[142:145]
	v_mfma_f32_16x16x32_bf16 v[138:141], v[78:81], v[198:201], v[138:141]
	v_mfma_f32_16x16x32_bf16 v[126:129], v[70:73], v[206:209], v[126:129]
	v_mfma_f32_16x16x32_bf16 v[122:125], v[78:81], v[206:209], v[122:125]
	v_mfma_f32_16x16x32_bf16 v[110:113], v[70:73], v[214:217], v[110:113]
	v_mfma_f32_16x16x32_bf16 v[106:109], v[78:81], v[214:217], v[106:109]
	v_mfma_f32_16x16x32_bf16 v[94:97], v[70:73], v[222:225], v[94:97]
	v_mfma_f32_16x16x32_bf16 v[90:93], v[78:81], v[222:225], v[90:93]
	v_mfma_f32_16x16x32_bf16 v[134:137], v[162:165], v[194:197], v[134:137]
	v_mfma_f32_16x16x32_bf16 v[130:133], v[186:189], v[194:197], v[130:133]
	v_mfma_f32_16x16x32_bf16 v[118:121], v[162:165], v[202:205], v[118:121]
	v_mfma_f32_16x16x32_bf16 v[114:117], v[186:189], v[202:205], v[114:117]
	v_mfma_f32_16x16x32_bf16 v[102:105], v[162:165], v[210:213], v[102:105]
	v_mfma_f32_16x16x32_bf16 v[98:101], v[186:189], v[210:213], v[98:101]
	v_mfma_f32_16x16x32_bf16 v[86:89], v[162:165], v[218:221], v[86:89]
	v_mfma_f32_16x16x32_bf16 v[82:85], v[186:189], v[218:221], v[82:85]
	v_mfma_f32_16x16x32_bf16 v[134:137], v[182:185], v[198:201], v[134:137]
	v_mfma_f32_16x16x32_bf16 v[130:133], v[190:193], v[198:201], v[130:133]
	v_mfma_f32_16x16x32_bf16 v[118:121], v[182:185], v[206:209], v[118:121]
	v_mfma_f32_16x16x32_bf16 v[114:117], v[190:193], v[206:209], v[114:117]
	v_mfma_f32_16x16x32_bf16 v[102:105], v[182:185], v[214:217], v[102:105]
	v_mfma_f32_16x16x32_bf16 v[98:101], v[190:193], v[214:217], v[98:101]
	v_mfma_f32_16x16x32_bf16 v[86:89], v[182:185], v[222:225], v[86:89]
	v_mfma_f32_16x16x32_bf16 v[82:85], v[190:193], v[222:225], v[82:85]
	s_barrier
	s_add_i32 s20, s57, s27
	v_lshl_add_u64 v[166:167], s[50:51], 0, v[150:151]
	s_mov_b32 m0, s20
	ds_read_b128 v[194:197], v176 offset:16384
	ds_read_b128 v[198:201], v176 offset:17408
	ds_read_b128 v[202:205], v176 offset:18432
	ds_read_b128 v[206:209], v176 offset:19456
	ds_read_b128 v[210:213], v176 offset:20480
	ds_read_b128 v[214:217], v176 offset:21504
	ds_read_b128 v[218:221], v176 offset:22528
	ds_read_b128 v[222:225], v176 offset:23552
	global_load_lds_dwordx4 v[166:167], off
	s_add_i32 m0, s20, 0x2000
	s_add_u32 s20, s50, 0x80000
	v_lshl_add_u64 v[226:227], s[50:51], 0, v[146:147]
	s_addc_u32 s21, s51, 0
	s_add_i32 s22, s58, s27
	global_load_lds_dwordx4 v[226:227], off
	s_mov_b32 m0, s22
	v_lshl_add_u64 v[230:231], s[52:53], 0, v[148:149]
	global_load_lds_dwordx4 v150, s[20:21]
	s_add_i32 m0, s22, 0x2000
	s_nop 0
	global_load_lds_dwordx4 v146, s[20:21]
	v_lshl_add_u64 v[228:229], s[52:53], 0, v[152:153]
	s_mov_b32 m0, s33
	s_nop 0
	global_load_lds_dwordx4 v[228:229], off
	s_mov_b32 m0, s34
	s_nop 0
	global_load_lds_dwordx4 v[230:231], off
	s_waitcnt vmcnt(8)
	s_waitcnt lgkmcnt(0)
	s_barrier
	s_waitcnt lgkmcnt(0)
	v_mfma_f32_16x16x32_bf16 v[62:65], v[66:69], v[194:197], v[62:65]
	v_mfma_f32_16x16x32_bf16 v[58:61], v[74:77], v[194:197], v[58:61]
	v_mfma_f32_16x16x32_bf16 v[46:49], v[66:69], v[202:205], v[46:49]
	v_mfma_f32_16x16x32_bf16 v[42:45], v[74:77], v[202:205], v[42:45]
	v_mfma_f32_16x16x32_bf16 v[30:33], v[66:69], v[210:213], v[30:33]
	v_mfma_f32_16x16x32_bf16 v[26:29], v[74:77], v[210:213], v[26:29]
	v_mfma_f32_16x16x32_bf16 v[14:17], v[66:69], v[218:221], v[14:17]
	v_mfma_f32_16x16x32_bf16 v[10:13], v[74:77], v[218:221], v[10:13]
	v_mfma_f32_16x16x32_bf16 v[62:65], v[70:73], v[198:201], v[62:65]
	v_mfma_f32_16x16x32_bf16 v[58:61], v[78:81], v[198:201], v[58:61]
	v_mfma_f32_16x16x32_bf16 v[46:49], v[70:73], v[206:209], v[46:49]
	v_mfma_f32_16x16x32_bf16 v[42:45], v[78:81], v[206:209], v[42:45]
	v_mfma_f32_16x16x32_bf16 v[30:33], v[70:73], v[214:217], v[30:33]
	v_mfma_f32_16x16x32_bf16 v[26:29], v[78:81], v[214:217], v[26:29]
	v_mfma_f32_16x16x32_bf16 v[14:17], v[70:73], v[222:225], v[14:17]
	v_mfma_f32_16x16x32_bf16 v[10:13], v[78:81], v[222:225], v[10:13]
	v_mfma_f32_16x16x32_bf16 v[54:57], v[162:165], v[194:197], v[54:57]
	v_mfma_f32_16x16x32_bf16 v[50:53], v[186:189], v[194:197], v[50:53]
	v_mfma_f32_16x16x32_bf16 v[38:41], v[162:165], v[202:205], v[38:41]
	v_mfma_f32_16x16x32_bf16 v[34:37], v[186:189], v[202:205], v[34:37]
	v_mfma_f32_16x16x32_bf16 v[22:25], v[162:165], v[210:213], v[22:25]
	v_mfma_f32_16x16x32_bf16 v[18:21], v[186:189], v[210:213], v[18:21]
	v_mfma_f32_16x16x32_bf16 v[6:9], v[162:165], v[218:221], v[6:9]
	v_mfma_f32_16x16x32_bf16 v[2:5], v[186:189], v[218:221], v[2:5]
	v_mfma_f32_16x16x32_bf16 v[54:57], v[182:185], v[198:201], v[54:57]
	v_mfma_f32_16x16x32_bf16 v[50:53], v[190:193], v[198:201], v[50:53]
	v_mfma_f32_16x16x32_bf16 v[38:41], v[182:185], v[206:209], v[38:41]
	v_mfma_f32_16x16x32_bf16 v[34:37], v[190:193], v[206:209], v[34:37]
	v_mfma_f32_16x16x32_bf16 v[22:25], v[182:185], v[214:217], v[22:25]
	v_mfma_f32_16x16x32_bf16 v[18:21], v[190:193], v[214:217], v[18:21]
	v_mfma_f32_16x16x32_bf16 v[6:9], v[182:185], v[222:225], v[6:9]
	v_mfma_f32_16x16x32_bf16 v[2:5], v[190:193], v[222:225], v[2:5]
	s_barrier
; #define PG8_STAGE(bufoff, gbase, voff) do { _Pragma("unroll") for (int _i = 0; _i < 2; ++_i) \
;         __builtin_amdgcn_global_load_lds((const unsigned*)((const char*)(gbase) + (voff)[_i]), (LAS unsigned*)(lds + (bufoff) + ldsw + _i * 8192), 16, 0, 0); } while (0)
; #define PG8_LDA(dst, b, h) do { _Pragma("unroll") for (int m = 0; m < 4; ++m) _Pragma("unroll") for (int k = 0; k < 2; ++k) dst[m][k] = *(const LAS bf16x8*)(lds + PG8_SA(b, h) + aoff + m * 2048 + k * 1024); } while (0)
; #define PG8_LDB(dst, b, h) do { _Pragma("unroll") for (int n = 0; n < 2; ++n) _Pragma("unroll") for (int k = 0; k < 2; ++k) dst[n][k] = *(const LAS bf16x8*)(lds + PG8_SB(b, h) + boff + n * 2048 + k * 1024); } while (0)
; #define PG8_MMA(ai, bj, At, Bt) do { __builtin_amdgcn_s_setprio(1); _Pragma("unroll") for (int m = 0; m < 4; ++m) _Pragma("unroll") for (int n = 0; n < 2; ++n) _Pragma("unroll") for (int k = 0; k < 2; ++k) \
;         acc[ai][bj][m][n] = __builtin_amdgcn_mfma_f32_16x16x32_bf16(Bt[n][k], At[m][k], acc[ai][bj][m][n], 0, 0, 0); __builtin_amdgcn_s_setprio(0); } while (0)
; #define PG8_WAIT_V(n) asm volatile("s_waitcnt vmcnt(" #n ")" ::: "memory")
; #define PG8_WAIT_L(n) asm volatile("s_waitcnt lgkmcnt(" #n ")" ::: "memory")
; #define PG8_BAR __builtin_amdgcn_s_barrier()
; #define PG8_SCHED __builtin_amdgcn_sched_barrier(0)
; template <class Epi, class Sched, bool ALIGN_EPI = false, bool SP2 = false>
; __device__ __forceinline__ void gemm_phase(LAS unsigned char* lds, const Gemm g, const Sched& S, const Epi& E) {
;     ...
;             PG8_LDB(B0, 1, 0); PG8_LDB(B1, 1, 1); PG8_SCHED; PG8_LDA(At, 1, 0); PG8_STAGE(PG8_SA(0, 1), a2 + hstep, voffA);
;             PG8_WAIT_V(8); PG8_WAIT_L(0); PG8_BAR; PG8_MMA(0, 0, At, B0); PG8_MMA(0, 1, At, B1); PG8_BAR; PG8_SCHED;
;             PG8_LDA(At, 1, 1); PG8_STAGE(PG8_SB(1, 0), b3, voffB); PG8_STAGE(PG8_SB(1, 1), b3 + hstepB, voffB); PG8_STAGE(PG8_SA(1, 0), a3, voffA);
;             PG8_WAIT_V(8); PG8_WAIT_L(0); PG8_BAR; PG8_MMA(1, 0, At, B0); PG8_MMA(1, 1, At, B1); PG8_BAR; PG8_SCHED;
;     ...
;         if constexpr (ALIGN_EPI) { if (wr == 0) PG8_BAR; }
	s_add_i32 s22, 0, 0x18000
	s_add_i32 s23, 0, 0x1c000
	v_add_u32_e32 v78, s22, v170
	v_add_u32_e32 v168, s23, v170
	ds_read_b128 v[66:69], v78
	ds_read_b128 v[70:73], v78 offset:1024
	ds_read_b128 v[74:77], v78 offset:2048
	ds_read_b128 v[78:81], v78 offset:3072
	ds_read_b128 v[162:165], v168
	ds_read_b128 v[182:185], v168 offset:1024
	ds_read_b128 v[186:189], v168 offset:2048
	ds_read_b128 v[190:193], v168 offset:3072
	s_add_u32 s20, s52, 0x80000
	s_addc_u32 s21, s53, 0
	s_mov_b32 m0, s35
	ds_read_b128 v[194:197], v176 offset:32768
	ds_read_b128 v[198:201], v176 offset:33792
	ds_read_b128 v[202:205], v176 offset:34816
	ds_read_b128 v[206:209], v176 offset:35840
	ds_read_b128 v[210:213], v176 offset:36864
	ds_read_b128 v[214:217], v176 offset:37888
	ds_read_b128 v[218:221], v176 offset:38912
	ds_read_b128 v[222:225], v176 offset:39936
	global_load_lds_dwordx4 v152, s[20:21]
	s_mov_b32 m0, s36
	s_nop 0
	global_load_lds_dwordx4 v148, s[20:21]
	s_waitcnt vmcnt(8)
	s_waitcnt lgkmcnt(0)
	s_barrier
	s_waitcnt lgkmcnt(0)
	v_mfma_f32_16x16x32_bf16 v[142:145], v[66:69], v[194:197], v[142:145]
	v_mfma_f32_16x16x32_bf16 v[138:141], v[74:77], v[194:197], v[138:141]
	v_mfma_f32_16x16x32_bf16 v[126:129], v[66:69], v[202:205], v[126:129]
	v_mfma_f32_16x16x32_bf16 v[122:125], v[74:77], v[202:205], v[122:125]
	v_mfma_f32_16x16x32_bf16 v[110:113], v[66:69], v[210:213], v[110:113]
	v_mfma_f32_16x16x32_bf16 v[106:109], v[74:77], v[210:213], v[106:109]
	v_mfma_f32_16x16x32_bf16 v[94:97], v[66:69], v[218:221], v[94:97]
	v_mfma_f32_16x16x32_bf16 v[90:93], v[74:77], v[218:221], v[90:93]
	v_mfma_f32_16x16x32_bf16 v[142:145], v[70:73], v[198:201], v[142:145]
	v_mfma_f32_16x16x32_bf16 v[138:141], v[78:81], v[198:201], v[138:141]
	v_mfma_f32_16x16x32_bf16 v[126:129], v[70:73], v[206:209], v[126:129]
	v_mfma_f32_16x16x32_bf16 v[122:125], v[78:81], v[206:209], v[122:125]
	v_mfma_f32_16x16x32_bf16 v[110:113], v[70:73], v[214:217], v[110:113]
	v_mfma_f32_16x16x32_bf16 v[106:109], v[78:81], v[214:217], v[106:109]
	v_mfma_f32_16x16x32_bf16 v[94:97], v[70:73], v[222:225], v[94:97]
	v_mfma_f32_16x16x32_bf16 v[90:93], v[78:81], v[222:225], v[90:93]
	v_mfma_f32_16x16x32_bf16 v[134:137], v[162:165], v[194:197], v[134:137]
	v_mfma_f32_16x16x32_bf16 v[130:133], v[186:189], v[194:197], v[130:133]
	v_mfma_f32_16x16x32_bf16 v[118:121], v[162:165], v[202:205], v[118:121]
	v_mfma_f32_16x16x32_bf16 v[114:117], v[186:189], v[202:205], v[114:117]
	v_mfma_f32_16x16x32_bf16 v[102:105], v[162:165], v[210:213], v[102:105]
	v_mfma_f32_16x16x32_bf16 v[98:101], v[186:189], v[210:213], v[98:101]
	v_mfma_f32_16x16x32_bf16 v[86:89], v[162:165], v[218:221], v[86:89]
	v_mfma_f32_16x16x32_bf16 v[82:85], v[186:189], v[218:221], v[82:85]
	v_mfma_f32_16x16x32_bf16 v[134:137], v[182:185], v[198:201], v[134:137]
	v_mfma_f32_16x16x32_bf16 v[130:133], v[190:193], v[198:201], v[130:133]
	v_mfma_f32_16x16x32_bf16 v[118:121], v[182:185], v[206:209], v[118:121]
	v_mfma_f32_16x16x32_bf16 v[114:117], v[190:193], v[206:209], v[114:117]
	v_mfma_f32_16x16x32_bf16 v[102:105], v[182:185], v[214:217], v[102:105]
	v_mfma_f32_16x16x32_bf16 v[98:101], v[190:193], v[214:217], v[98:101]
	v_mfma_f32_16x16x32_bf16 v[86:89], v[182:185], v[222:225], v[86:89]
	v_mfma_f32_16x16x32_bf16 v[82:85], v[190:193], v[222:225], v[82:85]
	s_barrier
	s_add_i32 s20, s22, s27
	v_lshl_add_u64 v[166:167], v[166:167], 0, s[10:11]
	s_mov_b32 m0, s20
	ds_read_b128 v[194:197], v176 offset:49152
	ds_read_b128 v[198:201], v176 offset:50176
	ds_read_b128 v[202:205], v176 offset:51200
	ds_read_b128 v[206:209], v176 offset:52224
	ds_read_b128 v[210:213], v176 offset:53248
	ds_read_b128 v[214:217], v176 offset:54272
	ds_read_b128 v[218:221], v176 offset:55296
	ds_read_b128 v[222:225], v176 offset:56320
	global_load_lds_dwordx4 v[166:167], off
	s_add_i32 m0, s20, 0x2000
	s_add_u32 s20, s50, 0x80080
	v_lshl_add_u64 v[166:167], v[226:227], 0, s[10:11]
	s_addc_u32 s21, s51, 0
	s_add_i32 s22, s23, s27
	global_load_lds_dwordx4 v[166:167], off
	s_mov_b32 m0, s22
	s_nop 0
	global_load_lds_dwordx4 v150, s[20:21]
	s_add_i32 m0, s22, 0x2000
	s_nop 0
	global_load_lds_dwordx4 v146, s[20:21]
	v_lshl_add_u64 v[166:167], v[228:229], 0, s[10:11]
	s_mov_b32 m0, s55
	s_nop 0
	global_load_lds_dwordx4 v[166:167], off
	v_lshl_add_u64 v[166:167], v[230:231], 0, s[10:11]
	s_mov_b32 m0, s56
	s_nop 0
	global_load_lds_dwordx4 v[166:167], off
	s_waitcnt vmcnt(8)
	s_waitcnt lgkmcnt(0)
	s_barrier
	s_waitcnt lgkmcnt(0)
	v_mfma_f32_16x16x32_bf16 v[62:65], v[66:69], v[194:197], v[62:65]
	v_mfma_f32_16x16x32_bf16 v[58:61], v[74:77], v[194:197], v[58:61]
	v_mfma_f32_16x16x32_bf16 v[46:49], v[66:69], v[202:205], v[46:49]
	v_mfma_f32_16x16x32_bf16 v[42:45], v[74:77], v[202:205], v[42:45]
	v_mfma_f32_16x16x32_bf16 v[30:33], v[66:69], v[210:213], v[30:33]
	v_mfma_f32_16x16x32_bf16 v[26:29], v[74:77], v[210:213], v[26:29]
	v_mfma_f32_16x16x32_bf16 v[14:17], v[66:69], v[218:221], v[14:17]
	v_mfma_f32_16x16x32_bf16 v[10:13], v[74:77], v[218:221], v[10:13]
	v_mfma_f32_16x16x32_bf16 v[62:65], v[70:73], v[198:201], v[62:65]
	v_mfma_f32_16x16x32_bf16 v[58:61], v[78:81], v[198:201], v[58:61]
	v_mfma_f32_16x16x32_bf16 v[46:49], v[70:73], v[206:209], v[46:49]
	v_mfma_f32_16x16x32_bf16 v[42:45], v[78:81], v[206:209], v[42:45]
	v_mfma_f32_16x16x32_bf16 v[30:33], v[70:73], v[214:217], v[30:33]
	v_mfma_f32_16x16x32_bf16 v[26:29], v[78:81], v[214:217], v[26:29]
	v_mfma_f32_16x16x32_bf16 v[14:17], v[70:73], v[222:225], v[14:17]
	v_mfma_f32_16x16x32_bf16 v[10:13], v[78:81], v[222:225], v[10:13]
	v_mfma_f32_16x16x32_bf16 v[54:57], v[162:165], v[194:197], v[54:57]
	v_mfma_f32_16x16x32_bf16 v[50:53], v[186:189], v[194:197], v[50:53]
	v_mfma_f32_16x16x32_bf16 v[38:41], v[162:165], v[202:205], v[38:41]
	v_mfma_f32_16x16x32_bf16 v[34:37], v[186:189], v[202:205], v[34:37]
	v_mfma_f32_16x16x32_bf16 v[22:25], v[162:165], v[210:213], v[22:25]
	v_mfma_f32_16x16x32_bf16 v[18:21], v[186:189], v[210:213], v[18:21]
	v_mfma_f32_16x16x32_bf16 v[6:9], v[162:165], v[218:221], v[6:9]
	v_mfma_f32_16x16x32_bf16 v[2:5], v[186:189], v[218:221], v[2:5]
	v_mfma_f32_16x16x32_bf16 v[54:57], v[182:185], v[198:201], v[54:57]
	v_mfma_f32_16x16x32_bf16 v[50:53], v[190:193], v[198:201], v[50:53]
	v_mfma_f32_16x16x32_bf16 v[38:41], v[182:185], v[206:209], v[38:41]
	v_mfma_f32_16x16x32_bf16 v[34:37], v[190:193], v[206:209], v[34:37]
	v_mfma_f32_16x16x32_bf16 v[22:25], v[182:185], v[214:217], v[22:25]
	v_mfma_f32_16x16x32_bf16 v[18:21], v[190:193], v[214:217], v[18:21]
	v_mfma_f32_16x16x32_bf16 v[6:9], v[182:185], v[222:225], v[6:9]
	v_mfma_f32_16x16x32_bf16 v[2:5], v[190:193], v[222:225], v[2:5]
	s_barrier
	s_add_i32 s19, s19, 2
	s_add_u32 s16, s16, 0x100
	s_addc_u32 s17, s17, 0
	s_add_u32 s15, s15, 0x100
	s_addc_u32 s18, s18, 0
	s_cmp_gt_u32 s19, 29
	s_cbranch_scc0 .LBB0_188
	s_setprio 0
	s_and_b64 vcc, exec, s[40:41]
	s_cbranch_vccz .LBB0_191
	s_barrier

; #define PG8_STAGE(bufoff, gbase, voff) do { _Pragma("unroll") for (int _i = 0; _i < 2; ++_i) \
;         __builtin_amdgcn_global_load_lds((const unsigned*)((const char*)(gbase) + (voff)[_i]), (LAS unsigned*)(lds + (bufoff) + ldsw + _i * 8192), 16, 0, 0); } while (0)
; #define PG8_LDA(dst, b, h) do { _Pragma("unroll") for (int m = 0; m < 4; ++m) _Pragma("unroll") for (int k = 0; k < 2; ++k) dst[m][k] = *(const LAS bf16x8*)(lds + PG8_SA(b, h) + aoff + m * 2048 + k * 1024); } while (0)
; #define PG8_LDB(dst, b, h) do { _Pragma("unroll") for (int n = 0; n < 2; ++n) _Pragma("unroll") for (int k = 0; k < 2; ++k) dst[n][k] = *(const LAS bf16x8*)(lds + PG8_SB(b, h) + boff + n * 2048 + k * 1024); } while (0)
; #define PG8_MMA(ai, bj, At, Bt) do { __builtin_amdgcn_s_setprio(1); _Pragma("unroll") for (int m = 0; m < 4; ++m) _Pragma("unroll") for (int n = 0; n < 2; ++n) _Pragma("unroll") for (int k = 0; k < 2; ++k) \
;         acc[ai][bj][m][n] = __builtin_amdgcn_mfma_f32_16x16x32_bf16(Bt[n][k], At[m][k], acc[ai][bj][m][n], 0, 0, 0); __builtin_amdgcn_s_setprio(0); } while (0)
; #define PG8_WAIT_V(n) asm volatile("s_waitcnt vmcnt(" #n ")" ::: "memory")
; #define PG8_WAIT_L(n) asm volatile("s_waitcnt lgkmcnt(" #n ")" ::: "memory")
; template <class Epi, class Sched, bool ALIGN_EPI = false, bool SP2 = false>
; __device__ __forceinline__ void gemm_phase(LAS unsigned char* lds, const Gemm g, const Sched& S, const Epi& E) {
;     ...
;         for (int t = 0; t < nt; t += 2) {
;             const bool last = (t == nt - 2);
;             const char* a1 = cA + (size_t)(t + 1) * kstep;
;             const char* a2 = last ? nA : cA + (size_t)(t + 2) * kstep; const char* b2 = last ? nB : cB + (size_t)(t + 2) * kstep;
;             const char* a3 = a2 + kstep; const char* b3 = b2 + kstep;
;             if (last && has_next) S.a_ready(nxt);
;             if constexpr (SP2) {
;             PG8_LDB(B0, 0, 0); PG8_LDB(B1, 0, 1); PG8_SCHED; PG8_LDA(At, 0, 0); PG8_STAGE(PG8_SA(1, 1), a1 + hstep, voffA);
;             PG8_WAIT_V(8); PG8_WAIT_L(0); PG8_BAR; PG8_MMA(0, 0, At, B0); PG8_MMA(0, 1, At, B1); PG8_BAR; PG8_SCHED;
;             PG8_LDA(At, 0, 1); PG8_STAGE(PG8_SB(0, 0), b2, voffB); PG8_STAGE(PG8_SB(0, 1), b2 + hstepB, voffB); PG8_STAGE(PG8_SA(0, 0), a2, voffA);
;             PG8_WAIT_V(8); PG8_WAIT_L(0); PG8_BAR; PG8_MMA(1, 0, At, B0); PG8_MMA(1, 1, At, B1); PG8_BAR; PG8_SCHED;
.Lprio_317:
	ds_read_b128 v[130:133], v196
	ds_read_b128 v[134:137], v196 offset:1024
	ds_read_b128 v[138:141], v196 offset:2048
	ds_read_b128 v[142:145], v196 offset:3072
	ds_read_b128 v[166:169], v197
	ds_read_b128 v[170:173], v197 offset:1024
	ds_read_b128 v[174:177], v197 offset:2048
	ds_read_b128 v[178:181], v197 offset:3072
	s_add_u32 s54, s16, 0x100
	s_addc_u32 s55, s17, 0
	s_cmpk_eq_i32 s13, 0x54
	s_cselect_b32 s59, s3, s55
	s_cselect_b32 s58, s2, s54
	s_cselect_b32 s57, s53, s12
	s_cselect_b32 s56, s52, s5
	v_lshl_add_u64 v[190:191], s[16:17], 0, v[158:159]
	s_add_i32 m0, s29, 0xc000
	ds_read_b128 v[182:185], v198
	ds_read_b128 v[186:189], v198 offset:1024
	ds_read_b128 v[202:205], v198 offset:2048
	ds_read_b128 v[206:209], v198 offset:3072
	ds_read_b128 v[210:213], v198 offset:4096
	ds_read_b128 v[214:217], v198 offset:5120
	ds_read_b128 v[218:221], v198 offset:6144
	ds_read_b128 v[222:225], v198 offset:7168
	global_load_lds_dwordx4 v[190:191], off
	v_lshl_add_u64 v[190:191], s[16:17], 0, v[160:161]
	s_add_i32 m0, s29, 0xe000
	s_nop 0
	global_load_lds_dwordx4 v[190:191], off
	s_waitcnt lgkmcnt(0)
	s_barrier
	s_waitcnt lgkmcnt(0)
	v_mfma_f32_16x16x32_bf16 v[126:129], v[130:133], v[182:185], 0
	v_mfma_f32_16x16x32_bf16 v[122:125], v[138:141], v[182:185], 0
	v_mfma_f32_16x16x32_bf16 v[110:113], v[130:133], v[202:205], 0
	v_mfma_f32_16x16x32_bf16 v[106:109], v[138:141], v[202:205], 0
	v_mfma_f32_16x16x32_bf16 v[94:97], v[130:133], v[210:213], 0
	v_mfma_f32_16x16x32_bf16 v[90:93], v[138:141], v[210:213], 0
	v_mfma_f32_16x16x32_bf16 v[78:81], v[130:133], v[218:221], 0
	v_mfma_f32_16x16x32_bf16 v[74:77], v[138:141], v[218:221], 0
	v_mfma_f32_16x16x32_bf16 v[126:129], v[134:137], v[186:189], v[126:129]
	v_mfma_f32_16x16x32_bf16 v[122:125], v[142:145], v[186:189], v[122:125]
	v_mfma_f32_16x16x32_bf16 v[110:113], v[134:137], v[206:209], v[110:113]
	v_mfma_f32_16x16x32_bf16 v[106:109], v[142:145], v[206:209], v[106:109]
	v_mfma_f32_16x16x32_bf16 v[94:97], v[134:137], v[214:217], v[94:97]
	v_mfma_f32_16x16x32_bf16 v[90:93], v[142:145], v[214:217], v[90:93]
	v_mfma_f32_16x16x32_bf16 v[78:81], v[134:137], v[222:225], v[78:81]
	v_mfma_f32_16x16x32_bf16 v[74:77], v[142:145], v[222:225], v[74:77]
	v_mfma_f32_16x16x32_bf16 v[118:121], v[166:169], v[182:185], 0
	v_mfma_f32_16x16x32_bf16 v[114:117], v[174:177], v[182:185], 0
	v_mfma_f32_16x16x32_bf16 v[102:105], v[166:169], v[202:205], 0
	v_mfma_f32_16x16x32_bf16 v[98:101], v[174:177], v[202:205], 0
	v_mfma_f32_16x16x32_bf16 v[86:89], v[166:169], v[210:213], 0
	v_mfma_f32_16x16x32_bf16 v[82:85], v[174:177], v[210:213], 0
	v_mfma_f32_16x16x32_bf16 v[70:73], v[166:169], v[218:221], 0
	v_mfma_f32_16x16x32_bf16 v[66:69], v[174:177], v[218:221], 0
	v_mfma_f32_16x16x32_bf16 v[118:121], v[170:173], v[186:189], v[118:121]
	v_mfma_f32_16x16x32_bf16 v[114:117], v[178:181], v[186:189], v[114:117]
	v_mfma_f32_16x16x32_bf16 v[102:105], v[170:173], v[206:209], v[102:105]
	v_mfma_f32_16x16x32_bf16 v[98:101], v[178:181], v[206:209], v[98:101]
	v_mfma_f32_16x16x32_bf16 v[86:89], v[170:173], v[214:217], v[86:89]
	v_mfma_f32_16x16x32_bf16 v[82:85], v[178:181], v[214:217], v[82:85]
	v_mfma_f32_16x16x32_bf16 v[70:73], v[170:173], v[222:225], v[70:73]
	v_mfma_f32_16x16x32_bf16 v[66:69], v[178:181], v[222:225], v[66:69]
	s_barrier
	s_add_i32 s14, s64, s28
	v_lshl_add_u64 v[190:191], s[56:57], 0, v[148:149]
	s_mov_b32 m0, s14
	ds_read_b128 v[182:185], v198 offset:16384
	ds_read_b128 v[186:189], v198 offset:17408
	ds_read_b128 v[202:205], v198 offset:18432
	ds_read_b128 v[206:209], v198 offset:19456
	ds_read_b128 v[210:213], v198 offset:20480
	ds_read_b128 v[214:217], v198 offset:21504
	ds_read_b128 v[218:221], v198 offset:22528
	ds_read_b128 v[222:225], v198 offset:23552
	global_load_lds_dwordx4 v[190:191], off
	s_add_i32 m0, s14, 0x2000
	s_add_u32 s14, s56, 0x58000
	v_lshl_add_u64 v[226:227], s[56:57], 0, v[152:153]
	s_addc_u32 s15, s57, 0
	s_add_i32 s16, s65, s28
	global_load_lds_dwordx4 v[226:227], off
	s_mov_b32 m0, s16
	v_lshl_add_u64 v[230:231], s[58:59], 0, v[150:151]
	global_load_lds_dwordx4 v148, s[14:15]
	s_add_i32 m0, s16, 0x2000
	s_nop 0
	global_load_lds_dwordx4 v152, s[14:15]
	v_lshl_add_u64 v[228:229], s[58:59], 0, v[146:147]
	s_mov_b32 m0, s29
	s_nop 0
	global_load_lds_dwordx4 v[228:229], off
	s_mov_b32 m0, s30
	s_nop 0
	global_load_lds_dwordx4 v[230:231], off
	s_waitcnt lgkmcnt(0)
	s_barrier
	s_waitcnt lgkmcnt(0)
	v_mfma_f32_16x16x32_bf16 v[62:65], v[130:133], v[182:185], 0
	v_mfma_f32_16x16x32_bf16 v[58:61], v[138:141], v[182:185], 0
	v_mfma_f32_16x16x32_bf16 v[46:49], v[130:133], v[202:205], 0
	v_mfma_f32_16x16x32_bf16 v[42:45], v[138:141], v[202:205], 0
	v_mfma_f32_16x16x32_bf16 v[30:33], v[130:133], v[210:213], 0
	v_mfma_f32_16x16x32_bf16 v[26:29], v[138:141], v[210:213], 0
	v_mfma_f32_16x16x32_bf16 v[14:17], v[130:133], v[218:221], 0
	v_mfma_f32_16x16x32_bf16 v[10:13], v[138:141], v[218:221], 0
	v_mfma_f32_16x16x32_bf16 v[62:65], v[134:137], v[186:189], v[62:65]
	v_mfma_f32_16x16x32_bf16 v[58:61], v[142:145], v[186:189], v[58:61]
	v_mfma_f32_16x16x32_bf16 v[46:49], v[134:137], v[206:209], v[46:49]
	v_mfma_f32_16x16x32_bf16 v[42:45], v[142:145], v[206:209], v[42:45]
	v_mfma_f32_16x16x32_bf16 v[30:33], v[134:137], v[214:217], v[30:33]
	v_mfma_f32_16x16x32_bf16 v[26:29], v[142:145], v[214:217], v[26:29]
	v_mfma_f32_16x16x32_bf16 v[14:17], v[134:137], v[222:225], v[14:17]
	v_mfma_f32_16x16x32_bf16 v[10:13], v[142:145], v[222:225], v[10:13]
	v_mfma_f32_16x16x32_bf16 v[54:57], v[166:169], v[182:185], 0
	v_mfma_f32_16x16x32_bf16 v[50:53], v[174:177], v[182:185], 0
	v_mfma_f32_16x16x32_bf16 v[38:41], v[166:169], v[202:205], 0
	v_mfma_f32_16x16x32_bf16 v[34:37], v[174:177], v[202:205], 0
	v_mfma_f32_16x16x32_bf16 v[22:25], v[166:169], v[210:213], 0
	v_mfma_f32_16x16x32_bf16 v[18:21], v[174:177], v[210:213], 0
	v_mfma_f32_16x16x32_bf16 v[6:9], v[166:169], v[218:221], 0
	v_mfma_f32_16x16x32_bf16 v[2:5], v[174:177], v[218:221], 0
	v_mfma_f32_16x16x32_bf16 v[54:57], v[170:173], v[186:189], v[54:57]
	v_mfma_f32_16x16x32_bf16 v[50:53], v[178:181], v[186:189], v[50:53]
	v_mfma_f32_16x16x32_bf16 v[38:41], v[170:173], v[206:209], v[38:41]
	v_mfma_f32_16x16x32_bf16 v[34:37], v[178:181], v[206:209], v[34:37]
	v_mfma_f32_16x16x32_bf16 v[22:25], v[170:173], v[214:217], v[22:25]
	v_mfma_f32_16x16x32_bf16 v[18:21], v[178:181], v[214:217], v[18:21]
	v_mfma_f32_16x16x32_bf16 v[6:9], v[170:173], v[222:225], v[6:9]
	v_mfma_f32_16x16x32_bf16 v[2:5], v[178:181], v[222:225], v[2:5]
	s_barrier
; #define PG8_STAGE(bufoff, gbase, voff) do { _Pragma("unroll") for (int _i = 0; _i < 2; ++_i) \
;         __builtin_amdgcn_global_load_lds((const unsigned*)((const char*)(gbase) + (voff)[_i]), (LAS unsigned*)(lds + (bufoff) + ldsw + _i * 8192), 16, 0, 0); } while (0)
; #define PG8_LDA(dst, b, h) do { _Pragma("unroll") for (int m = 0; m < 4; ++m) _Pragma("unroll") for (int k = 0; k < 2; ++k) dst[m][k] = *(const LAS bf16x8*)(lds + PG8_SA(b, h) + aoff + m * 2048 + k * 1024); } while (0)
; #define PG8_LDB(dst, b, h) do { _Pragma("unroll") for (int n = 0; n < 2; ++n) _Pragma("unroll") for (int k = 0; k < 2; ++k) dst[n][k] = *(const LAS bf16x8*)(lds + PG8_SB(b, h) + boff + n * 2048 + k * 1024); } while (0)
; #define PG8_MMA(ai, bj, At, Bt) do { __builtin_amdgcn_s_setprio(1); _Pragma("unroll") for (int m = 0; m < 4; ++m) _Pragma("unroll") for (int n = 0; n < 2; ++n) _Pragma("unroll") for (int k = 0; k < 2; ++k) \
;         acc[ai][bj][m][n] = __builtin_amdgcn_mfma_f32_16x16x32_bf16(Bt[n][k], At[m][k], acc[ai][bj][m][n], 0, 0, 0); __builtin_amdgcn_s_setprio(0); } while (0)
; #define PG8_WAIT_V(n) asm volatile("s_waitcnt vmcnt(" #n ")" ::: "memory")
; #define PG8_WAIT_L(n) asm volatile("s_waitcnt lgkmcnt(" #n ")" ::: "memory")
; #define PG8_BAR __builtin_amdgcn_s_barrier()
; #define PG8_SCHED __builtin_amdgcn_sched_barrier(0)
; template <class Epi, class Sched, bool ALIGN_EPI = false, bool SP2 = false>
; __device__ __forceinline__ void gemm_phase(LAS unsigned char* lds, const Gemm g, const Sched& S, const Epi& E) {
;     ...
;             PG8_LDB(B0, 1, 0); PG8_LDB(B1, 1, 1); PG8_SCHED; PG8_LDA(At, 1, 0); PG8_STAGE(PG8_SA(0, 1), a2 + hstep, voffA);
;             PG8_WAIT_V(8); PG8_WAIT_L(0); PG8_BAR; PG8_MMA(0, 0, At, B0); PG8_MMA(0, 1, At, B1); PG8_BAR; PG8_SCHED;
;             PG8_LDA(At, 1, 1); PG8_STAGE(PG8_SB(1, 0), b3, voffB); PG8_STAGE(PG8_SB(1, 1), b3 + hstepB, voffB); PG8_STAGE(PG8_SA(1, 0), a3, voffA);
;             PG8_WAIT_V(8); PG8_WAIT_L(0); PG8_BAR; PG8_MMA(1, 0, At, B0); PG8_MMA(1, 1, At, B1); PG8_BAR; PG8_SCHED;
	s_add_i32 s16, 0, 0x18000
	s_add_i32 s17, 0, 0x1c000
	v_add_u32_e32 v142, s16, v1
	v_add_u32_e32 v154, s17, v1
	ds_read_b128 v[130:133], v142
	ds_read_b128 v[134:137], v142 offset:1024
	ds_read_b128 v[138:141], v142 offset:2048
	ds_read_b128 v[142:145], v142 offset:3072
	ds_read_b128 v[166:169], v154
	ds_read_b128 v[170:173], v154 offset:1024
	ds_read_b128 v[174:177], v154 offset:2048
	ds_read_b128 v[178:181], v154 offset:3072
	s_add_u32 s14, s58, 0x160000
	s_addc_u32 s15, s59, 0
	s_mov_b32 m0, s31
	ds_read_b128 v[182:185], v198 offset:32768
	ds_read_b128 v[186:189], v198 offset:33792
	ds_read_b128 v[202:205], v198 offset:34816
	ds_read_b128 v[206:209], v198 offset:35840
	ds_read_b128 v[210:213], v198 offset:36864
	ds_read_b128 v[214:217], v198 offset:37888
	ds_read_b128 v[218:221], v198 offset:38912
	ds_read_b128 v[222:225], v198 offset:39936
	global_load_lds_dwordx4 v146, s[14:15]
	s_mov_b32 m0, s33
	s_nop 0
	global_load_lds_dwordx4 v150, s[14:15]
	s_waitcnt vmcnt(8)
	s_waitcnt lgkmcnt(0)
	s_barrier
	s_waitcnt lgkmcnt(0)
	v_mfma_f32_16x16x32_bf16 v[126:129], v[130:133], v[182:185], v[126:129]
	v_mfma_f32_16x16x32_bf16 v[122:125], v[138:141], v[182:185], v[122:125]
	v_mfma_f32_16x16x32_bf16 v[110:113], v[130:133], v[202:205], v[110:113]
	v_mfma_f32_16x16x32_bf16 v[106:109], v[138:141], v[202:205], v[106:109]
	v_mfma_f32_16x16x32_bf16 v[94:97], v[130:133], v[210:213], v[94:97]
	v_mfma_f32_16x16x32_bf16 v[90:93], v[138:141], v[210:213], v[90:93]
	v_mfma_f32_16x16x32_bf16 v[78:81], v[130:133], v[218:221], v[78:81]
	v_mfma_f32_16x16x32_bf16 v[74:77], v[138:141], v[218:221], v[74:77]
	v_mfma_f32_16x16x32_bf16 v[126:129], v[134:137], v[186:189], v[126:129]
	v_mfma_f32_16x16x32_bf16 v[122:125], v[142:145], v[186:189], v[122:125]
	v_mfma_f32_16x16x32_bf16 v[110:113], v[134:137], v[206:209], v[110:113]
	v_mfma_f32_16x16x32_bf16 v[106:109], v[142:145], v[206:209], v[106:109]
	v_mfma_f32_16x16x32_bf16 v[94:97], v[134:137], v[214:217], v[94:97]
	v_mfma_f32_16x16x32_bf16 v[90:93], v[142:145], v[214:217], v[90:93]
	v_mfma_f32_16x16x32_bf16 v[78:81], v[134:137], v[222:225], v[78:81]
	v_mfma_f32_16x16x32_bf16 v[74:77], v[142:145], v[222:225], v[74:77]
	v_mfma_f32_16x16x32_bf16 v[118:121], v[166:169], v[182:185], v[118:121]
	v_mfma_f32_16x16x32_bf16 v[114:117], v[174:177], v[182:185], v[114:117]
	v_mfma_f32_16x16x32_bf16 v[102:105], v[166:169], v[202:205], v[102:105]
	v_mfma_f32_16x16x32_bf16 v[98:101], v[174:177], v[202:205], v[98:101]
	v_mfma_f32_16x16x32_bf16 v[86:89], v[166:169], v[210:213], v[86:89]
	v_mfma_f32_16x16x32_bf16 v[82:85], v[174:177], v[210:213], v[82:85]
	v_mfma_f32_16x16x32_bf16 v[70:73], v[166:169], v[218:221], v[70:73]
	v_mfma_f32_16x16x32_bf16 v[66:69], v[174:177], v[218:221], v[66:69]
	v_mfma_f32_16x16x32_bf16 v[118:121], v[170:173], v[186:189], v[118:121]
	v_mfma_f32_16x16x32_bf16 v[114:117], v[178:181], v[186:189], v[114:117]
	v_mfma_f32_16x16x32_bf16 v[102:105], v[170:173], v[206:209], v[102:105]
	v_mfma_f32_16x16x32_bf16 v[98:101], v[178:181], v[206:209], v[98:101]
	v_mfma_f32_16x16x32_bf16 v[86:89], v[170:173], v[214:217], v[86:89]
	v_mfma_f32_16x16x32_bf16 v[82:85], v[178:181], v[214:217], v[82:85]
	v_mfma_f32_16x16x32_bf16 v[70:73], v[170:173], v[222:225], v[70:73]
	v_mfma_f32_16x16x32_bf16 v[66:69], v[178:181], v[222:225], v[66:69]
	s_barrier
	s_add_i32 s14, s16, s28
	v_lshl_add_u64 v[190:191], v[190:191], 0, s[48:49]
	s_mov_b32 m0, s14
	ds_read_b128 v[182:185], v198 offset:49152
	ds_read_b128 v[186:189], v198 offset:50176
	ds_read_b128 v[202:205], v198 offset:51200
	ds_read_b128 v[206:209], v198 offset:52224
	ds_read_b128 v[210:213], v198 offset:53248
	ds_read_b128 v[214:217], v198 offset:54272
	ds_read_b128 v[218:221], v198 offset:55296
	ds_read_b128 v[222:225], v198 offset:56320
	global_load_lds_dwordx4 v[190:191], off
	s_add_i32 m0, s14, 0x2000
	s_add_u32 s14, s56, 0x58080
	v_lshl_add_u64 v[190:191], v[226:227], 0, s[48:49]
	s_addc_u32 s15, s57, 0
	s_add_i32 s16, s17, s28
	global_load_lds_dwordx4 v[190:191], off
	s_mov_b32 m0, s16
	s_nop 0
	global_load_lds_dwordx4 v148, s[14:15]
	s_add_i32 m0, s16, 0x2000
	s_nop 0
	global_load_lds_dwordx4 v152, s[14:15]
	v_lshl_add_u64 v[190:191], v[228:229], 0, s[48:49]
	s_mov_b32 m0, s61
	s_nop 0
	global_load_lds_dwordx4 v[190:191], off
	v_lshl_add_u64 v[190:191], v[230:231], 0, s[48:49]
	s_mov_b32 m0, s62
	s_nop 0
	global_load_lds_dwordx4 v[190:191], off
	s_waitcnt vmcnt(8)
	s_waitcnt lgkmcnt(0)
	s_barrier
	s_waitcnt lgkmcnt(0)
	v_mfma_f32_16x16x32_bf16 v[62:65], v[130:133], v[182:185], v[62:65]
	v_mfma_f32_16x16x32_bf16 v[58:61], v[138:141], v[182:185], v[58:61]
	v_mfma_f32_16x16x32_bf16 v[46:49], v[130:133], v[202:205], v[46:49]
	v_mfma_f32_16x16x32_bf16 v[42:45], v[138:141], v[202:205], v[42:45]
	v_mfma_f32_16x16x32_bf16 v[30:33], v[130:133], v[210:213], v[30:33]
	v_mfma_f32_16x16x32_bf16 v[26:29], v[138:141], v[210:213], v[26:29]
	v_mfma_f32_16x16x32_bf16 v[14:17], v[130:133], v[218:221], v[14:17]
	v_mfma_f32_16x16x32_bf16 v[10:13], v[138:141], v[218:221], v[10:13]
	v_mfma_f32_16x16x32_bf16 v[62:65], v[134:137], v[186:189], v[62:65]
	v_mfma_f32_16x16x32_bf16 v[58:61], v[142:145], v[186:189], v[58:61]
	v_mfma_f32_16x16x32_bf16 v[46:49], v[134:137], v[206:209], v[46:49]
	v_mfma_f32_16x16x32_bf16 v[42:45], v[142:145], v[206:209], v[42:45]
	v_mfma_f32_16x16x32_bf16 v[30:33], v[134:137], v[214:217], v[30:33]
	v_mfma_f32_16x16x32_bf16 v[26:29], v[142:145], v[214:217], v[26:29]
	v_mfma_f32_16x16x32_bf16 v[14:17], v[134:137], v[222:225], v[14:17]
	v_mfma_f32_16x16x32_bf16 v[10:13], v[142:145], v[222:225], v[10:13]
	v_mfma_f32_16x16x32_bf16 v[54:57], v[166:169], v[182:185], v[54:57]
	v_mfma_f32_16x16x32_bf16 v[50:53], v[174:177], v[182:185], v[50:53]
	v_mfma_f32_16x16x32_bf16 v[38:41], v[166:169], v[202:205], v[38:41]
	v_mfma_f32_16x16x32_bf16 v[34:37], v[174:177], v[202:205], v[34:37]
	v_mfma_f32_16x16x32_bf16 v[22:25], v[166:169], v[210:213], v[22:25]
	v_mfma_f32_16x16x32_bf16 v[18:21], v[174:177], v[210:213], v[18:21]
	v_mfma_f32_16x16x32_bf16 v[6:9], v[166:169], v[218:221], v[6:9]
	v_mfma_f32_16x16x32_bf16 v[2:5], v[174:177], v[218:221], v[2:5]
	v_mfma_f32_16x16x32_bf16 v[54:57], v[170:173], v[186:189], v[54:57]
	v_mfma_f32_16x16x32_bf16 v[50:53], v[178:181], v[186:189], v[50:53]
	v_mfma_f32_16x16x32_bf16 v[38:41], v[170:173], v[206:209], v[38:41]
	v_mfma_f32_16x16x32_bf16 v[34:37], v[178:181], v[206:209], v[34:37]
	v_mfma_f32_16x16x32_bf16 v[22:25], v[170:173], v[214:217], v[22:25]
	v_mfma_f32_16x16x32_bf16 v[18:21], v[178:181], v[214:217], v[18:21]
	v_mfma_f32_16x16x32_bf16 v[6:9], v[170:173], v[222:225], v[6:9]
	v_mfma_f32_16x16x32_bf16 v[2:5], v[178:181], v[222:225], v[2:5]
	s_barrier
	s_add_i32 s13, s13, 2
	s_add_u32 s5, s5, 0x100
	s_addc_u32 s12, s12, 0
	s_cmpk_gt_u32 s13, 0x55
	s_mov_b64 s[16:17], s[54:55]
; #define PG8_STAGE(bufoff, gbase, voff) do { _Pragma("unroll") for (int _i = 0; _i < 2; ++_i) \
;         __builtin_amdgcn_global_load_lds((const unsigned*)((const char*)(gbase) + (voff)[_i]), (LAS unsigned*)(lds + (bufoff) + ldsw + _i * 8192), 16, 0, 0); } while (0)
; #define PG8_LDA(dst, b, h) do { _Pragma("unroll") for (int m = 0; m < 4; ++m) _Pragma("unroll") for (int k = 0; k < 2; ++k) dst[m][k] = *(const LAS bf16x8*)(lds + PG8_SA(b, h) + aoff + m * 2048 + k * 1024); } while (0)
; #define PG8_LDB(dst, b, h) do { _Pragma("unroll") for (int n = 0; n < 2; ++n) _Pragma("unroll") for (int k = 0; k < 2; ++k) dst[n][k] = *(const LAS bf16x8*)(lds + PG8_SB(b, h) + boff + n * 2048 + k * 1024); } while (0)
; #define PG8_MMA(ai, bj, At, Bt) do { __builtin_amdgcn_s_setprio(1); _Pragma("unroll") for (int m = 0; m < 4; ++m) _Pragma("unroll") for (int n = 0; n < 2; ++n) _Pragma("unroll") for (int k = 0; k < 2; ++k) \
;         acc[ai][bj][m][n] = __builtin_amdgcn_mfma_f32_16x16x32_bf16(Bt[n][k], At[m][k], acc[ai][bj][m][n], 0, 0, 0); __builtin_amdgcn_s_setprio(0); } while (0)
; #define PG8_WAIT_V(n) asm volatile("s_waitcnt vmcnt(" #n ")" ::: "memory")
; #define PG8_WAIT_L(n) asm volatile("s_waitcnt lgkmcnt(" #n ")" ::: "memory")
; #define PG8_BAR __builtin_amdgcn_s_barrier()
; #define PG8_SCHED __builtin_amdgcn_sched_barrier(0)
; template <class Epi, class Sched, bool ALIGN_EPI = false, bool SP2 = false>
; __device__ __forceinline__ void gemm_phase(LAS unsigned char* lds, const Gemm g, const Sched& S, const Epi& E) {
;     ...
;             if constexpr (SP2) {
;             PG8_LDB(B0, 0, 0); PG8_LDB(B1, 0, 1); PG8_SCHED; PG8_LDA(At, 0, 0); PG8_STAGE(PG8_SA(1, 1), a1 + hstep, voffA);
;             PG8_WAIT_V(8); PG8_WAIT_L(0); PG8_BAR; PG8_MMA(0, 0, At, B0); PG8_MMA(0, 1, At, B1); PG8_BAR; PG8_SCHED;
;             PG8_LDA(At, 0, 1); PG8_STAGE(PG8_SB(0, 0), b2, voffB); PG8_STAGE(PG8_SB(0, 1), b2 + hstepB, voffB); PG8_STAGE(PG8_SA(0, 0), a2, voffA);
;             PG8_WAIT_V(8); PG8_WAIT_L(0); PG8_BAR; PG8_MMA(1, 0, At, B0); PG8_MMA(1, 1, At, B1); PG8_BAR; PG8_SCHED;
.LBB0_317:
	ds_read_b128 v[130:133], v196
	ds_read_b128 v[134:137], v196 offset:1024
	ds_read_b128 v[138:141], v196 offset:2048
	ds_read_b128 v[142:145], v196 offset:3072
	ds_read_b128 v[166:169], v197
	ds_read_b128 v[170:173], v197 offset:1024
	ds_read_b128 v[174:177], v197 offset:2048
	ds_read_b128 v[178:181], v197 offset:3072
	s_add_u32 s54, s16, 0x100
	s_addc_u32 s55, s17, 0
	s_cmpk_eq_i32 s13, 0x54
	s_cselect_b32 s59, s3, s55
	s_cselect_b32 s58, s2, s54
	s_cselect_b32 s57, s53, s12
	s_cselect_b32 s56, s52, s5
	v_lshl_add_u64 v[190:191], s[16:17], 0, v[158:159]
	s_add_i32 m0, s29, 0xc000
	ds_read_b128 v[182:185], v198
	ds_read_b128 v[186:189], v198 offset:1024
	ds_read_b128 v[202:205], v198 offset:2048
	ds_read_b128 v[206:209], v198 offset:3072
	ds_read_b128 v[210:213], v198 offset:4096
	ds_read_b128 v[214:217], v198 offset:5120
	ds_read_b128 v[218:221], v198 offset:6144
	ds_read_b128 v[222:225], v198 offset:7168
	global_load_lds_dwordx4 v[190:191], off
	v_lshl_add_u64 v[190:191], s[16:17], 0, v[160:161]
	s_add_i32 m0, s29, 0xe000
	s_nop 0
	global_load_lds_dwordx4 v[190:191], off
	s_waitcnt vmcnt(8)
	s_waitcnt lgkmcnt(0)
	s_barrier
	s_waitcnt lgkmcnt(0)
	v_mfma_f32_16x16x32_bf16 v[126:129], v[130:133], v[182:185], v[126:129]
	v_mfma_f32_16x16x32_bf16 v[122:125], v[138:141], v[182:185], v[122:125]
	v_mfma_f32_16x16x32_bf16 v[110:113], v[130:133], v[202:205], v[110:113]
	v_mfma_f32_16x16x32_bf16 v[106:109], v[138:141], v[202:205], v[106:109]
	v_mfma_f32_16x16x32_bf16 v[94:97], v[130:133], v[210:213], v[94:97]
	v_mfma_f32_16x16x32_bf16 v[90:93], v[138:141], v[210:213], v[90:93]
	v_mfma_f32_16x16x32_bf16 v[78:81], v[130:133], v[218:221], v[78:81]
	v_mfma_f32_16x16x32_bf16 v[74:77], v[138:141], v[218:221], v[74:77]
	v_mfma_f32_16x16x32_bf16 v[126:129], v[134:137], v[186:189], v[126:129]
	v_mfma_f32_16x16x32_bf16 v[122:125], v[142:145], v[186:189], v[122:125]
	v_mfma_f32_16x16x32_bf16 v[110:113], v[134:137], v[206:209], v[110:113]
	v_mfma_f32_16x16x32_bf16 v[106:109], v[142:145], v[206:209], v[106:109]
	v_mfma_f32_16x16x32_bf16 v[94:97], v[134:137], v[214:217], v[94:97]
	v_mfma_f32_16x16x32_bf16 v[90:93], v[142:145], v[214:217], v[90:93]
	v_mfma_f32_16x16x32_bf16 v[78:81], v[134:137], v[222:225], v[78:81]
	v_mfma_f32_16x16x32_bf16 v[74:77], v[142:145], v[222:225], v[74:77]
	v_mfma_f32_16x16x32_bf16 v[118:121], v[166:169], v[182:185], v[118:121]
	v_mfma_f32_16x16x32_bf16 v[114:117], v[174:177], v[182:185], v[114:117]
	v_mfma_f32_16x16x32_bf16 v[102:105], v[166:169], v[202:205], v[102:105]
	v_mfma_f32_16x16x32_bf16 v[98:101], v[174:177], v[202:205], v[98:101]
	v_mfma_f32_16x16x32_bf16 v[86:89], v[166:169], v[210:213], v[86:89]
	v_mfma_f32_16x16x32_bf16 v[82:85], v[174:177], v[210:213], v[82:85]
	v_mfma_f32_16x16x32_bf16 v[70:73], v[166:169], v[218:221], v[70:73]
	v_mfma_f32_16x16x32_bf16 v[66:69], v[174:177], v[218:221], v[66:69]
	v_mfma_f32_16x16x32_bf16 v[118:121], v[170:173], v[186:189], v[118:121]
	v_mfma_f32_16x16x32_bf16 v[114:117], v[178:181], v[186:189], v[114:117]
	v_mfma_f32_16x16x32_bf16 v[102:105], v[170:173], v[206:209], v[102:105]
	v_mfma_f32_16x16x32_bf16 v[98:101], v[178:181], v[206:209], v[98:101]
	v_mfma_f32_16x16x32_bf16 v[86:89], v[170:173], v[214:217], v[86:89]
	v_mfma_f32_16x16x32_bf16 v[82:85], v[178:181], v[214:217], v[82:85]
	v_mfma_f32_16x16x32_bf16 v[70:73], v[170:173], v[222:225], v[70:73]
	v_mfma_f32_16x16x32_bf16 v[66:69], v[178:181], v[222:225], v[66:69]
	s_barrier
	s_add_i32 s14, s64, s28
	v_lshl_add_u64 v[190:191], s[56:57], 0, v[148:149]
	s_mov_b32 m0, s14
	ds_read_b128 v[182:185], v198 offset:16384
	ds_read_b128 v[186:189], v198 offset:17408
	ds_read_b128 v[202:205], v198 offset:18432
	ds_read_b128 v[206:209], v198 offset:19456
	ds_read_b128 v[210:213], v198 offset:20480
	ds_read_b128 v[214:217], v198 offset:21504
	ds_read_b128 v[218:221], v198 offset:22528
	ds_read_b128 v[222:225], v198 offset:23552
	global_load_lds_dwordx4 v[190:191], off
	s_add_i32 m0, s14, 0x2000
	s_add_u32 s14, s56, 0x58000
	v_lshl_add_u64 v[226:227], s[56:57], 0, v[152:153]
	s_addc_u32 s15, s57, 0
	s_add_i32 s16, s65, s28
	global_load_lds_dwordx4 v[226:227], off
	s_mov_b32 m0, s16
	v_lshl_add_u64 v[230:231], s[58:59], 0, v[150:151]
	global_load_lds_dwordx4 v148, s[14:15]
	s_add_i32 m0, s16, 0x2000
	s_nop 0
	global_load_lds_dwordx4 v152, s[14:15]
	v_lshl_add_u64 v[228:229], s[58:59], 0, v[146:147]
	s_mov_b32 m0, s29
	s_nop 0
	global_load_lds_dwordx4 v[228:229], off
	s_mov_b32 m0, s30
	s_nop 0
	global_load_lds_dwordx4 v[230:231], off
	s_waitcnt vmcnt(8)
	s_waitcnt lgkmcnt(0)
	s_barrier
; #define PG8_STAGE(bufoff, gbase, voff) do { _Pragma("unroll") for (int _i = 0; _i < 2; ++_i) \
;         __builtin_amdgcn_global_load_lds((const unsigned*)((const char*)(gbase) + (voff)[_i]), (LAS unsigned*)(lds + (bufoff) + ldsw + _i * 8192), 16, 0, 0); } while (0)
; #define PG8_LDA(dst, b, h) do { _Pragma("unroll") for (int m = 0; m < 4; ++m) _Pragma("unroll") for (int k = 0; k < 2; ++k) dst[m][k] = *(const LAS bf16x8*)(lds + PG8_SA(b, h) + aoff + m * 2048 + k * 1024); } while (0)
; #define PG8_LDB(dst, b, h) do { _Pragma("unroll") for (int n = 0; n < 2; ++n) _Pragma("unroll") for (int k = 0; k < 2; ++k) dst[n][k] = *(const LAS bf16x8*)(lds + PG8_SB(b, h) + boff + n * 2048 + k * 1024); } while (0)
; #define PG8_MMA(ai, bj, At, Bt) do { __builtin_amdgcn_s_setprio(1); _Pragma("unroll") for (int m = 0; m < 4; ++m) _Pragma("unroll") for (int n = 0; n < 2; ++n) _Pragma("unroll") for (int k = 0; k < 2; ++k) \
;         acc[ai][bj][m][n] = __builtin_amdgcn_mfma_f32_16x16x32_bf16(Bt[n][k], At[m][k], acc[ai][bj][m][n], 0, 0, 0); __builtin_amdgcn_s_setprio(0); } while (0)
; #define PG8_WAIT_V(n) asm volatile("s_waitcnt vmcnt(" #n ")" ::: "memory")
; #define PG8_WAIT_L(n) asm volatile("s_waitcnt lgkmcnt(" #n ")" ::: "memory")
; #define PG8_BAR __builtin_amdgcn_s_barrier()
; #define PG8_SCHED __builtin_amdgcn_sched_barrier(0)
; template <class Epi, class Sched, bool ALIGN_EPI = false, bool SP2 = false>
; __device__ __forceinline__ void gemm_phase(LAS unsigned char* lds, const Gemm g, const Sched& S, const Epi& E) {
;     ...
;             PG8_WAIT_V(8); PG8_WAIT_L(0); PG8_BAR; PG8_MMA(1, 0, At, B0); PG8_MMA(1, 1, At, B1); PG8_BAR; PG8_SCHED;
;             PG8_LDB(B0, 1, 0); PG8_LDB(B1, 1, 1); PG8_SCHED; PG8_LDA(At, 1, 0); PG8_STAGE(PG8_SA(0, 1), a2 + hstep, voffA);
;             PG8_WAIT_V(8); PG8_WAIT_L(0); PG8_BAR; PG8_MMA(0, 0, At, B0); PG8_MMA(0, 1, At, B1); PG8_BAR; PG8_SCHED;
	s_waitcnt lgkmcnt(0)
	v_mfma_f32_16x16x32_bf16 v[62:65], v[130:133], v[182:185], v[62:65]
	v_mfma_f32_16x16x32_bf16 v[58:61], v[138:141], v[182:185], v[58:61]
	v_mfma_f32_16x16x32_bf16 v[46:49], v[130:133], v[202:205], v[46:49]
	v_mfma_f32_16x16x32_bf16 v[42:45], v[138:141], v[202:205], v[42:45]
	v_mfma_f32_16x16x32_bf16 v[30:33], v[130:133], v[210:213], v[30:33]
	v_mfma_f32_16x16x32_bf16 v[26:29], v[138:141], v[210:213], v[26:29]
	v_mfma_f32_16x16x32_bf16 v[14:17], v[130:133], v[218:221], v[14:17]
	v_mfma_f32_16x16x32_bf16 v[10:13], v[138:141], v[218:221], v[10:13]
	v_mfma_f32_16x16x32_bf16 v[62:65], v[134:137], v[186:189], v[62:65]
	v_mfma_f32_16x16x32_bf16 v[58:61], v[142:145], v[186:189], v[58:61]
	v_mfma_f32_16x16x32_bf16 v[46:49], v[134:137], v[206:209], v[46:49]
	v_mfma_f32_16x16x32_bf16 v[42:45], v[142:145], v[206:209], v[42:45]
	v_mfma_f32_16x16x32_bf16 v[30:33], v[134:137], v[214:217], v[30:33]
	v_mfma_f32_16x16x32_bf16 v[26:29], v[142:145], v[214:217], v[26:29]
	v_mfma_f32_16x16x32_bf16 v[14:17], v[134:137], v[222:225], v[14:17]
	v_mfma_f32_16x16x32_bf16 v[10:13], v[142:145], v[222:225], v[10:13]
	v_mfma_f32_16x16x32_bf16 v[54:57], v[166:169], v[182:185], v[54:57]
	v_mfma_f32_16x16x32_bf16 v[50:53], v[174:177], v[182:185], v[50:53]
	v_mfma_f32_16x16x32_bf16 v[38:41], v[166:169], v[202:205], v[38:41]
	v_mfma_f32_16x16x32_bf16 v[34:37], v[174:177], v[202:205], v[34:37]
	v_mfma_f32_16x16x32_bf16 v[22:25], v[166:169], v[210:213], v[22:25]
	v_mfma_f32_16x16x32_bf16 v[18:21], v[174:177], v[210:213], v[18:21]
	v_mfma_f32_16x16x32_bf16 v[6:9], v[166:169], v[218:221], v[6:9]
	v_mfma_f32_16x16x32_bf16 v[2:5], v[174:177], v[218:221], v[2:5]
	v_mfma_f32_16x16x32_bf16 v[54:57], v[170:173], v[186:189], v[54:57]
	v_mfma_f32_16x16x32_bf16 v[50:53], v[178:181], v[186:189], v[50:53]
	v_mfma_f32_16x16x32_bf16 v[38:41], v[170:173], v[206:209], v[38:41]
	v_mfma_f32_16x16x32_bf16 v[34:37], v[178:181], v[206:209], v[34:37]
	v_mfma_f32_16x16x32_bf16 v[22:25], v[170:173], v[214:217], v[22:25]
	v_mfma_f32_16x16x32_bf16 v[18:21], v[178:181], v[214:217], v[18:21]
	v_mfma_f32_16x16x32_bf16 v[6:9], v[170:173], v[222:225], v[6:9]
	v_mfma_f32_16x16x32_bf16 v[2:5], v[178:181], v[222:225], v[2:5]
	s_barrier
	s_add_i32 s16, 0, 0x18000
	s_add_i32 s17, 0, 0x1c000
	v_add_u32_e32 v142, s16, v1
	v_add_u32_e32 v154, s17, v1
	ds_read_b128 v[130:133], v142
	ds_read_b128 v[134:137], v142 offset:1024
	ds_read_b128 v[138:141], v142 offset:2048
	ds_read_b128 v[142:145], v142 offset:3072
	ds_read_b128 v[166:169], v154
	ds_read_b128 v[170:173], v154 offset:1024
	ds_read_b128 v[174:177], v154 offset:2048
	ds_read_b128 v[178:181], v154 offset:3072
	s_add_u32 s14, s58, 0x160000
	s_addc_u32 s15, s59, 0
	s_mov_b32 m0, s31
	ds_read_b128 v[182:185], v198 offset:32768
	ds_read_b128 v[186:189], v198 offset:33792
	ds_read_b128 v[202:205], v198 offset:34816
	ds_read_b128 v[206:209], v198 offset:35840
	ds_read_b128 v[210:213], v198 offset:36864
	ds_read_b128 v[214:217], v198 offset:37888
	ds_read_b128 v[218:221], v198 offset:38912
	ds_read_b128 v[222:225], v198 offset:39936
	global_load_lds_dwordx4 v146, s[14:15]
	s_mov_b32 m0, s33
	s_nop 0
	global_load_lds_dwordx4 v150, s[14:15]
	s_waitcnt vmcnt(8)
	s_waitcnt lgkmcnt(0)
	s_barrier
	s_waitcnt lgkmcnt(0)
	v_mfma_f32_16x16x32_bf16 v[126:129], v[130:133], v[182:185], v[126:129]
	v_mfma_f32_16x16x32_bf16 v[122:125], v[138:141], v[182:185], v[122:125]
	v_mfma_f32_16x16x32_bf16 v[110:113], v[130:133], v[202:205], v[110:113]
	v_mfma_f32_16x16x32_bf16 v[106:109], v[138:141], v[202:205], v[106:109]
	v_mfma_f32_16x16x32_bf16 v[94:97], v[130:133], v[210:213], v[94:97]
	v_mfma_f32_16x16x32_bf16 v[90:93], v[138:141], v[210:213], v[90:93]
	v_mfma_f32_16x16x32_bf16 v[78:81], v[130:133], v[218:221], v[78:81]
	v_mfma_f32_16x16x32_bf16 v[74:77], v[138:141], v[218:221], v[74:77]
	v_mfma_f32_16x16x32_bf16 v[126:129], v[134:137], v[186:189], v[126:129]
	v_mfma_f32_16x16x32_bf16 v[122:125], v[142:145], v[186:189], v[122:125]
	v_mfma_f32_16x16x32_bf16 v[110:113], v[134:137], v[206:209], v[110:113]
	v_mfma_f32_16x16x32_bf16 v[106:109], v[142:145], v[206:209], v[106:109]
	v_mfma_f32_16x16x32_bf16 v[94:97], v[134:137], v[214:217], v[94:97]
	v_mfma_f32_16x16x32_bf16 v[90:93], v[142:145], v[214:217], v[90:93]
	v_mfma_f32_16x16x32_bf16 v[78:81], v[134:137], v[222:225], v[78:81]
	v_mfma_f32_16x16x32_bf16 v[74:77], v[142:145], v[222:225], v[74:77]
	v_mfma_f32_16x16x32_bf16 v[118:121], v[166:169], v[182:185], v[118:121]
	v_mfma_f32_16x16x32_bf16 v[114:117], v[174:177], v[182:185], v[114:117]
	v_mfma_f32_16x16x32_bf16 v[102:105], v[166:169], v[202:205], v[102:105]
	v_mfma_f32_16x16x32_bf16 v[98:101], v[174:177], v[202:205], v[98:101]
	v_mfma_f32_16x16x32_bf16 v[86:89], v[166:169], v[210:213], v[86:89]
	v_mfma_f32_16x16x32_bf16 v[82:85], v[174:177], v[210:213], v[82:85]
	v_mfma_f32_16x16x32_bf16 v[70:73], v[166:169], v[218:221], v[70:73]
	v_mfma_f32_16x16x32_bf16 v[66:69], v[174:177], v[218:221], v[66:69]
	v_mfma_f32_16x16x32_bf16 v[118:121], v[170:173], v[186:189], v[118:121]
	v_mfma_f32_16x16x32_bf16 v[114:117], v[178:181], v[186:189], v[114:117]
	v_mfma_f32_16x16x32_bf16 v[102:105], v[170:173], v[206:209], v[102:105]
	v_mfma_f32_16x16x32_bf16 v[98:101], v[178:181], v[206:209], v[98:101]
	v_mfma_f32_16x16x32_bf16 v[86:89], v[170:173], v[214:217], v[86:89]
	v_mfma_f32_16x16x32_bf16 v[82:85], v[178:181], v[214:217], v[82:85]
	v_mfma_f32_16x16x32_bf16 v[70:73], v[170:173], v[222:225], v[70:73]
	v_mfma_f32_16x16x32_bf16 v[66:69], v[178:181], v[222:225], v[66:69]
	s_barrier
; #define PG8_STAGE(bufoff, gbase, voff) do { _Pragma("unroll") for (int _i = 0; _i < 2; ++_i) \
;         __builtin_amdgcn_global_load_lds((const unsigned*)((const char*)(gbase) + (voff)[_i]), (LAS unsigned*)(lds + (bufoff) + ldsw + _i * 8192), 16, 0, 0); } while (0)
; #define PG8_LDA(dst, b, h) do { _Pragma("unroll") for (int m = 0; m < 4; ++m) _Pragma("unroll") for (int k = 0; k < 2; ++k) dst[m][k] = *(const LAS bf16x8*)(lds + PG8_SA(b, h) + aoff + m * 2048 + k * 1024); } while (0)
; #define PG8_MMA(ai, bj, At, Bt) do { __builtin_amdgcn_s_setprio(1); _Pragma("unroll") for (int m = 0; m < 4; ++m) _Pragma("unroll") for (int n = 0; n < 2; ++n) _Pragma("unroll") for (int k = 0; k < 2; ++k) \
;         acc[ai][bj][m][n] = __builtin_amdgcn_mfma_f32_16x16x32_bf16(Bt[n][k], At[m][k], acc[ai][bj][m][n], 0, 0, 0); __builtin_amdgcn_s_setprio(0); } while (0)
; #define PG8_WAIT_V(n) asm volatile("s_waitcnt vmcnt(" #n ")" ::: "memory")
; #define PG8_WAIT_L(n) asm volatile("s_waitcnt lgkmcnt(" #n ")" ::: "memory")
; #define PG8_BAR __builtin_amdgcn_s_barrier()
; #define PG8_SCHED __builtin_amdgcn_sched_barrier(0)
; template <class Epi, class Sched, bool ALIGN_EPI = false, bool SP2 = false>
; __device__ __forceinline__ void gemm_phase(LAS unsigned char* lds, const Gemm g, const Sched& S, const Epi& E) {
;     ...
;             PG8_LDA(At, 1, 1); PG8_STAGE(PG8_SB(1, 0), b3, voffB); PG8_STAGE(PG8_SB(1, 1), b3 + hstepB, voffB); PG8_STAGE(PG8_SA(1, 0), a3, voffA);
;             PG8_WAIT_V(8); PG8_WAIT_L(0); PG8_BAR; PG8_MMA(1, 0, At, B0); PG8_MMA(1, 1, At, B1); PG8_BAR; PG8_SCHED;
;     ...
;         if constexpr (ALIGN_EPI) { if (wr == 0) PG8_BAR; }
	s_add_i32 s14, s16, s28
	v_lshl_add_u64 v[190:191], v[190:191], 0, s[48:49]
	s_mov_b32 m0, s14
	ds_read_b128 v[182:185], v198 offset:49152
	ds_read_b128 v[186:189], v198 offset:50176
	ds_read_b128 v[202:205], v198 offset:51200
	ds_read_b128 v[206:209], v198 offset:52224
	ds_read_b128 v[210:213], v198 offset:53248
	ds_read_b128 v[214:217], v198 offset:54272
	ds_read_b128 v[218:221], v198 offset:55296
	ds_read_b128 v[222:225], v198 offset:56320
	global_load_lds_dwordx4 v[190:191], off
	s_add_i32 m0, s14, 0x2000
	s_add_u32 s14, s56, 0x58080
	v_lshl_add_u64 v[190:191], v[226:227], 0, s[48:49]
	s_addc_u32 s15, s57, 0
	s_add_i32 s16, s17, s28
	global_load_lds_dwordx4 v[190:191], off
	s_mov_b32 m0, s16
	s_nop 0
	global_load_lds_dwordx4 v148, s[14:15]
	s_add_i32 m0, s16, 0x2000
	s_nop 0
	global_load_lds_dwordx4 v152, s[14:15]
	v_lshl_add_u64 v[190:191], v[228:229], 0, s[48:49]
	s_mov_b32 m0, s61
	s_nop 0
	global_load_lds_dwordx4 v[190:191], off
	v_lshl_add_u64 v[190:191], v[230:231], 0, s[48:49]
	s_mov_b32 m0, s62
	s_nop 0
	global_load_lds_dwordx4 v[190:191], off
	s_waitcnt vmcnt(8)
	s_waitcnt lgkmcnt(0)
	s_barrier
	s_waitcnt lgkmcnt(0)
	v_mfma_f32_16x16x32_bf16 v[62:65], v[130:133], v[182:185], v[62:65]
	v_mfma_f32_16x16x32_bf16 v[58:61], v[138:141], v[182:185], v[58:61]
	v_mfma_f32_16x16x32_bf16 v[46:49], v[130:133], v[202:205], v[46:49]
	v_mfma_f32_16x16x32_bf16 v[42:45], v[138:141], v[202:205], v[42:45]
	v_mfma_f32_16x16x32_bf16 v[30:33], v[130:133], v[210:213], v[30:33]
	v_mfma_f32_16x16x32_bf16 v[26:29], v[138:141], v[210:213], v[26:29]
	v_mfma_f32_16x16x32_bf16 v[14:17], v[130:133], v[218:221], v[14:17]
	v_mfma_f32_16x16x32_bf16 v[10:13], v[138:141], v[218:221], v[10:13]
	v_mfma_f32_16x16x32_bf16 v[62:65], v[134:137], v[186:189], v[62:65]
	v_mfma_f32_16x16x32_bf16 v[58:61], v[142:145], v[186:189], v[58:61]
	v_mfma_f32_16x16x32_bf16 v[46:49], v[134:137], v[206:209], v[46:49]
	v_mfma_f32_16x16x32_bf16 v[42:45], v[142:145], v[206:209], v[42:45]
	v_mfma_f32_16x16x32_bf16 v[30:33], v[134:137], v[214:217], v[30:33]
	v_mfma_f32_16x16x32_bf16 v[26:29], v[142:145], v[214:217], v[26:29]
	v_mfma_f32_16x16x32_bf16 v[14:17], v[134:137], v[222:225], v[14:17]
	v_mfma_f32_16x16x32_bf16 v[10:13], v[142:145], v[222:225], v[10:13]
	v_mfma_f32_16x16x32_bf16 v[54:57], v[166:169], v[182:185], v[54:57]
	v_mfma_f32_16x16x32_bf16 v[50:53], v[174:177], v[182:185], v[50:53]
	v_mfma_f32_16x16x32_bf16 v[38:41], v[166:169], v[202:205], v[38:41]
	v_mfma_f32_16x16x32_bf16 v[34:37], v[174:177], v[202:205], v[34:37]
	v_mfma_f32_16x16x32_bf16 v[22:25], v[166:169], v[210:213], v[22:25]
	v_mfma_f32_16x16x32_bf16 v[18:21], v[174:177], v[210:213], v[18:21]
	v_mfma_f32_16x16x32_bf16 v[6:9], v[166:169], v[218:221], v[6:9]
	v_mfma_f32_16x16x32_bf16 v[2:5], v[174:177], v[218:221], v[2:5]
	v_mfma_f32_16x16x32_bf16 v[54:57], v[170:173], v[186:189], v[54:57]
	v_mfma_f32_16x16x32_bf16 v[50:53], v[178:181], v[186:189], v[50:53]
	v_mfma_f32_16x16x32_bf16 v[38:41], v[170:173], v[206:209], v[38:41]
	v_mfma_f32_16x16x32_bf16 v[34:37], v[178:181], v[206:209], v[34:37]
	v_mfma_f32_16x16x32_bf16 v[22:25], v[170:173], v[214:217], v[22:25]
	v_mfma_f32_16x16x32_bf16 v[18:21], v[178:181], v[214:217], v[18:21]
	v_mfma_f32_16x16x32_bf16 v[6:9], v[170:173], v[222:225], v[6:9]
	v_mfma_f32_16x16x32_bf16 v[2:5], v[178:181], v[222:225], v[2:5]
	s_barrier
	s_add_i32 s13, s13, 2
	s_add_u32 s5, s5, 0x100
	s_addc_u32 s12, s12, 0
	s_cmpk_gt_u32 s13, 0x55
	s_mov_b64 s[16:17], s[54:55]
	s_cbranch_scc0 .LBB0_317
	s_setprio 0
	s_and_b64 vcc, exec, s[50:51]
	s_cbranch_vccz .LBB0_320
	s_barrier

; #define PG8_STAGE(bufoff, gbase, voff) do { _Pragma("unroll") for (int _i = 0; _i < 2; ++_i) \
;         __builtin_amdgcn_global_load_lds((const unsigned*)((const char*)(gbase) + (voff)[_i]), (LAS unsigned*)(lds + (bufoff) + ldsw + _i * 8192), 16, 0, 0); } while (0)
; #define PG8_LDA(dst, b, h) do { _Pragma("unroll") for (int m = 0; m < 4; ++m) _Pragma("unroll") for (int k = 0; k < 2; ++k) dst[m][k] = *(const LAS bf16x8*)(lds + PG8_SA(b, h) + aoff + m * 2048 + k * 1024); } while (0)
; #define PG8_LDB(dst, b, h) do { _Pragma("unroll") for (int n = 0; n < 2; ++n) _Pragma("unroll") for (int k = 0; k < 2; ++k) dst[n][k] = *(const LAS bf16x8*)(lds + PG8_SB(b, h) + boff + n * 2048 + k * 1024); } while (0)
; #define PG8_MMA(ai, bj, At, Bt) do { __builtin_amdgcn_s_setprio(1); _Pragma("unroll") for (int m = 0; m < 4; ++m) _Pragma("unroll") for (int n = 0; n < 2; ++n) _Pragma("unroll") for (int k = 0; k < 2; ++k) \
;         acc[ai][bj][m][n] = __builtin_amdgcn_mfma_f32_16x16x32_bf16(Bt[n][k], At[m][k], acc[ai][bj][m][n], 0, 0, 0); __builtin_amdgcn_s_setprio(0); } while (0)
; #define PG8_WAIT_V(n) asm volatile("s_waitcnt vmcnt(" #n ")" ::: "memory")
; #define PG8_WAIT_L(n) asm volatile("s_waitcnt lgkmcnt(" #n ")" ::: "memory")
; template <class Epi, class Sched, bool ALIGN_EPI = false, bool SP2 = false>
; __device__ __forceinline__ void gemm_phase(LAS unsigned char* lds, const Gemm g, const Sched& S, const Epi& E) {
;     ...
;         for (int t = 0; t < nt; t += 2) {
;             const bool last = (t == nt - 2);
;             const char* a1 = cA + (size_t)(t + 1) * kstep;
;             const char* a2 = last ? nA : cA + (size_t)(t + 2) * kstep; const char* b2 = last ? nB : cB + (size_t)(t + 2) * kstep;
;             const char* a3 = a2 + kstep; const char* b3 = b2 + kstep;
;             if (last && has_next) S.a_ready(nxt);
;             if constexpr (SP2) {
;             PG8_LDB(B0, 0, 0); PG8_LDB(B1, 0, 1); PG8_SCHED; PG8_LDA(At, 0, 0); PG8_STAGE(PG8_SA(1, 1), a1 + hstep, voffA);
;             PG8_WAIT_V(8); PG8_WAIT_L(0); PG8_BAR; PG8_MMA(0, 0, At, B0); PG8_MMA(0, 1, At, B1); PG8_BAR; PG8_SCHED;
;             PG8_LDA(At, 0, 1); PG8_STAGE(PG8_SB(0, 0), b2, voffB); PG8_STAGE(PG8_SB(0, 1), b2 + hstepB, voffB); PG8_STAGE(PG8_SA(0, 0), a2, voffA);
;             PG8_WAIT_V(8); PG8_WAIT_L(0); PG8_BAR; PG8_MMA(1, 0, At, B0); PG8_MMA(1, 1, At, B1); PG8_BAR; PG8_SCHED;
.Lprio_535:
	ds_read_b128 v[34:37], v203
	ds_read_b128 v[38:41], v203 offset:1024
	ds_read_b128 v[42:45], v203 offset:2048
	ds_read_b128 v[46:49], v203 offset:3072
	s_waitcnt vmcnt(0)
	ds_read_b128 v[98:101], v204
	ds_read_b128 v[102:105], v204 offset:1024
	ds_read_b128 v[106:109], v204 offset:2048
	ds_read_b128 v[110:113], v204 offset:3072
	s_add_u32 s21, s16, 0xfff80080
	s_addc_u32 s22, s17, -1
	s_cmp_eq_u32 s20, 28
	s_cselect_b32 s59, s0, s22
	s_cselect_b32 s58, s3, s21
	s_cselect_b32 s49, s14, s19
	s_cselect_b32 s48, s15, s18
	s_add_i32 m0, s30, 0xc000
	ds_read_b128 v[212:215], v205
	ds_read_b128 v[216:219], v205 offset:1024
	ds_read_b128 v[220:223], v205 offset:2048
	ds_read_b128 v[224:227], v205 offset:3072
	ds_read_b128 v[228:231], v205 offset:4096
	ds_read_b128 v[232:235], v205 offset:5120
	ds_read_b128 v[236:239], v205 offset:6144
	ds_read_b128 v[240:243], v205 offset:7168
	global_load_lds_dwordx4 v172, s[16:17]
	s_add_i32 m0, s30, 0xe000
	s_nop 0
	global_load_lds_dwordx4 v174, s[16:17]
	s_waitcnt lgkmcnt(0)
	s_barrier
	s_waitcnt lgkmcnt(0)
	v_mfma_f32_16x16x32_bf16 v[158:161], v[34:37], v[212:215], 0
	v_mfma_f32_16x16x32_bf16 v[154:157], v[42:45], v[212:215], 0
	v_mfma_f32_16x16x32_bf16 v[142:145], v[34:37], v[220:223], 0
	v_mfma_f32_16x16x32_bf16 v[138:141], v[42:45], v[220:223], 0
	v_mfma_f32_16x16x32_bf16 v[126:129], v[34:37], v[228:231], 0
	v_mfma_f32_16x16x32_bf16 v[122:125], v[42:45], v[228:231], 0
	v_mfma_f32_16x16x32_bf16 v[94:97], v[34:37], v[236:239], 0
	v_mfma_f32_16x16x32_bf16 v[90:93], v[42:45], v[236:239], 0
	v_mfma_f32_16x16x32_bf16 v[158:161], v[38:41], v[216:219], v[158:161]
	v_mfma_f32_16x16x32_bf16 v[154:157], v[46:49], v[216:219], v[154:157]
	v_mfma_f32_16x16x32_bf16 v[142:145], v[38:41], v[224:227], v[142:145]
	v_mfma_f32_16x16x32_bf16 v[138:141], v[46:49], v[224:227], v[138:141]
	v_mfma_f32_16x16x32_bf16 v[126:129], v[38:41], v[232:235], v[126:129]
	v_mfma_f32_16x16x32_bf16 v[122:125], v[46:49], v[232:235], v[122:125]
	v_mfma_f32_16x16x32_bf16 v[94:97], v[38:41], v[240:243], v[94:97]
	v_mfma_f32_16x16x32_bf16 v[90:93], v[46:49], v[240:243], v[90:93]
	v_mfma_f32_16x16x32_bf16 v[150:153], v[98:101], v[212:215], 0
	v_mfma_f32_16x16x32_bf16 v[146:149], v[106:109], v[212:215], 0
	v_mfma_f32_16x16x32_bf16 v[134:137], v[98:101], v[220:223], 0
	v_mfma_f32_16x16x32_bf16 v[130:133], v[106:109], v[220:223], 0
	v_mfma_f32_16x16x32_bf16 v[118:121], v[98:101], v[228:231], 0
	v_mfma_f32_16x16x32_bf16 v[114:117], v[106:109], v[228:231], 0
	v_mfma_f32_16x16x32_bf16 v[86:89], v[98:101], v[236:239], 0
	v_mfma_f32_16x16x32_bf16 v[82:85], v[106:109], v[236:239], 0
	v_mfma_f32_16x16x32_bf16 v[150:153], v[102:105], v[216:219], v[150:153]
	v_mfma_f32_16x16x32_bf16 v[146:149], v[110:113], v[216:219], v[146:149]
	v_mfma_f32_16x16x32_bf16 v[134:137], v[102:105], v[224:227], v[134:137]
	v_mfma_f32_16x16x32_bf16 v[130:133], v[110:113], v[224:227], v[130:133]
	v_mfma_f32_16x16x32_bf16 v[118:121], v[102:105], v[232:235], v[118:121]
	v_mfma_f32_16x16x32_bf16 v[114:117], v[110:113], v[232:235], v[114:117]
	v_mfma_f32_16x16x32_bf16 v[86:89], v[102:105], v[240:243], v[86:89]
	v_mfma_f32_16x16x32_bf16 v[82:85], v[110:113], v[240:243], v[82:85]
	s_barrier
	s_add_i32 s21, s68, s29
	v_lshl_add_u64 v[182:183], s[48:49], 0, v[164:165]
	s_mov_b32 m0, s21
	ds_read_b128 v[212:215], v205 offset:16384
	ds_read_b128 v[216:219], v205 offset:17408
	ds_read_b128 v[220:223], v205 offset:18432
	ds_read_b128 v[224:227], v205 offset:19456
	ds_read_b128 v[228:231], v205 offset:20480
	ds_read_b128 v[232:235], v205 offset:21504
	ds_read_b128 v[236:239], v205 offset:22528
	ds_read_b128 v[240:243], v205 offset:23552
	global_load_lds_dwordx4 v[182:183], off
	s_add_i32 m0, s21, 0x2000
	s_add_u32 s22, s48, 0x20000
	v_lshl_add_u64 v[244:245], s[48:49], 0, v[168:169]
	s_addc_u32 s23, s49, 0
	s_add_i32 s21, s69, s29
	global_load_lds_dwordx4 v[244:245], off
	s_mov_b32 m0, s21
	v_lshl_add_u64 v[248:249], s[58:59], 0, v[166:167]
	global_load_lds_dwordx4 v164, s[22:23]
	s_add_i32 m0, s21, 0x2000
	s_nop 0
	global_load_lds_dwordx4 v168, s[22:23]
	v_lshl_add_u64 v[246:247], s[58:59], 0, v[162:163]
	s_mov_b32 m0, s30
	s_nop 0
	global_load_lds_dwordx4 v[246:247], off
	s_mov_b32 m0, s31
	s_nop 0
	global_load_lds_dwordx4 v[248:249], off
	s_waitcnt lgkmcnt(0)
	s_barrier
	s_waitcnt lgkmcnt(0)
	v_mfma_f32_16x16x32_bf16 v[78:81], v[34:37], v[212:215], 0
	v_mfma_f32_16x16x32_bf16 v[74:77], v[42:45], v[212:215], 0
	v_mfma_f32_16x16x32_bf16 v[62:65], v[34:37], v[220:223], 0
	v_mfma_f32_16x16x32_bf16 v[58:61], v[42:45], v[220:223], 0
	v_mfma_f32_16x16x32_bf16 v[30:33], v[34:37], v[228:231], 0
	v_mfma_f32_16x16x32_bf16 v[26:29], v[42:45], v[228:231], 0
	v_mfma_f32_16x16x32_bf16 v[14:17], v[34:37], v[236:239], 0
	v_mfma_f32_16x16x32_bf16 v[10:13], v[42:45], v[236:239], 0
	v_mfma_f32_16x16x32_bf16 v[78:81], v[38:41], v[216:219], v[78:81]
	v_mfma_f32_16x16x32_bf16 v[74:77], v[46:49], v[216:219], v[74:77]
	v_mfma_f32_16x16x32_bf16 v[62:65], v[38:41], v[224:227], v[62:65]
	v_mfma_f32_16x16x32_bf16 v[58:61], v[46:49], v[224:227], v[58:61]
	v_mfma_f32_16x16x32_bf16 v[30:33], v[38:41], v[232:235], v[30:33]
	v_mfma_f32_16x16x32_bf16 v[26:29], v[46:49], v[232:235], v[26:29]
	v_mfma_f32_16x16x32_bf16 v[14:17], v[38:41], v[240:243], v[14:17]
	v_mfma_f32_16x16x32_bf16 v[10:13], v[46:49], v[240:243], v[10:13]
	v_mfma_f32_16x16x32_bf16 v[22:25], v[98:101], v[228:231], 0
	v_mfma_f32_16x16x32_bf16 v[18:21], v[106:109], v[228:231], 0
	v_mfma_f32_16x16x32_bf16 v[6:9], v[98:101], v[236:239], 0
	v_mfma_f32_16x16x32_bf16 v[2:5], v[106:109], v[236:239], 0
	v_mfma_f32_16x16x32_bf16 v[34:37], v[98:101], v[212:215], 0
	v_mfma_f32_16x16x32_bf16 v[38:41], v[106:109], v[212:215], 0
	v_mfma_f32_16x16x32_bf16 v[42:45], v[98:101], v[220:223], 0
	v_mfma_f32_16x16x32_bf16 v[46:49], v[106:109], v[220:223], 0
	v_mfma_f32_16x16x32_bf16 v[22:25], v[102:105], v[232:235], v[22:25]
	v_mfma_f32_16x16x32_bf16 v[18:21], v[110:113], v[232:235], v[18:21]
	v_mfma_f32_16x16x32_bf16 v[6:9], v[102:105], v[240:243], v[6:9]
	v_mfma_f32_16x16x32_bf16 v[2:5], v[110:113], v[240:243], v[2:5]
	v_mfma_f32_16x16x32_bf16 v[34:37], v[102:105], v[216:219], v[34:37]
	v_mfma_f32_16x16x32_bf16 v[38:41], v[110:113], v[216:219], v[38:41]
	v_mfma_f32_16x16x32_bf16 v[42:45], v[102:105], v[224:227], v[42:45]
	v_mfma_f32_16x16x32_bf16 v[46:49], v[110:113], v[224:227], v[46:49]
	s_barrier
; #define PG8_STAGE(bufoff, gbase, voff) do { _Pragma("unroll") for (int _i = 0; _i < 2; ++_i) \
;         __builtin_amdgcn_global_load_lds((const unsigned*)((const char*)(gbase) + (voff)[_i]), (LAS unsigned*)(lds + (bufoff) + ldsw + _i * 8192), 16, 0, 0); } while (0)
; #define PG8_LDA(dst, b, h) do { _Pragma("unroll") for (int m = 0; m < 4; ++m) _Pragma("unroll") for (int k = 0; k < 2; ++k) dst[m][k] = *(const LAS bf16x8*)(lds + PG8_SA(b, h) + aoff + m * 2048 + k * 1024); } while (0)
; #define PG8_LDB(dst, b, h) do { _Pragma("unroll") for (int n = 0; n < 2; ++n) _Pragma("unroll") for (int k = 0; k < 2; ++k) dst[n][k] = *(const LAS bf16x8*)(lds + PG8_SB(b, h) + boff + n * 2048 + k * 1024); } while (0)
; #define PG8_MMA(ai, bj, At, Bt) do { __builtin_amdgcn_s_setprio(1); _Pragma("unroll") for (int m = 0; m < 4; ++m) _Pragma("unroll") for (int n = 0; n < 2; ++n) _Pragma("unroll") for (int k = 0; k < 2; ++k) \
;         acc[ai][bj][m][n] = __builtin_amdgcn_mfma_f32_16x16x32_bf16(Bt[n][k], At[m][k], acc[ai][bj][m][n], 0, 0, 0); __builtin_amdgcn_s_setprio(0); } while (0)
; #define PG8_WAIT_V(n) asm volatile("s_waitcnt vmcnt(" #n ")" ::: "memory")
; #define PG8_WAIT_L(n) asm volatile("s_waitcnt lgkmcnt(" #n ")" ::: "memory")
; #define PG8_BAR __builtin_amdgcn_s_barrier()
; #define PG8_SCHED __builtin_amdgcn_sched_barrier(0)
; template <class Epi, class Sched, bool ALIGN_EPI = false, bool SP2 = false>
; __device__ __forceinline__ void gemm_phase(LAS unsigned char* lds, const Gemm g, const Sched& S, const Epi& E) {
;     ...
;             PG8_LDB(B0, 1, 0); PG8_LDB(B1, 1, 1); PG8_SCHED; PG8_LDA(At, 1, 0); PG8_STAGE(PG8_SA(0, 1), a2 + hstep, voffA);
;             PG8_WAIT_V(8); PG8_WAIT_L(0); PG8_BAR; PG8_MMA(0, 0, At, B0); PG8_MMA(0, 1, At, B1); PG8_BAR; PG8_SCHED;
;             PG8_LDA(At, 1, 1); PG8_STAGE(PG8_SB(1, 0), b3, voffB); PG8_STAGE(PG8_SB(1, 1), b3 + hstepB, voffB); PG8_STAGE(PG8_SA(1, 0), a3, voffA);
;             PG8_WAIT_V(8); PG8_WAIT_L(0); PG8_BAR; PG8_MMA(1, 0, At, B0); PG8_MMA(1, 1, At, B1); PG8_BAR; PG8_SCHED;
	s_add_i32 s21, 0, 0x18000
	s_add_i32 s24, 0, 0x1c000
	v_add_u32_e32 v70, s21, v186
	v_add_u32_e32 v110, s24, v186
	ds_read_b128 v[50:53], v70
	ds_read_b128 v[54:57], v70 offset:1024
	ds_read_b128 v[66:69], v70 offset:2048
	ds_read_b128 v[70:73], v70 offset:3072
	ds_read_b128 v[98:101], v110
	ds_read_b128 v[102:105], v110 offset:1024
	ds_read_b128 v[106:109], v110 offset:2048
	ds_read_b128 v[110:113], v110 offset:3072
	s_add_u32 s22, s58, 0x80000
	s_addc_u32 s23, s59, 0
	s_mov_b32 m0, s33
	ds_read_b128 v[212:215], v205 offset:32768
	ds_read_b128 v[216:219], v205 offset:33792
	ds_read_b128 v[220:223], v205 offset:34816
	ds_read_b128 v[224:227], v205 offset:35840
	ds_read_b128 v[228:231], v205 offset:36864
	ds_read_b128 v[232:235], v205 offset:37888
	ds_read_b128 v[236:239], v205 offset:38912
	ds_read_b128 v[240:243], v205 offset:39936
	global_load_lds_dwordx4 v162, s[22:23]
	s_mov_b32 m0, s60
	s_nop 0
	global_load_lds_dwordx4 v166, s[22:23]
	s_waitcnt vmcnt(8)
	s_waitcnt lgkmcnt(0)
	s_barrier
	s_waitcnt lgkmcnt(0)
	v_mfma_f32_16x16x32_bf16 v[158:161], v[50:53], v[212:215], v[158:161]
	v_mfma_f32_16x16x32_bf16 v[154:157], v[66:69], v[212:215], v[154:157]
	v_mfma_f32_16x16x32_bf16 v[142:145], v[50:53], v[220:223], v[142:145]
	v_mfma_f32_16x16x32_bf16 v[138:141], v[66:69], v[220:223], v[138:141]
	v_mfma_f32_16x16x32_bf16 v[126:129], v[50:53], v[228:231], v[126:129]
	v_mfma_f32_16x16x32_bf16 v[122:125], v[66:69], v[228:231], v[122:125]
	v_mfma_f32_16x16x32_bf16 v[94:97], v[50:53], v[236:239], v[94:97]
	v_mfma_f32_16x16x32_bf16 v[90:93], v[66:69], v[236:239], v[90:93]
	v_mfma_f32_16x16x32_bf16 v[158:161], v[54:57], v[216:219], v[158:161]
	v_mfma_f32_16x16x32_bf16 v[154:157], v[70:73], v[216:219], v[154:157]
	v_mfma_f32_16x16x32_bf16 v[142:145], v[54:57], v[224:227], v[142:145]
	v_mfma_f32_16x16x32_bf16 v[138:141], v[70:73], v[224:227], v[138:141]
	v_mfma_f32_16x16x32_bf16 v[126:129], v[54:57], v[232:235], v[126:129]
	v_mfma_f32_16x16x32_bf16 v[122:125], v[70:73], v[232:235], v[122:125]
	v_mfma_f32_16x16x32_bf16 v[94:97], v[54:57], v[240:243], v[94:97]
	v_mfma_f32_16x16x32_bf16 v[90:93], v[70:73], v[240:243], v[90:93]
	v_mfma_f32_16x16x32_bf16 v[150:153], v[98:101], v[212:215], v[150:153]
	v_mfma_f32_16x16x32_bf16 v[146:149], v[106:109], v[212:215], v[146:149]
	v_mfma_f32_16x16x32_bf16 v[134:137], v[98:101], v[220:223], v[134:137]
	v_mfma_f32_16x16x32_bf16 v[130:133], v[106:109], v[220:223], v[130:133]
	v_mfma_f32_16x16x32_bf16 v[118:121], v[98:101], v[228:231], v[118:121]
	v_mfma_f32_16x16x32_bf16 v[114:117], v[106:109], v[228:231], v[114:117]
	v_mfma_f32_16x16x32_bf16 v[86:89], v[98:101], v[236:239], v[86:89]
	v_mfma_f32_16x16x32_bf16 v[82:85], v[106:109], v[236:239], v[82:85]
	v_mfma_f32_16x16x32_bf16 v[150:153], v[102:105], v[216:219], v[150:153]
	v_mfma_f32_16x16x32_bf16 v[146:149], v[110:113], v[216:219], v[146:149]
	v_mfma_f32_16x16x32_bf16 v[134:137], v[102:105], v[224:227], v[134:137]
	v_mfma_f32_16x16x32_bf16 v[130:133], v[110:113], v[224:227], v[130:133]
	v_mfma_f32_16x16x32_bf16 v[118:121], v[102:105], v[232:235], v[118:121]
	v_mfma_f32_16x16x32_bf16 v[114:117], v[110:113], v[232:235], v[114:117]
	v_mfma_f32_16x16x32_bf16 v[86:89], v[102:105], v[240:243], v[86:89]
	v_mfma_f32_16x16x32_bf16 v[82:85], v[110:113], v[240:243], v[82:85]
	s_barrier
	s_add_i32 s21, s21, s29
	v_lshl_add_u64 v[182:183], v[182:183], 0, s[34:35]
	s_mov_b32 m0, s21
	ds_read_b128 v[212:215], v205 offset:49152
	ds_read_b128 v[216:219], v205 offset:50176
	ds_read_b128 v[220:223], v205 offset:51200
	ds_read_b128 v[224:227], v205 offset:52224
	ds_read_b128 v[228:231], v205 offset:53248
	ds_read_b128 v[232:235], v205 offset:54272
	ds_read_b128 v[236:239], v205 offset:55296
	ds_read_b128 v[240:243], v205 offset:56320
	global_load_lds_dwordx4 v[182:183], off
	s_add_i32 m0, s21, 0x2000
	s_add_u32 s22, s48, 0x20080
	v_lshl_add_u64 v[182:183], v[244:245], 0, s[34:35]
	s_addc_u32 s23, s49, 0
	s_add_i32 s21, s24, s29
	global_load_lds_dwordx4 v[182:183], off
	s_mov_b32 m0, s21
	s_nop 0
	global_load_lds_dwordx4 v164, s[22:23]
	s_add_i32 m0, s21, 0x2000
	s_nop 0
	global_load_lds_dwordx4 v168, s[22:23]
	v_lshl_add_u64 v[182:183], v[246:247], 0, s[34:35]
	s_mov_b32 m0, s65
	s_nop 0
	global_load_lds_dwordx4 v[182:183], off
	v_lshl_add_u64 v[182:183], v[248:249], 0, s[34:35]
	s_mov_b32 m0, s66
	s_nop 0
	global_load_lds_dwordx4 v[182:183], off
	s_waitcnt vmcnt(8)
	s_waitcnt lgkmcnt(0)
	s_barrier
	s_waitcnt lgkmcnt(0)
	v_mfma_f32_16x16x32_bf16 v[78:81], v[50:53], v[212:215], v[78:81]
	v_mfma_f32_16x16x32_bf16 v[74:77], v[66:69], v[212:215], v[74:77]
	v_mfma_f32_16x16x32_bf16 v[62:65], v[50:53], v[220:223], v[62:65]
	v_mfma_f32_16x16x32_bf16 v[58:61], v[66:69], v[220:223], v[58:61]
	v_mfma_f32_16x16x32_bf16 v[30:33], v[50:53], v[228:231], v[30:33]
	v_mfma_f32_16x16x32_bf16 v[26:29], v[66:69], v[228:231], v[26:29]
	v_mfma_f32_16x16x32_bf16 v[14:17], v[50:53], v[236:239], v[14:17]
	v_mfma_f32_16x16x32_bf16 v[10:13], v[66:69], v[236:239], v[10:13]
	v_mfma_f32_16x16x32_bf16 v[78:81], v[54:57], v[216:219], v[78:81]
	v_mfma_f32_16x16x32_bf16 v[74:77], v[70:73], v[216:219], v[74:77]
	v_mfma_f32_16x16x32_bf16 v[62:65], v[54:57], v[224:227], v[62:65]
	v_mfma_f32_16x16x32_bf16 v[58:61], v[70:73], v[224:227], v[58:61]
	v_mfma_f32_16x16x32_bf16 v[30:33], v[54:57], v[232:235], v[30:33]
	v_mfma_f32_16x16x32_bf16 v[26:29], v[70:73], v[232:235], v[26:29]
	v_mfma_f32_16x16x32_bf16 v[14:17], v[54:57], v[240:243], v[14:17]
	v_mfma_f32_16x16x32_bf16 v[10:13], v[70:73], v[240:243], v[10:13]
	v_mfma_f32_16x16x32_bf16 v[34:37], v[98:101], v[212:215], v[34:37]
	v_mfma_f32_16x16x32_bf16 v[70:73], v[102:105], v[216:219], v[34:37]
	v_mfma_f32_16x16x32_bf16 v[34:37], v[106:109], v[212:215], v[38:41]
	v_mfma_f32_16x16x32_bf16 v[66:69], v[110:113], v[216:219], v[34:37]
	v_mfma_f32_16x16x32_bf16 v[34:37], v[98:101], v[220:223], v[42:45]
	v_mfma_f32_16x16x32_bf16 v[54:57], v[102:105], v[224:227], v[34:37]
	v_mfma_f32_16x16x32_bf16 v[34:37], v[106:109], v[220:223], v[46:49]
	v_mfma_f32_16x16x32_bf16 v[22:25], v[98:101], v[228:231], v[22:25]
	v_mfma_f32_16x16x32_bf16 v[18:21], v[106:109], v[228:231], v[18:21]
	v_mfma_f32_16x16x32_bf16 v[6:9], v[98:101], v[236:239], v[6:9]
	v_mfma_f32_16x16x32_bf16 v[2:5], v[106:109], v[236:239], v[2:5]
	v_mfma_f32_16x16x32_bf16 v[50:53], v[110:113], v[224:227], v[34:37]
	v_mfma_f32_16x16x32_bf16 v[22:25], v[102:105], v[232:235], v[22:25]
	v_mfma_f32_16x16x32_bf16 v[18:21], v[110:113], v[232:235], v[18:21]
	v_mfma_f32_16x16x32_bf16 v[6:9], v[102:105], v[240:243], v[6:9]
	v_mfma_f32_16x16x32_bf16 v[2:5], v[110:113], v[240:243], v[2:5]
	s_barrier
	s_add_i32 s20, s20, 2
	s_add_u32 s16, s16, 0x100
	s_addc_u32 s17, s17, 0
	s_add_u32 s18, s18, 0x100
	s_addc_u32 s19, s19, 0
	s_cmp_gt_u32 s20, 29
; #define PG8_STAGE(bufoff, gbase, voff) do { _Pragma("unroll") for (int _i = 0; _i < 2; ++_i) \
;         __builtin_amdgcn_global_load_lds((const unsigned*)((const char*)(gbase) + (voff)[_i]), (LAS unsigned*)(lds + (bufoff) + ldsw + _i * 8192), 16, 0, 0); } while (0)
; #define PG8_LDA(dst, b, h) do { _Pragma("unroll") for (int m = 0; m < 4; ++m) _Pragma("unroll") for (int k = 0; k < 2; ++k) dst[m][k] = *(const LAS bf16x8*)(lds + PG8_SA(b, h) + aoff + m * 2048 + k * 1024); } while (0)
; #define PG8_LDB(dst, b, h) do { _Pragma("unroll") for (int n = 0; n < 2; ++n) _Pragma("unroll") for (int k = 0; k < 2; ++k) dst[n][k] = *(const LAS bf16x8*)(lds + PG8_SB(b, h) + boff + n * 2048 + k * 1024); } while (0)
; #define PG8_WAIT_V(n) asm volatile("s_waitcnt vmcnt(" #n ")" ::: "memory")
; #define PG8_WAIT_L(n) asm volatile("s_waitcnt lgkmcnt(" #n ")" ::: "memory")
; #define PG8_BAR __builtin_amdgcn_s_barrier()
; #define PG8_SCHED __builtin_amdgcn_sched_barrier(0)
; template <class Epi, class Sched, bool ALIGN_EPI = false, bool SP2 = false>
; __device__ __forceinline__ void gemm_phase(LAS unsigned char* lds, const Gemm g, const Sched& S, const Epi& E) {
;     ...
;         for (int t = 0; t < nt; t += 2) {
;             const bool last = (t == nt - 2);
;             const char* a1 = cA + (size_t)(t + 1) * kstep;
;             const char* a2 = last ? nA : cA + (size_t)(t + 2) * kstep; const char* b2 = last ? nB : cB + (size_t)(t + 2) * kstep;
;             const char* a3 = a2 + kstep; const char* b3 = b2 + kstep;
;             if (last && has_next) S.a_ready(nxt);
;             if constexpr (SP2) {
;             PG8_LDB(B0, 0, 0); PG8_LDB(B1, 0, 1); PG8_SCHED; PG8_LDA(At, 0, 0); PG8_STAGE(PG8_SA(1, 1), a1 + hstep, voffA);
;             PG8_WAIT_V(8); PG8_WAIT_L(0); PG8_BAR; PG8_MMA(0, 0, At, B0); PG8_MMA(0, 1, At, B1); PG8_BAR; PG8_SCHED;
;             PG8_LDA(At, 0, 1); PG8_STAGE(PG8_SB(0, 0), b2, voffB); PG8_STAGE(PG8_SB(0, 1), b2 + hstepB, voffB); PG8_STAGE(PG8_SA(0, 0), a2, voffA);
;             PG8_WAIT_V(8); PG8_WAIT_L(0); PG8_BAR; PG8_MMA(1, 0, At, B0); PG8_MMA(1, 1, At, B1); PG8_BAR; PG8_SCHED;
;             PG8_LDB(B0, 1, 0); PG8_LDB(B1, 1, 1); PG8_SCHED; PG8_LDA(At, 1, 0); PG8_STAGE(PG8_SA(0, 1), a2 + hstep, voffA);
;             PG8_WAIT_V(8); PG8_WAIT_L(0); PG8_BAR; PG8_MMA(0, 0, At, B0); PG8_MMA(0, 1, At, B1); PG8_BAR; PG8_SCHED;
.LBB0_535:
	ds_read_b128 v[34:37], v203
	ds_read_b128 v[38:41], v203 offset:1024
	ds_read_b128 v[42:45], v203 offset:2048
	ds_read_b128 v[46:49], v203 offset:3072
	s_waitcnt vmcnt(0)
	ds_read_b128 v[98:101], v204
	ds_read_b128 v[102:105], v204 offset:1024
	ds_read_b128 v[106:109], v204 offset:2048
	ds_read_b128 v[110:113], v204 offset:3072
	s_add_u32 s21, s16, 0xfff80080
	s_addc_u32 s22, s17, -1
	s_cmp_eq_u32 s20, 28
	s_cselect_b32 s59, s0, s22
	s_cselect_b32 s58, s3, s21
	s_cselect_b32 s49, s14, s19
	s_cselect_b32 s48, s15, s18
	s_add_i32 m0, s30, 0xc000
	ds_read_b128 v[212:215], v205
	ds_read_b128 v[216:219], v205 offset:1024
	ds_read_b128 v[220:223], v205 offset:2048
	ds_read_b128 v[224:227], v205 offset:3072
	ds_read_b128 v[228:231], v205 offset:4096
	ds_read_b128 v[232:235], v205 offset:5120
	ds_read_b128 v[236:239], v205 offset:6144
	ds_read_b128 v[240:243], v205 offset:7168
	global_load_lds_dwordx4 v172, s[16:17]
	s_add_i32 m0, s30, 0xe000
	s_nop 0
	global_load_lds_dwordx4 v174, s[16:17]
	s_waitcnt vmcnt(8)
	s_waitcnt lgkmcnt(0)
	s_barrier
	s_waitcnt lgkmcnt(0)
	v_mfma_f32_16x16x32_bf16 v[158:161], v[34:37], v[212:215], v[158:161]
	v_mfma_f32_16x16x32_bf16 v[154:157], v[42:45], v[212:215], v[154:157]
	v_mfma_f32_16x16x32_bf16 v[142:145], v[34:37], v[220:223], v[142:145]
	v_mfma_f32_16x16x32_bf16 v[138:141], v[42:45], v[220:223], v[138:141]
	v_mfma_f32_16x16x32_bf16 v[126:129], v[34:37], v[228:231], v[126:129]
	v_mfma_f32_16x16x32_bf16 v[122:125], v[42:45], v[228:231], v[122:125]
	v_mfma_f32_16x16x32_bf16 v[94:97], v[34:37], v[236:239], v[94:97]
	v_mfma_f32_16x16x32_bf16 v[90:93], v[42:45], v[236:239], v[90:93]
	v_mfma_f32_16x16x32_bf16 v[158:161], v[38:41], v[216:219], v[158:161]
	v_mfma_f32_16x16x32_bf16 v[154:157], v[46:49], v[216:219], v[154:157]
	v_mfma_f32_16x16x32_bf16 v[142:145], v[38:41], v[224:227], v[142:145]
	v_mfma_f32_16x16x32_bf16 v[138:141], v[46:49], v[224:227], v[138:141]
	v_mfma_f32_16x16x32_bf16 v[126:129], v[38:41], v[232:235], v[126:129]
	v_mfma_f32_16x16x32_bf16 v[122:125], v[46:49], v[232:235], v[122:125]
	v_mfma_f32_16x16x32_bf16 v[94:97], v[38:41], v[240:243], v[94:97]
	v_mfma_f32_16x16x32_bf16 v[90:93], v[46:49], v[240:243], v[90:93]
	v_mfma_f32_16x16x32_bf16 v[150:153], v[98:101], v[212:215], v[150:153]
	v_mfma_f32_16x16x32_bf16 v[146:149], v[106:109], v[212:215], v[146:149]
	v_mfma_f32_16x16x32_bf16 v[134:137], v[98:101], v[220:223], v[134:137]
	v_mfma_f32_16x16x32_bf16 v[130:133], v[106:109], v[220:223], v[130:133]
	v_mfma_f32_16x16x32_bf16 v[118:121], v[98:101], v[228:231], v[118:121]
	v_mfma_f32_16x16x32_bf16 v[114:117], v[106:109], v[228:231], v[114:117]
	v_mfma_f32_16x16x32_bf16 v[86:89], v[98:101], v[236:239], v[86:89]
	v_mfma_f32_16x16x32_bf16 v[82:85], v[106:109], v[236:239], v[82:85]
	v_mfma_f32_16x16x32_bf16 v[150:153], v[102:105], v[216:219], v[150:153]
	v_mfma_f32_16x16x32_bf16 v[146:149], v[110:113], v[216:219], v[146:149]
	v_mfma_f32_16x16x32_bf16 v[134:137], v[102:105], v[224:227], v[134:137]
	v_mfma_f32_16x16x32_bf16 v[130:133], v[110:113], v[224:227], v[130:133]
	v_mfma_f32_16x16x32_bf16 v[118:121], v[102:105], v[232:235], v[118:121]
	v_mfma_f32_16x16x32_bf16 v[114:117], v[110:113], v[232:235], v[114:117]
	v_mfma_f32_16x16x32_bf16 v[86:89], v[102:105], v[240:243], v[86:89]
	v_mfma_f32_16x16x32_bf16 v[82:85], v[110:113], v[240:243], v[82:85]
	s_barrier
	s_add_i32 s21, s68, s29
	v_lshl_add_u64 v[182:183], s[48:49], 0, v[164:165]
	s_mov_b32 m0, s21
	ds_read_b128 v[212:215], v205 offset:16384
	ds_read_b128 v[216:219], v205 offset:17408
	ds_read_b128 v[220:223], v205 offset:18432
	ds_read_b128 v[224:227], v205 offset:19456
	ds_read_b128 v[228:231], v205 offset:20480
	ds_read_b128 v[232:235], v205 offset:21504
	ds_read_b128 v[236:239], v205 offset:22528
	ds_read_b128 v[240:243], v205 offset:23552
	global_load_lds_dwordx4 v[182:183], off
	s_add_i32 m0, s21, 0x2000
	s_add_u32 s22, s48, 0x20000
	v_lshl_add_u64 v[244:245], s[48:49], 0, v[168:169]
	s_addc_u32 s23, s49, 0
	s_add_i32 s21, s69, s29
	global_load_lds_dwordx4 v[244:245], off
	s_mov_b32 m0, s21
	v_lshl_add_u64 v[248:249], s[58:59], 0, v[166:167]
	global_load_lds_dwordx4 v164, s[22:23]
	s_add_i32 m0, s21, 0x2000
	s_nop 0
	global_load_lds_dwordx4 v168, s[22:23]
	v_lshl_add_u64 v[246:247], s[58:59], 0, v[162:163]
	s_mov_b32 m0, s30
	s_nop 0
	global_load_lds_dwordx4 v[246:247], off
	s_mov_b32 m0, s31
	s_nop 0
	global_load_lds_dwordx4 v[248:249], off
	s_waitcnt vmcnt(8)
	s_waitcnt lgkmcnt(0)
	s_barrier
	s_waitcnt lgkmcnt(0)
	v_mfma_f32_16x16x32_bf16 v[78:81], v[34:37], v[212:215], v[78:81]
	v_mfma_f32_16x16x32_bf16 v[74:77], v[42:45], v[212:215], v[74:77]
	v_mfma_f32_16x16x32_bf16 v[62:65], v[34:37], v[220:223], v[62:65]
	v_mfma_f32_16x16x32_bf16 v[58:61], v[42:45], v[220:223], v[58:61]
	v_mfma_f32_16x16x32_bf16 v[30:33], v[34:37], v[228:231], v[30:33]
	v_mfma_f32_16x16x32_bf16 v[26:29], v[42:45], v[228:231], v[26:29]
	v_mfma_f32_16x16x32_bf16 v[14:17], v[34:37], v[236:239], v[14:17]
	v_mfma_f32_16x16x32_bf16 v[10:13], v[42:45], v[236:239], v[10:13]
	v_mfma_f32_16x16x32_bf16 v[78:81], v[38:41], v[216:219], v[78:81]
	v_mfma_f32_16x16x32_bf16 v[74:77], v[46:49], v[216:219], v[74:77]
	v_mfma_f32_16x16x32_bf16 v[62:65], v[38:41], v[224:227], v[62:65]
	v_mfma_f32_16x16x32_bf16 v[58:61], v[46:49], v[224:227], v[58:61]
	v_mfma_f32_16x16x32_bf16 v[30:33], v[38:41], v[232:235], v[30:33]
	v_mfma_f32_16x16x32_bf16 v[26:29], v[46:49], v[232:235], v[26:29]
	v_mfma_f32_16x16x32_bf16 v[14:17], v[38:41], v[240:243], v[14:17]
	v_mfma_f32_16x16x32_bf16 v[10:13], v[46:49], v[240:243], v[10:13]
	v_mfma_f32_16x16x32_bf16 v[22:25], v[98:101], v[228:231], v[22:25]
	v_mfma_f32_16x16x32_bf16 v[18:21], v[106:109], v[228:231], v[18:21]
	v_mfma_f32_16x16x32_bf16 v[6:9], v[98:101], v[236:239], v[6:9]
	v_mfma_f32_16x16x32_bf16 v[2:5], v[106:109], v[236:239], v[2:5]
	v_mfma_f32_16x16x32_bf16 v[34:37], v[98:101], v[212:215], v[70:73]
	v_mfma_f32_16x16x32_bf16 v[38:41], v[106:109], v[212:215], v[66:69]
	v_mfma_f32_16x16x32_bf16 v[42:45], v[98:101], v[220:223], v[54:57]
	v_mfma_f32_16x16x32_bf16 v[46:49], v[106:109], v[220:223], v[50:53]
	v_mfma_f32_16x16x32_bf16 v[22:25], v[102:105], v[232:235], v[22:25]
	v_mfma_f32_16x16x32_bf16 v[18:21], v[110:113], v[232:235], v[18:21]
	v_mfma_f32_16x16x32_bf16 v[6:9], v[102:105], v[240:243], v[6:9]
	v_mfma_f32_16x16x32_bf16 v[2:5], v[110:113], v[240:243], v[2:5]
	v_mfma_f32_16x16x32_bf16 v[34:37], v[102:105], v[216:219], v[34:37]
	v_mfma_f32_16x16x32_bf16 v[38:41], v[110:113], v[216:219], v[38:41]
	v_mfma_f32_16x16x32_bf16 v[42:45], v[102:105], v[224:227], v[42:45]
	v_mfma_f32_16x16x32_bf16 v[46:49], v[110:113], v[224:227], v[46:49]
	s_barrier
; #define PG8_STAGE(bufoff, gbase, voff) do { _Pragma("unroll") for (int _i = 0; _i < 2; ++_i) \
;         __builtin_amdgcn_global_load_lds((const unsigned*)((const char*)(gbase) + (voff)[_i]), (LAS unsigned*)(lds + (bufoff) + ldsw + _i * 8192), 16, 0, 0); } while (0)
; #define PG8_LDA(dst, b, h) do { _Pragma("unroll") for (int m = 0; m < 4; ++m) _Pragma("unroll") for (int k = 0; k < 2; ++k) dst[m][k] = *(const LAS bf16x8*)(lds + PG8_SA(b, h) + aoff + m * 2048 + k * 1024); } while (0)
; #define PG8_LDB(dst, b, h) do { _Pragma("unroll") for (int n = 0; n < 2; ++n) _Pragma("unroll") for (int k = 0; k < 2; ++k) dst[n][k] = *(const LAS bf16x8*)(lds + PG8_SB(b, h) + boff + n * 2048 + k * 1024); } while (0)
; #define PG8_MMA(ai, bj, At, Bt) do { __builtin_amdgcn_s_setprio(1); _Pragma("unroll") for (int m = 0; m < 4; ++m) _Pragma("unroll") for (int n = 0; n < 2; ++n) _Pragma("unroll") for (int k = 0; k < 2; ++k) \
;         acc[ai][bj][m][n] = __builtin_amdgcn_mfma_f32_16x16x32_bf16(Bt[n][k], At[m][k], acc[ai][bj][m][n], 0, 0, 0); __builtin_amdgcn_s_setprio(0); } while (0)
; #define PG8_WAIT_V(n) asm volatile("s_waitcnt vmcnt(" #n ")" ::: "memory")
; #define PG8_WAIT_L(n) asm volatile("s_waitcnt lgkmcnt(" #n ")" ::: "memory")
; #define PG8_BAR __builtin_amdgcn_s_barrier()
; #define PG8_SCHED __builtin_amdgcn_sched_barrier(0)
; template <class Epi, class Sched, bool ALIGN_EPI = false, bool SP2 = false>
; __device__ __forceinline__ void gemm_phase(LAS unsigned char* lds, const Gemm g, const Sched& S, const Epi& E) {
;     ...
;             PG8_LDB(B0, 1, 0); PG8_LDB(B1, 1, 1); PG8_SCHED; PG8_LDA(At, 1, 0); PG8_STAGE(PG8_SA(0, 1), a2 + hstep, voffA);
;             PG8_WAIT_V(8); PG8_WAIT_L(0); PG8_BAR; PG8_MMA(0, 0, At, B0); PG8_MMA(0, 1, At, B1); PG8_BAR; PG8_SCHED;
;             PG8_LDA(At, 1, 1); PG8_STAGE(PG8_SB(1, 0), b3, voffB); PG8_STAGE(PG8_SB(1, 1), b3 + hstepB, voffB); PG8_STAGE(PG8_SA(1, 0), a3, voffA);
;             PG8_WAIT_V(8); PG8_WAIT_L(0); PG8_BAR; PG8_MMA(1, 0, At, B0); PG8_MMA(1, 1, At, B1); PG8_BAR; PG8_SCHED;
;     ...
;         if constexpr (ALIGN_EPI) { if (wr == 0) PG8_BAR; }
	s_add_i32 s21, 0, 0x18000
	s_add_i32 s24, 0, 0x1c000
	v_add_u32_e32 v70, s21, v186
	v_add_u32_e32 v110, s24, v186
	ds_read_b128 v[50:53], v70
	ds_read_b128 v[54:57], v70 offset:1024
	ds_read_b128 v[66:69], v70 offset:2048
	ds_read_b128 v[70:73], v70 offset:3072
	ds_read_b128 v[98:101], v110
	ds_read_b128 v[102:105], v110 offset:1024
	ds_read_b128 v[106:109], v110 offset:2048
	ds_read_b128 v[110:113], v110 offset:3072
	s_add_u32 s22, s58, 0x80000
	s_addc_u32 s23, s59, 0
	s_mov_b32 m0, s33
	ds_read_b128 v[212:215], v205 offset:32768
	ds_read_b128 v[216:219], v205 offset:33792
	ds_read_b128 v[220:223], v205 offset:34816
	ds_read_b128 v[224:227], v205 offset:35840
	ds_read_b128 v[228:231], v205 offset:36864
	ds_read_b128 v[232:235], v205 offset:37888
	ds_read_b128 v[236:239], v205 offset:38912
	ds_read_b128 v[240:243], v205 offset:39936
	global_load_lds_dwordx4 v162, s[22:23]
	s_mov_b32 m0, s60
	s_nop 0
	global_load_lds_dwordx4 v166, s[22:23]
	s_waitcnt vmcnt(8)
	s_waitcnt lgkmcnt(0)
	s_barrier
	s_waitcnt lgkmcnt(0)
	v_mfma_f32_16x16x32_bf16 v[158:161], v[50:53], v[212:215], v[158:161]
	v_mfma_f32_16x16x32_bf16 v[154:157], v[66:69], v[212:215], v[154:157]
	v_mfma_f32_16x16x32_bf16 v[142:145], v[50:53], v[220:223], v[142:145]
	v_mfma_f32_16x16x32_bf16 v[138:141], v[66:69], v[220:223], v[138:141]
	v_mfma_f32_16x16x32_bf16 v[126:129], v[50:53], v[228:231], v[126:129]
	v_mfma_f32_16x16x32_bf16 v[122:125], v[66:69], v[228:231], v[122:125]
	v_mfma_f32_16x16x32_bf16 v[94:97], v[50:53], v[236:239], v[94:97]
	v_mfma_f32_16x16x32_bf16 v[90:93], v[66:69], v[236:239], v[90:93]
	v_mfma_f32_16x16x32_bf16 v[158:161], v[54:57], v[216:219], v[158:161]
	v_mfma_f32_16x16x32_bf16 v[154:157], v[70:73], v[216:219], v[154:157]
	v_mfma_f32_16x16x32_bf16 v[142:145], v[54:57], v[224:227], v[142:145]
	v_mfma_f32_16x16x32_bf16 v[138:141], v[70:73], v[224:227], v[138:141]
	v_mfma_f32_16x16x32_bf16 v[126:129], v[54:57], v[232:235], v[126:129]
	v_mfma_f32_16x16x32_bf16 v[122:125], v[70:73], v[232:235], v[122:125]
	v_mfma_f32_16x16x32_bf16 v[94:97], v[54:57], v[240:243], v[94:97]
	v_mfma_f32_16x16x32_bf16 v[90:93], v[70:73], v[240:243], v[90:93]
	v_mfma_f32_16x16x32_bf16 v[150:153], v[98:101], v[212:215], v[150:153]
	v_mfma_f32_16x16x32_bf16 v[146:149], v[106:109], v[212:215], v[146:149]
	v_mfma_f32_16x16x32_bf16 v[134:137], v[98:101], v[220:223], v[134:137]
	v_mfma_f32_16x16x32_bf16 v[130:133], v[106:109], v[220:223], v[130:133]
	v_mfma_f32_16x16x32_bf16 v[118:121], v[98:101], v[228:231], v[118:121]
	v_mfma_f32_16x16x32_bf16 v[114:117], v[106:109], v[228:231], v[114:117]
	v_mfma_f32_16x16x32_bf16 v[86:89], v[98:101], v[236:239], v[86:89]
	v_mfma_f32_16x16x32_bf16 v[82:85], v[106:109], v[236:239], v[82:85]
	v_mfma_f32_16x16x32_bf16 v[150:153], v[102:105], v[216:219], v[150:153]
	v_mfma_f32_16x16x32_bf16 v[146:149], v[110:113], v[216:219], v[146:149]
	v_mfma_f32_16x16x32_bf16 v[134:137], v[102:105], v[224:227], v[134:137]
	v_mfma_f32_16x16x32_bf16 v[130:133], v[110:113], v[224:227], v[130:133]
	v_mfma_f32_16x16x32_bf16 v[118:121], v[102:105], v[232:235], v[118:121]
	v_mfma_f32_16x16x32_bf16 v[114:117], v[110:113], v[232:235], v[114:117]
	v_mfma_f32_16x16x32_bf16 v[86:89], v[102:105], v[240:243], v[86:89]
	v_mfma_f32_16x16x32_bf16 v[82:85], v[110:113], v[240:243], v[82:85]
	s_barrier
	s_add_i32 s21, s21, s29
	v_lshl_add_u64 v[182:183], v[182:183], 0, s[34:35]
	s_mov_b32 m0, s21
	ds_read_b128 v[212:215], v205 offset:49152
	ds_read_b128 v[216:219], v205 offset:50176
	ds_read_b128 v[220:223], v205 offset:51200
	ds_read_b128 v[224:227], v205 offset:52224
	ds_read_b128 v[228:231], v205 offset:53248
	ds_read_b128 v[232:235], v205 offset:54272
	ds_read_b128 v[236:239], v205 offset:55296
	ds_read_b128 v[240:243], v205 offset:56320
	global_load_lds_dwordx4 v[182:183], off
	s_add_i32 m0, s21, 0x2000
	s_add_u32 s22, s48, 0x20080
	v_lshl_add_u64 v[182:183], v[244:245], 0, s[34:35]
	s_addc_u32 s23, s49, 0
	s_add_i32 s21, s24, s29
	global_load_lds_dwordx4 v[182:183], off
	s_mov_b32 m0, s21
	s_nop 0
	global_load_lds_dwordx4 v164, s[22:23]
	s_add_i32 m0, s21, 0x2000
	s_nop 0
	global_load_lds_dwordx4 v168, s[22:23]
	v_lshl_add_u64 v[182:183], v[246:247], 0, s[34:35]
	s_mov_b32 m0, s65
	s_nop 0
	global_load_lds_dwordx4 v[182:183], off
	v_lshl_add_u64 v[182:183], v[248:249], 0, s[34:35]
	s_mov_b32 m0, s66
	s_nop 0
	global_load_lds_dwordx4 v[182:183], off
	s_waitcnt vmcnt(8)
	s_waitcnt lgkmcnt(0)
	s_barrier
	s_waitcnt lgkmcnt(0)
	v_mfma_f32_16x16x32_bf16 v[78:81], v[50:53], v[212:215], v[78:81]
	v_mfma_f32_16x16x32_bf16 v[74:77], v[66:69], v[212:215], v[74:77]
	v_mfma_f32_16x16x32_bf16 v[62:65], v[50:53], v[220:223], v[62:65]
	v_mfma_f32_16x16x32_bf16 v[58:61], v[66:69], v[220:223], v[58:61]
	v_mfma_f32_16x16x32_bf16 v[30:33], v[50:53], v[228:231], v[30:33]
	v_mfma_f32_16x16x32_bf16 v[26:29], v[66:69], v[228:231], v[26:29]
	v_mfma_f32_16x16x32_bf16 v[14:17], v[50:53], v[236:239], v[14:17]
	v_mfma_f32_16x16x32_bf16 v[10:13], v[66:69], v[236:239], v[10:13]
	v_mfma_f32_16x16x32_bf16 v[78:81], v[54:57], v[216:219], v[78:81]
	v_mfma_f32_16x16x32_bf16 v[74:77], v[70:73], v[216:219], v[74:77]
	v_mfma_f32_16x16x32_bf16 v[62:65], v[54:57], v[224:227], v[62:65]
	v_mfma_f32_16x16x32_bf16 v[58:61], v[70:73], v[224:227], v[58:61]
	v_mfma_f32_16x16x32_bf16 v[30:33], v[54:57], v[232:235], v[30:33]
	v_mfma_f32_16x16x32_bf16 v[26:29], v[70:73], v[232:235], v[26:29]
	v_mfma_f32_16x16x32_bf16 v[14:17], v[54:57], v[240:243], v[14:17]
	v_mfma_f32_16x16x32_bf16 v[10:13], v[70:73], v[240:243], v[10:13]
	v_mfma_f32_16x16x32_bf16 v[34:37], v[98:101], v[212:215], v[34:37]
	v_mfma_f32_16x16x32_bf16 v[70:73], v[102:105], v[216:219], v[34:37]
	v_mfma_f32_16x16x32_bf16 v[34:37], v[106:109], v[212:215], v[38:41]
	v_mfma_f32_16x16x32_bf16 v[66:69], v[110:113], v[216:219], v[34:37]
	v_mfma_f32_16x16x32_bf16 v[34:37], v[98:101], v[220:223], v[42:45]
	v_mfma_f32_16x16x32_bf16 v[54:57], v[102:105], v[224:227], v[34:37]
	v_mfma_f32_16x16x32_bf16 v[34:37], v[106:109], v[220:223], v[46:49]
	v_mfma_f32_16x16x32_bf16 v[22:25], v[98:101], v[228:231], v[22:25]
	v_mfma_f32_16x16x32_bf16 v[18:21], v[106:109], v[228:231], v[18:21]
	v_mfma_f32_16x16x32_bf16 v[6:9], v[98:101], v[236:239], v[6:9]
	v_mfma_f32_16x16x32_bf16 v[2:5], v[106:109], v[236:239], v[2:5]
	v_mfma_f32_16x16x32_bf16 v[50:53], v[110:113], v[224:227], v[34:37]
	v_mfma_f32_16x16x32_bf16 v[22:25], v[102:105], v[232:235], v[22:25]
	v_mfma_f32_16x16x32_bf16 v[18:21], v[110:113], v[232:235], v[18:21]
	v_mfma_f32_16x16x32_bf16 v[6:9], v[102:105], v[240:243], v[6:9]
	v_mfma_f32_16x16x32_bf16 v[2:5], v[110:113], v[240:243], v[2:5]
	s_barrier
	s_add_i32 s20, s20, 2
	s_add_u32 s16, s16, 0x100
	s_addc_u32 s17, s17, 0
	s_add_u32 s18, s18, 0x100
	s_addc_u32 s19, s19, 0
	s_cmp_gt_u32 s20, 29
	s_cbranch_scc0 .LBB0_535
	s_setprio 0
	s_and_b64 vcc, exec, s[76:77]
	s_cbranch_vccz .LBB0_538
	s_barrier

; #define PG8_STAGE(bufoff, gbase, voff) do { _Pragma("unroll") for (int _i = 0; _i < 2; ++_i) \
;         __builtin_amdgcn_global_load_lds((const unsigned*)((const char*)(gbase) + (voff)[_i]), (LAS unsigned*)(lds + (bufoff) + ldsw + _i * 8192), 16, 0, 0); } while (0)
; #define PG8_LDA(dst, b, h) do { _Pragma("unroll") for (int m = 0; m < 4; ++m) _Pragma("unroll") for (int k = 0; k < 2; ++k) dst[m][k] = *(const LAS bf16x8*)(lds + PG8_SA(b, h) + aoff + m * 2048 + k * 1024); } while (0)
; #define PG8_LDB(dst, b, h) do { _Pragma("unroll") for (int n = 0; n < 2; ++n) _Pragma("unroll") for (int k = 0; k < 2; ++k) dst[n][k] = *(const LAS bf16x8*)(lds + PG8_SB(b, h) + boff + n * 2048 + k * 1024); } while (0)
; #define PG8_MMA(ai, bj, At, Bt) do { __builtin_amdgcn_s_setprio(1); _Pragma("unroll") for (int m = 0; m < 4; ++m) _Pragma("unroll") for (int n = 0; n < 2; ++n) _Pragma("unroll") for (int k = 0; k < 2; ++k) \
;         acc[ai][bj][m][n] = __builtin_amdgcn_mfma_f32_16x16x32_bf16(Bt[n][k], At[m][k], acc[ai][bj][m][n], 0, 0, 0); __builtin_amdgcn_s_setprio(0); } while (0)
; #define PG8_WAIT_V(n) asm volatile("s_waitcnt vmcnt(" #n ")" ::: "memory")
; #define PG8_WAIT_L(n) asm volatile("s_waitcnt lgkmcnt(" #n ")" ::: "memory")
; template <class Epi, class Sched, bool ALIGN_EPI = false, bool SP2 = false>
; __device__ __forceinline__ void gemm_phase(LAS unsigned char* lds, const Gemm g, const Sched& S, const Epi& E) {
;     ...
;         for (int t = 0; t < nt; t += 2) {
;             const bool last = (t == nt - 2);
;             const char* a1 = cA + (size_t)(t + 1) * kstep;
;             const char* a2 = last ? nA : cA + (size_t)(t + 2) * kstep; const char* b2 = last ? nB : cB + (size_t)(t + 2) * kstep;
;             const char* a3 = a2 + kstep; const char* b3 = b2 + kstep;
;             if (last && has_next) S.a_ready(nxt);
;             if constexpr (SP2) {
;             PG8_LDB(B0, 0, 0); PG8_LDB(B1, 0, 1); PG8_SCHED; PG8_LDA(At, 0, 0); PG8_STAGE(PG8_SA(1, 1), a1 + hstep, voffA);
;             PG8_WAIT_V(8); PG8_WAIT_L(0); PG8_BAR; PG8_MMA(0, 0, At, B0); PG8_MMA(0, 1, At, B1); PG8_BAR; PG8_SCHED;
;             PG8_LDA(At, 0, 1); PG8_STAGE(PG8_SB(0, 0), b2, voffB); PG8_STAGE(PG8_SB(0, 1), b2 + hstepB, voffB); PG8_STAGE(PG8_SA(0, 0), a2, voffA);
;             PG8_WAIT_V(8); PG8_WAIT_L(0); PG8_BAR; PG8_MMA(1, 0, At, B0); PG8_MMA(1, 1, At, B1); PG8_BAR; PG8_SCHED;
.Lprio_1250:
	ds_read_b128 v[50:53], v196
	ds_read_b128 v[54:57], v196 offset:1024
	ds_read_b128 v[138:141], v196 offset:2048
	ds_read_b128 v[142:145], v196 offset:3072
	ds_read_b128 v[146:149], v197
	ds_read_b128 v[150:153], v197 offset:1024
	ds_read_b128 v[174:177], v197 offset:2048
	ds_read_b128 v[178:181], v197 offset:3072
	s_add_u32 s48, s16, 0xfff80080
	s_addc_u32 s49, s17, -1
	s_cmp_eq_u32 s47, 28
	s_cselect_b32 s51, s0, s49
	s_cselect_b32 s50, s3, s48
	s_cselect_b32 s49, s15, s25
	s_cselect_b32 s48, s19, s24
	s_add_i32 m0, s29, 0xc000
	ds_read_b128 v[182:185], v198
	ds_read_b128 v[186:189], v198 offset:1024
	ds_read_b128 v[202:205], v198 offset:2048
	ds_read_b128 v[206:209], v198 offset:3072
	ds_read_b128 v[210:213], v198 offset:4096
	ds_read_b128 v[214:217], v198 offset:5120
	ds_read_b128 v[218:221], v198 offset:6144
	ds_read_b128 v[222:225], v198 offset:7168
	global_load_lds_dwordx4 v166, s[16:17]
	s_add_i32 m0, s29, 0xe000
	s_nop 0
	global_load_lds_dwordx4 v168, s[16:17]
	s_waitcnt lgkmcnt(0)
	s_barrier
	s_waitcnt lgkmcnt(0)
	v_mfma_f32_16x16x32_bf16 v[134:137], v[50:53], v[182:185], 0
	v_mfma_f32_16x16x32_bf16 v[130:133], v[138:141], v[182:185], 0
	v_mfma_f32_16x16x32_bf16 v[118:121], v[50:53], v[202:205], 0
	v_mfma_f32_16x16x32_bf16 v[114:117], v[138:141], v[202:205], 0
	v_mfma_f32_16x16x32_bf16 v[102:105], v[50:53], v[210:213], 0
	v_mfma_f32_16x16x32_bf16 v[98:101], v[138:141], v[210:213], 0
	v_mfma_f32_16x16x32_bf16 v[86:89], v[50:53], v[218:221], 0
	v_mfma_f32_16x16x32_bf16 v[82:85], v[138:141], v[218:221], 0
	v_mfma_f32_16x16x32_bf16 v[134:137], v[54:57], v[186:189], v[134:137]
	v_mfma_f32_16x16x32_bf16 v[130:133], v[142:145], v[186:189], v[130:133]
	v_mfma_f32_16x16x32_bf16 v[118:121], v[54:57], v[206:209], v[118:121]
	v_mfma_f32_16x16x32_bf16 v[114:117], v[142:145], v[206:209], v[114:117]
	v_mfma_f32_16x16x32_bf16 v[102:105], v[54:57], v[214:217], v[102:105]
	v_mfma_f32_16x16x32_bf16 v[98:101], v[142:145], v[214:217], v[98:101]
	v_mfma_f32_16x16x32_bf16 v[86:89], v[54:57], v[222:225], v[86:89]
	v_mfma_f32_16x16x32_bf16 v[82:85], v[142:145], v[222:225], v[82:85]
	v_mfma_f32_16x16x32_bf16 v[126:129], v[146:149], v[182:185], 0
	v_mfma_f32_16x16x32_bf16 v[122:125], v[174:177], v[182:185], 0
	v_mfma_f32_16x16x32_bf16 v[110:113], v[146:149], v[202:205], 0
	v_mfma_f32_16x16x32_bf16 v[106:109], v[174:177], v[202:205], 0
	v_mfma_f32_16x16x32_bf16 v[94:97], v[146:149], v[210:213], 0
	v_mfma_f32_16x16x32_bf16 v[90:93], v[174:177], v[210:213], 0
	v_mfma_f32_16x16x32_bf16 v[78:81], v[146:149], v[218:221], 0
	v_mfma_f32_16x16x32_bf16 v[74:77], v[174:177], v[218:221], 0
	v_mfma_f32_16x16x32_bf16 v[126:129], v[150:153], v[186:189], v[126:129]
	v_mfma_f32_16x16x32_bf16 v[122:125], v[178:181], v[186:189], v[122:125]
	v_mfma_f32_16x16x32_bf16 v[110:113], v[150:153], v[206:209], v[110:113]
	v_mfma_f32_16x16x32_bf16 v[106:109], v[178:181], v[206:209], v[106:109]
	v_mfma_f32_16x16x32_bf16 v[94:97], v[150:153], v[214:217], v[94:97]
	v_mfma_f32_16x16x32_bf16 v[90:93], v[178:181], v[214:217], v[90:93]
	v_mfma_f32_16x16x32_bf16 v[78:81], v[150:153], v[222:225], v[78:81]
	v_mfma_f32_16x16x32_bf16 v[74:77], v[178:181], v[222:225], v[74:77]
	s_barrier
	s_add_i32 s58, s56, s28
	v_lshl_add_u64 v[190:191], s[48:49], 0, v[156:157]
	s_mov_b32 m0, s58
	ds_read_b128 v[182:185], v198 offset:16384
	ds_read_b128 v[186:189], v198 offset:17408
	ds_read_b128 v[202:205], v198 offset:18432
	ds_read_b128 v[206:209], v198 offset:19456
	ds_read_b128 v[210:213], v198 offset:20480
	ds_read_b128 v[214:217], v198 offset:21504
	ds_read_b128 v[218:221], v198 offset:22528
	ds_read_b128 v[222:225], v198 offset:23552
	global_load_lds_dwordx4 v[190:191], off
	s_add_i32 m0, s58, 0x2000
	s_add_u32 s58, s48, 0x20000
	v_lshl_add_u64 v[226:227], s[48:49], 0, v[160:161]
	s_addc_u32 s59, s49, 0
	s_add_i32 s60, s57, s28
	global_load_lds_dwordx4 v[226:227], off
	s_mov_b32 m0, s60
	v_lshl_add_u64 v[230:231], s[50:51], 0, v[158:159]
	global_load_lds_dwordx4 v156, s[58:59]
	s_add_i32 m0, s60, 0x2000
	s_nop 0
	global_load_lds_dwordx4 v160, s[58:59]
	v_lshl_add_u64 v[228:229], s[50:51], 0, v[154:155]
	s_mov_b32 m0, s29
	s_nop 0
	global_load_lds_dwordx4 v[228:229], off
	s_mov_b32 m0, s30
	s_nop 0
	global_load_lds_dwordx4 v[230:231], off
	s_waitcnt lgkmcnt(0)
	s_barrier
	s_waitcnt lgkmcnt(0)
	v_mfma_f32_16x16x32_bf16 v[70:73], v[50:53], v[182:185], 0
	v_mfma_f32_16x16x32_bf16 v[66:69], v[138:141], v[182:185], 0
	v_mfma_f32_16x16x32_bf16 v[46:49], v[50:53], v[202:205], 0
	v_mfma_f32_16x16x32_bf16 v[42:45], v[138:141], v[202:205], 0
	v_mfma_f32_16x16x32_bf16 v[30:33], v[50:53], v[210:213], 0
	v_mfma_f32_16x16x32_bf16 v[26:29], v[138:141], v[210:213], 0
	v_mfma_f32_16x16x32_bf16 v[14:17], v[50:53], v[218:221], 0
	v_mfma_f32_16x16x32_bf16 v[10:13], v[138:141], v[218:221], 0
	v_mfma_f32_16x16x32_bf16 v[70:73], v[54:57], v[186:189], v[70:73]
	v_mfma_f32_16x16x32_bf16 v[66:69], v[142:145], v[186:189], v[66:69]
	v_mfma_f32_16x16x32_bf16 v[46:49], v[54:57], v[206:209], v[46:49]
	v_mfma_f32_16x16x32_bf16 v[42:45], v[142:145], v[206:209], v[42:45]
	v_mfma_f32_16x16x32_bf16 v[30:33], v[54:57], v[214:217], v[30:33]
	v_mfma_f32_16x16x32_bf16 v[26:29], v[142:145], v[214:217], v[26:29]
	v_mfma_f32_16x16x32_bf16 v[14:17], v[54:57], v[222:225], v[14:17]
	v_mfma_f32_16x16x32_bf16 v[10:13], v[142:145], v[222:225], v[10:13]
	v_mfma_f32_16x16x32_bf16 v[38:41], v[146:149], v[202:205], 0
	v_mfma_f32_16x16x32_bf16 v[34:37], v[174:177], v[202:205], 0
	v_mfma_f32_16x16x32_bf16 v[22:25], v[146:149], v[210:213], 0
	v_mfma_f32_16x16x32_bf16 v[18:21], v[174:177], v[210:213], 0
	v_mfma_f32_16x16x32_bf16 v[6:9], v[146:149], v[218:221], 0
	v_mfma_f32_16x16x32_bf16 v[2:5], v[174:177], v[218:221], 0
	v_mfma_f32_16x16x32_bf16 v[50:53], v[146:149], v[182:185], 0
	v_mfma_f32_16x16x32_bf16 v[54:57], v[174:177], v[182:185], 0
	v_mfma_f32_16x16x32_bf16 v[38:41], v[150:153], v[206:209], v[38:41]
	v_mfma_f32_16x16x32_bf16 v[34:37], v[178:181], v[206:209], v[34:37]
	v_mfma_f32_16x16x32_bf16 v[22:25], v[150:153], v[214:217], v[22:25]
	v_mfma_f32_16x16x32_bf16 v[18:21], v[178:181], v[214:217], v[18:21]
	v_mfma_f32_16x16x32_bf16 v[6:9], v[150:153], v[222:225], v[6:9]
	v_mfma_f32_16x16x32_bf16 v[2:5], v[178:181], v[222:225], v[2:5]
	v_mfma_f32_16x16x32_bf16 v[50:53], v[150:153], v[186:189], v[50:53]
	v_mfma_f32_16x16x32_bf16 v[54:57], v[178:181], v[186:189], v[54:57]
	s_barrier
; #define PG8_STAGE(bufoff, gbase, voff) do { _Pragma("unroll") for (int _i = 0; _i < 2; ++_i) \
;         __builtin_amdgcn_global_load_lds((const unsigned*)((const char*)(gbase) + (voff)[_i]), (LAS unsigned*)(lds + (bufoff) + ldsw + _i * 8192), 16, 0, 0); } while (0)
; #define PG8_LDA(dst, b, h) do { _Pragma("unroll") for (int m = 0; m < 4; ++m) _Pragma("unroll") for (int k = 0; k < 2; ++k) dst[m][k] = *(const LAS bf16x8*)(lds + PG8_SA(b, h) + aoff + m * 2048 + k * 1024); } while (0)
; #define PG8_LDB(dst, b, h) do { _Pragma("unroll") for (int n = 0; n < 2; ++n) _Pragma("unroll") for (int k = 0; k < 2; ++k) dst[n][k] = *(const LAS bf16x8*)(lds + PG8_SB(b, h) + boff + n * 2048 + k * 1024); } while (0)
; #define PG8_MMA(ai, bj, At, Bt) do { __builtin_amdgcn_s_setprio(1); _Pragma("unroll") for (int m = 0; m < 4; ++m) _Pragma("unroll") for (int n = 0; n < 2; ++n) _Pragma("unroll") for (int k = 0; k < 2; ++k) \
;         acc[ai][bj][m][n] = __builtin_amdgcn_mfma_f32_16x16x32_bf16(Bt[n][k], At[m][k], acc[ai][bj][m][n], 0, 0, 0); __builtin_amdgcn_s_setprio(0); } while (0)
; #define PG8_WAIT_V(n) asm volatile("s_waitcnt vmcnt(" #n ")" ::: "memory")
; #define PG8_WAIT_L(n) asm volatile("s_waitcnt lgkmcnt(" #n ")" ::: "memory")
; #define PG8_BAR __builtin_amdgcn_s_barrier()
; #define PG8_SCHED __builtin_amdgcn_sched_barrier(0)
; template <class Epi, class Sched, bool ALIGN_EPI = false, bool SP2 = false>
; __device__ __forceinline__ void gemm_phase(LAS unsigned char* lds, const Gemm g, const Sched& S, const Epi& E) {
;     ...
;             PG8_LDB(B0, 1, 0); PG8_LDB(B1, 1, 1); PG8_SCHED; PG8_LDA(At, 1, 0); PG8_STAGE(PG8_SA(0, 1), a2 + hstep, voffA);
;             PG8_WAIT_V(8); PG8_WAIT_L(0); PG8_BAR; PG8_MMA(0, 0, At, B0); PG8_MMA(0, 1, At, B1); PG8_BAR; PG8_SCHED;
;             PG8_LDA(At, 1, 1); PG8_STAGE(PG8_SB(1, 0), b3, voffB); PG8_STAGE(PG8_SB(1, 1), b3 + hstepB, voffB); PG8_STAGE(PG8_SA(1, 0), a3, voffA);
;             PG8_WAIT_V(8); PG8_WAIT_L(0); PG8_BAR; PG8_MMA(1, 0, At, B0); PG8_MMA(1, 1, At, B1); PG8_BAR; PG8_SCHED;
	s_add_i32 s58, 0, 0x18000
	s_add_i32 s59, 0, 0x1c000
	v_add_u32_e32 v142, s58, v1
	v_add_u32_e32 v162, s59, v1
	ds_read_b128 v[58:61], v142
	ds_read_b128 v[62:65], v142 offset:1024
	ds_read_b128 v[138:141], v142 offset:2048
	ds_read_b128 v[142:145], v142 offset:3072
	ds_read_b128 v[146:149], v162
	ds_read_b128 v[150:153], v162 offset:1024
	ds_read_b128 v[174:177], v162 offset:2048
	ds_read_b128 v[178:181], v162 offset:3072
	s_add_u32 s50, s50, 0x80000
	s_addc_u32 s51, s51, 0
	s_mov_b32 m0, s31
	ds_read_b128 v[182:185], v198 offset:32768
	ds_read_b128 v[186:189], v198 offset:33792
	ds_read_b128 v[202:205], v198 offset:34816
	ds_read_b128 v[206:209], v198 offset:35840
	ds_read_b128 v[210:213], v198 offset:36864
	ds_read_b128 v[214:217], v198 offset:37888
	ds_read_b128 v[218:221], v198 offset:38912
	ds_read_b128 v[222:225], v198 offset:39936
	global_load_lds_dwordx4 v154, s[50:51]
	s_mov_b32 m0, s33
	s_nop 0
	global_load_lds_dwordx4 v158, s[50:51]
	s_waitcnt vmcnt(8)
	s_waitcnt lgkmcnt(0)
	s_barrier
	s_waitcnt lgkmcnt(0)
	v_mfma_f32_16x16x32_bf16 v[134:137], v[58:61], v[182:185], v[134:137]
	v_mfma_f32_16x16x32_bf16 v[130:133], v[138:141], v[182:185], v[130:133]
	v_mfma_f32_16x16x32_bf16 v[118:121], v[58:61], v[202:205], v[118:121]
	v_mfma_f32_16x16x32_bf16 v[114:117], v[138:141], v[202:205], v[114:117]
	v_mfma_f32_16x16x32_bf16 v[102:105], v[58:61], v[210:213], v[102:105]
	v_mfma_f32_16x16x32_bf16 v[98:101], v[138:141], v[210:213], v[98:101]
	v_mfma_f32_16x16x32_bf16 v[86:89], v[58:61], v[218:221], v[86:89]
	v_mfma_f32_16x16x32_bf16 v[82:85], v[138:141], v[218:221], v[82:85]
	v_mfma_f32_16x16x32_bf16 v[134:137], v[62:65], v[186:189], v[134:137]
	v_mfma_f32_16x16x32_bf16 v[130:133], v[142:145], v[186:189], v[130:133]
	v_mfma_f32_16x16x32_bf16 v[118:121], v[62:65], v[206:209], v[118:121]
	v_mfma_f32_16x16x32_bf16 v[114:117], v[142:145], v[206:209], v[114:117]
	v_mfma_f32_16x16x32_bf16 v[102:105], v[62:65], v[214:217], v[102:105]
	v_mfma_f32_16x16x32_bf16 v[98:101], v[142:145], v[214:217], v[98:101]
	v_mfma_f32_16x16x32_bf16 v[86:89], v[62:65], v[222:225], v[86:89]
	v_mfma_f32_16x16x32_bf16 v[82:85], v[142:145], v[222:225], v[82:85]
	v_mfma_f32_16x16x32_bf16 v[126:129], v[146:149], v[182:185], v[126:129]
	v_mfma_f32_16x16x32_bf16 v[122:125], v[174:177], v[182:185], v[122:125]
	v_mfma_f32_16x16x32_bf16 v[110:113], v[146:149], v[202:205], v[110:113]
	v_mfma_f32_16x16x32_bf16 v[106:109], v[174:177], v[202:205], v[106:109]
	v_mfma_f32_16x16x32_bf16 v[94:97], v[146:149], v[210:213], v[94:97]
	v_mfma_f32_16x16x32_bf16 v[90:93], v[174:177], v[210:213], v[90:93]
	v_mfma_f32_16x16x32_bf16 v[78:81], v[146:149], v[218:221], v[78:81]
	v_mfma_f32_16x16x32_bf16 v[74:77], v[174:177], v[218:221], v[74:77]
	v_mfma_f32_16x16x32_bf16 v[126:129], v[150:153], v[186:189], v[126:129]
	v_mfma_f32_16x16x32_bf16 v[122:125], v[178:181], v[186:189], v[122:125]
	v_mfma_f32_16x16x32_bf16 v[110:113], v[150:153], v[206:209], v[110:113]
	v_mfma_f32_16x16x32_bf16 v[106:109], v[178:181], v[206:209], v[106:109]
	v_mfma_f32_16x16x32_bf16 v[94:97], v[150:153], v[214:217], v[94:97]
	v_mfma_f32_16x16x32_bf16 v[90:93], v[178:181], v[214:217], v[90:93]
	v_mfma_f32_16x16x32_bf16 v[78:81], v[150:153], v[222:225], v[78:81]
	v_mfma_f32_16x16x32_bf16 v[74:77], v[178:181], v[222:225], v[74:77]
	s_barrier
	s_add_i32 s50, s58, s28
	v_lshl_add_u64 v[190:191], v[190:191], 0, s[10:11]
	s_mov_b32 m0, s50
	ds_read_b128 v[182:185], v198 offset:49152
	ds_read_b128 v[186:189], v198 offset:50176
	ds_read_b128 v[202:205], v198 offset:51200
	ds_read_b128 v[206:209], v198 offset:52224
	ds_read_b128 v[210:213], v198 offset:53248
	ds_read_b128 v[214:217], v198 offset:54272
	ds_read_b128 v[218:221], v198 offset:55296
	ds_read_b128 v[222:225], v198 offset:56320
	global_load_lds_dwordx4 v[190:191], off
	s_add_i32 m0, s50, 0x2000
	s_add_u32 s48, s48, 0x20080
	v_lshl_add_u64 v[190:191], v[226:227], 0, s[10:11]
	s_addc_u32 s49, s49, 0
	s_add_i32 s50, s59, s28
	global_load_lds_dwordx4 v[190:191], off
	s_mov_b32 m0, s50
	s_nop 0
	global_load_lds_dwordx4 v156, s[48:49]
	s_add_i32 m0, s50, 0x2000
	s_nop 0
	global_load_lds_dwordx4 v160, s[48:49]
	v_lshl_add_u64 v[190:191], v[228:229], 0, s[10:11]
	s_mov_b32 m0, s53
	s_nop 0
	global_load_lds_dwordx4 v[190:191], off
	v_lshl_add_u64 v[190:191], v[230:231], 0, s[10:11]
	s_mov_b32 m0, s54
	s_nop 0
	global_load_lds_dwordx4 v[190:191], off
	s_waitcnt vmcnt(8)
	s_waitcnt lgkmcnt(0)
	s_barrier
	s_waitcnt lgkmcnt(0)
	v_mfma_f32_16x16x32_bf16 v[70:73], v[58:61], v[182:185], v[70:73]
	v_mfma_f32_16x16x32_bf16 v[66:69], v[138:141], v[182:185], v[66:69]
	v_mfma_f32_16x16x32_bf16 v[46:49], v[58:61], v[202:205], v[46:49]
	v_mfma_f32_16x16x32_bf16 v[42:45], v[138:141], v[202:205], v[42:45]
	v_mfma_f32_16x16x32_bf16 v[30:33], v[58:61], v[210:213], v[30:33]
	v_mfma_f32_16x16x32_bf16 v[26:29], v[138:141], v[210:213], v[26:29]
	v_mfma_f32_16x16x32_bf16 v[14:17], v[58:61], v[218:221], v[14:17]
	v_mfma_f32_16x16x32_bf16 v[10:13], v[138:141], v[218:221], v[10:13]
	v_mfma_f32_16x16x32_bf16 v[70:73], v[62:65], v[186:189], v[70:73]
	v_mfma_f32_16x16x32_bf16 v[66:69], v[142:145], v[186:189], v[66:69]
	v_mfma_f32_16x16x32_bf16 v[46:49], v[62:65], v[206:209], v[46:49]
	v_mfma_f32_16x16x32_bf16 v[42:45], v[142:145], v[206:209], v[42:45]
	v_mfma_f32_16x16x32_bf16 v[30:33], v[62:65], v[214:217], v[30:33]
	v_mfma_f32_16x16x32_bf16 v[26:29], v[142:145], v[214:217], v[26:29]
	v_mfma_f32_16x16x32_bf16 v[14:17], v[62:65], v[222:225], v[14:17]
	v_mfma_f32_16x16x32_bf16 v[10:13], v[142:145], v[222:225], v[10:13]
	v_mfma_f32_16x16x32_bf16 v[50:53], v[146:149], v[182:185], v[50:53]
	v_mfma_f32_16x16x32_bf16 v[62:65], v[150:153], v[186:189], v[50:53]
	v_mfma_f32_16x16x32_bf16 v[50:53], v[174:177], v[182:185], v[54:57]
	v_mfma_f32_16x16x32_bf16 v[38:41], v[146:149], v[202:205], v[38:41]
	v_mfma_f32_16x16x32_bf16 v[34:37], v[174:177], v[202:205], v[34:37]
	v_mfma_f32_16x16x32_bf16 v[22:25], v[146:149], v[210:213], v[22:25]
	v_mfma_f32_16x16x32_bf16 v[18:21], v[174:177], v[210:213], v[18:21]
	v_mfma_f32_16x16x32_bf16 v[6:9], v[146:149], v[218:221], v[6:9]
	v_mfma_f32_16x16x32_bf16 v[2:5], v[174:177], v[218:221], v[2:5]
	v_mfma_f32_16x16x32_bf16 v[58:61], v[178:181], v[186:189], v[50:53]
	v_mfma_f32_16x16x32_bf16 v[38:41], v[150:153], v[206:209], v[38:41]
	v_mfma_f32_16x16x32_bf16 v[34:37], v[178:181], v[206:209], v[34:37]
	v_mfma_f32_16x16x32_bf16 v[22:25], v[150:153], v[214:217], v[22:25]
	v_mfma_f32_16x16x32_bf16 v[18:21], v[178:181], v[214:217], v[18:21]
	v_mfma_f32_16x16x32_bf16 v[6:9], v[150:153], v[222:225], v[6:9]
	v_mfma_f32_16x16x32_bf16 v[2:5], v[178:181], v[222:225], v[2:5]
	s_barrier
	s_add_i32 s47, s47, 2
	s_add_u32 s16, s16, 0x100
	s_addc_u32 s17, s17, 0
	s_add_u32 s24, s24, 0x100
	s_addc_u32 s25, s25, 0
	s_cmp_gt_u32 s47, 29
; #define PG8_STAGE(bufoff, gbase, voff) do { _Pragma("unroll") for (int _i = 0; _i < 2; ++_i) \
;         __builtin_amdgcn_global_load_lds((const unsigned*)((const char*)(gbase) + (voff)[_i]), (LAS unsigned*)(lds + (bufoff) + ldsw + _i * 8192), 16, 0, 0); } while (0)
; #define PG8_LDA(dst, b, h) do { _Pragma("unroll") for (int m = 0; m < 4; ++m) _Pragma("unroll") for (int k = 0; k < 2; ++k) dst[m][k] = *(const LAS bf16x8*)(lds + PG8_SA(b, h) + aoff + m * 2048 + k * 1024); } while (0)
; #define PG8_LDB(dst, b, h) do { _Pragma("unroll") for (int n = 0; n < 2; ++n) _Pragma("unroll") for (int k = 0; k < 2; ++k) dst[n][k] = *(const LAS bf16x8*)(lds + PG8_SB(b, h) + boff + n * 2048 + k * 1024); } while (0)
; #define PG8_WAIT_V(n) asm volatile("s_waitcnt vmcnt(" #n ")" ::: "memory")
; #define PG8_WAIT_L(n) asm volatile("s_waitcnt lgkmcnt(" #n ")" ::: "memory")
; #define PG8_BAR __builtin_amdgcn_s_barrier()
; #define PG8_SCHED __builtin_amdgcn_sched_barrier(0)
; template <class Epi, class Sched, bool ALIGN_EPI = false, bool SP2 = false>
; __device__ __forceinline__ void gemm_phase(LAS unsigned char* lds, const Gemm g, const Sched& S, const Epi& E) {
;     ...
;         for (int t = 0; t < nt; t += 2) {
;             const bool last = (t == nt - 2);
;             const char* a1 = cA + (size_t)(t + 1) * kstep;
;             const char* a2 = last ? nA : cA + (size_t)(t + 2) * kstep; const char* b2 = last ? nB : cB + (size_t)(t + 2) * kstep;
;             const char* a3 = a2 + kstep; const char* b3 = b2 + kstep;
;             if (last && has_next) S.a_ready(nxt);
;             if constexpr (SP2) {
;             PG8_LDB(B0, 0, 0); PG8_LDB(B1, 0, 1); PG8_SCHED; PG8_LDA(At, 0, 0); PG8_STAGE(PG8_SA(1, 1), a1 + hstep, voffA);
;             PG8_WAIT_V(8); PG8_WAIT_L(0); PG8_BAR; PG8_MMA(0, 0, At, B0); PG8_MMA(0, 1, At, B1); PG8_BAR; PG8_SCHED;
;             PG8_LDA(At, 0, 1); PG8_STAGE(PG8_SB(0, 0), b2, voffB); PG8_STAGE(PG8_SB(0, 1), b2 + hstepB, voffB); PG8_STAGE(PG8_SA(0, 0), a2, voffA);
;             PG8_WAIT_V(8); PG8_WAIT_L(0); PG8_BAR; PG8_MMA(1, 0, At, B0); PG8_MMA(1, 1, At, B1); PG8_BAR; PG8_SCHED;
;             PG8_LDB(B0, 1, 0); PG8_LDB(B1, 1, 1); PG8_SCHED; PG8_LDA(At, 1, 0); PG8_STAGE(PG8_SA(0, 1), a2 + hstep, voffA);
;             PG8_WAIT_V(8); PG8_WAIT_L(0); PG8_BAR; PG8_MMA(0, 0, At, B0); PG8_MMA(0, 1, At, B1); PG8_BAR; PG8_SCHED;
.LBB0_1250:
	ds_read_b128 v[50:53], v196
	ds_read_b128 v[54:57], v196 offset:1024
	ds_read_b128 v[138:141], v196 offset:2048
	ds_read_b128 v[142:145], v196 offset:3072
	ds_read_b128 v[146:149], v197
	ds_read_b128 v[150:153], v197 offset:1024
	ds_read_b128 v[174:177], v197 offset:2048
	ds_read_b128 v[178:181], v197 offset:3072
	s_add_u32 s48, s16, 0xfff80080
	s_addc_u32 s49, s17, -1
	s_cmp_eq_u32 s47, 28
	s_cselect_b32 s51, s0, s49
	s_cselect_b32 s50, s3, s48
	s_cselect_b32 s49, s15, s25
	s_cselect_b32 s48, s19, s24
	s_add_i32 m0, s29, 0xc000
	ds_read_b128 v[182:185], v198
	ds_read_b128 v[186:189], v198 offset:1024
	ds_read_b128 v[202:205], v198 offset:2048
	ds_read_b128 v[206:209], v198 offset:3072
	ds_read_b128 v[210:213], v198 offset:4096
	ds_read_b128 v[214:217], v198 offset:5120
	ds_read_b128 v[218:221], v198 offset:6144
	ds_read_b128 v[222:225], v198 offset:7168
	global_load_lds_dwordx4 v166, s[16:17]
	s_add_i32 m0, s29, 0xe000
	s_nop 0
	global_load_lds_dwordx4 v168, s[16:17]
	s_waitcnt vmcnt(8)
	s_waitcnt lgkmcnt(0)
	s_barrier
	s_waitcnt lgkmcnt(0)
	v_mfma_f32_16x16x32_bf16 v[134:137], v[50:53], v[182:185], v[134:137]
	v_mfma_f32_16x16x32_bf16 v[130:133], v[138:141], v[182:185], v[130:133]
	v_mfma_f32_16x16x32_bf16 v[118:121], v[50:53], v[202:205], v[118:121]
	v_mfma_f32_16x16x32_bf16 v[114:117], v[138:141], v[202:205], v[114:117]
	v_mfma_f32_16x16x32_bf16 v[102:105], v[50:53], v[210:213], v[102:105]
	v_mfma_f32_16x16x32_bf16 v[98:101], v[138:141], v[210:213], v[98:101]
	v_mfma_f32_16x16x32_bf16 v[86:89], v[50:53], v[218:221], v[86:89]
	v_mfma_f32_16x16x32_bf16 v[82:85], v[138:141], v[218:221], v[82:85]
	v_mfma_f32_16x16x32_bf16 v[134:137], v[54:57], v[186:189], v[134:137]
	v_mfma_f32_16x16x32_bf16 v[130:133], v[142:145], v[186:189], v[130:133]
	v_mfma_f32_16x16x32_bf16 v[118:121], v[54:57], v[206:209], v[118:121]
	v_mfma_f32_16x16x32_bf16 v[114:117], v[142:145], v[206:209], v[114:117]
	v_mfma_f32_16x16x32_bf16 v[102:105], v[54:57], v[214:217], v[102:105]
	v_mfma_f32_16x16x32_bf16 v[98:101], v[142:145], v[214:217], v[98:101]
	v_mfma_f32_16x16x32_bf16 v[86:89], v[54:57], v[222:225], v[86:89]
	v_mfma_f32_16x16x32_bf16 v[82:85], v[142:145], v[222:225], v[82:85]
	v_mfma_f32_16x16x32_bf16 v[126:129], v[146:149], v[182:185], v[126:129]
	v_mfma_f32_16x16x32_bf16 v[122:125], v[174:177], v[182:185], v[122:125]
	v_mfma_f32_16x16x32_bf16 v[110:113], v[146:149], v[202:205], v[110:113]
	v_mfma_f32_16x16x32_bf16 v[106:109], v[174:177], v[202:205], v[106:109]
	v_mfma_f32_16x16x32_bf16 v[94:97], v[146:149], v[210:213], v[94:97]
	v_mfma_f32_16x16x32_bf16 v[90:93], v[174:177], v[210:213], v[90:93]
	v_mfma_f32_16x16x32_bf16 v[78:81], v[146:149], v[218:221], v[78:81]
	v_mfma_f32_16x16x32_bf16 v[74:77], v[174:177], v[218:221], v[74:77]
	v_mfma_f32_16x16x32_bf16 v[126:129], v[150:153], v[186:189], v[126:129]
	v_mfma_f32_16x16x32_bf16 v[122:125], v[178:181], v[186:189], v[122:125]
	v_mfma_f32_16x16x32_bf16 v[110:113], v[150:153], v[206:209], v[110:113]
	v_mfma_f32_16x16x32_bf16 v[106:109], v[178:181], v[206:209], v[106:109]
	v_mfma_f32_16x16x32_bf16 v[94:97], v[150:153], v[214:217], v[94:97]
	v_mfma_f32_16x16x32_bf16 v[90:93], v[178:181], v[214:217], v[90:93]
	v_mfma_f32_16x16x32_bf16 v[78:81], v[150:153], v[222:225], v[78:81]
	v_mfma_f32_16x16x32_bf16 v[74:77], v[178:181], v[222:225], v[74:77]
	s_barrier
	s_add_i32 s58, s56, s28
	v_lshl_add_u64 v[190:191], s[48:49], 0, v[156:157]
	s_mov_b32 m0, s58
	ds_read_b128 v[182:185], v198 offset:16384
	ds_read_b128 v[186:189], v198 offset:17408
	ds_read_b128 v[202:205], v198 offset:18432
	ds_read_b128 v[206:209], v198 offset:19456
	ds_read_b128 v[210:213], v198 offset:20480
	ds_read_b128 v[214:217], v198 offset:21504
	ds_read_b128 v[218:221], v198 offset:22528
	ds_read_b128 v[222:225], v198 offset:23552
	global_load_lds_dwordx4 v[190:191], off
	s_add_i32 m0, s58, 0x2000
	s_add_u32 s58, s48, 0x20000
	v_lshl_add_u64 v[226:227], s[48:49], 0, v[160:161]
	s_addc_u32 s59, s49, 0
	s_add_i32 s60, s57, s28
	global_load_lds_dwordx4 v[226:227], off
	s_mov_b32 m0, s60
	v_lshl_add_u64 v[230:231], s[50:51], 0, v[158:159]
	global_load_lds_dwordx4 v156, s[58:59]
	s_add_i32 m0, s60, 0x2000
	s_nop 0
	global_load_lds_dwordx4 v160, s[58:59]
	v_lshl_add_u64 v[228:229], s[50:51], 0, v[154:155]
	s_mov_b32 m0, s29
	s_nop 0
	global_load_lds_dwordx4 v[228:229], off
	s_mov_b32 m0, s30
	s_nop 0
	global_load_lds_dwordx4 v[230:231], off
	s_waitcnt vmcnt(8)
	s_waitcnt lgkmcnt(0)
	s_barrier
	s_waitcnt lgkmcnt(0)
	v_mfma_f32_16x16x32_bf16 v[70:73], v[50:53], v[182:185], v[70:73]
	v_mfma_f32_16x16x32_bf16 v[66:69], v[138:141], v[182:185], v[66:69]
	v_mfma_f32_16x16x32_bf16 v[46:49], v[50:53], v[202:205], v[46:49]
	v_mfma_f32_16x16x32_bf16 v[42:45], v[138:141], v[202:205], v[42:45]
	v_mfma_f32_16x16x32_bf16 v[30:33], v[50:53], v[210:213], v[30:33]
	v_mfma_f32_16x16x32_bf16 v[26:29], v[138:141], v[210:213], v[26:29]
	v_mfma_f32_16x16x32_bf16 v[14:17], v[50:53], v[218:221], v[14:17]
	v_mfma_f32_16x16x32_bf16 v[10:13], v[138:141], v[218:221], v[10:13]
	v_mfma_f32_16x16x32_bf16 v[70:73], v[54:57], v[186:189], v[70:73]
	v_mfma_f32_16x16x32_bf16 v[66:69], v[142:145], v[186:189], v[66:69]
	v_mfma_f32_16x16x32_bf16 v[46:49], v[54:57], v[206:209], v[46:49]
	v_mfma_f32_16x16x32_bf16 v[42:45], v[142:145], v[206:209], v[42:45]
	v_mfma_f32_16x16x32_bf16 v[30:33], v[54:57], v[214:217], v[30:33]
	v_mfma_f32_16x16x32_bf16 v[26:29], v[142:145], v[214:217], v[26:29]
	v_mfma_f32_16x16x32_bf16 v[14:17], v[54:57], v[222:225], v[14:17]
	v_mfma_f32_16x16x32_bf16 v[10:13], v[142:145], v[222:225], v[10:13]
	v_mfma_f32_16x16x32_bf16 v[38:41], v[146:149], v[202:205], v[38:41]
	v_mfma_f32_16x16x32_bf16 v[34:37], v[174:177], v[202:205], v[34:37]
	v_mfma_f32_16x16x32_bf16 v[22:25], v[146:149], v[210:213], v[22:25]
	v_mfma_f32_16x16x32_bf16 v[18:21], v[174:177], v[210:213], v[18:21]
	v_mfma_f32_16x16x32_bf16 v[6:9], v[146:149], v[218:221], v[6:9]
	v_mfma_f32_16x16x32_bf16 v[2:5], v[174:177], v[218:221], v[2:5]
	v_mfma_f32_16x16x32_bf16 v[50:53], v[146:149], v[182:185], v[62:65]
	v_mfma_f32_16x16x32_bf16 v[54:57], v[174:177], v[182:185], v[58:61]
	v_mfma_f32_16x16x32_bf16 v[38:41], v[150:153], v[206:209], v[38:41]
	v_mfma_f32_16x16x32_bf16 v[34:37], v[178:181], v[206:209], v[34:37]
	v_mfma_f32_16x16x32_bf16 v[22:25], v[150:153], v[214:217], v[22:25]
	v_mfma_f32_16x16x32_bf16 v[18:21], v[178:181], v[214:217], v[18:21]
	v_mfma_f32_16x16x32_bf16 v[6:9], v[150:153], v[222:225], v[6:9]
	v_mfma_f32_16x16x32_bf16 v[2:5], v[178:181], v[222:225], v[2:5]
	v_mfma_f32_16x16x32_bf16 v[50:53], v[150:153], v[186:189], v[50:53]
	v_mfma_f32_16x16x32_bf16 v[54:57], v[178:181], v[186:189], v[54:57]
	s_barrier
; #define PG8_STAGE(bufoff, gbase, voff) do { _Pragma("unroll") for (int _i = 0; _i < 2; ++_i) \
;         __builtin_amdgcn_global_load_lds((const unsigned*)((const char*)(gbase) + (voff)[_i]), (LAS unsigned*)(lds + (bufoff) + ldsw + _i * 8192), 16, 0, 0); } while (0)
; #define PG8_LDA(dst, b, h) do { _Pragma("unroll") for (int m = 0; m < 4; ++m) _Pragma("unroll") for (int k = 0; k < 2; ++k) dst[m][k] = *(const LAS bf16x8*)(lds + PG8_SA(b, h) + aoff + m * 2048 + k * 1024); } while (0)
; #define PG8_LDB(dst, b, h) do { _Pragma("unroll") for (int n = 0; n < 2; ++n) _Pragma("unroll") for (int k = 0; k < 2; ++k) dst[n][k] = *(const LAS bf16x8*)(lds + PG8_SB(b, h) + boff + n * 2048 + k * 1024); } while (0)
; #define PG8_MMA(ai, bj, At, Bt) do { __builtin_amdgcn_s_setprio(1); _Pragma("unroll") for (int m = 0; m < 4; ++m) _Pragma("unroll") for (int n = 0; n < 2; ++n) _Pragma("unroll") for (int k = 0; k < 2; ++k) \
;         acc[ai][bj][m][n] = __builtin_amdgcn_mfma_f32_16x16x32_bf16(Bt[n][k], At[m][k], acc[ai][bj][m][n], 0, 0, 0); __builtin_amdgcn_s_setprio(0); } while (0)
; #define PG8_WAIT_V(n) asm volatile("s_waitcnt vmcnt(" #n ")" ::: "memory")
; #define PG8_WAIT_L(n) asm volatile("s_waitcnt lgkmcnt(" #n ")" ::: "memory")
; #define PG8_BAR __builtin_amdgcn_s_barrier()
; #define PG8_SCHED __builtin_amdgcn_sched_barrier(0)
; template <class Epi, class Sched, bool ALIGN_EPI = false, bool SP2 = false>
; __device__ __forceinline__ void gemm_phase(LAS unsigned char* lds, const Gemm g, const Sched& S, const Epi& E) {
;     ...
;             PG8_LDB(B0, 1, 0); PG8_LDB(B1, 1, 1); PG8_SCHED; PG8_LDA(At, 1, 0); PG8_STAGE(PG8_SA(0, 1), a2 + hstep, voffA);
;             PG8_WAIT_V(8); PG8_WAIT_L(0); PG8_BAR; PG8_MMA(0, 0, At, B0); PG8_MMA(0, 1, At, B1); PG8_BAR; PG8_SCHED;
;             PG8_LDA(At, 1, 1); PG8_STAGE(PG8_SB(1, 0), b3, voffB); PG8_STAGE(PG8_SB(1, 1), b3 + hstepB, voffB); PG8_STAGE(PG8_SA(1, 0), a3, voffA);
;             PG8_WAIT_V(8); PG8_WAIT_L(0); PG8_BAR; PG8_MMA(1, 0, At, B0); PG8_MMA(1, 1, At, B1); PG8_BAR; PG8_SCHED;
;     ...
;         if constexpr (ALIGN_EPI) { if (wr == 0) PG8_BAR; }
	s_add_i32 s58, 0, 0x18000
	s_add_i32 s59, 0, 0x1c000
	v_add_u32_e32 v142, s58, v1
	v_add_u32_e32 v162, s59, v1
	ds_read_b128 v[58:61], v142
	ds_read_b128 v[62:65], v142 offset:1024
	ds_read_b128 v[138:141], v142 offset:2048
	ds_read_b128 v[142:145], v142 offset:3072
	ds_read_b128 v[146:149], v162
	ds_read_b128 v[150:153], v162 offset:1024
	ds_read_b128 v[174:177], v162 offset:2048
	ds_read_b128 v[178:181], v162 offset:3072
	s_add_u32 s50, s50, 0x80000
	s_addc_u32 s51, s51, 0
	s_mov_b32 m0, s31
	ds_read_b128 v[182:185], v198 offset:32768
	ds_read_b128 v[186:189], v198 offset:33792
	ds_read_b128 v[202:205], v198 offset:34816
	ds_read_b128 v[206:209], v198 offset:35840
	ds_read_b128 v[210:213], v198 offset:36864
	ds_read_b128 v[214:217], v198 offset:37888
	ds_read_b128 v[218:221], v198 offset:38912
	ds_read_b128 v[222:225], v198 offset:39936
	global_load_lds_dwordx4 v154, s[50:51]
	s_mov_b32 m0, s33
	s_nop 0
	global_load_lds_dwordx4 v158, s[50:51]
	s_waitcnt vmcnt(8)
	s_waitcnt lgkmcnt(0)
	s_barrier
	s_waitcnt lgkmcnt(0)
	v_mfma_f32_16x16x32_bf16 v[134:137], v[58:61], v[182:185], v[134:137]
	v_mfma_f32_16x16x32_bf16 v[130:133], v[138:141], v[182:185], v[130:133]
	v_mfma_f32_16x16x32_bf16 v[118:121], v[58:61], v[202:205], v[118:121]
	v_mfma_f32_16x16x32_bf16 v[114:117], v[138:141], v[202:205], v[114:117]
	v_mfma_f32_16x16x32_bf16 v[102:105], v[58:61], v[210:213], v[102:105]
	v_mfma_f32_16x16x32_bf16 v[98:101], v[138:141], v[210:213], v[98:101]
	v_mfma_f32_16x16x32_bf16 v[86:89], v[58:61], v[218:221], v[86:89]
	v_mfma_f32_16x16x32_bf16 v[82:85], v[138:141], v[218:221], v[82:85]
	v_mfma_f32_16x16x32_bf16 v[134:137], v[62:65], v[186:189], v[134:137]
	v_mfma_f32_16x16x32_bf16 v[130:133], v[142:145], v[186:189], v[130:133]
	v_mfma_f32_16x16x32_bf16 v[118:121], v[62:65], v[206:209], v[118:121]
	v_mfma_f32_16x16x32_bf16 v[114:117], v[142:145], v[206:209], v[114:117]
	v_mfma_f32_16x16x32_bf16 v[102:105], v[62:65], v[214:217], v[102:105]
	v_mfma_f32_16x16x32_bf16 v[98:101], v[142:145], v[214:217], v[98:101]
	v_mfma_f32_16x16x32_bf16 v[86:89], v[62:65], v[222:225], v[86:89]
	v_mfma_f32_16x16x32_bf16 v[82:85], v[142:145], v[222:225], v[82:85]
	v_mfma_f32_16x16x32_bf16 v[126:129], v[146:149], v[182:185], v[126:129]
	v_mfma_f32_16x16x32_bf16 v[122:125], v[174:177], v[182:185], v[122:125]
	v_mfma_f32_16x16x32_bf16 v[110:113], v[146:149], v[202:205], v[110:113]
	v_mfma_f32_16x16x32_bf16 v[106:109], v[174:177], v[202:205], v[106:109]
	v_mfma_f32_16x16x32_bf16 v[94:97], v[146:149], v[210:213], v[94:97]
	v_mfma_f32_16x16x32_bf16 v[90:93], v[174:177], v[210:213], v[90:93]
	v_mfma_f32_16x16x32_bf16 v[78:81], v[146:149], v[218:221], v[78:81]
	v_mfma_f32_16x16x32_bf16 v[74:77], v[174:177], v[218:221], v[74:77]
	v_mfma_f32_16x16x32_bf16 v[126:129], v[150:153], v[186:189], v[126:129]
	v_mfma_f32_16x16x32_bf16 v[122:125], v[178:181], v[186:189], v[122:125]
	v_mfma_f32_16x16x32_bf16 v[110:113], v[150:153], v[206:209], v[110:113]
	v_mfma_f32_16x16x32_bf16 v[106:109], v[178:181], v[206:209], v[106:109]
	v_mfma_f32_16x16x32_bf16 v[94:97], v[150:153], v[214:217], v[94:97]
	v_mfma_f32_16x16x32_bf16 v[90:93], v[178:181], v[214:217], v[90:93]
	v_mfma_f32_16x16x32_bf16 v[78:81], v[150:153], v[222:225], v[78:81]
	v_mfma_f32_16x16x32_bf16 v[74:77], v[178:181], v[222:225], v[74:77]
	s_barrier
	s_add_i32 s50, s58, s28
	v_lshl_add_u64 v[190:191], v[190:191], 0, s[10:11]
	s_mov_b32 m0, s50
	ds_read_b128 v[182:185], v198 offset:49152
	ds_read_b128 v[186:189], v198 offset:50176
	ds_read_b128 v[202:205], v198 offset:51200
	ds_read_b128 v[206:209], v198 offset:52224
	ds_read_b128 v[210:213], v198 offset:53248
	ds_read_b128 v[214:217], v198 offset:54272
	ds_read_b128 v[218:221], v198 offset:55296
	ds_read_b128 v[222:225], v198 offset:56320
	global_load_lds_dwordx4 v[190:191], off
	s_add_i32 m0, s50, 0x2000
	s_add_u32 s48, s48, 0x20080
	v_lshl_add_u64 v[190:191], v[226:227], 0, s[10:11]
	s_addc_u32 s49, s49, 0
	s_add_i32 s50, s59, s28
	global_load_lds_dwordx4 v[190:191], off
	s_mov_b32 m0, s50
	s_nop 0
	global_load_lds_dwordx4 v156, s[48:49]
	s_add_i32 m0, s50, 0x2000
	s_nop 0
	global_load_lds_dwordx4 v160, s[48:49]
	v_lshl_add_u64 v[190:191], v[228:229], 0, s[10:11]
	s_mov_b32 m0, s53
	s_nop 0
	global_load_lds_dwordx4 v[190:191], off
	v_lshl_add_u64 v[190:191], v[230:231], 0, s[10:11]
	s_mov_b32 m0, s54
	s_nop 0
	global_load_lds_dwordx4 v[190:191], off
	s_waitcnt vmcnt(8)
	s_waitcnt lgkmcnt(0)
	s_barrier
	s_waitcnt lgkmcnt(0)
	v_mfma_f32_16x16x32_bf16 v[70:73], v[58:61], v[182:185], v[70:73]
	v_mfma_f32_16x16x32_bf16 v[66:69], v[138:141], v[182:185], v[66:69]
	v_mfma_f32_16x16x32_bf16 v[46:49], v[58:61], v[202:205], v[46:49]
	v_mfma_f32_16x16x32_bf16 v[42:45], v[138:141], v[202:205], v[42:45]
	v_mfma_f32_16x16x32_bf16 v[30:33], v[58:61], v[210:213], v[30:33]
	v_mfma_f32_16x16x32_bf16 v[26:29], v[138:141], v[210:213], v[26:29]
	v_mfma_f32_16x16x32_bf16 v[14:17], v[58:61], v[218:221], v[14:17]
	v_mfma_f32_16x16x32_bf16 v[10:13], v[138:141], v[218:221], v[10:13]
	v_mfma_f32_16x16x32_bf16 v[70:73], v[62:65], v[186:189], v[70:73]
	v_mfma_f32_16x16x32_bf16 v[66:69], v[142:145], v[186:189], v[66:69]
	v_mfma_f32_16x16x32_bf16 v[46:49], v[62:65], v[206:209], v[46:49]
	v_mfma_f32_16x16x32_bf16 v[42:45], v[142:145], v[206:209], v[42:45]
	v_mfma_f32_16x16x32_bf16 v[30:33], v[62:65], v[214:217], v[30:33]
	v_mfma_f32_16x16x32_bf16 v[26:29], v[142:145], v[214:217], v[26:29]
	v_mfma_f32_16x16x32_bf16 v[14:17], v[62:65], v[222:225], v[14:17]
	v_mfma_f32_16x16x32_bf16 v[10:13], v[142:145], v[222:225], v[10:13]
	v_mfma_f32_16x16x32_bf16 v[50:53], v[146:149], v[182:185], v[50:53]
	v_mfma_f32_16x16x32_bf16 v[62:65], v[150:153], v[186:189], v[50:53]
	v_mfma_f32_16x16x32_bf16 v[50:53], v[174:177], v[182:185], v[54:57]
	v_mfma_f32_16x16x32_bf16 v[38:41], v[146:149], v[202:205], v[38:41]
	v_mfma_f32_16x16x32_bf16 v[34:37], v[174:177], v[202:205], v[34:37]
	v_mfma_f32_16x16x32_bf16 v[22:25], v[146:149], v[210:213], v[22:25]
	v_mfma_f32_16x16x32_bf16 v[18:21], v[174:177], v[210:213], v[18:21]
	v_mfma_f32_16x16x32_bf16 v[6:9], v[146:149], v[218:221], v[6:9]
	v_mfma_f32_16x16x32_bf16 v[2:5], v[174:177], v[218:221], v[2:5]
	v_mfma_f32_16x16x32_bf16 v[58:61], v[178:181], v[186:189], v[50:53]
	v_mfma_f32_16x16x32_bf16 v[38:41], v[150:153], v[206:209], v[38:41]
	v_mfma_f32_16x16x32_bf16 v[34:37], v[178:181], v[206:209], v[34:37]
	v_mfma_f32_16x16x32_bf16 v[22:25], v[150:153], v[214:217], v[22:25]
	v_mfma_f32_16x16x32_bf16 v[18:21], v[178:181], v[214:217], v[18:21]
	v_mfma_f32_16x16x32_bf16 v[6:9], v[150:153], v[222:225], v[6:9]
	v_mfma_f32_16x16x32_bf16 v[2:5], v[178:181], v[222:225], v[2:5]
	s_barrier
	s_add_i32 s47, s47, 2
	s_add_u32 s16, s16, 0x100
	s_addc_u32 s17, s17, 0
	s_add_u32 s24, s24, 0x100
	s_addc_u32 s25, s25, 0
	s_cmp_gt_u32 s47, 29
	s_cbranch_scc0 .LBB0_1250
	s_setprio 0
	s_and_b64 vcc, exec, s[12:13]
	s_cbranch_vccz .LBB0_1253
	s_barrier

; #define PG8_STAGE(bufoff, gbase, voff) do { _Pragma("unroll") for (int _i = 0; _i < 2; ++_i) \
;         __builtin_amdgcn_global_load_lds((const unsigned*)((const char*)(gbase) + (voff)[_i]), (LAS unsigned*)(lds + (bufoff) + ldsw + _i * 8192), 16, 0, 0); } while (0)
; #define PG8_LDA(dst, b, h) do { _Pragma("unroll") for (int m = 0; m < 4; ++m) _Pragma("unroll") for (int k = 0; k < 2; ++k) dst[m][k] = *(const LAS bf16x8*)(lds + PG8_SA(b, h) + aoff + m * 2048 + k * 1024); } while (0)
; #define PG8_LDB(dst, b, h) do { _Pragma("unroll") for (int n = 0; n < 2; ++n) _Pragma("unroll") for (int k = 0; k < 2; ++k) dst[n][k] = *(const LAS bf16x8*)(lds + PG8_SB(b, h) + boff + n * 2048 + k * 1024); } while (0)
; #define PG8_MMA(ai, bj, At, Bt) do { __builtin_amdgcn_s_setprio(1); _Pragma("unroll") for (int m = 0; m < 4; ++m) _Pragma("unroll") for (int n = 0; n < 2; ++n) _Pragma("unroll") for (int k = 0; k < 2; ++k) \
;         acc[ai][bj][m][n] = __builtin_amdgcn_mfma_f32_16x16x32_bf16(Bt[n][k], At[m][k], acc[ai][bj][m][n], 0, 0, 0); __builtin_amdgcn_s_setprio(0); } while (0)
; #define PG8_WAIT_V(n) asm volatile("s_waitcnt vmcnt(" #n ")" ::: "memory")
; #define PG8_WAIT_L(n) asm volatile("s_waitcnt lgkmcnt(" #n ")" ::: "memory")
; template <class Epi, class Sched, bool ALIGN_EPI = false, bool SP2 = false>
; __device__ __forceinline__ void gemm_phase(LAS unsigned char* lds, const Gemm g, const Sched& S, const Epi& E) {
;     ...
;         for (int t = 0; t < nt; t += 2) {
;             const bool last = (t == nt - 2);
;             const char* a1 = cA + (size_t)(t + 1) * kstep;
;             const char* a2 = last ? nA : cA + (size_t)(t + 2) * kstep; const char* b2 = last ? nB : cB + (size_t)(t + 2) * kstep;
;             const char* a3 = a2 + kstep; const char* b3 = b2 + kstep;
;             if (last && has_next) S.a_ready(nxt);
;             if constexpr (SP2) {
;             PG8_LDB(B0, 0, 0); PG8_LDB(B1, 0, 1); PG8_SCHED; PG8_LDA(At, 0, 0); PG8_STAGE(PG8_SA(1, 1), a1 + hstep, voffA);
;             PG8_WAIT_V(8); PG8_WAIT_L(0); PG8_BAR; PG8_MMA(0, 0, At, B0); PG8_MMA(0, 1, At, B1); PG8_BAR; PG8_SCHED;
;             PG8_LDA(At, 0, 1); PG8_STAGE(PG8_SB(0, 0), b2, voffB); PG8_STAGE(PG8_SB(0, 1), b2 + hstepB, voffB); PG8_STAGE(PG8_SA(0, 0), a2, voffA);
;             PG8_WAIT_V(8); PG8_WAIT_L(0); PG8_BAR; PG8_MMA(1, 0, At, B0); PG8_MMA(1, 1, At, B1); PG8_BAR; PG8_SCHED;
.Lprio_1465:
	ds_read_b128 v[66:69], v174
	ds_read_b128 v[70:73], v174 offset:1024
	ds_read_b128 v[74:77], v174 offset:2048
	ds_read_b128 v[78:81], v174 offset:3072
	ds_read_b128 v[162:165], v175
	ds_read_b128 v[182:185], v175 offset:1024
	ds_read_b128 v[186:189], v175 offset:2048
	ds_read_b128 v[190:193], v175 offset:3072
	s_add_u32 s22, s16, 0xfff80080
	s_addc_u32 s23, s17, -1
	s_cmp_eq_u32 s53, 28
	s_cselect_b32 s41, s3, s23
	s_cselect_b32 s40, s15, s22
	s_cselect_b32 s23, s13, s52
	s_cselect_b32 s22, s24, s25
	s_add_i32 m0, s33, 0xc000
	ds_read_b128 v[194:197], v176
	ds_read_b128 v[198:201], v176 offset:1024
	ds_read_b128 v[202:205], v176 offset:2048
	ds_read_b128 v[206:209], v176 offset:3072
	ds_read_b128 v[210:213], v176 offset:4096
	ds_read_b128 v[214:217], v176 offset:5120
	ds_read_b128 v[218:221], v176 offset:6144
	ds_read_b128 v[222:225], v176 offset:7168
	global_load_lds_dwordx4 v154, s[16:17]
	s_add_i32 m0, s33, 0xe000
	s_nop 0
	global_load_lds_dwordx4 v156, s[16:17]
	s_waitcnt lgkmcnt(0)
	s_barrier
	s_waitcnt lgkmcnt(0)
	v_mfma_f32_16x16x32_bf16 v[142:145], v[66:69], v[194:197], 0
	v_mfma_f32_16x16x32_bf16 v[138:141], v[74:77], v[194:197], 0
	v_mfma_f32_16x16x32_bf16 v[126:129], v[66:69], v[202:205], 0
	v_mfma_f32_16x16x32_bf16 v[122:125], v[74:77], v[202:205], 0
	v_mfma_f32_16x16x32_bf16 v[110:113], v[66:69], v[210:213], 0
	v_mfma_f32_16x16x32_bf16 v[106:109], v[74:77], v[210:213], 0
	v_mfma_f32_16x16x32_bf16 v[94:97], v[66:69], v[218:221], 0
	v_mfma_f32_16x16x32_bf16 v[90:93], v[74:77], v[218:221], 0
	v_mfma_f32_16x16x32_bf16 v[142:145], v[70:73], v[198:201], v[142:145]
	v_mfma_f32_16x16x32_bf16 v[138:141], v[78:81], v[198:201], v[138:141]
	v_mfma_f32_16x16x32_bf16 v[126:129], v[70:73], v[206:209], v[126:129]
	v_mfma_f32_16x16x32_bf16 v[122:125], v[78:81], v[206:209], v[122:125]
	v_mfma_f32_16x16x32_bf16 v[110:113], v[70:73], v[214:217], v[110:113]
	v_mfma_f32_16x16x32_bf16 v[106:109], v[78:81], v[214:217], v[106:109]
	v_mfma_f32_16x16x32_bf16 v[94:97], v[70:73], v[222:225], v[94:97]
	v_mfma_f32_16x16x32_bf16 v[90:93], v[78:81], v[222:225], v[90:93]
	v_mfma_f32_16x16x32_bf16 v[134:137], v[162:165], v[194:197], 0
	v_mfma_f32_16x16x32_bf16 v[130:133], v[186:189], v[194:197], 0
	v_mfma_f32_16x16x32_bf16 v[118:121], v[162:165], v[202:205], 0
	v_mfma_f32_16x16x32_bf16 v[114:117], v[186:189], v[202:205], 0
	v_mfma_f32_16x16x32_bf16 v[102:105], v[162:165], v[210:213], 0
	v_mfma_f32_16x16x32_bf16 v[98:101], v[186:189], v[210:213], 0
	v_mfma_f32_16x16x32_bf16 v[86:89], v[162:165], v[218:221], 0
	v_mfma_f32_16x16x32_bf16 v[82:85], v[186:189], v[218:221], 0
	v_mfma_f32_16x16x32_bf16 v[134:137], v[182:185], v[198:201], v[134:137]
	v_mfma_f32_16x16x32_bf16 v[130:133], v[190:193], v[198:201], v[130:133]
	v_mfma_f32_16x16x32_bf16 v[118:121], v[182:185], v[206:209], v[118:121]
	v_mfma_f32_16x16x32_bf16 v[114:117], v[190:193], v[206:209], v[114:117]
	v_mfma_f32_16x16x32_bf16 v[102:105], v[182:185], v[214:217], v[102:105]
	v_mfma_f32_16x16x32_bf16 v[98:101], v[190:193], v[214:217], v[98:101]
	v_mfma_f32_16x16x32_bf16 v[86:89], v[182:185], v[222:225], v[86:89]
	v_mfma_f32_16x16x32_bf16 v[82:85], v[190:193], v[222:225], v[82:85]
	s_barrier
	s_add_i32 s54, s47, s29
	v_lshl_add_u64 v[166:167], s[22:23], 0, v[150:151]
	s_mov_b32 m0, s54
	ds_read_b128 v[194:197], v176 offset:16384
	ds_read_b128 v[198:201], v176 offset:17408
	ds_read_b128 v[202:205], v176 offset:18432
	ds_read_b128 v[206:209], v176 offset:19456
	ds_read_b128 v[210:213], v176 offset:20480
	ds_read_b128 v[214:217], v176 offset:21504
	ds_read_b128 v[218:221], v176 offset:22528
	ds_read_b128 v[222:225], v176 offset:23552
	global_load_lds_dwordx4 v[166:167], off
	s_add_i32 m0, s54, 0x2000
	s_add_u32 s54, s22, 0x80000
	v_lshl_add_u64 v[226:227], s[22:23], 0, v[146:147]
	s_addc_u32 s55, s23, 0
	s_add_i32 s56, s48, s29
	global_load_lds_dwordx4 v[226:227], off
	s_mov_b32 m0, s56
	v_lshl_add_u64 v[230:231], s[40:41], 0, v[148:149]
	global_load_lds_dwordx4 v150, s[54:55]
	s_add_i32 m0, s56, 0x2000
	s_nop 0
	global_load_lds_dwordx4 v146, s[54:55]
	v_lshl_add_u64 v[228:229], s[40:41], 0, v[152:153]
	s_mov_b32 m0, s33
	s_nop 0
	global_load_lds_dwordx4 v[228:229], off
	s_mov_b32 m0, s34
	s_nop 0
	global_load_lds_dwordx4 v[230:231], off
	s_waitcnt lgkmcnt(0)
	s_barrier
	s_waitcnt lgkmcnt(0)
	v_mfma_f32_16x16x32_bf16 v[62:65], v[66:69], v[194:197], 0
	v_mfma_f32_16x16x32_bf16 v[58:61], v[74:77], v[194:197], 0
	v_mfma_f32_16x16x32_bf16 v[46:49], v[66:69], v[202:205], 0
	v_mfma_f32_16x16x32_bf16 v[42:45], v[74:77], v[202:205], 0
	v_mfma_f32_16x16x32_bf16 v[30:33], v[66:69], v[210:213], 0
	v_mfma_f32_16x16x32_bf16 v[26:29], v[74:77], v[210:213], 0
	v_mfma_f32_16x16x32_bf16 v[14:17], v[66:69], v[218:221], 0
	v_mfma_f32_16x16x32_bf16 v[10:13], v[74:77], v[218:221], 0
	v_mfma_f32_16x16x32_bf16 v[62:65], v[70:73], v[198:201], v[62:65]
	v_mfma_f32_16x16x32_bf16 v[58:61], v[78:81], v[198:201], v[58:61]
	v_mfma_f32_16x16x32_bf16 v[46:49], v[70:73], v[206:209], v[46:49]
	v_mfma_f32_16x16x32_bf16 v[42:45], v[78:81], v[206:209], v[42:45]
	v_mfma_f32_16x16x32_bf16 v[30:33], v[70:73], v[214:217], v[30:33]
	v_mfma_f32_16x16x32_bf16 v[26:29], v[78:81], v[214:217], v[26:29]
	v_mfma_f32_16x16x32_bf16 v[14:17], v[70:73], v[222:225], v[14:17]
	v_mfma_f32_16x16x32_bf16 v[10:13], v[78:81], v[222:225], v[10:13]
	v_mfma_f32_16x16x32_bf16 v[54:57], v[162:165], v[194:197], 0
	v_mfma_f32_16x16x32_bf16 v[50:53], v[186:189], v[194:197], 0
	v_mfma_f32_16x16x32_bf16 v[38:41], v[162:165], v[202:205], 0
	v_mfma_f32_16x16x32_bf16 v[34:37], v[186:189], v[202:205], 0
	v_mfma_f32_16x16x32_bf16 v[22:25], v[162:165], v[210:213], 0
	v_mfma_f32_16x16x32_bf16 v[18:21], v[186:189], v[210:213], 0
	v_mfma_f32_16x16x32_bf16 v[6:9], v[162:165], v[218:221], 0
	v_mfma_f32_16x16x32_bf16 v[2:5], v[186:189], v[218:221], 0
	v_mfma_f32_16x16x32_bf16 v[54:57], v[182:185], v[198:201], v[54:57]
	v_mfma_f32_16x16x32_bf16 v[50:53], v[190:193], v[198:201], v[50:53]
	v_mfma_f32_16x16x32_bf16 v[38:41], v[182:185], v[206:209], v[38:41]
	v_mfma_f32_16x16x32_bf16 v[34:37], v[190:193], v[206:209], v[34:37]
	v_mfma_f32_16x16x32_bf16 v[22:25], v[182:185], v[214:217], v[22:25]
	v_mfma_f32_16x16x32_bf16 v[18:21], v[190:193], v[214:217], v[18:21]
	v_mfma_f32_16x16x32_bf16 v[6:9], v[182:185], v[222:225], v[6:9]
	v_mfma_f32_16x16x32_bf16 v[2:5], v[190:193], v[222:225], v[2:5]
	s_barrier
; #define PG8_STAGE(bufoff, gbase, voff) do { _Pragma("unroll") for (int _i = 0; _i < 2; ++_i) \
;         __builtin_amdgcn_global_load_lds((const unsigned*)((const char*)(gbase) + (voff)[_i]), (LAS unsigned*)(lds + (bufoff) + ldsw + _i * 8192), 16, 0, 0); } while (0)
; #define PG8_LDA(dst, b, h) do { _Pragma("unroll") for (int m = 0; m < 4; ++m) _Pragma("unroll") for (int k = 0; k < 2; ++k) dst[m][k] = *(const LAS bf16x8*)(lds + PG8_SA(b, h) + aoff + m * 2048 + k * 1024); } while (0)
; #define PG8_LDB(dst, b, h) do { _Pragma("unroll") for (int n = 0; n < 2; ++n) _Pragma("unroll") for (int k = 0; k < 2; ++k) dst[n][k] = *(const LAS bf16x8*)(lds + PG8_SB(b, h) + boff + n * 2048 + k * 1024); } while (0)
; #define PG8_MMA(ai, bj, At, Bt) do { __builtin_amdgcn_s_setprio(1); _Pragma("unroll") for (int m = 0; m < 4; ++m) _Pragma("unroll") for (int n = 0; n < 2; ++n) _Pragma("unroll") for (int k = 0; k < 2; ++k) \
;         acc[ai][bj][m][n] = __builtin_amdgcn_mfma_f32_16x16x32_bf16(Bt[n][k], At[m][k], acc[ai][bj][m][n], 0, 0, 0); __builtin_amdgcn_s_setprio(0); } while (0)
; #define PG8_WAIT_V(n) asm volatile("s_waitcnt vmcnt(" #n ")" ::: "memory")
; #define PG8_WAIT_L(n) asm volatile("s_waitcnt lgkmcnt(" #n ")" ::: "memory")
; #define PG8_BAR __builtin_amdgcn_s_barrier()
; #define PG8_SCHED __builtin_amdgcn_sched_barrier(0)
; template <class Epi, class Sched, bool ALIGN_EPI = false, bool SP2 = false>
; __device__ __forceinline__ void gemm_phase(LAS unsigned char* lds, const Gemm g, const Sched& S, const Epi& E) {
;     ...
;             PG8_LDB(B0, 1, 0); PG8_LDB(B1, 1, 1); PG8_SCHED; PG8_LDA(At, 1, 0); PG8_STAGE(PG8_SA(0, 1), a2 + hstep, voffA);
;             PG8_WAIT_V(8); PG8_WAIT_L(0); PG8_BAR; PG8_MMA(0, 0, At, B0); PG8_MMA(0, 1, At, B1); PG8_BAR; PG8_SCHED;
;             PG8_LDA(At, 1, 1); PG8_STAGE(PG8_SB(1, 0), b3, voffB); PG8_STAGE(PG8_SB(1, 1), b3 + hstepB, voffB); PG8_STAGE(PG8_SA(1, 0), a3, voffA);
;             PG8_WAIT_V(8); PG8_WAIT_L(0); PG8_BAR; PG8_MMA(1, 0, At, B0); PG8_MMA(1, 1, At, B1); PG8_BAR; PG8_SCHED;
	s_add_i32 s54, 0, 0x18000
	s_add_i32 s55, 0, 0x1c000
	v_add_u32_e32 v78, s54, v170
	v_add_u32_e32 v168, s55, v170
	ds_read_b128 v[66:69], v78
	ds_read_b128 v[70:73], v78 offset:1024
	ds_read_b128 v[74:77], v78 offset:2048
	ds_read_b128 v[78:81], v78 offset:3072
	ds_read_b128 v[162:165], v168
	ds_read_b128 v[182:185], v168 offset:1024
	ds_read_b128 v[186:189], v168 offset:2048
	ds_read_b128 v[190:193], v168 offset:3072
	s_add_u32 s40, s40, 0x80000
	s_addc_u32 s41, s41, 0
	s_mov_b32 m0, s35
	ds_read_b128 v[194:197], v176 offset:32768
	ds_read_b128 v[198:201], v176 offset:33792
	ds_read_b128 v[202:205], v176 offset:34816
	ds_read_b128 v[206:209], v176 offset:35840
	ds_read_b128 v[210:213], v176 offset:36864
	ds_read_b128 v[214:217], v176 offset:37888
	ds_read_b128 v[218:221], v176 offset:38912
	ds_read_b128 v[222:225], v176 offset:39936
	global_load_lds_dwordx4 v152, s[40:41]
	s_mov_b32 m0, s36
	s_nop 0
	global_load_lds_dwordx4 v148, s[40:41]
	s_waitcnt vmcnt(8)
	s_waitcnt lgkmcnt(0)
	s_barrier
	s_waitcnt lgkmcnt(0)
	v_mfma_f32_16x16x32_bf16 v[142:145], v[66:69], v[194:197], v[142:145]
	v_mfma_f32_16x16x32_bf16 v[138:141], v[74:77], v[194:197], v[138:141]
	v_mfma_f32_16x16x32_bf16 v[126:129], v[66:69], v[202:205], v[126:129]
	v_mfma_f32_16x16x32_bf16 v[122:125], v[74:77], v[202:205], v[122:125]
	v_mfma_f32_16x16x32_bf16 v[110:113], v[66:69], v[210:213], v[110:113]
	v_mfma_f32_16x16x32_bf16 v[106:109], v[74:77], v[210:213], v[106:109]
	v_mfma_f32_16x16x32_bf16 v[94:97], v[66:69], v[218:221], v[94:97]
	v_mfma_f32_16x16x32_bf16 v[90:93], v[74:77], v[218:221], v[90:93]
	v_mfma_f32_16x16x32_bf16 v[142:145], v[70:73], v[198:201], v[142:145]
	v_mfma_f32_16x16x32_bf16 v[138:141], v[78:81], v[198:201], v[138:141]
	v_mfma_f32_16x16x32_bf16 v[126:129], v[70:73], v[206:209], v[126:129]
	v_mfma_f32_16x16x32_bf16 v[122:125], v[78:81], v[206:209], v[122:125]
	v_mfma_f32_16x16x32_bf16 v[110:113], v[70:73], v[214:217], v[110:113]
	v_mfma_f32_16x16x32_bf16 v[106:109], v[78:81], v[214:217], v[106:109]
	v_mfma_f32_16x16x32_bf16 v[94:97], v[70:73], v[222:225], v[94:97]
	v_mfma_f32_16x16x32_bf16 v[90:93], v[78:81], v[222:225], v[90:93]
	v_mfma_f32_16x16x32_bf16 v[134:137], v[162:165], v[194:197], v[134:137]
	v_mfma_f32_16x16x32_bf16 v[130:133], v[186:189], v[194:197], v[130:133]
	v_mfma_f32_16x16x32_bf16 v[118:121], v[162:165], v[202:205], v[118:121]
	v_mfma_f32_16x16x32_bf16 v[114:117], v[186:189], v[202:205], v[114:117]
	v_mfma_f32_16x16x32_bf16 v[102:105], v[162:165], v[210:213], v[102:105]
	v_mfma_f32_16x16x32_bf16 v[98:101], v[186:189], v[210:213], v[98:101]
	v_mfma_f32_16x16x32_bf16 v[86:89], v[162:165], v[218:221], v[86:89]
	v_mfma_f32_16x16x32_bf16 v[82:85], v[186:189], v[218:221], v[82:85]
	v_mfma_f32_16x16x32_bf16 v[134:137], v[182:185], v[198:201], v[134:137]
	v_mfma_f32_16x16x32_bf16 v[130:133], v[190:193], v[198:201], v[130:133]
	v_mfma_f32_16x16x32_bf16 v[118:121], v[182:185], v[206:209], v[118:121]
	v_mfma_f32_16x16x32_bf16 v[114:117], v[190:193], v[206:209], v[114:117]
	v_mfma_f32_16x16x32_bf16 v[102:105], v[182:185], v[214:217], v[102:105]
	v_mfma_f32_16x16x32_bf16 v[98:101], v[190:193], v[214:217], v[98:101]
	v_mfma_f32_16x16x32_bf16 v[86:89], v[182:185], v[222:225], v[86:89]
	v_mfma_f32_16x16x32_bf16 v[82:85], v[190:193], v[222:225], v[82:85]
	s_barrier
	s_add_i32 s40, s54, s29
	v_lshl_add_u64 v[166:167], v[166:167], 0, s[8:9]
	s_mov_b32 m0, s40
	ds_read_b128 v[194:197], v176 offset:49152
	ds_read_b128 v[198:201], v176 offset:50176
	ds_read_b128 v[202:205], v176 offset:51200
	ds_read_b128 v[206:209], v176 offset:52224
	ds_read_b128 v[210:213], v176 offset:53248
	ds_read_b128 v[214:217], v176 offset:54272
	ds_read_b128 v[218:221], v176 offset:55296
	ds_read_b128 v[222:225], v176 offset:56320
	global_load_lds_dwordx4 v[166:167], off
	s_add_i32 m0, s40, 0x2000
	s_add_u32 s22, s22, 0x80080
	v_lshl_add_u64 v[166:167], v[226:227], 0, s[8:9]
	s_addc_u32 s23, s23, 0
	s_add_i32 s40, s55, s29
	global_load_lds_dwordx4 v[166:167], off
	s_mov_b32 m0, s40
	s_nop 0
	global_load_lds_dwordx4 v150, s[22:23]
	s_add_i32 m0, s40, 0x2000
	s_nop 0
	global_load_lds_dwordx4 v146, s[22:23]
	v_lshl_add_u64 v[166:167], v[228:229], 0, s[8:9]
	s_mov_b32 m0, s45
	s_nop 0
	global_load_lds_dwordx4 v[166:167], off
	v_lshl_add_u64 v[166:167], v[230:231], 0, s[8:9]
	s_mov_b32 m0, s46
	s_nop 0
	global_load_lds_dwordx4 v[166:167], off
	s_waitcnt vmcnt(8)
	s_waitcnt lgkmcnt(0)
	s_barrier
	s_waitcnt lgkmcnt(0)
	v_mfma_f32_16x16x32_bf16 v[62:65], v[66:69], v[194:197], v[62:65]
	v_mfma_f32_16x16x32_bf16 v[58:61], v[74:77], v[194:197], v[58:61]
	v_mfma_f32_16x16x32_bf16 v[46:49], v[66:69], v[202:205], v[46:49]
	v_mfma_f32_16x16x32_bf16 v[42:45], v[74:77], v[202:205], v[42:45]
	v_mfma_f32_16x16x32_bf16 v[30:33], v[66:69], v[210:213], v[30:33]
	v_mfma_f32_16x16x32_bf16 v[26:29], v[74:77], v[210:213], v[26:29]
	v_mfma_f32_16x16x32_bf16 v[14:17], v[66:69], v[218:221], v[14:17]
	v_mfma_f32_16x16x32_bf16 v[10:13], v[74:77], v[218:221], v[10:13]
	v_mfma_f32_16x16x32_bf16 v[62:65], v[70:73], v[198:201], v[62:65]
	v_mfma_f32_16x16x32_bf16 v[58:61], v[78:81], v[198:201], v[58:61]
	v_mfma_f32_16x16x32_bf16 v[46:49], v[70:73], v[206:209], v[46:49]
	v_mfma_f32_16x16x32_bf16 v[42:45], v[78:81], v[206:209], v[42:45]
	v_mfma_f32_16x16x32_bf16 v[30:33], v[70:73], v[214:217], v[30:33]
	v_mfma_f32_16x16x32_bf16 v[26:29], v[78:81], v[214:217], v[26:29]
	v_mfma_f32_16x16x32_bf16 v[14:17], v[70:73], v[222:225], v[14:17]
	v_mfma_f32_16x16x32_bf16 v[10:13], v[78:81], v[222:225], v[10:13]
	v_mfma_f32_16x16x32_bf16 v[54:57], v[162:165], v[194:197], v[54:57]
	v_mfma_f32_16x16x32_bf16 v[50:53], v[186:189], v[194:197], v[50:53]
	v_mfma_f32_16x16x32_bf16 v[38:41], v[162:165], v[202:205], v[38:41]
	v_mfma_f32_16x16x32_bf16 v[34:37], v[186:189], v[202:205], v[34:37]
	v_mfma_f32_16x16x32_bf16 v[22:25], v[162:165], v[210:213], v[22:25]
	v_mfma_f32_16x16x32_bf16 v[18:21], v[186:189], v[210:213], v[18:21]
	v_mfma_f32_16x16x32_bf16 v[6:9], v[162:165], v[218:221], v[6:9]
	v_mfma_f32_16x16x32_bf16 v[2:5], v[186:189], v[218:221], v[2:5]
	v_mfma_f32_16x16x32_bf16 v[54:57], v[182:185], v[198:201], v[54:57]
	v_mfma_f32_16x16x32_bf16 v[50:53], v[190:193], v[198:201], v[50:53]
	v_mfma_f32_16x16x32_bf16 v[38:41], v[182:185], v[206:209], v[38:41]
	v_mfma_f32_16x16x32_bf16 v[34:37], v[190:193], v[206:209], v[34:37]
	v_mfma_f32_16x16x32_bf16 v[22:25], v[182:185], v[214:217], v[22:25]
	v_mfma_f32_16x16x32_bf16 v[18:21], v[190:193], v[214:217], v[18:21]
	v_mfma_f32_16x16x32_bf16 v[6:9], v[182:185], v[222:225], v[6:9]
	v_mfma_f32_16x16x32_bf16 v[2:5], v[190:193], v[222:225], v[2:5]
	s_barrier
	s_add_i32 s53, s53, 2
	s_add_u32 s16, s16, 0x100
	s_addc_u32 s17, s17, 0
	s_add_u32 s25, s25, 0x100
	s_addc_u32 s52, s52, 0
	s_cmp_gt_u32 s53, 29
; #define PG8_STAGE(bufoff, gbase, voff) do { _Pragma("unroll") for (int _i = 0; _i < 2; ++_i) \
;         __builtin_amdgcn_global_load_lds((const unsigned*)((const char*)(gbase) + (voff)[_i]), (LAS unsigned*)(lds + (bufoff) + ldsw + _i * 8192), 16, 0, 0); } while (0)
; #define PG8_LDA(dst, b, h) do { _Pragma("unroll") for (int m = 0; m < 4; ++m) _Pragma("unroll") for (int k = 0; k < 2; ++k) dst[m][k] = *(const LAS bf16x8*)(lds + PG8_SA(b, h) + aoff + m * 2048 + k * 1024); } while (0)
; #define PG8_LDB(dst, b, h) do { _Pragma("unroll") for (int n = 0; n < 2; ++n) _Pragma("unroll") for (int k = 0; k < 2; ++k) dst[n][k] = *(const LAS bf16x8*)(lds + PG8_SB(b, h) + boff + n * 2048 + k * 1024); } while (0)
; #define PG8_WAIT_V(n) asm volatile("s_waitcnt vmcnt(" #n ")" ::: "memory")
; #define PG8_WAIT_L(n) asm volatile("s_waitcnt lgkmcnt(" #n ")" ::: "memory")
; #define PG8_BAR __builtin_amdgcn_s_barrier()
; #define PG8_SCHED __builtin_amdgcn_sched_barrier(0)
; template <class Epi, class Sched, bool ALIGN_EPI = false, bool SP2 = false>
; __device__ __forceinline__ void gemm_phase(LAS unsigned char* lds, const Gemm g, const Sched& S, const Epi& E) {
;     ...
;         for (int t = 0; t < nt; t += 2) {
;             const bool last = (t == nt - 2);
;             const char* a1 = cA + (size_t)(t + 1) * kstep;
;             const char* a2 = last ? nA : cA + (size_t)(t + 2) * kstep; const char* b2 = last ? nB : cB + (size_t)(t + 2) * kstep;
;             const char* a3 = a2 + kstep; const char* b3 = b2 + kstep;
;             if (last && has_next) S.a_ready(nxt);
;             if constexpr (SP2) {
;             PG8_LDB(B0, 0, 0); PG8_LDB(B1, 0, 1); PG8_SCHED; PG8_LDA(At, 0, 0); PG8_STAGE(PG8_SA(1, 1), a1 + hstep, voffA);
;             PG8_WAIT_V(8); PG8_WAIT_L(0); PG8_BAR; PG8_MMA(0, 0, At, B0); PG8_MMA(0, 1, At, B1); PG8_BAR; PG8_SCHED;
;             PG8_LDA(At, 0, 1); PG8_STAGE(PG8_SB(0, 0), b2, voffB); PG8_STAGE(PG8_SB(0, 1), b2 + hstepB, voffB); PG8_STAGE(PG8_SA(0, 0), a2, voffA);
;             PG8_WAIT_V(8); PG8_WAIT_L(0); PG8_BAR; PG8_MMA(1, 0, At, B0); PG8_MMA(1, 1, At, B1); PG8_BAR; PG8_SCHED;
;             PG8_LDB(B0, 1, 0); PG8_LDB(B1, 1, 1); PG8_SCHED; PG8_LDA(At, 1, 0); PG8_STAGE(PG8_SA(0, 1), a2 + hstep, voffA);
;             PG8_WAIT_V(8); PG8_WAIT_L(0); PG8_BAR; PG8_MMA(0, 0, At, B0); PG8_MMA(0, 1, At, B1); PG8_BAR; PG8_SCHED;
.LBB0_1465:
	ds_read_b128 v[66:69], v174
	ds_read_b128 v[70:73], v174 offset:1024
	ds_read_b128 v[74:77], v174 offset:2048
	ds_read_b128 v[78:81], v174 offset:3072
	ds_read_b128 v[162:165], v175
	ds_read_b128 v[182:185], v175 offset:1024
	ds_read_b128 v[186:189], v175 offset:2048
	ds_read_b128 v[190:193], v175 offset:3072
	s_add_u32 s22, s16, 0xfff80080
	s_addc_u32 s23, s17, -1
	s_cmp_eq_u32 s53, 28
	s_cselect_b32 s41, s3, s23
	s_cselect_b32 s40, s15, s22
	s_cselect_b32 s23, s13, s52
	s_cselect_b32 s22, s24, s25
	s_add_i32 m0, s33, 0xc000
	ds_read_b128 v[194:197], v176
	ds_read_b128 v[198:201], v176 offset:1024
	ds_read_b128 v[202:205], v176 offset:2048
	ds_read_b128 v[206:209], v176 offset:3072
	ds_read_b128 v[210:213], v176 offset:4096
	ds_read_b128 v[214:217], v176 offset:5120
	ds_read_b128 v[218:221], v176 offset:6144
	ds_read_b128 v[222:225], v176 offset:7168
	global_load_lds_dwordx4 v154, s[16:17]
	s_add_i32 m0, s33, 0xe000
	s_nop 0
	global_load_lds_dwordx4 v156, s[16:17]
	s_waitcnt vmcnt(8)
	s_waitcnt lgkmcnt(0)
	s_barrier
	s_waitcnt lgkmcnt(0)
	v_mfma_f32_16x16x32_bf16 v[142:145], v[66:69], v[194:197], v[142:145]
	v_mfma_f32_16x16x32_bf16 v[138:141], v[74:77], v[194:197], v[138:141]
	v_mfma_f32_16x16x32_bf16 v[126:129], v[66:69], v[202:205], v[126:129]
	v_mfma_f32_16x16x32_bf16 v[122:125], v[74:77], v[202:205], v[122:125]
	v_mfma_f32_16x16x32_bf16 v[110:113], v[66:69], v[210:213], v[110:113]
	v_mfma_f32_16x16x32_bf16 v[106:109], v[74:77], v[210:213], v[106:109]
	v_mfma_f32_16x16x32_bf16 v[94:97], v[66:69], v[218:221], v[94:97]
	v_mfma_f32_16x16x32_bf16 v[90:93], v[74:77], v[218:221], v[90:93]
	v_mfma_f32_16x16x32_bf16 v[142:145], v[70:73], v[198:201], v[142:145]
	v_mfma_f32_16x16x32_bf16 v[138:141], v[78:81], v[198:201], v[138:141]
	v_mfma_f32_16x16x32_bf16 v[126:129], v[70:73], v[206:209], v[126:129]
	v_mfma_f32_16x16x32_bf16 v[122:125], v[78:81], v[206:209], v[122:125]
	v_mfma_f32_16x16x32_bf16 v[110:113], v[70:73], v[214:217], v[110:113]
	v_mfma_f32_16x16x32_bf16 v[106:109], v[78:81], v[214:217], v[106:109]
	v_mfma_f32_16x16x32_bf16 v[94:97], v[70:73], v[222:225], v[94:97]
	v_mfma_f32_16x16x32_bf16 v[90:93], v[78:81], v[222:225], v[90:93]
	v_mfma_f32_16x16x32_bf16 v[134:137], v[162:165], v[194:197], v[134:137]
	v_mfma_f32_16x16x32_bf16 v[130:133], v[186:189], v[194:197], v[130:133]
	v_mfma_f32_16x16x32_bf16 v[118:121], v[162:165], v[202:205], v[118:121]
	v_mfma_f32_16x16x32_bf16 v[114:117], v[186:189], v[202:205], v[114:117]
	v_mfma_f32_16x16x32_bf16 v[102:105], v[162:165], v[210:213], v[102:105]
	v_mfma_f32_16x16x32_bf16 v[98:101], v[186:189], v[210:213], v[98:101]
	v_mfma_f32_16x16x32_bf16 v[86:89], v[162:165], v[218:221], v[86:89]
	v_mfma_f32_16x16x32_bf16 v[82:85], v[186:189], v[218:221], v[82:85]
	v_mfma_f32_16x16x32_bf16 v[134:137], v[182:185], v[198:201], v[134:137]
	v_mfma_f32_16x16x32_bf16 v[130:133], v[190:193], v[198:201], v[130:133]
	v_mfma_f32_16x16x32_bf16 v[118:121], v[182:185], v[206:209], v[118:121]
	v_mfma_f32_16x16x32_bf16 v[114:117], v[190:193], v[206:209], v[114:117]
	v_mfma_f32_16x16x32_bf16 v[102:105], v[182:185], v[214:217], v[102:105]
	v_mfma_f32_16x16x32_bf16 v[98:101], v[190:193], v[214:217], v[98:101]
	v_mfma_f32_16x16x32_bf16 v[86:89], v[182:185], v[222:225], v[86:89]
	v_mfma_f32_16x16x32_bf16 v[82:85], v[190:193], v[222:225], v[82:85]
	s_barrier
	s_add_i32 s54, s47, s29
	v_lshl_add_u64 v[166:167], s[22:23], 0, v[150:151]
	s_mov_b32 m0, s54
	ds_read_b128 v[194:197], v176 offset:16384
	ds_read_b128 v[198:201], v176 offset:17408
	ds_read_b128 v[202:205], v176 offset:18432
	ds_read_b128 v[206:209], v176 offset:19456
	ds_read_b128 v[210:213], v176 offset:20480
	ds_read_b128 v[214:217], v176 offset:21504
	ds_read_b128 v[218:221], v176 offset:22528
	ds_read_b128 v[222:225], v176 offset:23552
	global_load_lds_dwordx4 v[166:167], off
	s_add_i32 m0, s54, 0x2000
	s_add_u32 s54, s22, 0x80000
	v_lshl_add_u64 v[226:227], s[22:23], 0, v[146:147]
	s_addc_u32 s55, s23, 0
	s_add_i32 s56, s48, s29
	global_load_lds_dwordx4 v[226:227], off
	s_mov_b32 m0, s56
	v_lshl_add_u64 v[230:231], s[40:41], 0, v[148:149]
	global_load_lds_dwordx4 v150, s[54:55]
	s_add_i32 m0, s56, 0x2000
	s_nop 0
	global_load_lds_dwordx4 v146, s[54:55]
	v_lshl_add_u64 v[228:229], s[40:41], 0, v[152:153]
	s_mov_b32 m0, s33
	s_nop 0
	global_load_lds_dwordx4 v[228:229], off
	s_mov_b32 m0, s34
	s_nop 0
	global_load_lds_dwordx4 v[230:231], off
	s_waitcnt vmcnt(8)
	s_waitcnt lgkmcnt(0)
	s_barrier
	s_waitcnt lgkmcnt(0)
	v_mfma_f32_16x16x32_bf16 v[62:65], v[66:69], v[194:197], v[62:65]
	v_mfma_f32_16x16x32_bf16 v[58:61], v[74:77], v[194:197], v[58:61]
	v_mfma_f32_16x16x32_bf16 v[46:49], v[66:69], v[202:205], v[46:49]
	v_mfma_f32_16x16x32_bf16 v[42:45], v[74:77], v[202:205], v[42:45]
	v_mfma_f32_16x16x32_bf16 v[30:33], v[66:69], v[210:213], v[30:33]
	v_mfma_f32_16x16x32_bf16 v[26:29], v[74:77], v[210:213], v[26:29]
	v_mfma_f32_16x16x32_bf16 v[14:17], v[66:69], v[218:221], v[14:17]
	v_mfma_f32_16x16x32_bf16 v[10:13], v[74:77], v[218:221], v[10:13]
	v_mfma_f32_16x16x32_bf16 v[62:65], v[70:73], v[198:201], v[62:65]
	v_mfma_f32_16x16x32_bf16 v[58:61], v[78:81], v[198:201], v[58:61]
	v_mfma_f32_16x16x32_bf16 v[46:49], v[70:73], v[206:209], v[46:49]
	v_mfma_f32_16x16x32_bf16 v[42:45], v[78:81], v[206:209], v[42:45]
	v_mfma_f32_16x16x32_bf16 v[30:33], v[70:73], v[214:217], v[30:33]
	v_mfma_f32_16x16x32_bf16 v[26:29], v[78:81], v[214:217], v[26:29]
	v_mfma_f32_16x16x32_bf16 v[14:17], v[70:73], v[222:225], v[14:17]
	v_mfma_f32_16x16x32_bf16 v[10:13], v[78:81], v[222:225], v[10:13]
	v_mfma_f32_16x16x32_bf16 v[54:57], v[162:165], v[194:197], v[54:57]
	v_mfma_f32_16x16x32_bf16 v[50:53], v[186:189], v[194:197], v[50:53]
	v_mfma_f32_16x16x32_bf16 v[38:41], v[162:165], v[202:205], v[38:41]
	v_mfma_f32_16x16x32_bf16 v[34:37], v[186:189], v[202:205], v[34:37]
	v_mfma_f32_16x16x32_bf16 v[22:25], v[162:165], v[210:213], v[22:25]
	v_mfma_f32_16x16x32_bf16 v[18:21], v[186:189], v[210:213], v[18:21]
	v_mfma_f32_16x16x32_bf16 v[6:9], v[162:165], v[218:221], v[6:9]
	v_mfma_f32_16x16x32_bf16 v[2:5], v[186:189], v[218:221], v[2:5]
	v_mfma_f32_16x16x32_bf16 v[54:57], v[182:185], v[198:201], v[54:57]
	v_mfma_f32_16x16x32_bf16 v[50:53], v[190:193], v[198:201], v[50:53]
	v_mfma_f32_16x16x32_bf16 v[38:41], v[182:185], v[206:209], v[38:41]
	v_mfma_f32_16x16x32_bf16 v[34:37], v[190:193], v[206:209], v[34:37]
	v_mfma_f32_16x16x32_bf16 v[22:25], v[182:185], v[214:217], v[22:25]
	v_mfma_f32_16x16x32_bf16 v[18:21], v[190:193], v[214:217], v[18:21]
	v_mfma_f32_16x16x32_bf16 v[6:9], v[182:185], v[222:225], v[6:9]
	v_mfma_f32_16x16x32_bf16 v[2:5], v[190:193], v[222:225], v[2:5]
	s_barrier
; #define PG8_STAGE(bufoff, gbase, voff) do { _Pragma("unroll") for (int _i = 0; _i < 2; ++_i) \
;         __builtin_amdgcn_global_load_lds((const unsigned*)((const char*)(gbase) + (voff)[_i]), (LAS unsigned*)(lds + (bufoff) + ldsw + _i * 8192), 16, 0, 0); } while (0)
; #define PG8_LDA(dst, b, h) do { _Pragma("unroll") for (int m = 0; m < 4; ++m) _Pragma("unroll") for (int k = 0; k < 2; ++k) dst[m][k] = *(const LAS bf16x8*)(lds + PG8_SA(b, h) + aoff + m * 2048 + k * 1024); } while (0)
; #define PG8_LDB(dst, b, h) do { _Pragma("unroll") for (int n = 0; n < 2; ++n) _Pragma("unroll") for (int k = 0; k < 2; ++k) dst[n][k] = *(const LAS bf16x8*)(lds + PG8_SB(b, h) + boff + n * 2048 + k * 1024); } while (0)
; #define PG8_MMA(ai, bj, At, Bt) do { __builtin_amdgcn_s_setprio(1); _Pragma("unroll") for (int m = 0; m < 4; ++m) _Pragma("unroll") for (int n = 0; n < 2; ++n) _Pragma("unroll") for (int k = 0; k < 2; ++k) \
;         acc[ai][bj][m][n] = __builtin_amdgcn_mfma_f32_16x16x32_bf16(Bt[n][k], At[m][k], acc[ai][bj][m][n], 0, 0, 0); __builtin_amdgcn_s_setprio(0); } while (0)
; #define PG8_WAIT_V(n) asm volatile("s_waitcnt vmcnt(" #n ")" ::: "memory")
; #define PG8_WAIT_L(n) asm volatile("s_waitcnt lgkmcnt(" #n ")" ::: "memory")
; #define PG8_BAR __builtin_amdgcn_s_barrier()
; #define PG8_SCHED __builtin_amdgcn_sched_barrier(0)
; template <class Epi, class Sched, bool ALIGN_EPI = false, bool SP2 = false>
; __device__ __forceinline__ void gemm_phase(LAS unsigned char* lds, const Gemm g, const Sched& S, const Epi& E) {
;     ...
;             PG8_LDB(B0, 1, 0); PG8_LDB(B1, 1, 1); PG8_SCHED; PG8_LDA(At, 1, 0); PG8_STAGE(PG8_SA(0, 1), a2 + hstep, voffA);
;             PG8_WAIT_V(8); PG8_WAIT_L(0); PG8_BAR; PG8_MMA(0, 0, At, B0); PG8_MMA(0, 1, At, B1); PG8_BAR; PG8_SCHED;
;             PG8_LDA(At, 1, 1); PG8_STAGE(PG8_SB(1, 0), b3, voffB); PG8_STAGE(PG8_SB(1, 1), b3 + hstepB, voffB); PG8_STAGE(PG8_SA(1, 0), a3, voffA);
;             PG8_WAIT_V(8); PG8_WAIT_L(0); PG8_BAR; PG8_MMA(1, 0, At, B0); PG8_MMA(1, 1, At, B1); PG8_BAR; PG8_SCHED;
;     ...
;         if constexpr (ALIGN_EPI) { if (wr == 0) PG8_BAR; }
	s_add_i32 s54, 0, 0x18000
	s_add_i32 s55, 0, 0x1c000
	v_add_u32_e32 v78, s54, v170
	v_add_u32_e32 v168, s55, v170
	ds_read_b128 v[66:69], v78
	ds_read_b128 v[70:73], v78 offset:1024
	ds_read_b128 v[74:77], v78 offset:2048
	ds_read_b128 v[78:81], v78 offset:3072
	ds_read_b128 v[162:165], v168
	ds_read_b128 v[182:185], v168 offset:1024
	ds_read_b128 v[186:189], v168 offset:2048
	ds_read_b128 v[190:193], v168 offset:3072
	s_add_u32 s40, s40, 0x80000
	s_addc_u32 s41, s41, 0
	s_mov_b32 m0, s35
	ds_read_b128 v[194:197], v176 offset:32768
	ds_read_b128 v[198:201], v176 offset:33792
	ds_read_b128 v[202:205], v176 offset:34816
	ds_read_b128 v[206:209], v176 offset:35840
	ds_read_b128 v[210:213], v176 offset:36864
	ds_read_b128 v[214:217], v176 offset:37888
	ds_read_b128 v[218:221], v176 offset:38912
	ds_read_b128 v[222:225], v176 offset:39936
	global_load_lds_dwordx4 v152, s[40:41]
	s_mov_b32 m0, s36
	s_nop 0
	global_load_lds_dwordx4 v148, s[40:41]
	s_waitcnt vmcnt(8)
	s_waitcnt lgkmcnt(0)
	s_barrier
	s_waitcnt lgkmcnt(0)
	v_mfma_f32_16x16x32_bf16 v[142:145], v[66:69], v[194:197], v[142:145]
	v_mfma_f32_16x16x32_bf16 v[138:141], v[74:77], v[194:197], v[138:141]
	v_mfma_f32_16x16x32_bf16 v[126:129], v[66:69], v[202:205], v[126:129]
	v_mfma_f32_16x16x32_bf16 v[122:125], v[74:77], v[202:205], v[122:125]
	v_mfma_f32_16x16x32_bf16 v[110:113], v[66:69], v[210:213], v[110:113]
	v_mfma_f32_16x16x32_bf16 v[106:109], v[74:77], v[210:213], v[106:109]
	v_mfma_f32_16x16x32_bf16 v[94:97], v[66:69], v[218:221], v[94:97]
	v_mfma_f32_16x16x32_bf16 v[90:93], v[74:77], v[218:221], v[90:93]
	v_mfma_f32_16x16x32_bf16 v[142:145], v[70:73], v[198:201], v[142:145]
	v_mfma_f32_16x16x32_bf16 v[138:141], v[78:81], v[198:201], v[138:141]
	v_mfma_f32_16x16x32_bf16 v[126:129], v[70:73], v[206:209], v[126:129]
	v_mfma_f32_16x16x32_bf16 v[122:125], v[78:81], v[206:209], v[122:125]
	v_mfma_f32_16x16x32_bf16 v[110:113], v[70:73], v[214:217], v[110:113]
	v_mfma_f32_16x16x32_bf16 v[106:109], v[78:81], v[214:217], v[106:109]
	v_mfma_f32_16x16x32_bf16 v[94:97], v[70:73], v[222:225], v[94:97]
	v_mfma_f32_16x16x32_bf16 v[90:93], v[78:81], v[222:225], v[90:93]
	v_mfma_f32_16x16x32_bf16 v[134:137], v[162:165], v[194:197], v[134:137]
	v_mfma_f32_16x16x32_bf16 v[130:133], v[186:189], v[194:197], v[130:133]
	v_mfma_f32_16x16x32_bf16 v[118:121], v[162:165], v[202:205], v[118:121]
	v_mfma_f32_16x16x32_bf16 v[114:117], v[186:189], v[202:205], v[114:117]
	v_mfma_f32_16x16x32_bf16 v[102:105], v[162:165], v[210:213], v[102:105]
	v_mfma_f32_16x16x32_bf16 v[98:101], v[186:189], v[210:213], v[98:101]
	v_mfma_f32_16x16x32_bf16 v[86:89], v[162:165], v[218:221], v[86:89]
	v_mfma_f32_16x16x32_bf16 v[82:85], v[186:189], v[218:221], v[82:85]
	v_mfma_f32_16x16x32_bf16 v[134:137], v[182:185], v[198:201], v[134:137]
	v_mfma_f32_16x16x32_bf16 v[130:133], v[190:193], v[198:201], v[130:133]
	v_mfma_f32_16x16x32_bf16 v[118:121], v[182:185], v[206:209], v[118:121]
	v_mfma_f32_16x16x32_bf16 v[114:117], v[190:193], v[206:209], v[114:117]
	v_mfma_f32_16x16x32_bf16 v[102:105], v[182:185], v[214:217], v[102:105]
	v_mfma_f32_16x16x32_bf16 v[98:101], v[190:193], v[214:217], v[98:101]
	v_mfma_f32_16x16x32_bf16 v[86:89], v[182:185], v[222:225], v[86:89]
	v_mfma_f32_16x16x32_bf16 v[82:85], v[190:193], v[222:225], v[82:85]
	s_barrier
	s_add_i32 s40, s54, s29
	v_lshl_add_u64 v[166:167], v[166:167], 0, s[8:9]
	s_mov_b32 m0, s40
	ds_read_b128 v[194:197], v176 offset:49152
	ds_read_b128 v[198:201], v176 offset:50176
	ds_read_b128 v[202:205], v176 offset:51200
	ds_read_b128 v[206:209], v176 offset:52224
	ds_read_b128 v[210:213], v176 offset:53248
	ds_read_b128 v[214:217], v176 offset:54272
	ds_read_b128 v[218:221], v176 offset:55296
	ds_read_b128 v[222:225], v176 offset:56320
	global_load_lds_dwordx4 v[166:167], off
	s_add_i32 m0, s40, 0x2000
	s_add_u32 s22, s22, 0x80080
	v_lshl_add_u64 v[166:167], v[226:227], 0, s[8:9]
	s_addc_u32 s23, s23, 0
	s_add_i32 s40, s55, s29
	global_load_lds_dwordx4 v[166:167], off
	s_mov_b32 m0, s40
	s_nop 0
	global_load_lds_dwordx4 v150, s[22:23]
	s_add_i32 m0, s40, 0x2000
	s_nop 0
	global_load_lds_dwordx4 v146, s[22:23]
	v_lshl_add_u64 v[166:167], v[228:229], 0, s[8:9]
	s_mov_b32 m0, s45
	s_nop 0
	global_load_lds_dwordx4 v[166:167], off
	v_lshl_add_u64 v[166:167], v[230:231], 0, s[8:9]
	s_mov_b32 m0, s46
	s_nop 0
	global_load_lds_dwordx4 v[166:167], off
	s_waitcnt vmcnt(8)
	s_waitcnt lgkmcnt(0)
	s_barrier
	s_waitcnt lgkmcnt(0)
	v_mfma_f32_16x16x32_bf16 v[62:65], v[66:69], v[194:197], v[62:65]
	v_mfma_f32_16x16x32_bf16 v[58:61], v[74:77], v[194:197], v[58:61]
	v_mfma_f32_16x16x32_bf16 v[46:49], v[66:69], v[202:205], v[46:49]
	v_mfma_f32_16x16x32_bf16 v[42:45], v[74:77], v[202:205], v[42:45]
	v_mfma_f32_16x16x32_bf16 v[30:33], v[66:69], v[210:213], v[30:33]
	v_mfma_f32_16x16x32_bf16 v[26:29], v[74:77], v[210:213], v[26:29]
	v_mfma_f32_16x16x32_bf16 v[14:17], v[66:69], v[218:221], v[14:17]
	v_mfma_f32_16x16x32_bf16 v[10:13], v[74:77], v[218:221], v[10:13]
	v_mfma_f32_16x16x32_bf16 v[62:65], v[70:73], v[198:201], v[62:65]
	v_mfma_f32_16x16x32_bf16 v[58:61], v[78:81], v[198:201], v[58:61]
	v_mfma_f32_16x16x32_bf16 v[46:49], v[70:73], v[206:209], v[46:49]
	v_mfma_f32_16x16x32_bf16 v[42:45], v[78:81], v[206:209], v[42:45]
	v_mfma_f32_16x16x32_bf16 v[30:33], v[70:73], v[214:217], v[30:33]
	v_mfma_f32_16x16x32_bf16 v[26:29], v[78:81], v[214:217], v[26:29]
	v_mfma_f32_16x16x32_bf16 v[14:17], v[70:73], v[222:225], v[14:17]
	v_mfma_f32_16x16x32_bf16 v[10:13], v[78:81], v[222:225], v[10:13]
	v_mfma_f32_16x16x32_bf16 v[54:57], v[162:165], v[194:197], v[54:57]
	v_mfma_f32_16x16x32_bf16 v[50:53], v[186:189], v[194:197], v[50:53]
	v_mfma_f32_16x16x32_bf16 v[38:41], v[162:165], v[202:205], v[38:41]
	v_mfma_f32_16x16x32_bf16 v[34:37], v[186:189], v[202:205], v[34:37]
	v_mfma_f32_16x16x32_bf16 v[22:25], v[162:165], v[210:213], v[22:25]
	v_mfma_f32_16x16x32_bf16 v[18:21], v[186:189], v[210:213], v[18:21]
	v_mfma_f32_16x16x32_bf16 v[6:9], v[162:165], v[218:221], v[6:9]
	v_mfma_f32_16x16x32_bf16 v[2:5], v[186:189], v[218:221], v[2:5]
	v_mfma_f32_16x16x32_bf16 v[54:57], v[182:185], v[198:201], v[54:57]
	v_mfma_f32_16x16x32_bf16 v[50:53], v[190:193], v[198:201], v[50:53]
	v_mfma_f32_16x16x32_bf16 v[38:41], v[182:185], v[206:209], v[38:41]
	v_mfma_f32_16x16x32_bf16 v[34:37], v[190:193], v[206:209], v[34:37]
	v_mfma_f32_16x16x32_bf16 v[22:25], v[182:185], v[214:217], v[22:25]
	v_mfma_f32_16x16x32_bf16 v[18:21], v[190:193], v[214:217], v[18:21]
	v_mfma_f32_16x16x32_bf16 v[6:9], v[182:185], v[222:225], v[6:9]
	v_mfma_f32_16x16x32_bf16 v[2:5], v[190:193], v[222:225], v[2:5]
	s_barrier
	s_add_i32 s53, s53, 2
	s_add_u32 s16, s16, 0x100
	s_addc_u32 s17, s17, 0
	s_add_u32 s25, s25, 0x100
	s_addc_u32 s52, s52, 0
	s_cmp_gt_u32 s53, 29
	s_cbranch_scc0 .LBB0_1465
	s_setprio 0
	s_and_b64 vcc, exec, s[10:11]
	s_cbranch_vccz .LBB0_1468
	s_barrier

; #define PG8_STAGE(bufoff, gbase, voff) do { _Pragma("unroll") for (int _i = 0; _i < 2; ++_i) \
;         __builtin_amdgcn_global_load_lds((const unsigned*)((const char*)(gbase) + (voff)[_i]), (LAS unsigned*)(lds + (bufoff) + ldsw + _i * 8192), 16, 0, 0); } while (0)
; #define PG8_LDA(dst, b, h) do { _Pragma("unroll") for (int m = 0; m < 4; ++m) _Pragma("unroll") for (int k = 0; k < 2; ++k) dst[m][k] = *(const LAS bf16x8*)(lds + PG8_SA(b, h) + aoff + m * 2048 + k * 1024); } while (0)
; #define PG8_LDB(dst, b, h) do { _Pragma("unroll") for (int n = 0; n < 2; ++n) _Pragma("unroll") for (int k = 0; k < 2; ++k) dst[n][k] = *(const LAS bf16x8*)(lds + PG8_SB(b, h) + boff + n * 2048 + k * 1024); } while (0)
; template <class Epi, class Sched, bool ALIGN_EPI = false, bool SP2 = false>
; __device__ __forceinline__ void gemm_phase(LAS unsigned char* lds, const Gemm g, const Sched& S, const Epi& E) {
;     ...
;         for (int t = 0; t < nt; t += 2) {
;             const bool last = (t == nt - 2);
;             const char* a1 = cA + (size_t)(t + 1) * kstep;
;             const char* a2 = last ? nA : cA + (size_t)(t + 2) * kstep; const char* b2 = last ? nB : cB + (size_t)(t + 2) * kstep;
;             const char* a3 = a2 + kstep; const char* b3 = b2 + kstep;
;             if (last && has_next) S.a_ready(nxt);
;             if constexpr (SP2) {
;             PG8_LDB(B0, 0, 0); PG8_LDB(B1, 0, 1); PG8_SCHED; PG8_LDA(At, 0, 0); PG8_STAGE(PG8_SA(1, 1), a1 + hstep, voffA);
;             PG8_WAIT_V(8); PG8_WAIT_L(0); PG8_BAR; PG8_MMA(0, 0, At, B0); PG8_MMA(0, 1, At, B1); PG8_BAR; PG8_SCHED;
;             PG8_LDA(At, 0, 1); PG8_STAGE(PG8_SB(0, 0), b2, voffB); PG8_STAGE(PG8_SB(0, 1), b2 + hstepB, voffB); PG8_STAGE(PG8_SA(0, 0), a2, voffA);
;             PG8_WAIT_V(8); PG8_WAIT_L(0); PG8_BAR; PG8_MMA(1, 0, At, B0); PG8_MMA(1, 1, At, B1); PG8_BAR; PG8_SCHED;
;             PG8_LDB(B0, 1, 0); PG8_LDB(B1, 1, 1); PG8_SCHED; PG8_LDA(At, 1, 0); PG8_STAGE(PG8_SA(0, 1), a2 + hstep, voffA);
;             PG8_WAIT_V(8); PG8_WAIT_L(0); PG8_BAR; PG8_MMA(0, 0, At, B0); PG8_MMA(0, 1, At, B1); PG8_BAR; PG8_SCHED;
;             PG8_LDA(At, 1, 1); PG8_STAGE(PG8_SB(1, 0), b3, voffB); PG8_STAGE(PG8_SB(1, 1), b3 + hstepB, voffB); PG8_STAGE(PG8_SA(1, 0), a3, voffA);
;             PG8_WAIT_V(8); PG8_WAIT_L(0); PG8_BAR; PG8_MMA(1, 0, At, B0); PG8_MMA(1, 1, At, B1); PG8_BAR; PG8_SCHED;
.Lprio_1595:
	ds_read_b128 v[130:133], v196
	ds_read_b128 v[134:137], v196 offset:1024
	ds_read_b128 v[138:141], v196 offset:2048
	ds_read_b128 v[142:145], v196 offset:3072
	ds_read_b128 v[166:169], v197
	ds_read_b128 v[170:173], v197 offset:1024
	ds_read_b128 v[174:177], v197 offset:2048
	ds_read_b128 v[178:181], v197 offset:3072
	s_add_u32 s20, s16, 0x100
	s_addc_u32 s21, s17, 0
	s_cmpk_eq_i32 s25, 0x54
	s_cselect_b32 s47, s3, s21
	s_cselect_b32 s46, s2, s20
	s_cselect_b32 s23, s19, s24
	s_cselect_b32 s22, s18, s9
	v_lshl_add_u64 v[190:191], s[16:17], 0, v[158:159]
	s_add_i32 m0, s31, 0xc000
	ds_read_b128 v[182:185], v198
	ds_read_b128 v[186:189], v198 offset:1024
	ds_read_b128 v[202:205], v198 offset:2048
	ds_read_b128 v[206:209], v198 offset:3072
	ds_read_b128 v[210:213], v198 offset:4096
	ds_read_b128 v[214:217], v198 offset:5120
	ds_read_b128 v[218:221], v198 offset:6144
	ds_read_b128 v[222:225], v198 offset:7168
	global_load_lds_dwordx4 v[190:191], off
	v_lshl_add_u64 v[190:191], s[16:17], 0, v[160:161]
	s_add_i32 m0, s31, 0xe000
	s_nop 0
	global_load_lds_dwordx4 v[190:191], off
	s_waitcnt lgkmcnt(0)
	s_barrier
	s_waitcnt lgkmcnt(0)
	v_mfma_f32_16x16x32_bf16 v[126:129], v[130:133], v[182:185], 0
	v_mfma_f32_16x16x32_bf16 v[122:125], v[138:141], v[182:185], 0
	v_mfma_f32_16x16x32_bf16 v[110:113], v[130:133], v[202:205], 0
	v_mfma_f32_16x16x32_bf16 v[106:109], v[138:141], v[202:205], 0
	v_mfma_f32_16x16x32_bf16 v[94:97], v[130:133], v[210:213], 0
	v_mfma_f32_16x16x32_bf16 v[90:93], v[138:141], v[210:213], 0
	v_mfma_f32_16x16x32_bf16 v[78:81], v[130:133], v[218:221], 0
	v_mfma_f32_16x16x32_bf16 v[74:77], v[138:141], v[218:221], 0
	v_mfma_f32_16x16x32_bf16 v[126:129], v[134:137], v[186:189], v[126:129]
	v_mfma_f32_16x16x32_bf16 v[122:125], v[142:145], v[186:189], v[122:125]
	v_mfma_f32_16x16x32_bf16 v[110:113], v[134:137], v[206:209], v[110:113]
	v_mfma_f32_16x16x32_bf16 v[106:109], v[142:145], v[206:209], v[106:109]
	v_mfma_f32_16x16x32_bf16 v[94:97], v[134:137], v[214:217], v[94:97]
	v_mfma_f32_16x16x32_bf16 v[90:93], v[142:145], v[214:217], v[90:93]
	v_mfma_f32_16x16x32_bf16 v[78:81], v[134:137], v[222:225], v[78:81]
	v_mfma_f32_16x16x32_bf16 v[74:77], v[142:145], v[222:225], v[74:77]
	v_mfma_f32_16x16x32_bf16 v[118:121], v[166:169], v[182:185], 0
	v_mfma_f32_16x16x32_bf16 v[114:117], v[174:177], v[182:185], 0
	v_mfma_f32_16x16x32_bf16 v[102:105], v[166:169], v[202:205], 0
	v_mfma_f32_16x16x32_bf16 v[98:101], v[174:177], v[202:205], 0
	v_mfma_f32_16x16x32_bf16 v[86:89], v[166:169], v[210:213], 0
	v_mfma_f32_16x16x32_bf16 v[82:85], v[174:177], v[210:213], 0
	v_mfma_f32_16x16x32_bf16 v[70:73], v[166:169], v[218:221], 0
	v_mfma_f32_16x16x32_bf16 v[66:69], v[174:177], v[218:221], 0
	v_mfma_f32_16x16x32_bf16 v[118:121], v[170:173], v[186:189], v[118:121]
	v_mfma_f32_16x16x32_bf16 v[114:117], v[178:181], v[186:189], v[114:117]
	v_mfma_f32_16x16x32_bf16 v[102:105], v[170:173], v[206:209], v[102:105]
	v_mfma_f32_16x16x32_bf16 v[98:101], v[178:181], v[206:209], v[98:101]
	v_mfma_f32_16x16x32_bf16 v[86:89], v[170:173], v[214:217], v[86:89]
	v_mfma_f32_16x16x32_bf16 v[82:85], v[178:181], v[214:217], v[82:85]
	v_mfma_f32_16x16x32_bf16 v[70:73], v[170:173], v[222:225], v[70:73]
	v_mfma_f32_16x16x32_bf16 v[66:69], v[178:181], v[222:225], v[66:69]
	s_barrier
	s_add_i32 s16, s52, s30
	v_lshl_add_u64 v[190:191], s[22:23], 0, v[148:149]
	s_mov_b32 m0, s16
	ds_read_b128 v[182:185], v198 offset:16384
	ds_read_b128 v[186:189], v198 offset:17408
	ds_read_b128 v[202:205], v198 offset:18432
	ds_read_b128 v[206:209], v198 offset:19456
	ds_read_b128 v[210:213], v198 offset:20480
	ds_read_b128 v[214:217], v198 offset:21504
	ds_read_b128 v[218:221], v198 offset:22528
	ds_read_b128 v[222:225], v198 offset:23552
	global_load_lds_dwordx4 v[190:191], off
	s_add_i32 m0, s16, 0x2000
	s_add_u32 s16, s22, 0x58000
	v_lshl_add_u64 v[226:227], s[22:23], 0, v[152:153]
	s_addc_u32 s17, s23, 0
	s_add_i32 s56, s53, s30
	global_load_lds_dwordx4 v[226:227], off
	s_mov_b32 m0, s56
	v_lshl_add_u64 v[230:231], s[46:47], 0, v[150:151]
	global_load_lds_dwordx4 v148, s[16:17]
	s_add_i32 m0, s56, 0x2000
	s_nop 0
	global_load_lds_dwordx4 v152, s[16:17]
	v_lshl_add_u64 v[228:229], s[46:47], 0, v[146:147]
	s_mov_b32 m0, s31
	s_nop 0
	global_load_lds_dwordx4 v[228:229], off
	s_mov_b32 m0, s33
	s_nop 0
	global_load_lds_dwordx4 v[230:231], off
	s_waitcnt lgkmcnt(0)
	s_barrier
	s_waitcnt lgkmcnt(0)
	v_mfma_f32_16x16x32_bf16 v[62:65], v[130:133], v[182:185], 0
	v_mfma_f32_16x16x32_bf16 v[58:61], v[138:141], v[182:185], 0
	v_mfma_f32_16x16x32_bf16 v[46:49], v[130:133], v[202:205], 0
	v_mfma_f32_16x16x32_bf16 v[42:45], v[138:141], v[202:205], 0
	v_mfma_f32_16x16x32_bf16 v[30:33], v[130:133], v[210:213], 0
	v_mfma_f32_16x16x32_bf16 v[26:29], v[138:141], v[210:213], 0
	v_mfma_f32_16x16x32_bf16 v[14:17], v[130:133], v[218:221], 0
	v_mfma_f32_16x16x32_bf16 v[10:13], v[138:141], v[218:221], 0
	v_mfma_f32_16x16x32_bf16 v[62:65], v[134:137], v[186:189], v[62:65]
	v_mfma_f32_16x16x32_bf16 v[58:61], v[142:145], v[186:189], v[58:61]
	v_mfma_f32_16x16x32_bf16 v[46:49], v[134:137], v[206:209], v[46:49]
	v_mfma_f32_16x16x32_bf16 v[42:45], v[142:145], v[206:209], v[42:45]
	v_mfma_f32_16x16x32_bf16 v[30:33], v[134:137], v[214:217], v[30:33]
	v_mfma_f32_16x16x32_bf16 v[26:29], v[142:145], v[214:217], v[26:29]
	v_mfma_f32_16x16x32_bf16 v[14:17], v[134:137], v[222:225], v[14:17]
	v_mfma_f32_16x16x32_bf16 v[10:13], v[142:145], v[222:225], v[10:13]
	v_mfma_f32_16x16x32_bf16 v[54:57], v[166:169], v[182:185], 0
	v_mfma_f32_16x16x32_bf16 v[50:53], v[174:177], v[182:185], 0
	v_mfma_f32_16x16x32_bf16 v[38:41], v[166:169], v[202:205], 0
	v_mfma_f32_16x16x32_bf16 v[34:37], v[174:177], v[202:205], 0
	v_mfma_f32_16x16x32_bf16 v[22:25], v[166:169], v[210:213], 0
	v_mfma_f32_16x16x32_bf16 v[18:21], v[174:177], v[210:213], 0
	v_mfma_f32_16x16x32_bf16 v[6:9], v[166:169], v[218:221], 0
	v_mfma_f32_16x16x32_bf16 v[2:5], v[174:177], v[218:221], 0
	v_mfma_f32_16x16x32_bf16 v[54:57], v[170:173], v[186:189], v[54:57]
	v_mfma_f32_16x16x32_bf16 v[50:53], v[178:181], v[186:189], v[50:53]
	v_mfma_f32_16x16x32_bf16 v[38:41], v[170:173], v[206:209], v[38:41]
	v_mfma_f32_16x16x32_bf16 v[34:37], v[178:181], v[206:209], v[34:37]
	v_mfma_f32_16x16x32_bf16 v[22:25], v[170:173], v[214:217], v[22:25]
	v_mfma_f32_16x16x32_bf16 v[18:21], v[178:181], v[214:217], v[18:21]
	v_mfma_f32_16x16x32_bf16 v[6:9], v[170:173], v[222:225], v[6:9]
	v_mfma_f32_16x16x32_bf16 v[2:5], v[178:181], v[222:225], v[2:5]
	s_barrier
; #define PG8_STAGE(bufoff, gbase, voff) do { _Pragma("unroll") for (int _i = 0; _i < 2; ++_i) \
;         __builtin_amdgcn_global_load_lds((const unsigned*)((const char*)(gbase) + (voff)[_i]), (LAS unsigned*)(lds + (bufoff) + ldsw + _i * 8192), 16, 0, 0); } while (0)
; #define PG8_LDA(dst, b, h) do { _Pragma("unroll") for (int m = 0; m < 4; ++m) _Pragma("unroll") for (int k = 0; k < 2; ++k) dst[m][k] = *(const LAS bf16x8*)(lds + PG8_SA(b, h) + aoff + m * 2048 + k * 1024); } while (0)
; #define PG8_LDB(dst, b, h) do { _Pragma("unroll") for (int n = 0; n < 2; ++n) _Pragma("unroll") for (int k = 0; k < 2; ++k) dst[n][k] = *(const LAS bf16x8*)(lds + PG8_SB(b, h) + boff + n * 2048 + k * 1024); } while (0)
; template <class Epi, class Sched, bool ALIGN_EPI = false, bool SP2 = false>
; __device__ __forceinline__ void gemm_phase(LAS unsigned char* lds, const Gemm g, const Sched& S, const Epi& E) {
;     ...
;         for (int t = 0; t < nt; t += 2) {
;             const bool last = (t == nt - 2);
;             const char* a1 = cA + (size_t)(t + 1) * kstep;
;             const char* a2 = last ? nA : cA + (size_t)(t + 2) * kstep; const char* b2 = last ? nB : cB + (size_t)(t + 2) * kstep;
;             const char* a3 = a2 + kstep; const char* b3 = b2 + kstep;
;             if (last && has_next) S.a_ready(nxt);
;             if constexpr (SP2) {
;             PG8_LDB(B0, 0, 0); PG8_LDB(B1, 0, 1); PG8_SCHED; PG8_LDA(At, 0, 0); PG8_STAGE(PG8_SA(1, 1), a1 + hstep, voffA);
;             PG8_WAIT_V(8); PG8_WAIT_L(0); PG8_BAR; PG8_MMA(0, 0, At, B0); PG8_MMA(0, 1, At, B1); PG8_BAR; PG8_SCHED;
;             PG8_LDA(At, 0, 1); PG8_STAGE(PG8_SB(0, 0), b2, voffB); PG8_STAGE(PG8_SB(0, 1), b2 + hstepB, voffB); PG8_STAGE(PG8_SA(0, 0), a2, voffA);
;             PG8_WAIT_V(8); PG8_WAIT_L(0); PG8_BAR; PG8_MMA(1, 0, At, B0); PG8_MMA(1, 1, At, B1); PG8_BAR; PG8_SCHED;
;             PG8_LDB(B0, 1, 0); PG8_LDB(B1, 1, 1); PG8_SCHED; PG8_LDA(At, 1, 0); PG8_STAGE(PG8_SA(0, 1), a2 + hstep, voffA);
;             PG8_WAIT_V(8); PG8_WAIT_L(0); PG8_BAR; PG8_MMA(0, 0, At, B0); PG8_MMA(0, 1, At, B1); PG8_BAR; PG8_SCHED;
;             PG8_LDA(At, 1, 1); PG8_STAGE(PG8_SB(1, 0), b3, voffB); PG8_STAGE(PG8_SB(1, 1), b3 + hstepB, voffB); PG8_STAGE(PG8_SA(1, 0), a3, voffA);
;             PG8_WAIT_V(8); PG8_WAIT_L(0); PG8_BAR; PG8_MMA(1, 0, At, B0); PG8_MMA(1, 1, At, B1); PG8_BAR; PG8_SCHED;
	s_add_i32 s56, 0, 0x18000
	s_add_i32 s57, 0, 0x1c000
	v_add_u32_e32 v142, s56, v1
	v_add_u32_e32 v154, s57, v1
	ds_read_b128 v[130:133], v142
	ds_read_b128 v[134:137], v142 offset:1024
	ds_read_b128 v[138:141], v142 offset:2048
	ds_read_b128 v[142:145], v142 offset:3072
	ds_read_b128 v[166:169], v154
	ds_read_b128 v[170:173], v154 offset:1024
	ds_read_b128 v[174:177], v154 offset:2048
	ds_read_b128 v[178:181], v154 offset:3072
	s_add_u32 s16, s46, 0x160000
	s_addc_u32 s17, s47, 0
	s_mov_b32 m0, s34
	ds_read_b128 v[182:185], v198 offset:32768
	ds_read_b128 v[186:189], v198 offset:33792
	ds_read_b128 v[202:205], v198 offset:34816
	ds_read_b128 v[206:209], v198 offset:35840
	ds_read_b128 v[210:213], v198 offset:36864
	ds_read_b128 v[214:217], v198 offset:37888
	ds_read_b128 v[218:221], v198 offset:38912
	ds_read_b128 v[222:225], v198 offset:39936
	global_load_lds_dwordx4 v146, s[16:17]
	s_mov_b32 m0, s35
	s_nop 0
	global_load_lds_dwordx4 v150, s[16:17]
	s_waitcnt vmcnt(8)
	s_waitcnt lgkmcnt(0)
	s_barrier
	s_waitcnt lgkmcnt(0)
	v_mfma_f32_16x16x32_bf16 v[126:129], v[130:133], v[182:185], v[126:129]
	v_mfma_f32_16x16x32_bf16 v[122:125], v[138:141], v[182:185], v[122:125]
	v_mfma_f32_16x16x32_bf16 v[110:113], v[130:133], v[202:205], v[110:113]
	v_mfma_f32_16x16x32_bf16 v[106:109], v[138:141], v[202:205], v[106:109]
	v_mfma_f32_16x16x32_bf16 v[94:97], v[130:133], v[210:213], v[94:97]
	v_mfma_f32_16x16x32_bf16 v[90:93], v[138:141], v[210:213], v[90:93]
	v_mfma_f32_16x16x32_bf16 v[78:81], v[130:133], v[218:221], v[78:81]
	v_mfma_f32_16x16x32_bf16 v[74:77], v[138:141], v[218:221], v[74:77]
	v_mfma_f32_16x16x32_bf16 v[126:129], v[134:137], v[186:189], v[126:129]
	v_mfma_f32_16x16x32_bf16 v[122:125], v[142:145], v[186:189], v[122:125]
	v_mfma_f32_16x16x32_bf16 v[110:113], v[134:137], v[206:209], v[110:113]
	v_mfma_f32_16x16x32_bf16 v[106:109], v[142:145], v[206:209], v[106:109]
	v_mfma_f32_16x16x32_bf16 v[94:97], v[134:137], v[214:217], v[94:97]
	v_mfma_f32_16x16x32_bf16 v[90:93], v[142:145], v[214:217], v[90:93]
	v_mfma_f32_16x16x32_bf16 v[78:81], v[134:137], v[222:225], v[78:81]
	v_mfma_f32_16x16x32_bf16 v[74:77], v[142:145], v[222:225], v[74:77]
	v_mfma_f32_16x16x32_bf16 v[118:121], v[166:169], v[182:185], v[118:121]
	v_mfma_f32_16x16x32_bf16 v[114:117], v[174:177], v[182:185], v[114:117]
	v_mfma_f32_16x16x32_bf16 v[102:105], v[166:169], v[202:205], v[102:105]
	v_mfma_f32_16x16x32_bf16 v[98:101], v[174:177], v[202:205], v[98:101]
	v_mfma_f32_16x16x32_bf16 v[86:89], v[166:169], v[210:213], v[86:89]
	v_mfma_f32_16x16x32_bf16 v[82:85], v[174:177], v[210:213], v[82:85]
	v_mfma_f32_16x16x32_bf16 v[70:73], v[166:169], v[218:221], v[70:73]
	v_mfma_f32_16x16x32_bf16 v[66:69], v[174:177], v[218:221], v[66:69]
	v_mfma_f32_16x16x32_bf16 v[118:121], v[170:173], v[186:189], v[118:121]
	v_mfma_f32_16x16x32_bf16 v[114:117], v[178:181], v[186:189], v[114:117]
	v_mfma_f32_16x16x32_bf16 v[102:105], v[170:173], v[206:209], v[102:105]
	v_mfma_f32_16x16x32_bf16 v[98:101], v[178:181], v[206:209], v[98:101]
	v_mfma_f32_16x16x32_bf16 v[86:89], v[170:173], v[214:217], v[86:89]
	v_mfma_f32_16x16x32_bf16 v[82:85], v[178:181], v[214:217], v[82:85]
	v_mfma_f32_16x16x32_bf16 v[70:73], v[170:173], v[222:225], v[70:73]
	v_mfma_f32_16x16x32_bf16 v[66:69], v[178:181], v[222:225], v[66:69]
	s_barrier
	s_add_i32 s16, s56, s30
	v_lshl_add_u64 v[190:191], v[190:191], 0, s[12:13]
	s_mov_b32 m0, s16
	ds_read_b128 v[182:185], v198 offset:49152
	ds_read_b128 v[186:189], v198 offset:50176
	ds_read_b128 v[202:205], v198 offset:51200
	ds_read_b128 v[206:209], v198 offset:52224
	ds_read_b128 v[210:213], v198 offset:53248
	ds_read_b128 v[214:217], v198 offset:54272
	ds_read_b128 v[218:221], v198 offset:55296
	ds_read_b128 v[222:225], v198 offset:56320
	global_load_lds_dwordx4 v[190:191], off
	s_add_i32 m0, s16, 0x2000
	s_add_u32 s16, s22, 0x58080
	v_lshl_add_u64 v[190:191], v[226:227], 0, s[12:13]
	s_addc_u32 s17, s23, 0
	s_add_i32 s22, s57, s30
	global_load_lds_dwordx4 v[190:191], off
	s_mov_b32 m0, s22
	s_nop 0
	global_load_lds_dwordx4 v148, s[16:17]
	s_add_i32 m0, s22, 0x2000
	s_nop 0
	global_load_lds_dwordx4 v152, s[16:17]
	v_lshl_add_u64 v[190:191], v[228:229], 0, s[12:13]
	s_mov_b32 m0, s49
	s_nop 0
	global_load_lds_dwordx4 v[190:191], off
	v_lshl_add_u64 v[190:191], v[230:231], 0, s[12:13]
	s_mov_b32 m0, s50
	s_nop 0
	global_load_lds_dwordx4 v[190:191], off
	s_waitcnt vmcnt(8)
	s_waitcnt lgkmcnt(0)
	s_barrier
	s_waitcnt lgkmcnt(0)
	v_mfma_f32_16x16x32_bf16 v[62:65], v[130:133], v[182:185], v[62:65]
	v_mfma_f32_16x16x32_bf16 v[58:61], v[138:141], v[182:185], v[58:61]
	v_mfma_f32_16x16x32_bf16 v[46:49], v[130:133], v[202:205], v[46:49]
	v_mfma_f32_16x16x32_bf16 v[42:45], v[138:141], v[202:205], v[42:45]
	v_mfma_f32_16x16x32_bf16 v[30:33], v[130:133], v[210:213], v[30:33]
	v_mfma_f32_16x16x32_bf16 v[26:29], v[138:141], v[210:213], v[26:29]
	v_mfma_f32_16x16x32_bf16 v[14:17], v[130:133], v[218:221], v[14:17]
	v_mfma_f32_16x16x32_bf16 v[10:13], v[138:141], v[218:221], v[10:13]
	v_mfma_f32_16x16x32_bf16 v[62:65], v[134:137], v[186:189], v[62:65]
	v_mfma_f32_16x16x32_bf16 v[58:61], v[142:145], v[186:189], v[58:61]
	v_mfma_f32_16x16x32_bf16 v[46:49], v[134:137], v[206:209], v[46:49]
	v_mfma_f32_16x16x32_bf16 v[42:45], v[142:145], v[206:209], v[42:45]
	v_mfma_f32_16x16x32_bf16 v[30:33], v[134:137], v[214:217], v[30:33]
	v_mfma_f32_16x16x32_bf16 v[26:29], v[142:145], v[214:217], v[26:29]
	v_mfma_f32_16x16x32_bf16 v[14:17], v[134:137], v[222:225], v[14:17]
	v_mfma_f32_16x16x32_bf16 v[10:13], v[142:145], v[222:225], v[10:13]
	v_mfma_f32_16x16x32_bf16 v[54:57], v[166:169], v[182:185], v[54:57]
	v_mfma_f32_16x16x32_bf16 v[50:53], v[174:177], v[182:185], v[50:53]
	v_mfma_f32_16x16x32_bf16 v[38:41], v[166:169], v[202:205], v[38:41]
	v_mfma_f32_16x16x32_bf16 v[34:37], v[174:177], v[202:205], v[34:37]
	v_mfma_f32_16x16x32_bf16 v[22:25], v[166:169], v[210:213], v[22:25]
	v_mfma_f32_16x16x32_bf16 v[18:21], v[174:177], v[210:213], v[18:21]
	v_mfma_f32_16x16x32_bf16 v[6:9], v[166:169], v[218:221], v[6:9]
	v_mfma_f32_16x16x32_bf16 v[2:5], v[174:177], v[218:221], v[2:5]
	v_mfma_f32_16x16x32_bf16 v[54:57], v[170:173], v[186:189], v[54:57]
	v_mfma_f32_16x16x32_bf16 v[50:53], v[178:181], v[186:189], v[50:53]
	v_mfma_f32_16x16x32_bf16 v[38:41], v[170:173], v[206:209], v[38:41]
	v_mfma_f32_16x16x32_bf16 v[34:37], v[178:181], v[206:209], v[34:37]
	v_mfma_f32_16x16x32_bf16 v[22:25], v[170:173], v[214:217], v[22:25]
	v_mfma_f32_16x16x32_bf16 v[18:21], v[178:181], v[214:217], v[18:21]
	v_mfma_f32_16x16x32_bf16 v[6:9], v[170:173], v[222:225], v[6:9]
	v_mfma_f32_16x16x32_bf16 v[2:5], v[178:181], v[222:225], v[2:5]
	s_barrier
	s_add_i32 s25, s25, 2
	s_add_u32 s9, s9, 0x100
	s_addc_u32 s24, s24, 0
	s_cmpk_gt_u32 s25, 0x55
	s_mov_b64 s[16:17], s[20:21]
; #define PG8_STAGE(bufoff, gbase, voff) do { _Pragma("unroll") for (int _i = 0; _i < 2; ++_i) \
;         __builtin_amdgcn_global_load_lds((const unsigned*)((const char*)(gbase) + (voff)[_i]), (LAS unsigned*)(lds + (bufoff) + ldsw + _i * 8192), 16, 0, 0); } while (0)
; #define PG8_LDA(dst, b, h) do { _Pragma("unroll") for (int m = 0; m < 4; ++m) _Pragma("unroll") for (int k = 0; k < 2; ++k) dst[m][k] = *(const LAS bf16x8*)(lds + PG8_SA(b, h) + aoff + m * 2048 + k * 1024); } while (0)
; #define PG8_LDB(dst, b, h) do { _Pragma("unroll") for (int n = 0; n < 2; ++n) _Pragma("unroll") for (int k = 0; k < 2; ++k) dst[n][k] = *(const LAS bf16x8*)(lds + PG8_SB(b, h) + boff + n * 2048 + k * 1024); } while (0)
; template <class Epi, class Sched, bool ALIGN_EPI = false, bool SP2 = false>
; __device__ __forceinline__ void gemm_phase(LAS unsigned char* lds, const Gemm g, const Sched& S, const Epi& E) {
;     ...
;         for (int t = 0; t < nt; t += 2) {
;             const bool last = (t == nt - 2);
;             const char* a1 = cA + (size_t)(t + 1) * kstep;
;             const char* a2 = last ? nA : cA + (size_t)(t + 2) * kstep; const char* b2 = last ? nB : cB + (size_t)(t + 2) * kstep;
;             const char* a3 = a2 + kstep; const char* b3 = b2 + kstep;
;             if (last && has_next) S.a_ready(nxt);
;             if constexpr (SP2) {
;             PG8_LDB(B0, 0, 0); PG8_LDB(B1, 0, 1); PG8_SCHED; PG8_LDA(At, 0, 0); PG8_STAGE(PG8_SA(1, 1), a1 + hstep, voffA);
;             PG8_WAIT_V(8); PG8_WAIT_L(0); PG8_BAR; PG8_MMA(0, 0, At, B0); PG8_MMA(0, 1, At, B1); PG8_BAR; PG8_SCHED;
;             PG8_LDA(At, 0, 1); PG8_STAGE(PG8_SB(0, 0), b2, voffB); PG8_STAGE(PG8_SB(0, 1), b2 + hstepB, voffB); PG8_STAGE(PG8_SA(0, 0), a2, voffA);
;             PG8_WAIT_V(8); PG8_WAIT_L(0); PG8_BAR; PG8_MMA(1, 0, At, B0); PG8_MMA(1, 1, At, B1); PG8_BAR; PG8_SCHED;
;             PG8_LDB(B0, 1, 0); PG8_LDB(B1, 1, 1); PG8_SCHED; PG8_LDA(At, 1, 0); PG8_STAGE(PG8_SA(0, 1), a2 + hstep, voffA);
;             PG8_WAIT_V(8); PG8_WAIT_L(0); PG8_BAR; PG8_MMA(0, 0, At, B0); PG8_MMA(0, 1, At, B1); PG8_BAR; PG8_SCHED;
;             PG8_LDA(At, 1, 1); PG8_STAGE(PG8_SB(1, 0), b3, voffB); PG8_STAGE(PG8_SB(1, 1), b3 + hstepB, voffB); PG8_STAGE(PG8_SA(1, 0), a3, voffA);
;             PG8_WAIT_V(8); PG8_WAIT_L(0); PG8_BAR; PG8_MMA(1, 0, At, B0); PG8_MMA(1, 1, At, B1); PG8_BAR; PG8_SCHED;
.LBB0_1595:
	ds_read_b128 v[130:133], v196
	ds_read_b128 v[134:137], v196 offset:1024
	ds_read_b128 v[138:141], v196 offset:2048
	ds_read_b128 v[142:145], v196 offset:3072
	ds_read_b128 v[166:169], v197
	ds_read_b128 v[170:173], v197 offset:1024
	ds_read_b128 v[174:177], v197 offset:2048
	ds_read_b128 v[178:181], v197 offset:3072
	s_add_u32 s20, s16, 0x100
	s_addc_u32 s21, s17, 0
	s_cmpk_eq_i32 s25, 0x54
	s_cselect_b32 s47, s3, s21
	s_cselect_b32 s46, s2, s20
	s_cselect_b32 s23, s19, s24
	s_cselect_b32 s22, s18, s9
	v_lshl_add_u64 v[190:191], s[16:17], 0, v[158:159]
	s_add_i32 m0, s31, 0xc000
	ds_read_b128 v[182:185], v198
	ds_read_b128 v[186:189], v198 offset:1024
	ds_read_b128 v[202:205], v198 offset:2048
	ds_read_b128 v[206:209], v198 offset:3072
	ds_read_b128 v[210:213], v198 offset:4096
	ds_read_b128 v[214:217], v198 offset:5120
	ds_read_b128 v[218:221], v198 offset:6144
	ds_read_b128 v[222:225], v198 offset:7168
	global_load_lds_dwordx4 v[190:191], off
	v_lshl_add_u64 v[190:191], s[16:17], 0, v[160:161]
	s_add_i32 m0, s31, 0xe000
	s_nop 0
	global_load_lds_dwordx4 v[190:191], off
	s_waitcnt vmcnt(8)
	s_waitcnt lgkmcnt(0)
	s_barrier
	s_waitcnt lgkmcnt(0)
	v_mfma_f32_16x16x32_bf16 v[126:129], v[130:133], v[182:185], v[126:129]
	v_mfma_f32_16x16x32_bf16 v[122:125], v[138:141], v[182:185], v[122:125]
	v_mfma_f32_16x16x32_bf16 v[110:113], v[130:133], v[202:205], v[110:113]
	v_mfma_f32_16x16x32_bf16 v[106:109], v[138:141], v[202:205], v[106:109]
	v_mfma_f32_16x16x32_bf16 v[94:97], v[130:133], v[210:213], v[94:97]
	v_mfma_f32_16x16x32_bf16 v[90:93], v[138:141], v[210:213], v[90:93]
	v_mfma_f32_16x16x32_bf16 v[78:81], v[130:133], v[218:221], v[78:81]
	v_mfma_f32_16x16x32_bf16 v[74:77], v[138:141], v[218:221], v[74:77]
	v_mfma_f32_16x16x32_bf16 v[126:129], v[134:137], v[186:189], v[126:129]
	v_mfma_f32_16x16x32_bf16 v[122:125], v[142:145], v[186:189], v[122:125]
	v_mfma_f32_16x16x32_bf16 v[110:113], v[134:137], v[206:209], v[110:113]
	v_mfma_f32_16x16x32_bf16 v[106:109], v[142:145], v[206:209], v[106:109]
	v_mfma_f32_16x16x32_bf16 v[94:97], v[134:137], v[214:217], v[94:97]
	v_mfma_f32_16x16x32_bf16 v[90:93], v[142:145], v[214:217], v[90:93]
	v_mfma_f32_16x16x32_bf16 v[78:81], v[134:137], v[222:225], v[78:81]
	v_mfma_f32_16x16x32_bf16 v[74:77], v[142:145], v[222:225], v[74:77]
	v_mfma_f32_16x16x32_bf16 v[118:121], v[166:169], v[182:185], v[118:121]
	v_mfma_f32_16x16x32_bf16 v[114:117], v[174:177], v[182:185], v[114:117]
	v_mfma_f32_16x16x32_bf16 v[102:105], v[166:169], v[202:205], v[102:105]
	v_mfma_f32_16x16x32_bf16 v[98:101], v[174:177], v[202:205], v[98:101]
	v_mfma_f32_16x16x32_bf16 v[86:89], v[166:169], v[210:213], v[86:89]
	v_mfma_f32_16x16x32_bf16 v[82:85], v[174:177], v[210:213], v[82:85]
	v_mfma_f32_16x16x32_bf16 v[70:73], v[166:169], v[218:221], v[70:73]
	v_mfma_f32_16x16x32_bf16 v[66:69], v[174:177], v[218:221], v[66:69]
	v_mfma_f32_16x16x32_bf16 v[118:121], v[170:173], v[186:189], v[118:121]
	v_mfma_f32_16x16x32_bf16 v[114:117], v[178:181], v[186:189], v[114:117]
	v_mfma_f32_16x16x32_bf16 v[102:105], v[170:173], v[206:209], v[102:105]
	v_mfma_f32_16x16x32_bf16 v[98:101], v[178:181], v[206:209], v[98:101]
	v_mfma_f32_16x16x32_bf16 v[86:89], v[170:173], v[214:217], v[86:89]
	v_mfma_f32_16x16x32_bf16 v[82:85], v[178:181], v[214:217], v[82:85]
	v_mfma_f32_16x16x32_bf16 v[70:73], v[170:173], v[222:225], v[70:73]
	v_mfma_f32_16x16x32_bf16 v[66:69], v[178:181], v[222:225], v[66:69]
	s_barrier
	s_add_i32 s16, s52, s30
	v_lshl_add_u64 v[190:191], s[22:23], 0, v[148:149]
	s_mov_b32 m0, s16
	ds_read_b128 v[182:185], v198 offset:16384
	ds_read_b128 v[186:189], v198 offset:17408
	ds_read_b128 v[202:205], v198 offset:18432
	ds_read_b128 v[206:209], v198 offset:19456
	ds_read_b128 v[210:213], v198 offset:20480
	ds_read_b128 v[214:217], v198 offset:21504
	ds_read_b128 v[218:221], v198 offset:22528
	ds_read_b128 v[222:225], v198 offset:23552
	global_load_lds_dwordx4 v[190:191], off
	s_add_i32 m0, s16, 0x2000
	s_add_u32 s16, s22, 0x58000
	v_lshl_add_u64 v[226:227], s[22:23], 0, v[152:153]
	s_addc_u32 s17, s23, 0
	s_add_i32 s56, s53, s30
	global_load_lds_dwordx4 v[226:227], off
	s_mov_b32 m0, s56
	v_lshl_add_u64 v[230:231], s[46:47], 0, v[150:151]
	global_load_lds_dwordx4 v148, s[16:17]
	s_add_i32 m0, s56, 0x2000
	s_nop 0
	global_load_lds_dwordx4 v152, s[16:17]
	v_lshl_add_u64 v[228:229], s[46:47], 0, v[146:147]
	s_mov_b32 m0, s31
	s_nop 0
	global_load_lds_dwordx4 v[228:229], off
	s_mov_b32 m0, s33
	s_nop 0
	global_load_lds_dwordx4 v[230:231], off
	s_waitcnt vmcnt(8)
	s_waitcnt lgkmcnt(0)
	s_barrier
; #define PG8_STAGE(bufoff, gbase, voff) do { _Pragma("unroll") for (int _i = 0; _i < 2; ++_i) \
;         __builtin_amdgcn_global_load_lds((const unsigned*)((const char*)(gbase) + (voff)[_i]), (LAS unsigned*)(lds + (bufoff) + ldsw + _i * 8192), 16, 0, 0); } while (0)
; #define PG8_LDA(dst, b, h) do { _Pragma("unroll") for (int m = 0; m < 4; ++m) _Pragma("unroll") for (int k = 0; k < 2; ++k) dst[m][k] = *(const LAS bf16x8*)(lds + PG8_SA(b, h) + aoff + m * 2048 + k * 1024); } while (0)
; #define PG8_LDB(dst, b, h) do { _Pragma("unroll") for (int n = 0; n < 2; ++n) _Pragma("unroll") for (int k = 0; k < 2; ++k) dst[n][k] = *(const LAS bf16x8*)(lds + PG8_SB(b, h) + boff + n * 2048 + k * 1024); } while (0)
; template <class Epi, class Sched, bool ALIGN_EPI = false, bool SP2 = false>
; __device__ __forceinline__ void gemm_phase(LAS unsigned char* lds, const Gemm g, const Sched& S, const Epi& E) {
;     ...
;         for (int t = 0; t < nt; t += 2) {
;             const bool last = (t == nt - 2);
;             const char* a1 = cA + (size_t)(t + 1) * kstep;
;             const char* a2 = last ? nA : cA + (size_t)(t + 2) * kstep; const char* b2 = last ? nB : cB + (size_t)(t + 2) * kstep;
;             const char* a3 = a2 + kstep; const char* b3 = b2 + kstep;
;             if (last && has_next) S.a_ready(nxt);
;             if constexpr (SP2) {
;             PG8_LDB(B0, 0, 0); PG8_LDB(B1, 0, 1); PG8_SCHED; PG8_LDA(At, 0, 0); PG8_STAGE(PG8_SA(1, 1), a1 + hstep, voffA);
;             PG8_WAIT_V(8); PG8_WAIT_L(0); PG8_BAR; PG8_MMA(0, 0, At, B0); PG8_MMA(0, 1, At, B1); PG8_BAR; PG8_SCHED;
;             PG8_LDA(At, 0, 1); PG8_STAGE(PG8_SB(0, 0), b2, voffB); PG8_STAGE(PG8_SB(0, 1), b2 + hstepB, voffB); PG8_STAGE(PG8_SA(0, 0), a2, voffA);
;             PG8_WAIT_V(8); PG8_WAIT_L(0); PG8_BAR; PG8_MMA(1, 0, At, B0); PG8_MMA(1, 1, At, B1); PG8_BAR; PG8_SCHED;
;             PG8_LDB(B0, 1, 0); PG8_LDB(B1, 1, 1); PG8_SCHED; PG8_LDA(At, 1, 0); PG8_STAGE(PG8_SA(0, 1), a2 + hstep, voffA);
;             PG8_WAIT_V(8); PG8_WAIT_L(0); PG8_BAR; PG8_MMA(0, 0, At, B0); PG8_MMA(0, 1, At, B1); PG8_BAR; PG8_SCHED;
;             PG8_LDA(At, 1, 1); PG8_STAGE(PG8_SB(1, 0), b3, voffB); PG8_STAGE(PG8_SB(1, 1), b3 + hstepB, voffB); PG8_STAGE(PG8_SA(1, 0), a3, voffA);
;             PG8_WAIT_V(8); PG8_WAIT_L(0); PG8_BAR; PG8_MMA(1, 0, At, B0); PG8_MMA(1, 1, At, B1); PG8_BAR; PG8_SCHED;
	s_waitcnt lgkmcnt(0)
	v_mfma_f32_16x16x32_bf16 v[62:65], v[130:133], v[182:185], v[62:65]
	v_mfma_f32_16x16x32_bf16 v[58:61], v[138:141], v[182:185], v[58:61]
	v_mfma_f32_16x16x32_bf16 v[46:49], v[130:133], v[202:205], v[46:49]
	v_mfma_f32_16x16x32_bf16 v[42:45], v[138:141], v[202:205], v[42:45]
	v_mfma_f32_16x16x32_bf16 v[30:33], v[130:133], v[210:213], v[30:33]
	v_mfma_f32_16x16x32_bf16 v[26:29], v[138:141], v[210:213], v[26:29]
	v_mfma_f32_16x16x32_bf16 v[14:17], v[130:133], v[218:221], v[14:17]
	v_mfma_f32_16x16x32_bf16 v[10:13], v[138:141], v[218:221], v[10:13]
	v_mfma_f32_16x16x32_bf16 v[62:65], v[134:137], v[186:189], v[62:65]
	v_mfma_f32_16x16x32_bf16 v[58:61], v[142:145], v[186:189], v[58:61]
	v_mfma_f32_16x16x32_bf16 v[46:49], v[134:137], v[206:209], v[46:49]
	v_mfma_f32_16x16x32_bf16 v[42:45], v[142:145], v[206:209], v[42:45]
	v_mfma_f32_16x16x32_bf16 v[30:33], v[134:137], v[214:217], v[30:33]
	v_mfma_f32_16x16x32_bf16 v[26:29], v[142:145], v[214:217], v[26:29]
	v_mfma_f32_16x16x32_bf16 v[14:17], v[134:137], v[222:225], v[14:17]
	v_mfma_f32_16x16x32_bf16 v[10:13], v[142:145], v[222:225], v[10:13]
	v_mfma_f32_16x16x32_bf16 v[54:57], v[166:169], v[182:185], v[54:57]
	v_mfma_f32_16x16x32_bf16 v[50:53], v[174:177], v[182:185], v[50:53]
	v_mfma_f32_16x16x32_bf16 v[38:41], v[166:169], v[202:205], v[38:41]
	v_mfma_f32_16x16x32_bf16 v[34:37], v[174:177], v[202:205], v[34:37]
	v_mfma_f32_16x16x32_bf16 v[22:25], v[166:169], v[210:213], v[22:25]
	v_mfma_f32_16x16x32_bf16 v[18:21], v[174:177], v[210:213], v[18:21]
	v_mfma_f32_16x16x32_bf16 v[6:9], v[166:169], v[218:221], v[6:9]
	v_mfma_f32_16x16x32_bf16 v[2:5], v[174:177], v[218:221], v[2:5]
	v_mfma_f32_16x16x32_bf16 v[54:57], v[170:173], v[186:189], v[54:57]
	v_mfma_f32_16x16x32_bf16 v[50:53], v[178:181], v[186:189], v[50:53]
	v_mfma_f32_16x16x32_bf16 v[38:41], v[170:173], v[206:209], v[38:41]
	v_mfma_f32_16x16x32_bf16 v[34:37], v[178:181], v[206:209], v[34:37]
	v_mfma_f32_16x16x32_bf16 v[22:25], v[170:173], v[214:217], v[22:25]
	v_mfma_f32_16x16x32_bf16 v[18:21], v[178:181], v[214:217], v[18:21]
	v_mfma_f32_16x16x32_bf16 v[6:9], v[170:173], v[222:225], v[6:9]
	v_mfma_f32_16x16x32_bf16 v[2:5], v[178:181], v[222:225], v[2:5]
	s_barrier
	s_add_i32 s56, 0, 0x18000
	s_add_i32 s57, 0, 0x1c000
	v_add_u32_e32 v142, s56, v1
	v_add_u32_e32 v154, s57, v1
	ds_read_b128 v[130:133], v142
	ds_read_b128 v[134:137], v142 offset:1024
	ds_read_b128 v[138:141], v142 offset:2048
	ds_read_b128 v[142:145], v142 offset:3072
	ds_read_b128 v[166:169], v154
	ds_read_b128 v[170:173], v154 offset:1024
	ds_read_b128 v[174:177], v154 offset:2048
	ds_read_b128 v[178:181], v154 offset:3072
	s_add_u32 s16, s46, 0x160000
	s_addc_u32 s17, s47, 0
	s_mov_b32 m0, s34
	ds_read_b128 v[182:185], v198 offset:32768
	ds_read_b128 v[186:189], v198 offset:33792
	ds_read_b128 v[202:205], v198 offset:34816
	ds_read_b128 v[206:209], v198 offset:35840
	ds_read_b128 v[210:213], v198 offset:36864
	ds_read_b128 v[214:217], v198 offset:37888
	ds_read_b128 v[218:221], v198 offset:38912
	ds_read_b128 v[222:225], v198 offset:39936
	global_load_lds_dwordx4 v146, s[16:17]
	s_mov_b32 m0, s35
	s_nop 0
	global_load_lds_dwordx4 v150, s[16:17]
	s_waitcnt vmcnt(8)
	s_waitcnt lgkmcnt(0)
	s_barrier
	s_waitcnt lgkmcnt(0)
	v_mfma_f32_16x16x32_bf16 v[126:129], v[130:133], v[182:185], v[126:129]
	v_mfma_f32_16x16x32_bf16 v[122:125], v[138:141], v[182:185], v[122:125]
	v_mfma_f32_16x16x32_bf16 v[110:113], v[130:133], v[202:205], v[110:113]
	v_mfma_f32_16x16x32_bf16 v[106:109], v[138:141], v[202:205], v[106:109]
	v_mfma_f32_16x16x32_bf16 v[94:97], v[130:133], v[210:213], v[94:97]
	v_mfma_f32_16x16x32_bf16 v[90:93], v[138:141], v[210:213], v[90:93]
	v_mfma_f32_16x16x32_bf16 v[78:81], v[130:133], v[218:221], v[78:81]
	v_mfma_f32_16x16x32_bf16 v[74:77], v[138:141], v[218:221], v[74:77]
	v_mfma_f32_16x16x32_bf16 v[126:129], v[134:137], v[186:189], v[126:129]
	v_mfma_f32_16x16x32_bf16 v[122:125], v[142:145], v[186:189], v[122:125]
	v_mfma_f32_16x16x32_bf16 v[110:113], v[134:137], v[206:209], v[110:113]
	v_mfma_f32_16x16x32_bf16 v[106:109], v[142:145], v[206:209], v[106:109]
	v_mfma_f32_16x16x32_bf16 v[94:97], v[134:137], v[214:217], v[94:97]
	v_mfma_f32_16x16x32_bf16 v[90:93], v[142:145], v[214:217], v[90:93]
	v_mfma_f32_16x16x32_bf16 v[78:81], v[134:137], v[222:225], v[78:81]
	v_mfma_f32_16x16x32_bf16 v[74:77], v[142:145], v[222:225], v[74:77]
	v_mfma_f32_16x16x32_bf16 v[118:121], v[166:169], v[182:185], v[118:121]
	v_mfma_f32_16x16x32_bf16 v[114:117], v[174:177], v[182:185], v[114:117]
	v_mfma_f32_16x16x32_bf16 v[102:105], v[166:169], v[202:205], v[102:105]
	v_mfma_f32_16x16x32_bf16 v[98:101], v[174:177], v[202:205], v[98:101]
	v_mfma_f32_16x16x32_bf16 v[86:89], v[166:169], v[210:213], v[86:89]
	v_mfma_f32_16x16x32_bf16 v[82:85], v[174:177], v[210:213], v[82:85]
	v_mfma_f32_16x16x32_bf16 v[70:73], v[166:169], v[218:221], v[70:73]
	v_mfma_f32_16x16x32_bf16 v[66:69], v[174:177], v[218:221], v[66:69]
	v_mfma_f32_16x16x32_bf16 v[118:121], v[170:173], v[186:189], v[118:121]
	v_mfma_f32_16x16x32_bf16 v[114:117], v[178:181], v[186:189], v[114:117]
	v_mfma_f32_16x16x32_bf16 v[102:105], v[170:173], v[206:209], v[102:105]
	v_mfma_f32_16x16x32_bf16 v[98:101], v[178:181], v[206:209], v[98:101]
	v_mfma_f32_16x16x32_bf16 v[86:89], v[170:173], v[214:217], v[86:89]
	v_mfma_f32_16x16x32_bf16 v[82:85], v[178:181], v[214:217], v[82:85]
	v_mfma_f32_16x16x32_bf16 v[70:73], v[170:173], v[222:225], v[70:73]
	v_mfma_f32_16x16x32_bf16 v[66:69], v[178:181], v[222:225], v[66:69]
	s_barrier
; #define PG8_STAGE(bufoff, gbase, voff) do { _Pragma("unroll") for (int _i = 0; _i < 2; ++_i) \
;         __builtin_amdgcn_global_load_lds((const unsigned*)((const char*)(gbase) + (voff)[_i]), (LAS unsigned*)(lds + (bufoff) + ldsw + _i * 8192), 16, 0, 0); } while (0)
; #define PG8_LDA(dst, b, h) do { _Pragma("unroll") for (int m = 0; m < 4; ++m) _Pragma("unroll") for (int k = 0; k < 2; ++k) dst[m][k] = *(const LAS bf16x8*)(lds + PG8_SA(b, h) + aoff + m * 2048 + k * 1024); } while (0)
; #define PG8_BAR __builtin_amdgcn_s_barrier()
; template <class Epi, class Sched, bool ALIGN_EPI = false, bool SP2 = false>
; __device__ __forceinline__ void gemm_phase(LAS unsigned char* lds, const Gemm g, const Sched& S, const Epi& E) {
;     ...
;         for (int t = 0; t < nt; t += 2) {
;             const bool last = (t == nt - 2);
;             const char* a1 = cA + (size_t)(t + 1) * kstep;
;             const char* a2 = last ? nA : cA + (size_t)(t + 2) * kstep; const char* b2 = last ? nB : cB + (size_t)(t + 2) * kstep;
;             const char* a3 = a2 + kstep; const char* b3 = b2 + kstep;
;             if (last && has_next) S.a_ready(nxt);
;             if constexpr (SP2) {
;             PG8_LDB(B0, 0, 0); PG8_LDB(B1, 0, 1); PG8_SCHED; PG8_LDA(At, 0, 0); PG8_STAGE(PG8_SA(1, 1), a1 + hstep, voffA);
;             PG8_WAIT_V(8); PG8_WAIT_L(0); PG8_BAR; PG8_MMA(0, 0, At, B0); PG8_MMA(0, 1, At, B1); PG8_BAR; PG8_SCHED;
;             PG8_LDA(At, 0, 1); PG8_STAGE(PG8_SB(0, 0), b2, voffB); PG8_STAGE(PG8_SB(0, 1), b2 + hstepB, voffB); PG8_STAGE(PG8_SA(0, 0), a2, voffA);
;             PG8_WAIT_V(8); PG8_WAIT_L(0); PG8_BAR; PG8_MMA(1, 0, At, B0); PG8_MMA(1, 1, At, B1); PG8_BAR; PG8_SCHED;
;             PG8_LDB(B0, 1, 0); PG8_LDB(B1, 1, 1); PG8_SCHED; PG8_LDA(At, 1, 0); PG8_STAGE(PG8_SA(0, 1), a2 + hstep, voffA);
;             PG8_WAIT_V(8); PG8_WAIT_L(0); PG8_BAR; PG8_MMA(0, 0, At, B0); PG8_MMA(0, 1, At, B1); PG8_BAR; PG8_SCHED;
;             PG8_LDA(At, 1, 1); PG8_STAGE(PG8_SB(1, 0), b3, voffB); PG8_STAGE(PG8_SB(1, 1), b3 + hstepB, voffB); PG8_STAGE(PG8_SA(1, 0), a3, voffA);
;             PG8_WAIT_V(8); PG8_WAIT_L(0); PG8_BAR; PG8_MMA(1, 0, At, B0); PG8_MMA(1, 1, At, B1); PG8_BAR; PG8_SCHED;
;     ...
;         if constexpr (ALIGN_EPI) { if (wr == 0) PG8_BAR; }
;         if constexpr (!Epi::AFTER_DRAIN) { E(acc, cur, wr, wc, fr, fq); S.done(cur); }
;         if (!has_next) break;
	s_add_i32 s16, s56, s30
	v_lshl_add_u64 v[190:191], v[190:191], 0, s[12:13]
	s_mov_b32 m0, s16
	ds_read_b128 v[182:185], v198 offset:49152
	ds_read_b128 v[186:189], v198 offset:50176
	ds_read_b128 v[202:205], v198 offset:51200
	ds_read_b128 v[206:209], v198 offset:52224
	ds_read_b128 v[210:213], v198 offset:53248
	ds_read_b128 v[214:217], v198 offset:54272
	ds_read_b128 v[218:221], v198 offset:55296
	ds_read_b128 v[222:225], v198 offset:56320
	global_load_lds_dwordx4 v[190:191], off
	s_add_i32 m0, s16, 0x2000
	s_add_u32 s16, s22, 0x58080
	v_lshl_add_u64 v[190:191], v[226:227], 0, s[12:13]
	s_addc_u32 s17, s23, 0
	s_add_i32 s22, s57, s30
	global_load_lds_dwordx4 v[190:191], off
	s_mov_b32 m0, s22
	s_nop 0
	global_load_lds_dwordx4 v148, s[16:17]
	s_add_i32 m0, s22, 0x2000
	s_nop 0
	global_load_lds_dwordx4 v152, s[16:17]
	v_lshl_add_u64 v[190:191], v[228:229], 0, s[12:13]
	s_mov_b32 m0, s49
	s_nop 0
	global_load_lds_dwordx4 v[190:191], off
	v_lshl_add_u64 v[190:191], v[230:231], 0, s[12:13]
	s_mov_b32 m0, s50
	s_nop 0
	global_load_lds_dwordx4 v[190:191], off
	s_waitcnt vmcnt(8)
	s_waitcnt lgkmcnt(0)
	s_barrier
	s_waitcnt lgkmcnt(0)
	v_mfma_f32_16x16x32_bf16 v[62:65], v[130:133], v[182:185], v[62:65]
	v_mfma_f32_16x16x32_bf16 v[58:61], v[138:141], v[182:185], v[58:61]
	v_mfma_f32_16x16x32_bf16 v[46:49], v[130:133], v[202:205], v[46:49]
	v_mfma_f32_16x16x32_bf16 v[42:45], v[138:141], v[202:205], v[42:45]
	v_mfma_f32_16x16x32_bf16 v[30:33], v[130:133], v[210:213], v[30:33]
	v_mfma_f32_16x16x32_bf16 v[26:29], v[138:141], v[210:213], v[26:29]
	v_mfma_f32_16x16x32_bf16 v[14:17], v[130:133], v[218:221], v[14:17]
	v_mfma_f32_16x16x32_bf16 v[10:13], v[138:141], v[218:221], v[10:13]
	v_mfma_f32_16x16x32_bf16 v[62:65], v[134:137], v[186:189], v[62:65]
	v_mfma_f32_16x16x32_bf16 v[58:61], v[142:145], v[186:189], v[58:61]
	v_mfma_f32_16x16x32_bf16 v[46:49], v[134:137], v[206:209], v[46:49]
	v_mfma_f32_16x16x32_bf16 v[42:45], v[142:145], v[206:209], v[42:45]
	v_mfma_f32_16x16x32_bf16 v[30:33], v[134:137], v[214:217], v[30:33]
	v_mfma_f32_16x16x32_bf16 v[26:29], v[142:145], v[214:217], v[26:29]
	v_mfma_f32_16x16x32_bf16 v[14:17], v[134:137], v[222:225], v[14:17]
	v_mfma_f32_16x16x32_bf16 v[10:13], v[142:145], v[222:225], v[10:13]
	v_mfma_f32_16x16x32_bf16 v[54:57], v[166:169], v[182:185], v[54:57]
	v_mfma_f32_16x16x32_bf16 v[50:53], v[174:177], v[182:185], v[50:53]
	v_mfma_f32_16x16x32_bf16 v[38:41], v[166:169], v[202:205], v[38:41]
	v_mfma_f32_16x16x32_bf16 v[34:37], v[174:177], v[202:205], v[34:37]
	v_mfma_f32_16x16x32_bf16 v[22:25], v[166:169], v[210:213], v[22:25]
	v_mfma_f32_16x16x32_bf16 v[18:21], v[174:177], v[210:213], v[18:21]
	v_mfma_f32_16x16x32_bf16 v[6:9], v[166:169], v[218:221], v[6:9]
	v_mfma_f32_16x16x32_bf16 v[2:5], v[174:177], v[218:221], v[2:5]
	v_mfma_f32_16x16x32_bf16 v[54:57], v[170:173], v[186:189], v[54:57]
	v_mfma_f32_16x16x32_bf16 v[50:53], v[178:181], v[186:189], v[50:53]
	v_mfma_f32_16x16x32_bf16 v[38:41], v[170:173], v[206:209], v[38:41]
	v_mfma_f32_16x16x32_bf16 v[34:37], v[178:181], v[206:209], v[34:37]
	v_mfma_f32_16x16x32_bf16 v[22:25], v[170:173], v[214:217], v[22:25]
	v_mfma_f32_16x16x32_bf16 v[18:21], v[178:181], v[214:217], v[18:21]
	v_mfma_f32_16x16x32_bf16 v[6:9], v[170:173], v[222:225], v[6:9]
	v_mfma_f32_16x16x32_bf16 v[2:5], v[178:181], v[222:225], v[2:5]
	s_barrier
	s_add_i32 s25, s25, 2
	s_add_u32 s9, s9, 0x100
	s_addc_u32 s24, s24, 0
	s_cmpk_gt_u32 s25, 0x55
	s_mov_b64 s[16:17], s[20:21]
	s_cbranch_scc0 .LBB0_1595
	s_setprio 0
	s_and_b64 vcc, exec, s[14:15]
	s_cbranch_vccz .LBB0_1598
	s_barrier

; #define PG8_STAGE(bufoff, gbase, voff) do { _Pragma("unroll") for (int _i = 0; _i < 2; ++_i) \
;         __builtin_amdgcn_global_load_lds((const unsigned*)((const char*)(gbase) + (voff)[_i]), (LAS unsigned*)(lds + (bufoff) + ldsw + _i * 8192), 16, 0, 0); } while (0)
; #define PG8_LDA(dst, b, h) do { _Pragma("unroll") for (int m = 0; m < 4; ++m) _Pragma("unroll") for (int k = 0; k < 2; ++k) dst[m][k] = *(const LAS bf16x8*)(lds + PG8_SA(b, h) + aoff + m * 2048 + k * 1024); } while (0)
; #define PG8_LDB(dst, b, h) do { _Pragma("unroll") for (int n = 0; n < 2; ++n) _Pragma("unroll") for (int k = 0; k < 2; ++k) dst[n][k] = *(const LAS bf16x8*)(lds + PG8_SB(b, h) + boff + n * 2048 + k * 1024); } while (0)
; template <class Epi, class Sched, bool ALIGN_EPI = false, bool SP2 = false>
; __device__ __forceinline__ void gemm_phase(LAS unsigned char* lds, const Gemm g, const Sched& S, const Epi& E) {
;     ...
;         for (int t = 0; t < nt; t += 2) {
;             const bool last = (t == nt - 2);
;             const char* a1 = cA + (size_t)(t + 1) * kstep;
;             const char* a2 = last ? nA : cA + (size_t)(t + 2) * kstep; const char* b2 = last ? nB : cB + (size_t)(t + 2) * kstep;
;             const char* a3 = a2 + kstep; const char* b3 = b2 + kstep;
;             if (last && has_next) S.a_ready(nxt);
;             if constexpr (SP2) {
;             PG8_LDB(B0, 0, 0); PG8_LDB(B1, 0, 1); PG8_SCHED; PG8_LDA(At, 0, 0); PG8_STAGE(PG8_SA(1, 1), a1 + hstep, voffA);
;             PG8_WAIT_V(8); PG8_WAIT_L(0); PG8_BAR; PG8_MMA(0, 0, At, B0); PG8_MMA(0, 1, At, B1); PG8_BAR; PG8_SCHED;
;             PG8_LDA(At, 0, 1); PG8_STAGE(PG8_SB(0, 0), b2, voffB); PG8_STAGE(PG8_SB(0, 1), b2 + hstepB, voffB); PG8_STAGE(PG8_SA(0, 0), a2, voffA);
;             PG8_WAIT_V(8); PG8_WAIT_L(0); PG8_BAR; PG8_MMA(1, 0, At, B0); PG8_MMA(1, 1, At, B1); PG8_BAR; PG8_SCHED;
;             PG8_LDB(B0, 1, 0); PG8_LDB(B1, 1, 1); PG8_SCHED; PG8_LDA(At, 1, 0); PG8_STAGE(PG8_SA(0, 1), a2 + hstep, voffA);
;             PG8_WAIT_V(8); PG8_WAIT_L(0); PG8_BAR; PG8_MMA(0, 0, At, B0); PG8_MMA(0, 1, At, B1); PG8_BAR; PG8_SCHED;
;             PG8_LDA(At, 1, 1); PG8_STAGE(PG8_SB(1, 0), b3, voffB); PG8_STAGE(PG8_SB(1, 1), b3 + hstepB, voffB); PG8_STAGE(PG8_SA(1, 0), a3, voffA);
;             PG8_WAIT_V(8); PG8_WAIT_L(0); PG8_BAR; PG8_MMA(1, 0, At, B0); PG8_MMA(1, 1, At, B1); PG8_BAR; PG8_SCHED;
.Lprio_1822:
	ds_read_b128 v[66:69], v173
	ds_read_b128 v[70:73], v173 offset:1024
	ds_read_b128 v[74:77], v173 offset:2048
	ds_read_b128 v[78:81], v173 offset:3072
	ds_read_b128 v[162:165], v174
	ds_read_b128 v[180:183], v174 offset:1024
	ds_read_b128 v[184:187], v174 offset:2048
	ds_read_b128 v[188:191], v174 offset:3072
	s_add_u32 s22, s16, 0xfff80080
	s_addc_u32 s23, s17, -1
	s_cmp_eq_u32 s50, 28
	s_cselect_b32 s41, s3, s23
	s_cselect_b32 s40, s15, s22
	s_cselect_b32 s23, s13, s49
	s_cselect_b32 s22, s24, s25
	s_add_i32 m0, s29, 0xc000
	ds_read_b128 v[192:195], v175
	ds_read_b128 v[196:199], v175 offset:1024
	ds_read_b128 v[200:203], v175 offset:2048
	ds_read_b128 v[204:207], v175 offset:3072
	ds_read_b128 v[208:211], v175 offset:4096
	ds_read_b128 v[212:215], v175 offset:5120
	ds_read_b128 v[216:219], v175 offset:6144
	ds_read_b128 v[220:223], v175 offset:7168
	global_load_lds_dwordx4 v156, s[16:17]
	s_add_i32 m0, s29, 0xe000
	s_nop 0
	global_load_lds_dwordx4 v154, s[16:17]
	s_waitcnt lgkmcnt(0)
	s_barrier
	s_waitcnt lgkmcnt(0)
	v_mfma_f32_16x16x32_bf16 v[142:145], v[66:69], v[192:195], 0
	v_mfma_f32_16x16x32_bf16 v[138:141], v[74:77], v[192:195], 0
	v_mfma_f32_16x16x32_bf16 v[126:129], v[66:69], v[200:203], 0
	v_mfma_f32_16x16x32_bf16 v[122:125], v[74:77], v[200:203], 0
	v_mfma_f32_16x16x32_bf16 v[110:113], v[66:69], v[208:211], 0
	v_mfma_f32_16x16x32_bf16 v[106:109], v[74:77], v[208:211], 0
	v_mfma_f32_16x16x32_bf16 v[94:97], v[66:69], v[216:219], 0
	v_mfma_f32_16x16x32_bf16 v[90:93], v[74:77], v[216:219], 0
	v_mfma_f32_16x16x32_bf16 v[142:145], v[70:73], v[196:199], v[142:145]
	v_mfma_f32_16x16x32_bf16 v[138:141], v[78:81], v[196:199], v[138:141]
	v_mfma_f32_16x16x32_bf16 v[126:129], v[70:73], v[204:207], v[126:129]
	v_mfma_f32_16x16x32_bf16 v[122:125], v[78:81], v[204:207], v[122:125]
	v_mfma_f32_16x16x32_bf16 v[110:113], v[70:73], v[212:215], v[110:113]
	v_mfma_f32_16x16x32_bf16 v[106:109], v[78:81], v[212:215], v[106:109]
	v_mfma_f32_16x16x32_bf16 v[94:97], v[70:73], v[220:223], v[94:97]
	v_mfma_f32_16x16x32_bf16 v[90:93], v[78:81], v[220:223], v[90:93]
	v_mfma_f32_16x16x32_bf16 v[134:137], v[162:165], v[192:195], 0
	v_mfma_f32_16x16x32_bf16 v[130:133], v[184:187], v[192:195], 0
	v_mfma_f32_16x16x32_bf16 v[118:121], v[162:165], v[200:203], 0
	v_mfma_f32_16x16x32_bf16 v[114:117], v[184:187], v[200:203], 0
	v_mfma_f32_16x16x32_bf16 v[102:105], v[162:165], v[208:211], 0
	v_mfma_f32_16x16x32_bf16 v[98:101], v[184:187], v[208:211], 0
	v_mfma_f32_16x16x32_bf16 v[86:89], v[162:165], v[216:219], 0
	v_mfma_f32_16x16x32_bf16 v[82:85], v[184:187], v[216:219], 0
	v_mfma_f32_16x16x32_bf16 v[134:137], v[180:183], v[196:199], v[134:137]
	v_mfma_f32_16x16x32_bf16 v[130:133], v[188:191], v[196:199], v[130:133]
	v_mfma_f32_16x16x32_bf16 v[118:121], v[180:183], v[204:207], v[118:121]
	v_mfma_f32_16x16x32_bf16 v[114:117], v[188:191], v[204:207], v[114:117]
	v_mfma_f32_16x16x32_bf16 v[102:105], v[180:183], v[212:215], v[102:105]
	v_mfma_f32_16x16x32_bf16 v[98:101], v[188:191], v[212:215], v[98:101]
	v_mfma_f32_16x16x32_bf16 v[86:89], v[180:183], v[220:223], v[86:89]
	v_mfma_f32_16x16x32_bf16 v[82:85], v[188:191], v[220:223], v[82:85]
	s_barrier
	s_add_i32 s51, s44, s26
	v_lshl_add_u64 v[166:167], s[22:23], 0, v[150:151]
	s_mov_b32 m0, s51
	ds_read_b128 v[192:195], v175 offset:16384
	ds_read_b128 v[196:199], v175 offset:17408
	ds_read_b128 v[200:203], v175 offset:18432
	ds_read_b128 v[204:207], v175 offset:19456
	ds_read_b128 v[208:211], v175 offset:20480
	ds_read_b128 v[212:215], v175 offset:21504
	ds_read_b128 v[216:219], v175 offset:22528
	ds_read_b128 v[220:223], v175 offset:23552
	global_load_lds_dwordx4 v[166:167], off
	s_add_i32 m0, s51, 0x2000
	s_add_u32 s52, s22, 0x80000
	v_lshl_add_u64 v[224:225], s[22:23], 0, v[146:147]
	s_addc_u32 s53, s23, 0
	s_add_i32 s51, s45, s26
	global_load_lds_dwordx4 v[224:225], off
	s_mov_b32 m0, s51
	v_lshl_add_u64 v[228:229], s[40:41], 0, v[148:149]
	global_load_lds_dwordx4 v150, s[52:53]
	s_add_i32 m0, s51, 0x2000
	s_nop 0
	global_load_lds_dwordx4 v146, s[52:53]
	v_lshl_add_u64 v[226:227], s[40:41], 0, v[152:153]
	s_mov_b32 m0, s29
	s_nop 0
	global_load_lds_dwordx4 v[226:227], off
	s_mov_b32 m0, s30
	s_nop 0
	global_load_lds_dwordx4 v[228:229], off
	s_waitcnt lgkmcnt(0)
	s_barrier
	s_waitcnt lgkmcnt(0)
	v_mfma_f32_16x16x32_bf16 v[62:65], v[66:69], v[192:195], 0
	v_mfma_f32_16x16x32_bf16 v[58:61], v[74:77], v[192:195], 0
	v_mfma_f32_16x16x32_bf16 v[46:49], v[66:69], v[200:203], 0
	v_mfma_f32_16x16x32_bf16 v[42:45], v[74:77], v[200:203], 0
	v_mfma_f32_16x16x32_bf16 v[30:33], v[66:69], v[208:211], 0
	v_mfma_f32_16x16x32_bf16 v[26:29], v[74:77], v[208:211], 0
	v_mfma_f32_16x16x32_bf16 v[14:17], v[66:69], v[216:219], 0
	v_mfma_f32_16x16x32_bf16 v[10:13], v[74:77], v[216:219], 0
	v_mfma_f32_16x16x32_bf16 v[62:65], v[70:73], v[196:199], v[62:65]
	v_mfma_f32_16x16x32_bf16 v[58:61], v[78:81], v[196:199], v[58:61]
	v_mfma_f32_16x16x32_bf16 v[46:49], v[70:73], v[204:207], v[46:49]
	v_mfma_f32_16x16x32_bf16 v[42:45], v[78:81], v[204:207], v[42:45]
	v_mfma_f32_16x16x32_bf16 v[30:33], v[70:73], v[212:215], v[30:33]
	v_mfma_f32_16x16x32_bf16 v[26:29], v[78:81], v[212:215], v[26:29]
	v_mfma_f32_16x16x32_bf16 v[14:17], v[70:73], v[220:223], v[14:17]
	v_mfma_f32_16x16x32_bf16 v[10:13], v[78:81], v[220:223], v[10:13]
	v_mfma_f32_16x16x32_bf16 v[54:57], v[162:165], v[192:195], 0
	v_mfma_f32_16x16x32_bf16 v[50:53], v[184:187], v[192:195], 0
	v_mfma_f32_16x16x32_bf16 v[38:41], v[162:165], v[200:203], 0
	v_mfma_f32_16x16x32_bf16 v[34:37], v[184:187], v[200:203], 0
	v_mfma_f32_16x16x32_bf16 v[22:25], v[162:165], v[208:211], 0
	v_mfma_f32_16x16x32_bf16 v[18:21], v[184:187], v[208:211], 0
	v_mfma_f32_16x16x32_bf16 v[6:9], v[162:165], v[216:219], 0
	v_mfma_f32_16x16x32_bf16 v[2:5], v[184:187], v[216:219], 0
	v_mfma_f32_16x16x32_bf16 v[54:57], v[180:183], v[196:199], v[54:57]
	v_mfma_f32_16x16x32_bf16 v[50:53], v[188:191], v[196:199], v[50:53]
	v_mfma_f32_16x16x32_bf16 v[38:41], v[180:183], v[204:207], v[38:41]
	v_mfma_f32_16x16x32_bf16 v[34:37], v[188:191], v[204:207], v[34:37]
	v_mfma_f32_16x16x32_bf16 v[22:25], v[180:183], v[212:215], v[22:25]
	v_mfma_f32_16x16x32_bf16 v[18:21], v[188:191], v[212:215], v[18:21]
	v_mfma_f32_16x16x32_bf16 v[6:9], v[180:183], v[220:223], v[6:9]
	v_mfma_f32_16x16x32_bf16 v[2:5], v[188:191], v[220:223], v[2:5]
	s_barrier
; #define PG8_STAGE(bufoff, gbase, voff) do { _Pragma("unroll") for (int _i = 0; _i < 2; ++_i) \
;         __builtin_amdgcn_global_load_lds((const unsigned*)((const char*)(gbase) + (voff)[_i]), (LAS unsigned*)(lds + (bufoff) + ldsw + _i * 8192), 16, 0, 0); } while (0)
; #define PG8_LDA(dst, b, h) do { _Pragma("unroll") for (int m = 0; m < 4; ++m) _Pragma("unroll") for (int k = 0; k < 2; ++k) dst[m][k] = *(const LAS bf16x8*)(lds + PG8_SA(b, h) + aoff + m * 2048 + k * 1024); } while (0)
; #define PG8_LDB(dst, b, h) do { _Pragma("unroll") for (int n = 0; n < 2; ++n) _Pragma("unroll") for (int k = 0; k < 2; ++k) dst[n][k] = *(const LAS bf16x8*)(lds + PG8_SB(b, h) + boff + n * 2048 + k * 1024); } while (0)
; template <class Epi, class Sched, bool ALIGN_EPI = false, bool SP2 = false>
; __device__ __forceinline__ void gemm_phase(LAS unsigned char* lds, const Gemm g, const Sched& S, const Epi& E) {
;     ...
;         for (int t = 0; t < nt; t += 2) {
;             const bool last = (t == nt - 2);
;             const char* a1 = cA + (size_t)(t + 1) * kstep;
;             const char* a2 = last ? nA : cA + (size_t)(t + 2) * kstep; const char* b2 = last ? nB : cB + (size_t)(t + 2) * kstep;
;             const char* a3 = a2 + kstep; const char* b3 = b2 + kstep;
;             if (last && has_next) S.a_ready(nxt);
;             if constexpr (SP2) {
;             PG8_LDB(B0, 0, 0); PG8_LDB(B1, 0, 1); PG8_SCHED; PG8_LDA(At, 0, 0); PG8_STAGE(PG8_SA(1, 1), a1 + hstep, voffA);
;             PG8_WAIT_V(8); PG8_WAIT_L(0); PG8_BAR; PG8_MMA(0, 0, At, B0); PG8_MMA(0, 1, At, B1); PG8_BAR; PG8_SCHED;
;             PG8_LDA(At, 0, 1); PG8_STAGE(PG8_SB(0, 0), b2, voffB); PG8_STAGE(PG8_SB(0, 1), b2 + hstepB, voffB); PG8_STAGE(PG8_SA(0, 0), a2, voffA);
;             PG8_WAIT_V(8); PG8_WAIT_L(0); PG8_BAR; PG8_MMA(1, 0, At, B0); PG8_MMA(1, 1, At, B1); PG8_BAR; PG8_SCHED;
;             PG8_LDB(B0, 1, 0); PG8_LDB(B1, 1, 1); PG8_SCHED; PG8_LDA(At, 1, 0); PG8_STAGE(PG8_SA(0, 1), a2 + hstep, voffA);
;             PG8_WAIT_V(8); PG8_WAIT_L(0); PG8_BAR; PG8_MMA(0, 0, At, B0); PG8_MMA(0, 1, At, B1); PG8_BAR; PG8_SCHED;
;             PG8_LDA(At, 1, 1); PG8_STAGE(PG8_SB(1, 0), b3, voffB); PG8_STAGE(PG8_SB(1, 1), b3 + hstepB, voffB); PG8_STAGE(PG8_SA(1, 0), a3, voffA);
;             PG8_WAIT_V(8); PG8_WAIT_L(0); PG8_BAR; PG8_MMA(1, 0, At, B0); PG8_MMA(1, 1, At, B1); PG8_BAR; PG8_SCHED;
	s_add_i32 s51, 0, 0x18000
	s_add_i32 s52, 0, 0x1c000
	v_add_u32_e32 v78, s51, v169
	v_add_u32_e32 v168, s52, v169
	ds_read_b128 v[66:69], v78
	ds_read_b128 v[70:73], v78 offset:1024
	ds_read_b128 v[74:77], v78 offset:2048
	ds_read_b128 v[78:81], v78 offset:3072
	ds_read_b128 v[162:165], v168
	ds_read_b128 v[180:183], v168 offset:1024
	ds_read_b128 v[184:187], v168 offset:2048
	ds_read_b128 v[188:191], v168 offset:3072
	s_add_u32 s40, s40, 0x80000
	s_addc_u32 s41, s41, 0
	s_mov_b32 m0, s31
	ds_read_b128 v[192:195], v175 offset:32768
	ds_read_b128 v[196:199], v175 offset:33792
	ds_read_b128 v[200:203], v175 offset:34816
	ds_read_b128 v[204:207], v175 offset:35840
	ds_read_b128 v[208:211], v175 offset:36864
	ds_read_b128 v[212:215], v175 offset:37888
	ds_read_b128 v[216:219], v175 offset:38912
	ds_read_b128 v[220:223], v175 offset:39936
	global_load_lds_dwordx4 v152, s[40:41]
	s_mov_b32 m0, s33
	s_nop 0
	global_load_lds_dwordx4 v148, s[40:41]
	s_waitcnt vmcnt(8)
	s_waitcnt lgkmcnt(0)
	s_barrier
	s_waitcnt lgkmcnt(0)
	v_mfma_f32_16x16x32_bf16 v[142:145], v[66:69], v[192:195], v[142:145]
	v_mfma_f32_16x16x32_bf16 v[138:141], v[74:77], v[192:195], v[138:141]
	v_mfma_f32_16x16x32_bf16 v[126:129], v[66:69], v[200:203], v[126:129]
	v_mfma_f32_16x16x32_bf16 v[122:125], v[74:77], v[200:203], v[122:125]
	v_mfma_f32_16x16x32_bf16 v[110:113], v[66:69], v[208:211], v[110:113]
	v_mfma_f32_16x16x32_bf16 v[106:109], v[74:77], v[208:211], v[106:109]
	v_mfma_f32_16x16x32_bf16 v[94:97], v[66:69], v[216:219], v[94:97]
	v_mfma_f32_16x16x32_bf16 v[90:93], v[74:77], v[216:219], v[90:93]
	v_mfma_f32_16x16x32_bf16 v[142:145], v[70:73], v[196:199], v[142:145]
	v_mfma_f32_16x16x32_bf16 v[138:141], v[78:81], v[196:199], v[138:141]
	v_mfma_f32_16x16x32_bf16 v[126:129], v[70:73], v[204:207], v[126:129]
	v_mfma_f32_16x16x32_bf16 v[122:125], v[78:81], v[204:207], v[122:125]
	v_mfma_f32_16x16x32_bf16 v[110:113], v[70:73], v[212:215], v[110:113]
	v_mfma_f32_16x16x32_bf16 v[106:109], v[78:81], v[212:215], v[106:109]
	v_mfma_f32_16x16x32_bf16 v[94:97], v[70:73], v[220:223], v[94:97]
	v_mfma_f32_16x16x32_bf16 v[90:93], v[78:81], v[220:223], v[90:93]
	v_mfma_f32_16x16x32_bf16 v[134:137], v[162:165], v[192:195], v[134:137]
	v_mfma_f32_16x16x32_bf16 v[130:133], v[184:187], v[192:195], v[130:133]
	v_mfma_f32_16x16x32_bf16 v[118:121], v[162:165], v[200:203], v[118:121]
	v_mfma_f32_16x16x32_bf16 v[114:117], v[184:187], v[200:203], v[114:117]
	v_mfma_f32_16x16x32_bf16 v[102:105], v[162:165], v[208:211], v[102:105]
	v_mfma_f32_16x16x32_bf16 v[98:101], v[184:187], v[208:211], v[98:101]
	v_mfma_f32_16x16x32_bf16 v[86:89], v[162:165], v[216:219], v[86:89]
	v_mfma_f32_16x16x32_bf16 v[82:85], v[184:187], v[216:219], v[82:85]
	v_mfma_f32_16x16x32_bf16 v[134:137], v[180:183], v[196:199], v[134:137]
	v_mfma_f32_16x16x32_bf16 v[130:133], v[188:191], v[196:199], v[130:133]
	v_mfma_f32_16x16x32_bf16 v[118:121], v[180:183], v[204:207], v[118:121]
	v_mfma_f32_16x16x32_bf16 v[114:117], v[188:191], v[204:207], v[114:117]
	v_mfma_f32_16x16x32_bf16 v[102:105], v[180:183], v[212:215], v[102:105]
	v_mfma_f32_16x16x32_bf16 v[98:101], v[188:191], v[212:215], v[98:101]
	v_mfma_f32_16x16x32_bf16 v[86:89], v[180:183], v[220:223], v[86:89]
	v_mfma_f32_16x16x32_bf16 v[82:85], v[188:191], v[220:223], v[82:85]
	s_barrier
	s_add_i32 s40, s51, s26
	v_lshl_add_u64 v[166:167], v[166:167], 0, s[8:9]
	s_mov_b32 m0, s40
	ds_read_b128 v[192:195], v175 offset:49152
	ds_read_b128 v[196:199], v175 offset:50176
	ds_read_b128 v[200:203], v175 offset:51200
	ds_read_b128 v[204:207], v175 offset:52224
	ds_read_b128 v[208:211], v175 offset:53248
	ds_read_b128 v[212:215], v175 offset:54272
	ds_read_b128 v[216:219], v175 offset:55296
	ds_read_b128 v[220:223], v175 offset:56320
	global_load_lds_dwordx4 v[166:167], off
	s_add_i32 m0, s40, 0x2000
	s_add_u32 s22, s22, 0x80080
	v_lshl_add_u64 v[166:167], v[224:225], 0, s[8:9]
	s_addc_u32 s23, s23, 0
	s_add_i32 s40, s52, s26
	global_load_lds_dwordx4 v[166:167], off
	s_mov_b32 m0, s40
	s_nop 0
	global_load_lds_dwordx4 v150, s[22:23]
	s_add_i32 m0, s40, 0x2000
	s_nop 0
	global_load_lds_dwordx4 v146, s[22:23]
	v_lshl_add_u64 v[166:167], v[226:227], 0, s[8:9]
	s_mov_b32 m0, s42
	s_nop 0
	global_load_lds_dwordx4 v[166:167], off
	v_lshl_add_u64 v[166:167], v[228:229], 0, s[8:9]
	s_mov_b32 m0, s43
	s_nop 0
	global_load_lds_dwordx4 v[166:167], off
	s_waitcnt vmcnt(8)
	s_waitcnt lgkmcnt(0)
	s_barrier
	s_waitcnt lgkmcnt(0)
	v_mfma_f32_16x16x32_bf16 v[62:65], v[66:69], v[192:195], v[62:65]
	v_mfma_f32_16x16x32_bf16 v[58:61], v[74:77], v[192:195], v[58:61]
	v_mfma_f32_16x16x32_bf16 v[46:49], v[66:69], v[200:203], v[46:49]
	v_mfma_f32_16x16x32_bf16 v[42:45], v[74:77], v[200:203], v[42:45]
	v_mfma_f32_16x16x32_bf16 v[30:33], v[66:69], v[208:211], v[30:33]
	v_mfma_f32_16x16x32_bf16 v[26:29], v[74:77], v[208:211], v[26:29]
	v_mfma_f32_16x16x32_bf16 v[14:17], v[66:69], v[216:219], v[14:17]
	v_mfma_f32_16x16x32_bf16 v[10:13], v[74:77], v[216:219], v[10:13]
	v_mfma_f32_16x16x32_bf16 v[62:65], v[70:73], v[196:199], v[62:65]
	v_mfma_f32_16x16x32_bf16 v[58:61], v[78:81], v[196:199], v[58:61]
	v_mfma_f32_16x16x32_bf16 v[46:49], v[70:73], v[204:207], v[46:49]
	v_mfma_f32_16x16x32_bf16 v[42:45], v[78:81], v[204:207], v[42:45]
	v_mfma_f32_16x16x32_bf16 v[30:33], v[70:73], v[212:215], v[30:33]
	v_mfma_f32_16x16x32_bf16 v[26:29], v[78:81], v[212:215], v[26:29]
	v_mfma_f32_16x16x32_bf16 v[14:17], v[70:73], v[220:223], v[14:17]
	v_mfma_f32_16x16x32_bf16 v[10:13], v[78:81], v[220:223], v[10:13]
	v_mfma_f32_16x16x32_bf16 v[54:57], v[162:165], v[192:195], v[54:57]
	v_mfma_f32_16x16x32_bf16 v[50:53], v[184:187], v[192:195], v[50:53]
	v_mfma_f32_16x16x32_bf16 v[38:41], v[162:165], v[200:203], v[38:41]
	v_mfma_f32_16x16x32_bf16 v[34:37], v[184:187], v[200:203], v[34:37]
	v_mfma_f32_16x16x32_bf16 v[22:25], v[162:165], v[208:211], v[22:25]
	v_mfma_f32_16x16x32_bf16 v[18:21], v[184:187], v[208:211], v[18:21]
	v_mfma_f32_16x16x32_bf16 v[6:9], v[162:165], v[216:219], v[6:9]
	v_mfma_f32_16x16x32_bf16 v[2:5], v[184:187], v[216:219], v[2:5]
	v_mfma_f32_16x16x32_bf16 v[54:57], v[180:183], v[196:199], v[54:57]
	v_mfma_f32_16x16x32_bf16 v[50:53], v[188:191], v[196:199], v[50:53]
	v_mfma_f32_16x16x32_bf16 v[38:41], v[180:183], v[204:207], v[38:41]
	v_mfma_f32_16x16x32_bf16 v[34:37], v[188:191], v[204:207], v[34:37]
	v_mfma_f32_16x16x32_bf16 v[22:25], v[180:183], v[212:215], v[22:25]
	v_mfma_f32_16x16x32_bf16 v[18:21], v[188:191], v[212:215], v[18:21]
	v_mfma_f32_16x16x32_bf16 v[6:9], v[180:183], v[220:223], v[6:9]
	v_mfma_f32_16x16x32_bf16 v[2:5], v[188:191], v[220:223], v[2:5]
	s_barrier
	s_add_i32 s50, s50, 2
	s_add_u32 s25, s25, 0x100
	s_addc_u32 s49, s49, 0
	s_add_u32 s16, s16, 0x100
	s_addc_u32 s17, s17, 0
	s_cmp_lt_u32 s50, 30
; #define PG8_STAGE(bufoff, gbase, voff) do { _Pragma("unroll") for (int _i = 0; _i < 2; ++_i) \
;         __builtin_amdgcn_global_load_lds((const unsigned*)((const char*)(gbase) + (voff)[_i]), (LAS unsigned*)(lds + (bufoff) + ldsw + _i * 8192), 16, 0, 0); } while (0)
; #define PG8_LDA(dst, b, h) do { _Pragma("unroll") for (int m = 0; m < 4; ++m) _Pragma("unroll") for (int k = 0; k < 2; ++k) dst[m][k] = *(const LAS bf16x8*)(lds + PG8_SA(b, h) + aoff + m * 2048 + k * 1024); } while (0)
; #define PG8_LDB(dst, b, h) do { _Pragma("unroll") for (int n = 0; n < 2; ++n) _Pragma("unroll") for (int k = 0; k < 2; ++k) dst[n][k] = *(const LAS bf16x8*)(lds + PG8_SB(b, h) + boff + n * 2048 + k * 1024); } while (0)
; template <class Epi, class Sched, bool ALIGN_EPI = false, bool SP2 = false>
; __device__ __forceinline__ void gemm_phase(LAS unsigned char* lds, const Gemm g, const Sched& S, const Epi& E) {
;     ...
;         for (int t = 0; t < nt; t += 2) {
;             const bool last = (t == nt - 2);
;             const char* a1 = cA + (size_t)(t + 1) * kstep;
;             const char* a2 = last ? nA : cA + (size_t)(t + 2) * kstep; const char* b2 = last ? nB : cB + (size_t)(t + 2) * kstep;
;             const char* a3 = a2 + kstep; const char* b3 = b2 + kstep;
;             if (last && has_next) S.a_ready(nxt);
;             if constexpr (SP2) {
;             PG8_LDB(B0, 0, 0); PG8_LDB(B1, 0, 1); PG8_SCHED; PG8_LDA(At, 0, 0); PG8_STAGE(PG8_SA(1, 1), a1 + hstep, voffA);
;             PG8_WAIT_V(8); PG8_WAIT_L(0); PG8_BAR; PG8_MMA(0, 0, At, B0); PG8_MMA(0, 1, At, B1); PG8_BAR; PG8_SCHED;
;             PG8_LDA(At, 0, 1); PG8_STAGE(PG8_SB(0, 0), b2, voffB); PG8_STAGE(PG8_SB(0, 1), b2 + hstepB, voffB); PG8_STAGE(PG8_SA(0, 0), a2, voffA);
;             PG8_WAIT_V(8); PG8_WAIT_L(0); PG8_BAR; PG8_MMA(1, 0, At, B0); PG8_MMA(1, 1, At, B1); PG8_BAR; PG8_SCHED;
;             PG8_LDB(B0, 1, 0); PG8_LDB(B1, 1, 1); PG8_SCHED; PG8_LDA(At, 1, 0); PG8_STAGE(PG8_SA(0, 1), a2 + hstep, voffA);
;             PG8_WAIT_V(8); PG8_WAIT_L(0); PG8_BAR; PG8_MMA(0, 0, At, B0); PG8_MMA(0, 1, At, B1); PG8_BAR; PG8_SCHED;
;             PG8_LDA(At, 1, 1); PG8_STAGE(PG8_SB(1, 0), b3, voffB); PG8_STAGE(PG8_SB(1, 1), b3 + hstepB, voffB); PG8_STAGE(PG8_SA(1, 0), a3, voffA);
;             PG8_WAIT_V(8); PG8_WAIT_L(0); PG8_BAR; PG8_MMA(1, 0, At, B0); PG8_MMA(1, 1, At, B1); PG8_BAR; PG8_SCHED;
.LBB0_1822:
	ds_read_b128 v[66:69], v173
	ds_read_b128 v[70:73], v173 offset:1024
	ds_read_b128 v[74:77], v173 offset:2048
	ds_read_b128 v[78:81], v173 offset:3072
	ds_read_b128 v[162:165], v174
	ds_read_b128 v[180:183], v174 offset:1024
	ds_read_b128 v[184:187], v174 offset:2048
	ds_read_b128 v[188:191], v174 offset:3072
	s_add_u32 s22, s16, 0xfff80080
	s_addc_u32 s23, s17, -1
	s_cmp_eq_u32 s50, 28
	s_cselect_b32 s41, s3, s23
	s_cselect_b32 s40, s15, s22
	s_cselect_b32 s23, s13, s49
	s_cselect_b32 s22, s24, s25
	s_add_i32 m0, s29, 0xc000
	ds_read_b128 v[192:195], v175
	ds_read_b128 v[196:199], v175 offset:1024
	ds_read_b128 v[200:203], v175 offset:2048
	ds_read_b128 v[204:207], v175 offset:3072
	ds_read_b128 v[208:211], v175 offset:4096
	ds_read_b128 v[212:215], v175 offset:5120
	ds_read_b128 v[216:219], v175 offset:6144
	ds_read_b128 v[220:223], v175 offset:7168
	global_load_lds_dwordx4 v156, s[16:17]
	s_add_i32 m0, s29, 0xe000
	s_nop 0
	global_load_lds_dwordx4 v154, s[16:17]
	s_waitcnt vmcnt(8)
	s_waitcnt lgkmcnt(0)
	s_barrier
	s_waitcnt lgkmcnt(0)
	v_mfma_f32_16x16x32_bf16 v[142:145], v[66:69], v[192:195], v[142:145]
	v_mfma_f32_16x16x32_bf16 v[138:141], v[74:77], v[192:195], v[138:141]
	v_mfma_f32_16x16x32_bf16 v[126:129], v[66:69], v[200:203], v[126:129]
	v_mfma_f32_16x16x32_bf16 v[122:125], v[74:77], v[200:203], v[122:125]
	v_mfma_f32_16x16x32_bf16 v[110:113], v[66:69], v[208:211], v[110:113]
	v_mfma_f32_16x16x32_bf16 v[106:109], v[74:77], v[208:211], v[106:109]
	v_mfma_f32_16x16x32_bf16 v[94:97], v[66:69], v[216:219], v[94:97]
	v_mfma_f32_16x16x32_bf16 v[90:93], v[74:77], v[216:219], v[90:93]
	v_mfma_f32_16x16x32_bf16 v[142:145], v[70:73], v[196:199], v[142:145]
	v_mfma_f32_16x16x32_bf16 v[138:141], v[78:81], v[196:199], v[138:141]
	v_mfma_f32_16x16x32_bf16 v[126:129], v[70:73], v[204:207], v[126:129]
	v_mfma_f32_16x16x32_bf16 v[122:125], v[78:81], v[204:207], v[122:125]
	v_mfma_f32_16x16x32_bf16 v[110:113], v[70:73], v[212:215], v[110:113]
	v_mfma_f32_16x16x32_bf16 v[106:109], v[78:81], v[212:215], v[106:109]
	v_mfma_f32_16x16x32_bf16 v[94:97], v[70:73], v[220:223], v[94:97]
	v_mfma_f32_16x16x32_bf16 v[90:93], v[78:81], v[220:223], v[90:93]
	v_mfma_f32_16x16x32_bf16 v[134:137], v[162:165], v[192:195], v[134:137]
	v_mfma_f32_16x16x32_bf16 v[130:133], v[184:187], v[192:195], v[130:133]
	v_mfma_f32_16x16x32_bf16 v[118:121], v[162:165], v[200:203], v[118:121]
	v_mfma_f32_16x16x32_bf16 v[114:117], v[184:187], v[200:203], v[114:117]
	v_mfma_f32_16x16x32_bf16 v[102:105], v[162:165], v[208:211], v[102:105]
	v_mfma_f32_16x16x32_bf16 v[98:101], v[184:187], v[208:211], v[98:101]
	v_mfma_f32_16x16x32_bf16 v[86:89], v[162:165], v[216:219], v[86:89]
	v_mfma_f32_16x16x32_bf16 v[82:85], v[184:187], v[216:219], v[82:85]
	v_mfma_f32_16x16x32_bf16 v[134:137], v[180:183], v[196:199], v[134:137]
	v_mfma_f32_16x16x32_bf16 v[130:133], v[188:191], v[196:199], v[130:133]
	v_mfma_f32_16x16x32_bf16 v[118:121], v[180:183], v[204:207], v[118:121]
	v_mfma_f32_16x16x32_bf16 v[114:117], v[188:191], v[204:207], v[114:117]
	v_mfma_f32_16x16x32_bf16 v[102:105], v[180:183], v[212:215], v[102:105]
	v_mfma_f32_16x16x32_bf16 v[98:101], v[188:191], v[212:215], v[98:101]
	v_mfma_f32_16x16x32_bf16 v[86:89], v[180:183], v[220:223], v[86:89]
	v_mfma_f32_16x16x32_bf16 v[82:85], v[188:191], v[220:223], v[82:85]
	s_barrier
	s_add_i32 s51, s44, s26
	v_lshl_add_u64 v[166:167], s[22:23], 0, v[150:151]
	s_mov_b32 m0, s51
	ds_read_b128 v[192:195], v175 offset:16384
	ds_read_b128 v[196:199], v175 offset:17408
	ds_read_b128 v[200:203], v175 offset:18432
	ds_read_b128 v[204:207], v175 offset:19456
	ds_read_b128 v[208:211], v175 offset:20480
	ds_read_b128 v[212:215], v175 offset:21504
	ds_read_b128 v[216:219], v175 offset:22528
	ds_read_b128 v[220:223], v175 offset:23552
	global_load_lds_dwordx4 v[166:167], off
	s_add_i32 m0, s51, 0x2000
	s_add_u32 s52, s22, 0x80000
	v_lshl_add_u64 v[224:225], s[22:23], 0, v[146:147]
	s_addc_u32 s53, s23, 0
	s_add_i32 s51, s45, s26
	global_load_lds_dwordx4 v[224:225], off
	s_mov_b32 m0, s51
	v_lshl_add_u64 v[228:229], s[40:41], 0, v[148:149]
	global_load_lds_dwordx4 v150, s[52:53]
	s_add_i32 m0, s51, 0x2000
	s_nop 0
	global_load_lds_dwordx4 v146, s[52:53]
	v_lshl_add_u64 v[226:227], s[40:41], 0, v[152:153]
	s_mov_b32 m0, s29
	s_nop 0
	global_load_lds_dwordx4 v[226:227], off
	s_mov_b32 m0, s30
	s_nop 0
	global_load_lds_dwordx4 v[228:229], off
	s_waitcnt vmcnt(8)
	s_waitcnt lgkmcnt(0)
	s_barrier
	s_waitcnt lgkmcnt(0)
	v_mfma_f32_16x16x32_bf16 v[62:65], v[66:69], v[192:195], v[62:65]
	v_mfma_f32_16x16x32_bf16 v[58:61], v[74:77], v[192:195], v[58:61]
	v_mfma_f32_16x16x32_bf16 v[46:49], v[66:69], v[200:203], v[46:49]
	v_mfma_f32_16x16x32_bf16 v[42:45], v[74:77], v[200:203], v[42:45]
	v_mfma_f32_16x16x32_bf16 v[30:33], v[66:69], v[208:211], v[30:33]
	v_mfma_f32_16x16x32_bf16 v[26:29], v[74:77], v[208:211], v[26:29]
	v_mfma_f32_16x16x32_bf16 v[14:17], v[66:69], v[216:219], v[14:17]
	v_mfma_f32_16x16x32_bf16 v[10:13], v[74:77], v[216:219], v[10:13]
	v_mfma_f32_16x16x32_bf16 v[62:65], v[70:73], v[196:199], v[62:65]
	v_mfma_f32_16x16x32_bf16 v[58:61], v[78:81], v[196:199], v[58:61]
	v_mfma_f32_16x16x32_bf16 v[46:49], v[70:73], v[204:207], v[46:49]
	v_mfma_f32_16x16x32_bf16 v[42:45], v[78:81], v[204:207], v[42:45]
	v_mfma_f32_16x16x32_bf16 v[30:33], v[70:73], v[212:215], v[30:33]
	v_mfma_f32_16x16x32_bf16 v[26:29], v[78:81], v[212:215], v[26:29]
	v_mfma_f32_16x16x32_bf16 v[14:17], v[70:73], v[220:223], v[14:17]
	v_mfma_f32_16x16x32_bf16 v[10:13], v[78:81], v[220:223], v[10:13]
	v_mfma_f32_16x16x32_bf16 v[54:57], v[162:165], v[192:195], v[54:57]
	v_mfma_f32_16x16x32_bf16 v[50:53], v[184:187], v[192:195], v[50:53]
	v_mfma_f32_16x16x32_bf16 v[38:41], v[162:165], v[200:203], v[38:41]
	v_mfma_f32_16x16x32_bf16 v[34:37], v[184:187], v[200:203], v[34:37]
	v_mfma_f32_16x16x32_bf16 v[22:25], v[162:165], v[208:211], v[22:25]
	v_mfma_f32_16x16x32_bf16 v[18:21], v[184:187], v[208:211], v[18:21]
	v_mfma_f32_16x16x32_bf16 v[6:9], v[162:165], v[216:219], v[6:9]
	v_mfma_f32_16x16x32_bf16 v[2:5], v[184:187], v[216:219], v[2:5]
	v_mfma_f32_16x16x32_bf16 v[54:57], v[180:183], v[196:199], v[54:57]
	v_mfma_f32_16x16x32_bf16 v[50:53], v[188:191], v[196:199], v[50:53]
	v_mfma_f32_16x16x32_bf16 v[38:41], v[180:183], v[204:207], v[38:41]
	v_mfma_f32_16x16x32_bf16 v[34:37], v[188:191], v[204:207], v[34:37]
	v_mfma_f32_16x16x32_bf16 v[22:25], v[180:183], v[212:215], v[22:25]
	v_mfma_f32_16x16x32_bf16 v[18:21], v[188:191], v[212:215], v[18:21]
	v_mfma_f32_16x16x32_bf16 v[6:9], v[180:183], v[220:223], v[6:9]
	v_mfma_f32_16x16x32_bf16 v[2:5], v[188:191], v[220:223], v[2:5]
	s_barrier
; #define PG8_STAGE(bufoff, gbase, voff) do { _Pragma("unroll") for (int _i = 0; _i < 2; ++_i) \
;         __builtin_amdgcn_global_load_lds((const unsigned*)((const char*)(gbase) + (voff)[_i]), (LAS unsigned*)(lds + (bufoff) + ldsw + _i * 8192), 16, 0, 0); } while (0)
; #define PG8_LDA(dst, b, h) do { _Pragma("unroll") for (int m = 0; m < 4; ++m) _Pragma("unroll") for (int k = 0; k < 2; ++k) dst[m][k] = *(const LAS bf16x8*)(lds + PG8_SA(b, h) + aoff + m * 2048 + k * 1024); } while (0)
; #define PG8_BAR __builtin_amdgcn_s_barrier()
; template <class Epi, class Sched, bool ALIGN_EPI = false, bool SP2 = false>
; __device__ __forceinline__ void gemm_phase(LAS unsigned char* lds, const Gemm g, const Sched& S, const Epi& E) {
;     ...
;         for (int t = 0; t < nt; t += 2) {
;             const bool last = (t == nt - 2);
;             const char* a1 = cA + (size_t)(t + 1) * kstep;
;             const char* a2 = last ? nA : cA + (size_t)(t + 2) * kstep; const char* b2 = last ? nB : cB + (size_t)(t + 2) * kstep;
;             const char* a3 = a2 + kstep; const char* b3 = b2 + kstep;
;             if (last && has_next) S.a_ready(nxt);
;             if constexpr (SP2) {
;             PG8_LDB(B0, 0, 0); PG8_LDB(B1, 0, 1); PG8_SCHED; PG8_LDA(At, 0, 0); PG8_STAGE(PG8_SA(1, 1), a1 + hstep, voffA);
;             PG8_WAIT_V(8); PG8_WAIT_L(0); PG8_BAR; PG8_MMA(0, 0, At, B0); PG8_MMA(0, 1, At, B1); PG8_BAR; PG8_SCHED;
;             PG8_LDA(At, 0, 1); PG8_STAGE(PG8_SB(0, 0), b2, voffB); PG8_STAGE(PG8_SB(0, 1), b2 + hstepB, voffB); PG8_STAGE(PG8_SA(0, 0), a2, voffA);
;             PG8_WAIT_V(8); PG8_WAIT_L(0); PG8_BAR; PG8_MMA(1, 0, At, B0); PG8_MMA(1, 1, At, B1); PG8_BAR; PG8_SCHED;
;             PG8_LDB(B0, 1, 0); PG8_LDB(B1, 1, 1); PG8_SCHED; PG8_LDA(At, 1, 0); PG8_STAGE(PG8_SA(0, 1), a2 + hstep, voffA);
;             PG8_WAIT_V(8); PG8_WAIT_L(0); PG8_BAR; PG8_MMA(0, 0, At, B0); PG8_MMA(0, 1, At, B1); PG8_BAR; PG8_SCHED;
;             PG8_LDA(At, 1, 1); PG8_STAGE(PG8_SB(1, 0), b3, voffB); PG8_STAGE(PG8_SB(1, 1), b3 + hstepB, voffB); PG8_STAGE(PG8_SA(1, 0), a3, voffA);
;             PG8_WAIT_V(8); PG8_WAIT_L(0); PG8_BAR; PG8_MMA(1, 0, At, B0); PG8_MMA(1, 1, At, B1); PG8_BAR; PG8_SCHED;
;     ...
;         if constexpr (ALIGN_EPI) { if (wr == 0) PG8_BAR; }
;         if constexpr (!Epi::AFTER_DRAIN) { E(acc, cur, wr, wc, fr, fq); S.done(cur); }
;         if (!has_next) break;
	s_add_i32 s51, 0, 0x18000
	s_add_i32 s52, 0, 0x1c000
	v_add_u32_e32 v78, s51, v169
	v_add_u32_e32 v168, s52, v169
	ds_read_b128 v[66:69], v78
	ds_read_b128 v[70:73], v78 offset:1024
	ds_read_b128 v[74:77], v78 offset:2048
	ds_read_b128 v[78:81], v78 offset:3072
	ds_read_b128 v[162:165], v168
	ds_read_b128 v[180:183], v168 offset:1024
	ds_read_b128 v[184:187], v168 offset:2048
	ds_read_b128 v[188:191], v168 offset:3072
	s_add_u32 s40, s40, 0x80000
	s_addc_u32 s41, s41, 0
	s_mov_b32 m0, s31
	ds_read_b128 v[192:195], v175 offset:32768
	ds_read_b128 v[196:199], v175 offset:33792
	ds_read_b128 v[200:203], v175 offset:34816
	ds_read_b128 v[204:207], v175 offset:35840
	ds_read_b128 v[208:211], v175 offset:36864
	ds_read_b128 v[212:215], v175 offset:37888
	ds_read_b128 v[216:219], v175 offset:38912
	ds_read_b128 v[220:223], v175 offset:39936
	global_load_lds_dwordx4 v152, s[40:41]
	s_mov_b32 m0, s33
	s_nop 0
	global_load_lds_dwordx4 v148, s[40:41]
	s_waitcnt vmcnt(8)
	s_waitcnt lgkmcnt(0)
	s_barrier
	s_waitcnt lgkmcnt(0)
	v_mfma_f32_16x16x32_bf16 v[142:145], v[66:69], v[192:195], v[142:145]
	v_mfma_f32_16x16x32_bf16 v[138:141], v[74:77], v[192:195], v[138:141]
	v_mfma_f32_16x16x32_bf16 v[126:129], v[66:69], v[200:203], v[126:129]
	v_mfma_f32_16x16x32_bf16 v[122:125], v[74:77], v[200:203], v[122:125]
	v_mfma_f32_16x16x32_bf16 v[110:113], v[66:69], v[208:211], v[110:113]
	v_mfma_f32_16x16x32_bf16 v[106:109], v[74:77], v[208:211], v[106:109]
	v_mfma_f32_16x16x32_bf16 v[94:97], v[66:69], v[216:219], v[94:97]
	v_mfma_f32_16x16x32_bf16 v[90:93], v[74:77], v[216:219], v[90:93]
	v_mfma_f32_16x16x32_bf16 v[142:145], v[70:73], v[196:199], v[142:145]
	v_mfma_f32_16x16x32_bf16 v[138:141], v[78:81], v[196:199], v[138:141]
	v_mfma_f32_16x16x32_bf16 v[126:129], v[70:73], v[204:207], v[126:129]
	v_mfma_f32_16x16x32_bf16 v[122:125], v[78:81], v[204:207], v[122:125]
	v_mfma_f32_16x16x32_bf16 v[110:113], v[70:73], v[212:215], v[110:113]
	v_mfma_f32_16x16x32_bf16 v[106:109], v[78:81], v[212:215], v[106:109]
	v_mfma_f32_16x16x32_bf16 v[94:97], v[70:73], v[220:223], v[94:97]
	v_mfma_f32_16x16x32_bf16 v[90:93], v[78:81], v[220:223], v[90:93]
	v_mfma_f32_16x16x32_bf16 v[134:137], v[162:165], v[192:195], v[134:137]
	v_mfma_f32_16x16x32_bf16 v[130:133], v[184:187], v[192:195], v[130:133]
	v_mfma_f32_16x16x32_bf16 v[118:121], v[162:165], v[200:203], v[118:121]
	v_mfma_f32_16x16x32_bf16 v[114:117], v[184:187], v[200:203], v[114:117]
	v_mfma_f32_16x16x32_bf16 v[102:105], v[162:165], v[208:211], v[102:105]
	v_mfma_f32_16x16x32_bf16 v[98:101], v[184:187], v[208:211], v[98:101]
	v_mfma_f32_16x16x32_bf16 v[86:89], v[162:165], v[216:219], v[86:89]
	v_mfma_f32_16x16x32_bf16 v[82:85], v[184:187], v[216:219], v[82:85]
	v_mfma_f32_16x16x32_bf16 v[134:137], v[180:183], v[196:199], v[134:137]
	v_mfma_f32_16x16x32_bf16 v[130:133], v[188:191], v[196:199], v[130:133]
	v_mfma_f32_16x16x32_bf16 v[118:121], v[180:183], v[204:207], v[118:121]
	v_mfma_f32_16x16x32_bf16 v[114:117], v[188:191], v[204:207], v[114:117]
	v_mfma_f32_16x16x32_bf16 v[102:105], v[180:183], v[212:215], v[102:105]
	v_mfma_f32_16x16x32_bf16 v[98:101], v[188:191], v[212:215], v[98:101]
	v_mfma_f32_16x16x32_bf16 v[86:89], v[180:183], v[220:223], v[86:89]
	v_mfma_f32_16x16x32_bf16 v[82:85], v[188:191], v[220:223], v[82:85]
	s_barrier
	s_add_i32 s40, s51, s26
	v_lshl_add_u64 v[166:167], v[166:167], 0, s[8:9]
	s_mov_b32 m0, s40
	ds_read_b128 v[192:195], v175 offset:49152
	ds_read_b128 v[196:199], v175 offset:50176
	ds_read_b128 v[200:203], v175 offset:51200
	ds_read_b128 v[204:207], v175 offset:52224
	ds_read_b128 v[208:211], v175 offset:53248
	ds_read_b128 v[212:215], v175 offset:54272
	ds_read_b128 v[216:219], v175 offset:55296
	ds_read_b128 v[220:223], v175 offset:56320
	global_load_lds_dwordx4 v[166:167], off
	s_add_i32 m0, s40, 0x2000
	s_add_u32 s22, s22, 0x80080
	v_lshl_add_u64 v[166:167], v[224:225], 0, s[8:9]
	s_addc_u32 s23, s23, 0
	s_add_i32 s40, s52, s26
	global_load_lds_dwordx4 v[166:167], off
	s_mov_b32 m0, s40
	s_nop 0
	global_load_lds_dwordx4 v150, s[22:23]
	s_add_i32 m0, s40, 0x2000
	s_nop 0
	global_load_lds_dwordx4 v146, s[22:23]
	v_lshl_add_u64 v[166:167], v[226:227], 0, s[8:9]
	s_mov_b32 m0, s42
	s_nop 0
	global_load_lds_dwordx4 v[166:167], off
	v_lshl_add_u64 v[166:167], v[228:229], 0, s[8:9]
	s_mov_b32 m0, s43
	s_nop 0
	global_load_lds_dwordx4 v[166:167], off
	s_waitcnt vmcnt(8)
	s_waitcnt lgkmcnt(0)
	s_barrier
	s_waitcnt lgkmcnt(0)
	v_mfma_f32_16x16x32_bf16 v[62:65], v[66:69], v[192:195], v[62:65]
	v_mfma_f32_16x16x32_bf16 v[58:61], v[74:77], v[192:195], v[58:61]
	v_mfma_f32_16x16x32_bf16 v[46:49], v[66:69], v[200:203], v[46:49]
	v_mfma_f32_16x16x32_bf16 v[42:45], v[74:77], v[200:203], v[42:45]
	v_mfma_f32_16x16x32_bf16 v[30:33], v[66:69], v[208:211], v[30:33]
	v_mfma_f32_16x16x32_bf16 v[26:29], v[74:77], v[208:211], v[26:29]
	v_mfma_f32_16x16x32_bf16 v[14:17], v[66:69], v[216:219], v[14:17]
	v_mfma_f32_16x16x32_bf16 v[10:13], v[74:77], v[216:219], v[10:13]
	v_mfma_f32_16x16x32_bf16 v[62:65], v[70:73], v[196:199], v[62:65]
	v_mfma_f32_16x16x32_bf16 v[58:61], v[78:81], v[196:199], v[58:61]
	v_mfma_f32_16x16x32_bf16 v[46:49], v[70:73], v[204:207], v[46:49]
	v_mfma_f32_16x16x32_bf16 v[42:45], v[78:81], v[204:207], v[42:45]
	v_mfma_f32_16x16x32_bf16 v[30:33], v[70:73], v[212:215], v[30:33]
	v_mfma_f32_16x16x32_bf16 v[26:29], v[78:81], v[212:215], v[26:29]
	v_mfma_f32_16x16x32_bf16 v[14:17], v[70:73], v[220:223], v[14:17]
	v_mfma_f32_16x16x32_bf16 v[10:13], v[78:81], v[220:223], v[10:13]
	v_mfma_f32_16x16x32_bf16 v[54:57], v[162:165], v[192:195], v[54:57]
	v_mfma_f32_16x16x32_bf16 v[50:53], v[184:187], v[192:195], v[50:53]
	v_mfma_f32_16x16x32_bf16 v[38:41], v[162:165], v[200:203], v[38:41]
	v_mfma_f32_16x16x32_bf16 v[34:37], v[184:187], v[200:203], v[34:37]
	v_mfma_f32_16x16x32_bf16 v[22:25], v[162:165], v[208:211], v[22:25]
	v_mfma_f32_16x16x32_bf16 v[18:21], v[184:187], v[208:211], v[18:21]
	v_mfma_f32_16x16x32_bf16 v[6:9], v[162:165], v[216:219], v[6:9]
	v_mfma_f32_16x16x32_bf16 v[2:5], v[184:187], v[216:219], v[2:5]
	v_mfma_f32_16x16x32_bf16 v[54:57], v[180:183], v[196:199], v[54:57]
	v_mfma_f32_16x16x32_bf16 v[50:53], v[188:191], v[196:199], v[50:53]
	v_mfma_f32_16x16x32_bf16 v[38:41], v[180:183], v[204:207], v[38:41]
	v_mfma_f32_16x16x32_bf16 v[34:37], v[188:191], v[204:207], v[34:37]
	v_mfma_f32_16x16x32_bf16 v[22:25], v[180:183], v[212:215], v[22:25]
	v_mfma_f32_16x16x32_bf16 v[18:21], v[188:191], v[212:215], v[18:21]
	v_mfma_f32_16x16x32_bf16 v[6:9], v[180:183], v[220:223], v[6:9]
	v_mfma_f32_16x16x32_bf16 v[2:5], v[188:191], v[220:223], v[2:5]
	s_barrier
	s_add_i32 s50, s50, 2
	s_add_u32 s25, s25, 0x100
	s_addc_u32 s49, s49, 0
	s_add_u32 s16, s16, 0x100
	s_addc_u32 s17, s17, 0
	s_cmp_lt_u32 s50, 30
	s_cbranch_scc1 .LBB0_1822
	s_setprio 0
	s_andn2_b64 vcc, exec, s[10:11]
	s_cbranch_vccnz .LBB0_1825
	s_barrier

; #define PG8_STAGE(bufoff, gbase, voff) do { _Pragma("unroll") for (int _i = 0; _i < 2; ++_i) \
;         __builtin_amdgcn_global_load_lds((const unsigned*)((const char*)(gbase) + (voff)[_i]), (LAS unsigned*)(lds + (bufoff) + ldsw + _i * 8192), 16, 0, 0); } while (0)
; #define PG8_LDA(dst, b, h) do { _Pragma("unroll") for (int m = 0; m < 4; ++m) _Pragma("unroll") for (int k = 0; k < 2; ++k) dst[m][k] = *(const LAS bf16x8*)(lds + PG8_SA(b, h) + aoff + m * 2048 + k * 1024); } while (0)
; #define PG8_LDB(dst, b, h) do { _Pragma("unroll") for (int n = 0; n < 2; ++n) _Pragma("unroll") for (int k = 0; k < 2; ++k) dst[n][k] = *(const LAS bf16x8*)(lds + PG8_SB(b, h) + boff + n * 2048 + k * 1024); } while (0)
; template <class Epi, class Sched, bool ALIGN_EPI = false, bool SP2 = false>
; __device__ __forceinline__ void gemm_phase(LAS unsigned char* lds, const Gemm g, const Sched& S, const Epi& E) {
;     ...
;         for (int t = 0; t < nt; t += 2) {
;             const bool last = (t == nt - 2);
;             const char* a1 = cA + (size_t)(t + 1) * kstep;
;             const char* a2 = last ? nA : cA + (size_t)(t + 2) * kstep; const char* b2 = last ? nB : cB + (size_t)(t + 2) * kstep;
;             const char* a3 = a2 + kstep; const char* b3 = b2 + kstep;
;             if (last && has_next) S.a_ready(nxt);
;             if constexpr (SP2) {
;             PG8_LDB(B0, 0, 0); PG8_LDB(B1, 0, 1); PG8_SCHED; PG8_LDA(At, 0, 0); PG8_STAGE(PG8_SA(1, 1), a1 + hstep, voffA);
;             PG8_WAIT_V(8); PG8_WAIT_L(0); PG8_BAR; PG8_MMA(0, 0, At, B0); PG8_MMA(0, 1, At, B1); PG8_BAR; PG8_SCHED;
;             PG8_LDA(At, 0, 1); PG8_STAGE(PG8_SB(0, 0), b2, voffB); PG8_STAGE(PG8_SB(0, 1), b2 + hstepB, voffB); PG8_STAGE(PG8_SA(0, 0), a2, voffA);
;             PG8_WAIT_V(8); PG8_WAIT_L(0); PG8_BAR; PG8_MMA(1, 0, At, B0); PG8_MMA(1, 1, At, B1); PG8_BAR; PG8_SCHED;
;             PG8_LDB(B0, 1, 0); PG8_LDB(B1, 1, 1); PG8_SCHED; PG8_LDA(At, 1, 0); PG8_STAGE(PG8_SA(0, 1), a2 + hstep, voffA);
;             PG8_WAIT_V(8); PG8_WAIT_L(0); PG8_BAR; PG8_MMA(0, 0, At, B0); PG8_MMA(0, 1, At, B1); PG8_BAR; PG8_SCHED;
;             PG8_LDA(At, 1, 1); PG8_STAGE(PG8_SB(1, 0), b3, voffB); PG8_STAGE(PG8_SB(1, 1), b3 + hstepB, voffB); PG8_STAGE(PG8_SA(1, 0), a3, voffA);
;             PG8_WAIT_V(8); PG8_WAIT_L(0); PG8_BAR; PG8_MMA(1, 0, At, B0); PG8_MMA(1, 1, At, B1); PG8_BAR; PG8_SCHED;
.Lprio_1926:
	ds_read_b128 v[130:133], v196
	ds_read_b128 v[134:137], v196 offset:1024
	ds_read_b128 v[138:141], v196 offset:2048
	ds_read_b128 v[142:145], v196 offset:3072
	ds_read_b128 v[166:169], v197
	ds_read_b128 v[170:173], v197 offset:1024
	ds_read_b128 v[174:177], v197 offset:2048
	ds_read_b128 v[178:181], v197 offset:3072
	s_add_u32 s20, s18, 0x100
	s_addc_u32 s21, s19, 0
	s_cmpk_eq_i32 s25, 0x54
	s_cselect_b32 s47, s17, s21
	s_cselect_b32 s46, s16, s20
	s_cselect_b32 s23, s3, s24
	s_cselect_b32 s22, s2, s5
	v_lshl_add_u64 v[190:191], s[18:19], 0, v[160:161]
	s_add_i32 m0, s27, 0xc000
	ds_read_b128 v[182:185], v198
	ds_read_b128 v[186:189], v198 offset:1024
	ds_read_b128 v[202:205], v198 offset:2048
	ds_read_b128 v[206:209], v198 offset:3072
	ds_read_b128 v[210:213], v198 offset:4096
	ds_read_b128 v[214:217], v198 offset:5120
	ds_read_b128 v[218:221], v198 offset:6144
	ds_read_b128 v[222:225], v198 offset:7168
	global_load_lds_dwordx4 v[190:191], off
	v_lshl_add_u64 v[190:191], s[18:19], 0, v[158:159]
	s_add_i32 m0, s27, 0xe000
	s_nop 0
	global_load_lds_dwordx4 v[190:191], off
	s_waitcnt lgkmcnt(0)
	s_barrier
	s_waitcnt lgkmcnt(0)
	v_mfma_f32_16x16x32_bf16 v[126:129], v[130:133], v[182:185], 0
	v_mfma_f32_16x16x32_bf16 v[122:125], v[138:141], v[182:185], 0
	v_mfma_f32_16x16x32_bf16 v[110:113], v[130:133], v[202:205], 0
	v_mfma_f32_16x16x32_bf16 v[106:109], v[138:141], v[202:205], 0
	v_mfma_f32_16x16x32_bf16 v[94:97], v[130:133], v[210:213], 0
	v_mfma_f32_16x16x32_bf16 v[90:93], v[138:141], v[210:213], 0
	v_mfma_f32_16x16x32_bf16 v[78:81], v[130:133], v[218:221], 0
	v_mfma_f32_16x16x32_bf16 v[74:77], v[138:141], v[218:221], 0
	v_mfma_f32_16x16x32_bf16 v[126:129], v[134:137], v[186:189], v[126:129]
	v_mfma_f32_16x16x32_bf16 v[122:125], v[142:145], v[186:189], v[122:125]
	v_mfma_f32_16x16x32_bf16 v[110:113], v[134:137], v[206:209], v[110:113]
	v_mfma_f32_16x16x32_bf16 v[106:109], v[142:145], v[206:209], v[106:109]
	v_mfma_f32_16x16x32_bf16 v[94:97], v[134:137], v[214:217], v[94:97]
	v_mfma_f32_16x16x32_bf16 v[90:93], v[142:145], v[214:217], v[90:93]
	v_mfma_f32_16x16x32_bf16 v[78:81], v[134:137], v[222:225], v[78:81]
	v_mfma_f32_16x16x32_bf16 v[74:77], v[142:145], v[222:225], v[74:77]
	v_mfma_f32_16x16x32_bf16 v[118:121], v[166:169], v[182:185], 0
	v_mfma_f32_16x16x32_bf16 v[114:117], v[174:177], v[182:185], 0
	v_mfma_f32_16x16x32_bf16 v[102:105], v[166:169], v[202:205], 0
	v_mfma_f32_16x16x32_bf16 v[98:101], v[174:177], v[202:205], 0
	v_mfma_f32_16x16x32_bf16 v[86:89], v[166:169], v[210:213], 0
	v_mfma_f32_16x16x32_bf16 v[82:85], v[174:177], v[210:213], 0
	v_mfma_f32_16x16x32_bf16 v[70:73], v[166:169], v[218:221], 0
	v_mfma_f32_16x16x32_bf16 v[66:69], v[174:177], v[218:221], 0
	v_mfma_f32_16x16x32_bf16 v[118:121], v[170:173], v[186:189], v[118:121]
	v_mfma_f32_16x16x32_bf16 v[114:117], v[178:181], v[186:189], v[114:117]
	v_mfma_f32_16x16x32_bf16 v[102:105], v[170:173], v[206:209], v[102:105]
	v_mfma_f32_16x16x32_bf16 v[98:101], v[178:181], v[206:209], v[98:101]
	v_mfma_f32_16x16x32_bf16 v[86:89], v[170:173], v[214:217], v[86:89]
	v_mfma_f32_16x16x32_bf16 v[82:85], v[178:181], v[214:217], v[82:85]
	v_mfma_f32_16x16x32_bf16 v[70:73], v[170:173], v[222:225], v[70:73]
	v_mfma_f32_16x16x32_bf16 v[66:69], v[178:181], v[222:225], v[66:69]
	s_barrier
	s_add_i32 s18, s50, s26
	v_lshl_add_u64 v[190:191], s[22:23], 0, v[148:149]
	s_mov_b32 m0, s18
	ds_read_b128 v[182:185], v198 offset:16384
	ds_read_b128 v[186:189], v198 offset:17408
	ds_read_b128 v[202:205], v198 offset:18432
	ds_read_b128 v[206:209], v198 offset:19456
	ds_read_b128 v[210:213], v198 offset:20480
	ds_read_b128 v[214:217], v198 offset:21504
	ds_read_b128 v[218:221], v198 offset:22528
	ds_read_b128 v[222:225], v198 offset:23552
	global_load_lds_dwordx4 v[190:191], off
	s_add_i32 m0, s18, 0x2000
	s_add_u32 s18, s22, 0x58000
	v_lshl_add_u64 v[226:227], s[22:23], 0, v[152:153]
	s_addc_u32 s19, s23, 0
	s_add_i32 s54, s51, s26
	global_load_lds_dwordx4 v[226:227], off
	s_mov_b32 m0, s54
	v_lshl_add_u64 v[230:231], s[46:47], 0, v[150:151]
	global_load_lds_dwordx4 v148, s[18:19]
	s_add_i32 m0, s54, 0x2000
	s_nop 0
	global_load_lds_dwordx4 v152, s[18:19]
	v_lshl_add_u64 v[228:229], s[46:47], 0, v[146:147]
	s_mov_b32 m0, s27
	s_nop 0
	global_load_lds_dwordx4 v[228:229], off
	s_mov_b32 m0, s28
	s_nop 0
	global_load_lds_dwordx4 v[230:231], off
	s_waitcnt lgkmcnt(0)
	s_barrier
	s_waitcnt lgkmcnt(0)
	v_mfma_f32_16x16x32_bf16 v[62:65], v[130:133], v[182:185], 0
	v_mfma_f32_16x16x32_bf16 v[58:61], v[138:141], v[182:185], 0
	v_mfma_f32_16x16x32_bf16 v[46:49], v[130:133], v[202:205], 0
	v_mfma_f32_16x16x32_bf16 v[42:45], v[138:141], v[202:205], 0
	v_mfma_f32_16x16x32_bf16 v[30:33], v[130:133], v[210:213], 0
	v_mfma_f32_16x16x32_bf16 v[26:29], v[138:141], v[210:213], 0
	v_mfma_f32_16x16x32_bf16 v[14:17], v[130:133], v[218:221], 0
	v_mfma_f32_16x16x32_bf16 v[10:13], v[138:141], v[218:221], 0
	v_mfma_f32_16x16x32_bf16 v[62:65], v[134:137], v[186:189], v[62:65]
	v_mfma_f32_16x16x32_bf16 v[58:61], v[142:145], v[186:189], v[58:61]
	v_mfma_f32_16x16x32_bf16 v[46:49], v[134:137], v[206:209], v[46:49]
	v_mfma_f32_16x16x32_bf16 v[42:45], v[142:145], v[206:209], v[42:45]
	v_mfma_f32_16x16x32_bf16 v[30:33], v[134:137], v[214:217], v[30:33]
	v_mfma_f32_16x16x32_bf16 v[26:29], v[142:145], v[214:217], v[26:29]
	v_mfma_f32_16x16x32_bf16 v[14:17], v[134:137], v[222:225], v[14:17]
	v_mfma_f32_16x16x32_bf16 v[10:13], v[142:145], v[222:225], v[10:13]
	v_mfma_f32_16x16x32_bf16 v[54:57], v[166:169], v[182:185], 0
	v_mfma_f32_16x16x32_bf16 v[50:53], v[174:177], v[182:185], 0
	v_mfma_f32_16x16x32_bf16 v[38:41], v[166:169], v[202:205], 0
	v_mfma_f32_16x16x32_bf16 v[34:37], v[174:177], v[202:205], 0
	v_mfma_f32_16x16x32_bf16 v[22:25], v[166:169], v[210:213], 0
	v_mfma_f32_16x16x32_bf16 v[18:21], v[174:177], v[210:213], 0
	v_mfma_f32_16x16x32_bf16 v[6:9], v[166:169], v[218:221], 0
	v_mfma_f32_16x16x32_bf16 v[2:5], v[174:177], v[218:221], 0
	v_mfma_f32_16x16x32_bf16 v[54:57], v[170:173], v[186:189], v[54:57]
	v_mfma_f32_16x16x32_bf16 v[50:53], v[178:181], v[186:189], v[50:53]
	v_mfma_f32_16x16x32_bf16 v[38:41], v[170:173], v[206:209], v[38:41]
	v_mfma_f32_16x16x32_bf16 v[34:37], v[178:181], v[206:209], v[34:37]
	v_mfma_f32_16x16x32_bf16 v[22:25], v[170:173], v[214:217], v[22:25]
	v_mfma_f32_16x16x32_bf16 v[18:21], v[178:181], v[214:217], v[18:21]
	v_mfma_f32_16x16x32_bf16 v[6:9], v[170:173], v[222:225], v[6:9]
	v_mfma_f32_16x16x32_bf16 v[2:5], v[178:181], v[222:225], v[2:5]
	s_barrier
; #define PG8_STAGE(bufoff, gbase, voff) do { _Pragma("unroll") for (int _i = 0; _i < 2; ++_i) \
;         __builtin_amdgcn_global_load_lds((const unsigned*)((const char*)(gbase) + (voff)[_i]), (LAS unsigned*)(lds + (bufoff) + ldsw + _i * 8192), 16, 0, 0); } while (0)
; #define PG8_LDA(dst, b, h) do { _Pragma("unroll") for (int m = 0; m < 4; ++m) _Pragma("unroll") for (int k = 0; k < 2; ++k) dst[m][k] = *(const LAS bf16x8*)(lds + PG8_SA(b, h) + aoff + m * 2048 + k * 1024); } while (0)
; #define PG8_LDB(dst, b, h) do { _Pragma("unroll") for (int n = 0; n < 2; ++n) _Pragma("unroll") for (int k = 0; k < 2; ++k) dst[n][k] = *(const LAS bf16x8*)(lds + PG8_SB(b, h) + boff + n * 2048 + k * 1024); } while (0)
; template <class Epi, class Sched, bool ALIGN_EPI = false, bool SP2 = false>
; __device__ __forceinline__ void gemm_phase(LAS unsigned char* lds, const Gemm g, const Sched& S, const Epi& E) {
;     ...
;         for (int t = 0; t < nt; t += 2) {
;             const bool last = (t == nt - 2);
;             const char* a1 = cA + (size_t)(t + 1) * kstep;
;             const char* a2 = last ? nA : cA + (size_t)(t + 2) * kstep; const char* b2 = last ? nB : cB + (size_t)(t + 2) * kstep;
;             const char* a3 = a2 + kstep; const char* b3 = b2 + kstep;
;             if (last && has_next) S.a_ready(nxt);
;             if constexpr (SP2) {
;             PG8_LDB(B0, 0, 0); PG8_LDB(B1, 0, 1); PG8_SCHED; PG8_LDA(At, 0, 0); PG8_STAGE(PG8_SA(1, 1), a1 + hstep, voffA);
;             PG8_WAIT_V(8); PG8_WAIT_L(0); PG8_BAR; PG8_MMA(0, 0, At, B0); PG8_MMA(0, 1, At, B1); PG8_BAR; PG8_SCHED;
;             PG8_LDA(At, 0, 1); PG8_STAGE(PG8_SB(0, 0), b2, voffB); PG8_STAGE(PG8_SB(0, 1), b2 + hstepB, voffB); PG8_STAGE(PG8_SA(0, 0), a2, voffA);
;             PG8_WAIT_V(8); PG8_WAIT_L(0); PG8_BAR; PG8_MMA(1, 0, At, B0); PG8_MMA(1, 1, At, B1); PG8_BAR; PG8_SCHED;
;             PG8_LDB(B0, 1, 0); PG8_LDB(B1, 1, 1); PG8_SCHED; PG8_LDA(At, 1, 0); PG8_STAGE(PG8_SA(0, 1), a2 + hstep, voffA);
;             PG8_WAIT_V(8); PG8_WAIT_L(0); PG8_BAR; PG8_MMA(0, 0, At, B0); PG8_MMA(0, 1, At, B1); PG8_BAR; PG8_SCHED;
;             PG8_LDA(At, 1, 1); PG8_STAGE(PG8_SB(1, 0), b3, voffB); PG8_STAGE(PG8_SB(1, 1), b3 + hstepB, voffB); PG8_STAGE(PG8_SA(1, 0), a3, voffA);
;             PG8_WAIT_V(8); PG8_WAIT_L(0); PG8_BAR; PG8_MMA(1, 0, At, B0); PG8_MMA(1, 1, At, B1); PG8_BAR; PG8_SCHED;
	s_add_i32 s54, 0, 0x18000
	s_add_i32 s55, 0, 0x1c000
	v_add_u32_e32 v142, s54, v1
	v_add_u32_e32 v154, s55, v1
	ds_read_b128 v[130:133], v142
	ds_read_b128 v[134:137], v142 offset:1024
	ds_read_b128 v[138:141], v142 offset:2048
	ds_read_b128 v[142:145], v142 offset:3072
	ds_read_b128 v[166:169], v154
	ds_read_b128 v[170:173], v154 offset:1024
	ds_read_b128 v[174:177], v154 offset:2048
	ds_read_b128 v[178:181], v154 offset:3072
	s_add_u32 s18, s46, 0x160000
	s_addc_u32 s19, s47, 0
	s_mov_b32 m0, s29
	ds_read_b128 v[182:185], v198 offset:32768
	ds_read_b128 v[186:189], v198 offset:33792
	ds_read_b128 v[202:205], v198 offset:34816
	ds_read_b128 v[206:209], v198 offset:35840
	ds_read_b128 v[210:213], v198 offset:36864
	ds_read_b128 v[214:217], v198 offset:37888
	ds_read_b128 v[218:221], v198 offset:38912
	ds_read_b128 v[222:225], v198 offset:39936
	global_load_lds_dwordx4 v146, s[18:19]
	s_mov_b32 m0, s30
	s_nop 0
	global_load_lds_dwordx4 v150, s[18:19]
	s_waitcnt vmcnt(8)
	s_waitcnt lgkmcnt(0)
	s_barrier
	s_waitcnt lgkmcnt(0)
	v_mfma_f32_16x16x32_bf16 v[126:129], v[130:133], v[182:185], v[126:129]
	v_mfma_f32_16x16x32_bf16 v[122:125], v[138:141], v[182:185], v[122:125]
	v_mfma_f32_16x16x32_bf16 v[110:113], v[130:133], v[202:205], v[110:113]
	v_mfma_f32_16x16x32_bf16 v[106:109], v[138:141], v[202:205], v[106:109]
	v_mfma_f32_16x16x32_bf16 v[94:97], v[130:133], v[210:213], v[94:97]
	v_mfma_f32_16x16x32_bf16 v[90:93], v[138:141], v[210:213], v[90:93]
	v_mfma_f32_16x16x32_bf16 v[78:81], v[130:133], v[218:221], v[78:81]
	v_mfma_f32_16x16x32_bf16 v[74:77], v[138:141], v[218:221], v[74:77]
	v_mfma_f32_16x16x32_bf16 v[126:129], v[134:137], v[186:189], v[126:129]
	v_mfma_f32_16x16x32_bf16 v[122:125], v[142:145], v[186:189], v[122:125]
	v_mfma_f32_16x16x32_bf16 v[110:113], v[134:137], v[206:209], v[110:113]
	v_mfma_f32_16x16x32_bf16 v[106:109], v[142:145], v[206:209], v[106:109]
	v_mfma_f32_16x16x32_bf16 v[94:97], v[134:137], v[214:217], v[94:97]
	v_mfma_f32_16x16x32_bf16 v[90:93], v[142:145], v[214:217], v[90:93]
	v_mfma_f32_16x16x32_bf16 v[78:81], v[134:137], v[222:225], v[78:81]
	v_mfma_f32_16x16x32_bf16 v[74:77], v[142:145], v[222:225], v[74:77]
	v_mfma_f32_16x16x32_bf16 v[118:121], v[166:169], v[182:185], v[118:121]
	v_mfma_f32_16x16x32_bf16 v[114:117], v[174:177], v[182:185], v[114:117]
	v_mfma_f32_16x16x32_bf16 v[102:105], v[166:169], v[202:205], v[102:105]
	v_mfma_f32_16x16x32_bf16 v[98:101], v[174:177], v[202:205], v[98:101]
	v_mfma_f32_16x16x32_bf16 v[86:89], v[166:169], v[210:213], v[86:89]
	v_mfma_f32_16x16x32_bf16 v[82:85], v[174:177], v[210:213], v[82:85]
	v_mfma_f32_16x16x32_bf16 v[70:73], v[166:169], v[218:221], v[70:73]
	v_mfma_f32_16x16x32_bf16 v[66:69], v[174:177], v[218:221], v[66:69]
	v_mfma_f32_16x16x32_bf16 v[118:121], v[170:173], v[186:189], v[118:121]
	v_mfma_f32_16x16x32_bf16 v[114:117], v[178:181], v[186:189], v[114:117]
	v_mfma_f32_16x16x32_bf16 v[102:105], v[170:173], v[206:209], v[102:105]
	v_mfma_f32_16x16x32_bf16 v[98:101], v[178:181], v[206:209], v[98:101]
	v_mfma_f32_16x16x32_bf16 v[86:89], v[170:173], v[214:217], v[86:89]
	v_mfma_f32_16x16x32_bf16 v[82:85], v[178:181], v[214:217], v[82:85]
	v_mfma_f32_16x16x32_bf16 v[70:73], v[170:173], v[222:225], v[70:73]
	v_mfma_f32_16x16x32_bf16 v[66:69], v[178:181], v[222:225], v[66:69]
	s_barrier
	s_add_i32 s18, s54, s26
	v_lshl_add_u64 v[190:191], v[190:191], 0, s[12:13]
	s_mov_b32 m0, s18
	ds_read_b128 v[182:185], v198 offset:49152
	ds_read_b128 v[186:189], v198 offset:50176
	ds_read_b128 v[202:205], v198 offset:51200
	ds_read_b128 v[206:209], v198 offset:52224
	ds_read_b128 v[210:213], v198 offset:53248
	ds_read_b128 v[214:217], v198 offset:54272
	ds_read_b128 v[218:221], v198 offset:55296
	ds_read_b128 v[222:225], v198 offset:56320
	global_load_lds_dwordx4 v[190:191], off
	s_add_i32 m0, s18, 0x2000
	s_add_u32 s18, s22, 0x58080
	v_lshl_add_u64 v[190:191], v[226:227], 0, s[12:13]
	s_addc_u32 s19, s23, 0
	s_add_i32 s22, s55, s26
	global_load_lds_dwordx4 v[190:191], off
	s_mov_b32 m0, s22
	s_nop 0
	global_load_lds_dwordx4 v148, s[18:19]
	s_add_i32 m0, s22, 0x2000
	s_nop 0
	global_load_lds_dwordx4 v152, s[18:19]
	v_lshl_add_u64 v[190:191], v[228:229], 0, s[12:13]
	s_mov_b32 m0, s37
	s_nop 0
	global_load_lds_dwordx4 v[190:191], off
	v_lshl_add_u64 v[190:191], v[230:231], 0, s[12:13]
	s_mov_b32 m0, s48
	s_nop 0
	global_load_lds_dwordx4 v[190:191], off
	s_waitcnt vmcnt(8)
	s_waitcnt lgkmcnt(0)
	s_barrier
	s_waitcnt lgkmcnt(0)
	v_mfma_f32_16x16x32_bf16 v[62:65], v[130:133], v[182:185], v[62:65]
	v_mfma_f32_16x16x32_bf16 v[58:61], v[138:141], v[182:185], v[58:61]
	v_mfma_f32_16x16x32_bf16 v[46:49], v[130:133], v[202:205], v[46:49]
	v_mfma_f32_16x16x32_bf16 v[42:45], v[138:141], v[202:205], v[42:45]
	v_mfma_f32_16x16x32_bf16 v[30:33], v[130:133], v[210:213], v[30:33]
	v_mfma_f32_16x16x32_bf16 v[26:29], v[138:141], v[210:213], v[26:29]
	v_mfma_f32_16x16x32_bf16 v[14:17], v[130:133], v[218:221], v[14:17]
	v_mfma_f32_16x16x32_bf16 v[10:13], v[138:141], v[218:221], v[10:13]
	v_mfma_f32_16x16x32_bf16 v[62:65], v[134:137], v[186:189], v[62:65]
	v_mfma_f32_16x16x32_bf16 v[58:61], v[142:145], v[186:189], v[58:61]
	v_mfma_f32_16x16x32_bf16 v[46:49], v[134:137], v[206:209], v[46:49]
	v_mfma_f32_16x16x32_bf16 v[42:45], v[142:145], v[206:209], v[42:45]
	v_mfma_f32_16x16x32_bf16 v[30:33], v[134:137], v[214:217], v[30:33]
	v_mfma_f32_16x16x32_bf16 v[26:29], v[142:145], v[214:217], v[26:29]
	v_mfma_f32_16x16x32_bf16 v[14:17], v[134:137], v[222:225], v[14:17]
	v_mfma_f32_16x16x32_bf16 v[10:13], v[142:145], v[222:225], v[10:13]
	v_mfma_f32_16x16x32_bf16 v[54:57], v[166:169], v[182:185], v[54:57]
	v_mfma_f32_16x16x32_bf16 v[50:53], v[174:177], v[182:185], v[50:53]
	v_mfma_f32_16x16x32_bf16 v[38:41], v[166:169], v[202:205], v[38:41]
	v_mfma_f32_16x16x32_bf16 v[34:37], v[174:177], v[202:205], v[34:37]
	v_mfma_f32_16x16x32_bf16 v[22:25], v[166:169], v[210:213], v[22:25]
	v_mfma_f32_16x16x32_bf16 v[18:21], v[174:177], v[210:213], v[18:21]
	v_mfma_f32_16x16x32_bf16 v[6:9], v[166:169], v[218:221], v[6:9]
	v_mfma_f32_16x16x32_bf16 v[2:5], v[174:177], v[218:221], v[2:5]
	v_mfma_f32_16x16x32_bf16 v[54:57], v[170:173], v[186:189], v[54:57]
	v_mfma_f32_16x16x32_bf16 v[50:53], v[178:181], v[186:189], v[50:53]
	v_mfma_f32_16x16x32_bf16 v[38:41], v[170:173], v[206:209], v[38:41]
	v_mfma_f32_16x16x32_bf16 v[34:37], v[178:181], v[206:209], v[34:37]
	v_mfma_f32_16x16x32_bf16 v[22:25], v[170:173], v[214:217], v[22:25]
	v_mfma_f32_16x16x32_bf16 v[18:21], v[178:181], v[214:217], v[18:21]
	v_mfma_f32_16x16x32_bf16 v[6:9], v[170:173], v[222:225], v[6:9]
	v_mfma_f32_16x16x32_bf16 v[2:5], v[178:181], v[222:225], v[2:5]
	s_barrier
	s_add_i32 s25, s25, 2
	s_add_u32 s5, s5, 0x100
	s_addc_u32 s24, s24, 0
	s_cmpk_lt_u32 s25, 0x56
	s_mov_b64 s[18:19], s[20:21]
; #define PG8_STAGE(bufoff, gbase, voff) do { _Pragma("unroll") for (int _i = 0; _i < 2; ++_i) \
;         __builtin_amdgcn_global_load_lds((const unsigned*)((const char*)(gbase) + (voff)[_i]), (LAS unsigned*)(lds + (bufoff) + ldsw + _i * 8192), 16, 0, 0); } while (0)
; #define PG8_LDA(dst, b, h) do { _Pragma("unroll") for (int m = 0; m < 4; ++m) _Pragma("unroll") for (int k = 0; k < 2; ++k) dst[m][k] = *(const LAS bf16x8*)(lds + PG8_SA(b, h) + aoff + m * 2048 + k * 1024); } while (0)
; #define PG8_LDB(dst, b, h) do { _Pragma("unroll") for (int n = 0; n < 2; ++n) _Pragma("unroll") for (int k = 0; k < 2; ++k) dst[n][k] = *(const LAS bf16x8*)(lds + PG8_SB(b, h) + boff + n * 2048 + k * 1024); } while (0)
; template <class Epi, class Sched, bool ALIGN_EPI = false, bool SP2 = false>
; __device__ __forceinline__ void gemm_phase(LAS unsigned char* lds, const Gemm g, const Sched& S, const Epi& E) {
;     ...
;         for (int t = 0; t < nt; t += 2) {
;             const bool last = (t == nt - 2);
;             const char* a1 = cA + (size_t)(t + 1) * kstep;
;             const char* a2 = last ? nA : cA + (size_t)(t + 2) * kstep; const char* b2 = last ? nB : cB + (size_t)(t + 2) * kstep;
;             const char* a3 = a2 + kstep; const char* b3 = b2 + kstep;
;             if (last && has_next) S.a_ready(nxt);
;             if constexpr (SP2) {
;             PG8_LDB(B0, 0, 0); PG8_LDB(B1, 0, 1); PG8_SCHED; PG8_LDA(At, 0, 0); PG8_STAGE(PG8_SA(1, 1), a1 + hstep, voffA);
;             PG8_WAIT_V(8); PG8_WAIT_L(0); PG8_BAR; PG8_MMA(0, 0, At, B0); PG8_MMA(0, 1, At, B1); PG8_BAR; PG8_SCHED;
;             PG8_LDA(At, 0, 1); PG8_STAGE(PG8_SB(0, 0), b2, voffB); PG8_STAGE(PG8_SB(0, 1), b2 + hstepB, voffB); PG8_STAGE(PG8_SA(0, 0), a2, voffA);
;             PG8_WAIT_V(8); PG8_WAIT_L(0); PG8_BAR; PG8_MMA(1, 0, At, B0); PG8_MMA(1, 1, At, B1); PG8_BAR; PG8_SCHED;
;             PG8_LDB(B0, 1, 0); PG8_LDB(B1, 1, 1); PG8_SCHED; PG8_LDA(At, 1, 0); PG8_STAGE(PG8_SA(0, 1), a2 + hstep, voffA);
;             PG8_WAIT_V(8); PG8_WAIT_L(0); PG8_BAR; PG8_MMA(0, 0, At, B0); PG8_MMA(0, 1, At, B1); PG8_BAR; PG8_SCHED;
;             PG8_LDA(At, 1, 1); PG8_STAGE(PG8_SB(1, 0), b3, voffB); PG8_STAGE(PG8_SB(1, 1), b3 + hstepB, voffB); PG8_STAGE(PG8_SA(1, 0), a3, voffA);
;             PG8_WAIT_V(8); PG8_WAIT_L(0); PG8_BAR; PG8_MMA(1, 0, At, B0); PG8_MMA(1, 1, At, B1); PG8_BAR; PG8_SCHED;
.LBB0_1926:
	ds_read_b128 v[130:133], v196
	ds_read_b128 v[134:137], v196 offset:1024
	ds_read_b128 v[138:141], v196 offset:2048
	ds_read_b128 v[142:145], v196 offset:3072
	ds_read_b128 v[166:169], v197
	ds_read_b128 v[170:173], v197 offset:1024
	ds_read_b128 v[174:177], v197 offset:2048
	ds_read_b128 v[178:181], v197 offset:3072
	s_add_u32 s20, s18, 0x100
	s_addc_u32 s21, s19, 0
	s_cmpk_eq_i32 s25, 0x54
	s_cselect_b32 s47, s17, s21
	s_cselect_b32 s46, s16, s20
	s_cselect_b32 s23, s3, s24
	s_cselect_b32 s22, s2, s5
	v_lshl_add_u64 v[190:191], s[18:19], 0, v[160:161]
	s_add_i32 m0, s27, 0xc000
	ds_read_b128 v[182:185], v198
	ds_read_b128 v[186:189], v198 offset:1024
	ds_read_b128 v[202:205], v198 offset:2048
	ds_read_b128 v[206:209], v198 offset:3072
	ds_read_b128 v[210:213], v198 offset:4096
	ds_read_b128 v[214:217], v198 offset:5120
	ds_read_b128 v[218:221], v198 offset:6144
	ds_read_b128 v[222:225], v198 offset:7168
	global_load_lds_dwordx4 v[190:191], off
	v_lshl_add_u64 v[190:191], s[18:19], 0, v[158:159]
	s_add_i32 m0, s27, 0xe000
	s_nop 0
	global_load_lds_dwordx4 v[190:191], off
	s_waitcnt vmcnt(8)
	s_waitcnt lgkmcnt(0)
	s_barrier
	s_waitcnt lgkmcnt(0)
	v_mfma_f32_16x16x32_bf16 v[126:129], v[130:133], v[182:185], v[126:129]
	v_mfma_f32_16x16x32_bf16 v[122:125], v[138:141], v[182:185], v[122:125]
	v_mfma_f32_16x16x32_bf16 v[110:113], v[130:133], v[202:205], v[110:113]
	v_mfma_f32_16x16x32_bf16 v[106:109], v[138:141], v[202:205], v[106:109]
	v_mfma_f32_16x16x32_bf16 v[94:97], v[130:133], v[210:213], v[94:97]
	v_mfma_f32_16x16x32_bf16 v[90:93], v[138:141], v[210:213], v[90:93]
	v_mfma_f32_16x16x32_bf16 v[78:81], v[130:133], v[218:221], v[78:81]
	v_mfma_f32_16x16x32_bf16 v[74:77], v[138:141], v[218:221], v[74:77]
	v_mfma_f32_16x16x32_bf16 v[126:129], v[134:137], v[186:189], v[126:129]
	v_mfma_f32_16x16x32_bf16 v[122:125], v[142:145], v[186:189], v[122:125]
	v_mfma_f32_16x16x32_bf16 v[110:113], v[134:137], v[206:209], v[110:113]
	v_mfma_f32_16x16x32_bf16 v[106:109], v[142:145], v[206:209], v[106:109]
	v_mfma_f32_16x16x32_bf16 v[94:97], v[134:137], v[214:217], v[94:97]
	v_mfma_f32_16x16x32_bf16 v[90:93], v[142:145], v[214:217], v[90:93]
	v_mfma_f32_16x16x32_bf16 v[78:81], v[134:137], v[222:225], v[78:81]
	v_mfma_f32_16x16x32_bf16 v[74:77], v[142:145], v[222:225], v[74:77]
	v_mfma_f32_16x16x32_bf16 v[118:121], v[166:169], v[182:185], v[118:121]
	v_mfma_f32_16x16x32_bf16 v[114:117], v[174:177], v[182:185], v[114:117]
	v_mfma_f32_16x16x32_bf16 v[102:105], v[166:169], v[202:205], v[102:105]
	v_mfma_f32_16x16x32_bf16 v[98:101], v[174:177], v[202:205], v[98:101]
	v_mfma_f32_16x16x32_bf16 v[86:89], v[166:169], v[210:213], v[86:89]
	v_mfma_f32_16x16x32_bf16 v[82:85], v[174:177], v[210:213], v[82:85]
	v_mfma_f32_16x16x32_bf16 v[70:73], v[166:169], v[218:221], v[70:73]
	v_mfma_f32_16x16x32_bf16 v[66:69], v[174:177], v[218:221], v[66:69]
	v_mfma_f32_16x16x32_bf16 v[118:121], v[170:173], v[186:189], v[118:121]
	v_mfma_f32_16x16x32_bf16 v[114:117], v[178:181], v[186:189], v[114:117]
	v_mfma_f32_16x16x32_bf16 v[102:105], v[170:173], v[206:209], v[102:105]
	v_mfma_f32_16x16x32_bf16 v[98:101], v[178:181], v[206:209], v[98:101]
	v_mfma_f32_16x16x32_bf16 v[86:89], v[170:173], v[214:217], v[86:89]
	v_mfma_f32_16x16x32_bf16 v[82:85], v[178:181], v[214:217], v[82:85]
	v_mfma_f32_16x16x32_bf16 v[70:73], v[170:173], v[222:225], v[70:73]
	v_mfma_f32_16x16x32_bf16 v[66:69], v[178:181], v[222:225], v[66:69]
	s_barrier
	s_add_i32 s18, s50, s26
	v_lshl_add_u64 v[190:191], s[22:23], 0, v[148:149]
	s_mov_b32 m0, s18
	ds_read_b128 v[182:185], v198 offset:16384
	ds_read_b128 v[186:189], v198 offset:17408
	ds_read_b128 v[202:205], v198 offset:18432
	ds_read_b128 v[206:209], v198 offset:19456
	ds_read_b128 v[210:213], v198 offset:20480
	ds_read_b128 v[214:217], v198 offset:21504
	ds_read_b128 v[218:221], v198 offset:22528
	ds_read_b128 v[222:225], v198 offset:23552
	global_load_lds_dwordx4 v[190:191], off
	s_add_i32 m0, s18, 0x2000
	s_add_u32 s18, s22, 0x58000
	v_lshl_add_u64 v[226:227], s[22:23], 0, v[152:153]
	s_addc_u32 s19, s23, 0
	s_add_i32 s54, s51, s26
	global_load_lds_dwordx4 v[226:227], off
	s_mov_b32 m0, s54
	v_lshl_add_u64 v[230:231], s[46:47], 0, v[150:151]
	global_load_lds_dwordx4 v148, s[18:19]
	s_add_i32 m0, s54, 0x2000
	s_nop 0
	global_load_lds_dwordx4 v152, s[18:19]
	v_lshl_add_u64 v[228:229], s[46:47], 0, v[146:147]
	s_mov_b32 m0, s27
	s_nop 0
	global_load_lds_dwordx4 v[228:229], off
	s_mov_b32 m0, s28
	s_nop 0
	global_load_lds_dwordx4 v[230:231], off
	s_waitcnt vmcnt(8)
	s_waitcnt lgkmcnt(0)
	s_barrier
; #define PG8_STAGE(bufoff, gbase, voff) do { _Pragma("unroll") for (int _i = 0; _i < 2; ++_i) \
;         __builtin_amdgcn_global_load_lds((const unsigned*)((const char*)(gbase) + (voff)[_i]), (LAS unsigned*)(lds + (bufoff) + ldsw + _i * 8192), 16, 0, 0); } while (0)
; #define PG8_LDA(dst, b, h) do { _Pragma("unroll") for (int m = 0; m < 4; ++m) _Pragma("unroll") for (int k = 0; k < 2; ++k) dst[m][k] = *(const LAS bf16x8*)(lds + PG8_SA(b, h) + aoff + m * 2048 + k * 1024); } while (0)
; #define PG8_LDB(dst, b, h) do { _Pragma("unroll") for (int n = 0; n < 2; ++n) _Pragma("unroll") for (int k = 0; k < 2; ++k) dst[n][k] = *(const LAS bf16x8*)(lds + PG8_SB(b, h) + boff + n * 2048 + k * 1024); } while (0)
; template <class Epi, class Sched, bool ALIGN_EPI = false, bool SP2 = false>
; __device__ __forceinline__ void gemm_phase(LAS unsigned char* lds, const Gemm g, const Sched& S, const Epi& E) {
;     ...
;         for (int t = 0; t < nt; t += 2) {
;             const bool last = (t == nt - 2);
;             const char* a1 = cA + (size_t)(t + 1) * kstep;
;             const char* a2 = last ? nA : cA + (size_t)(t + 2) * kstep; const char* b2 = last ? nB : cB + (size_t)(t + 2) * kstep;
;             const char* a3 = a2 + kstep; const char* b3 = b2 + kstep;
;             if (last && has_next) S.a_ready(nxt);
;             if constexpr (SP2) {
;             PG8_LDB(B0, 0, 0); PG8_LDB(B1, 0, 1); PG8_SCHED; PG8_LDA(At, 0, 0); PG8_STAGE(PG8_SA(1, 1), a1 + hstep, voffA);
;             PG8_WAIT_V(8); PG8_WAIT_L(0); PG8_BAR; PG8_MMA(0, 0, At, B0); PG8_MMA(0, 1, At, B1); PG8_BAR; PG8_SCHED;
;             PG8_LDA(At, 0, 1); PG8_STAGE(PG8_SB(0, 0), b2, voffB); PG8_STAGE(PG8_SB(0, 1), b2 + hstepB, voffB); PG8_STAGE(PG8_SA(0, 0), a2, voffA);
;             PG8_WAIT_V(8); PG8_WAIT_L(0); PG8_BAR; PG8_MMA(1, 0, At, B0); PG8_MMA(1, 1, At, B1); PG8_BAR; PG8_SCHED;
;             PG8_LDB(B0, 1, 0); PG8_LDB(B1, 1, 1); PG8_SCHED; PG8_LDA(At, 1, 0); PG8_STAGE(PG8_SA(0, 1), a2 + hstep, voffA);
;             PG8_WAIT_V(8); PG8_WAIT_L(0); PG8_BAR; PG8_MMA(0, 0, At, B0); PG8_MMA(0, 1, At, B1); PG8_BAR; PG8_SCHED;
;             PG8_LDA(At, 1, 1); PG8_STAGE(PG8_SB(1, 0), b3, voffB); PG8_STAGE(PG8_SB(1, 1), b3 + hstepB, voffB); PG8_STAGE(PG8_SA(1, 0), a3, voffA);
;             PG8_WAIT_V(8); PG8_WAIT_L(0); PG8_BAR; PG8_MMA(1, 0, At, B0); PG8_MMA(1, 1, At, B1); PG8_BAR; PG8_SCHED;
	s_waitcnt lgkmcnt(0)
	v_mfma_f32_16x16x32_bf16 v[62:65], v[130:133], v[182:185], v[62:65]
	v_mfma_f32_16x16x32_bf16 v[58:61], v[138:141], v[182:185], v[58:61]
	v_mfma_f32_16x16x32_bf16 v[46:49], v[130:133], v[202:205], v[46:49]
	v_mfma_f32_16x16x32_bf16 v[42:45], v[138:141], v[202:205], v[42:45]
	v_mfma_f32_16x16x32_bf16 v[30:33], v[130:133], v[210:213], v[30:33]
	v_mfma_f32_16x16x32_bf16 v[26:29], v[138:141], v[210:213], v[26:29]
	v_mfma_f32_16x16x32_bf16 v[14:17], v[130:133], v[218:221], v[14:17]
	v_mfma_f32_16x16x32_bf16 v[10:13], v[138:141], v[218:221], v[10:13]
	v_mfma_f32_16x16x32_bf16 v[62:65], v[134:137], v[186:189], v[62:65]
	v_mfma_f32_16x16x32_bf16 v[58:61], v[142:145], v[186:189], v[58:61]
	v_mfma_f32_16x16x32_bf16 v[46:49], v[134:137], v[206:209], v[46:49]
	v_mfma_f32_16x16x32_bf16 v[42:45], v[142:145], v[206:209], v[42:45]
	v_mfma_f32_16x16x32_bf16 v[30:33], v[134:137], v[214:217], v[30:33]
	v_mfma_f32_16x16x32_bf16 v[26:29], v[142:145], v[214:217], v[26:29]
	v_mfma_f32_16x16x32_bf16 v[14:17], v[134:137], v[222:225], v[14:17]
	v_mfma_f32_16x16x32_bf16 v[10:13], v[142:145], v[222:225], v[10:13]
	v_mfma_f32_16x16x32_bf16 v[54:57], v[166:169], v[182:185], v[54:57]
	v_mfma_f32_16x16x32_bf16 v[50:53], v[174:177], v[182:185], v[50:53]
	v_mfma_f32_16x16x32_bf16 v[38:41], v[166:169], v[202:205], v[38:41]
	v_mfma_f32_16x16x32_bf16 v[34:37], v[174:177], v[202:205], v[34:37]
	v_mfma_f32_16x16x32_bf16 v[22:25], v[166:169], v[210:213], v[22:25]
	v_mfma_f32_16x16x32_bf16 v[18:21], v[174:177], v[210:213], v[18:21]
	v_mfma_f32_16x16x32_bf16 v[6:9], v[166:169], v[218:221], v[6:9]
	v_mfma_f32_16x16x32_bf16 v[2:5], v[174:177], v[218:221], v[2:5]
	v_mfma_f32_16x16x32_bf16 v[54:57], v[170:173], v[186:189], v[54:57]
	v_mfma_f32_16x16x32_bf16 v[50:53], v[178:181], v[186:189], v[50:53]
	v_mfma_f32_16x16x32_bf16 v[38:41], v[170:173], v[206:209], v[38:41]
	v_mfma_f32_16x16x32_bf16 v[34:37], v[178:181], v[206:209], v[34:37]
	v_mfma_f32_16x16x32_bf16 v[22:25], v[170:173], v[214:217], v[22:25]
	v_mfma_f32_16x16x32_bf16 v[18:21], v[178:181], v[214:217], v[18:21]
	v_mfma_f32_16x16x32_bf16 v[6:9], v[170:173], v[222:225], v[6:9]
	v_mfma_f32_16x16x32_bf16 v[2:5], v[178:181], v[222:225], v[2:5]
	s_barrier
	s_add_i32 s54, 0, 0x18000
	s_add_i32 s55, 0, 0x1c000
	v_add_u32_e32 v142, s54, v1
	v_add_u32_e32 v154, s55, v1
	ds_read_b128 v[130:133], v142
	ds_read_b128 v[134:137], v142 offset:1024
	ds_read_b128 v[138:141], v142 offset:2048
	ds_read_b128 v[142:145], v142 offset:3072
	ds_read_b128 v[166:169], v154
	ds_read_b128 v[170:173], v154 offset:1024
	ds_read_b128 v[174:177], v154 offset:2048
	ds_read_b128 v[178:181], v154 offset:3072
	s_add_u32 s18, s46, 0x160000
	s_addc_u32 s19, s47, 0
	s_mov_b32 m0, s29
	ds_read_b128 v[182:185], v198 offset:32768
	ds_read_b128 v[186:189], v198 offset:33792
	ds_read_b128 v[202:205], v198 offset:34816
	ds_read_b128 v[206:209], v198 offset:35840
	ds_read_b128 v[210:213], v198 offset:36864
	ds_read_b128 v[214:217], v198 offset:37888
	ds_read_b128 v[218:221], v198 offset:38912
	ds_read_b128 v[222:225], v198 offset:39936
	global_load_lds_dwordx4 v146, s[18:19]
	s_mov_b32 m0, s30
	s_nop 0
	global_load_lds_dwordx4 v150, s[18:19]
	s_waitcnt vmcnt(8)
	s_waitcnt lgkmcnt(0)
	s_barrier
	s_waitcnt lgkmcnt(0)
	v_mfma_f32_16x16x32_bf16 v[126:129], v[130:133], v[182:185], v[126:129]
	v_mfma_f32_16x16x32_bf16 v[122:125], v[138:141], v[182:185], v[122:125]
	v_mfma_f32_16x16x32_bf16 v[110:113], v[130:133], v[202:205], v[110:113]
	v_mfma_f32_16x16x32_bf16 v[106:109], v[138:141], v[202:205], v[106:109]
	v_mfma_f32_16x16x32_bf16 v[94:97], v[130:133], v[210:213], v[94:97]
	v_mfma_f32_16x16x32_bf16 v[90:93], v[138:141], v[210:213], v[90:93]
	v_mfma_f32_16x16x32_bf16 v[78:81], v[130:133], v[218:221], v[78:81]
	v_mfma_f32_16x16x32_bf16 v[74:77], v[138:141], v[218:221], v[74:77]
	v_mfma_f32_16x16x32_bf16 v[126:129], v[134:137], v[186:189], v[126:129]
	v_mfma_f32_16x16x32_bf16 v[122:125], v[142:145], v[186:189], v[122:125]
	v_mfma_f32_16x16x32_bf16 v[110:113], v[134:137], v[206:209], v[110:113]
	v_mfma_f32_16x16x32_bf16 v[106:109], v[142:145], v[206:209], v[106:109]
	v_mfma_f32_16x16x32_bf16 v[94:97], v[134:137], v[214:217], v[94:97]
	v_mfma_f32_16x16x32_bf16 v[90:93], v[142:145], v[214:217], v[90:93]
	v_mfma_f32_16x16x32_bf16 v[78:81], v[134:137], v[222:225], v[78:81]
	v_mfma_f32_16x16x32_bf16 v[74:77], v[142:145], v[222:225], v[74:77]
	v_mfma_f32_16x16x32_bf16 v[118:121], v[166:169], v[182:185], v[118:121]
	v_mfma_f32_16x16x32_bf16 v[114:117], v[174:177], v[182:185], v[114:117]
	v_mfma_f32_16x16x32_bf16 v[102:105], v[166:169], v[202:205], v[102:105]
	v_mfma_f32_16x16x32_bf16 v[98:101], v[174:177], v[202:205], v[98:101]
	v_mfma_f32_16x16x32_bf16 v[86:89], v[166:169], v[210:213], v[86:89]
	v_mfma_f32_16x16x32_bf16 v[82:85], v[174:177], v[210:213], v[82:85]
	v_mfma_f32_16x16x32_bf16 v[70:73], v[166:169], v[218:221], v[70:73]
	v_mfma_f32_16x16x32_bf16 v[66:69], v[174:177], v[218:221], v[66:69]
	v_mfma_f32_16x16x32_bf16 v[118:121], v[170:173], v[186:189], v[118:121]
	v_mfma_f32_16x16x32_bf16 v[114:117], v[178:181], v[186:189], v[114:117]
	v_mfma_f32_16x16x32_bf16 v[102:105], v[170:173], v[206:209], v[102:105]
	v_mfma_f32_16x16x32_bf16 v[98:101], v[178:181], v[206:209], v[98:101]
	v_mfma_f32_16x16x32_bf16 v[86:89], v[170:173], v[214:217], v[86:89]
	v_mfma_f32_16x16x32_bf16 v[82:85], v[178:181], v[214:217], v[82:85]
	v_mfma_f32_16x16x32_bf16 v[70:73], v[170:173], v[222:225], v[70:73]
	v_mfma_f32_16x16x32_bf16 v[66:69], v[178:181], v[222:225], v[66:69]
	s_barrier
; #define PG8_STAGE(bufoff, gbase, voff) do { _Pragma("unroll") for (int _i = 0; _i < 2; ++_i) \
;         __builtin_amdgcn_global_load_lds((const unsigned*)((const char*)(gbase) + (voff)[_i]), (LAS unsigned*)(lds + (bufoff) + ldsw + _i * 8192), 16, 0, 0); } while (0)
; #define PG8_LDA(dst, b, h) do { _Pragma("unroll") for (int m = 0; m < 4; ++m) _Pragma("unroll") for (int k = 0; k < 2; ++k) dst[m][k] = *(const LAS bf16x8*)(lds + PG8_SA(b, h) + aoff + m * 2048 + k * 1024); } while (0)
; #define PG8_BAR __builtin_amdgcn_s_barrier()
; template <class Epi, class Sched, bool ALIGN_EPI = false, bool SP2 = false>
; __device__ __forceinline__ void gemm_phase(LAS unsigned char* lds, const Gemm g, const Sched& S, const Epi& E) {
;     ...
;         for (int t = 0; t < nt; t += 2) {
;             const bool last = (t == nt - 2);
;             const char* a1 = cA + (size_t)(t + 1) * kstep;
;             const char* a2 = last ? nA : cA + (size_t)(t + 2) * kstep; const char* b2 = last ? nB : cB + (size_t)(t + 2) * kstep;
;             const char* a3 = a2 + kstep; const char* b3 = b2 + kstep;
;             if (last && has_next) S.a_ready(nxt);
;             if constexpr (SP2) {
;             PG8_LDB(B0, 0, 0); PG8_LDB(B1, 0, 1); PG8_SCHED; PG8_LDA(At, 0, 0); PG8_STAGE(PG8_SA(1, 1), a1 + hstep, voffA);
;             PG8_WAIT_V(8); PG8_WAIT_L(0); PG8_BAR; PG8_MMA(0, 0, At, B0); PG8_MMA(0, 1, At, B1); PG8_BAR; PG8_SCHED;
;             PG8_LDA(At, 0, 1); PG8_STAGE(PG8_SB(0, 0), b2, voffB); PG8_STAGE(PG8_SB(0, 1), b2 + hstepB, voffB); PG8_STAGE(PG8_SA(0, 0), a2, voffA);
;             PG8_WAIT_V(8); PG8_WAIT_L(0); PG8_BAR; PG8_MMA(1, 0, At, B0); PG8_MMA(1, 1, At, B1); PG8_BAR; PG8_SCHED;
;             PG8_LDB(B0, 1, 0); PG8_LDB(B1, 1, 1); PG8_SCHED; PG8_LDA(At, 1, 0); PG8_STAGE(PG8_SA(0, 1), a2 + hstep, voffA);
;             PG8_WAIT_V(8); PG8_WAIT_L(0); PG8_BAR; PG8_MMA(0, 0, At, B0); PG8_MMA(0, 1, At, B1); PG8_BAR; PG8_SCHED;
;             PG8_LDA(At, 1, 1); PG8_STAGE(PG8_SB(1, 0), b3, voffB); PG8_STAGE(PG8_SB(1, 1), b3 + hstepB, voffB); PG8_STAGE(PG8_SA(1, 0), a3, voffA);
;             PG8_WAIT_V(8); PG8_WAIT_L(0); PG8_BAR; PG8_MMA(1, 0, At, B0); PG8_MMA(1, 1, At, B1); PG8_BAR; PG8_SCHED;
;     ...
;         if constexpr (ALIGN_EPI) { if (wr == 0) PG8_BAR; }
;         if constexpr (!Epi::AFTER_DRAIN) { E(acc, cur, wr, wc, fr, fq); S.done(cur); }
;         if (!has_next) break;
	s_add_i32 s18, s54, s26
	v_lshl_add_u64 v[190:191], v[190:191], 0, s[12:13]
	s_mov_b32 m0, s18
	ds_read_b128 v[182:185], v198 offset:49152
	ds_read_b128 v[186:189], v198 offset:50176
	ds_read_b128 v[202:205], v198 offset:51200
	ds_read_b128 v[206:209], v198 offset:52224
	ds_read_b128 v[210:213], v198 offset:53248
	ds_read_b128 v[214:217], v198 offset:54272
	ds_read_b128 v[218:221], v198 offset:55296
	ds_read_b128 v[222:225], v198 offset:56320
	global_load_lds_dwordx4 v[190:191], off
	s_add_i32 m0, s18, 0x2000
	s_add_u32 s18, s22, 0x58080
	v_lshl_add_u64 v[190:191], v[226:227], 0, s[12:13]
	s_addc_u32 s19, s23, 0
	s_add_i32 s22, s55, s26
	global_load_lds_dwordx4 v[190:191], off
	s_mov_b32 m0, s22
	s_nop 0
	global_load_lds_dwordx4 v148, s[18:19]
	s_add_i32 m0, s22, 0x2000
	s_nop 0
	global_load_lds_dwordx4 v152, s[18:19]
	v_lshl_add_u64 v[190:191], v[228:229], 0, s[12:13]
	s_mov_b32 m0, s37
	s_nop 0
	global_load_lds_dwordx4 v[190:191], off
	v_lshl_add_u64 v[190:191], v[230:231], 0, s[12:13]
	s_mov_b32 m0, s48
	s_nop 0
	global_load_lds_dwordx4 v[190:191], off
	s_waitcnt vmcnt(8)
	s_waitcnt lgkmcnt(0)
	s_barrier
	s_waitcnt lgkmcnt(0)
	v_mfma_f32_16x16x32_bf16 v[62:65], v[130:133], v[182:185], v[62:65]
	v_mfma_f32_16x16x32_bf16 v[58:61], v[138:141], v[182:185], v[58:61]
	v_mfma_f32_16x16x32_bf16 v[46:49], v[130:133], v[202:205], v[46:49]
	v_mfma_f32_16x16x32_bf16 v[42:45], v[138:141], v[202:205], v[42:45]
	v_mfma_f32_16x16x32_bf16 v[30:33], v[130:133], v[210:213], v[30:33]
	v_mfma_f32_16x16x32_bf16 v[26:29], v[138:141], v[210:213], v[26:29]
	v_mfma_f32_16x16x32_bf16 v[14:17], v[130:133], v[218:221], v[14:17]
	v_mfma_f32_16x16x32_bf16 v[10:13], v[138:141], v[218:221], v[10:13]
	v_mfma_f32_16x16x32_bf16 v[62:65], v[134:137], v[186:189], v[62:65]
	v_mfma_f32_16x16x32_bf16 v[58:61], v[142:145], v[186:189], v[58:61]
	v_mfma_f32_16x16x32_bf16 v[46:49], v[134:137], v[206:209], v[46:49]
	v_mfma_f32_16x16x32_bf16 v[42:45], v[142:145], v[206:209], v[42:45]
	v_mfma_f32_16x16x32_bf16 v[30:33], v[134:137], v[214:217], v[30:33]
	v_mfma_f32_16x16x32_bf16 v[26:29], v[142:145], v[214:217], v[26:29]
	v_mfma_f32_16x16x32_bf16 v[14:17], v[134:137], v[222:225], v[14:17]
	v_mfma_f32_16x16x32_bf16 v[10:13], v[142:145], v[222:225], v[10:13]
	v_mfma_f32_16x16x32_bf16 v[54:57], v[166:169], v[182:185], v[54:57]
	v_mfma_f32_16x16x32_bf16 v[50:53], v[174:177], v[182:185], v[50:53]
	v_mfma_f32_16x16x32_bf16 v[38:41], v[166:169], v[202:205], v[38:41]
	v_mfma_f32_16x16x32_bf16 v[34:37], v[174:177], v[202:205], v[34:37]
	v_mfma_f32_16x16x32_bf16 v[22:25], v[166:169], v[210:213], v[22:25]
	v_mfma_f32_16x16x32_bf16 v[18:21], v[174:177], v[210:213], v[18:21]
	v_mfma_f32_16x16x32_bf16 v[6:9], v[166:169], v[218:221], v[6:9]
	v_mfma_f32_16x16x32_bf16 v[2:5], v[174:177], v[218:221], v[2:5]
	v_mfma_f32_16x16x32_bf16 v[54:57], v[170:173], v[186:189], v[54:57]
	v_mfma_f32_16x16x32_bf16 v[50:53], v[178:181], v[186:189], v[50:53]
	v_mfma_f32_16x16x32_bf16 v[38:41], v[170:173], v[206:209], v[38:41]
	v_mfma_f32_16x16x32_bf16 v[34:37], v[178:181], v[206:209], v[34:37]
	v_mfma_f32_16x16x32_bf16 v[22:25], v[170:173], v[214:217], v[22:25]
	v_mfma_f32_16x16x32_bf16 v[18:21], v[178:181], v[214:217], v[18:21]
	v_mfma_f32_16x16x32_bf16 v[6:9], v[170:173], v[222:225], v[6:9]
	v_mfma_f32_16x16x32_bf16 v[2:5], v[178:181], v[222:225], v[2:5]
	s_barrier
	s_add_i32 s25, s25, 2
	s_add_u32 s5, s5, 0x100
	s_addc_u32 s24, s24, 0
	s_cmpk_lt_u32 s25, 0x56
	s_mov_b64 s[18:19], s[20:21]
	s_cbranch_scc1 .LBB0_1926
	s_setprio 0
	s_andn2_b64 vcc, exec, s[14:15]
	s_cbranch_vccnz .LBB0_1929
	s_barrier

; #define PG8_STAGE(bufoff, gbase, voff) do { _Pragma("unroll") for (int _i = 0; _i < 2; ++_i) \
;         __builtin_amdgcn_global_load_lds((const unsigned*)((const char*)(gbase) + (voff)[_i]), (LAS unsigned*)(lds + (bufoff) + ldsw + _i * 8192), 16, 0, 0); } while (0)
; #define PG8_LDA(dst, b, h) do { _Pragma("unroll") for (int m = 0; m < 4; ++m) _Pragma("unroll") for (int k = 0; k < 2; ++k) dst[m][k] = *(const LAS bf16x8*)(lds + PG8_SA(b, h) + aoff + m * 2048 + k * 1024); } while (0)
; #define PG8_LDB(dst, b, h) do { _Pragma("unroll") for (int n = 0; n < 2; ++n) _Pragma("unroll") for (int k = 0; k < 2; ++k) dst[n][k] = *(const LAS bf16x8*)(lds + PG8_SB(b, h) + boff + n * 2048 + k * 1024); } while (0)
; template <class Epi, class Sched, bool ALIGN_EPI = false, bool SP2 = false>
; __device__ __forceinline__ void gemm_phase(LAS unsigned char* lds, const Gemm g, const Sched& S, const Epi& E) {
;     ...
;         for (int t = 0; t < nt; t += 2) {
;             const bool last = (t == nt - 2);
;             const char* a1 = cA + (size_t)(t + 1) * kstep;
;             const char* a2 = last ? nA : cA + (size_t)(t + 2) * kstep; const char* b2 = last ? nB : cB + (size_t)(t + 2) * kstep;
;             const char* a3 = a2 + kstep; const char* b3 = b2 + kstep;
;             if (last && has_next) S.a_ready(nxt);
;             if constexpr (SP2) {
;             PG8_LDB(B0, 0, 0); PG8_LDB(B1, 0, 1); PG8_SCHED; PG8_LDA(At, 0, 0); PG8_STAGE(PG8_SA(1, 1), a1 + hstep, voffA);
;             PG8_WAIT_V(8); PG8_WAIT_L(0); PG8_BAR; PG8_MMA(0, 0, At, B0); PG8_MMA(0, 1, At, B1); PG8_BAR; PG8_SCHED;
;             PG8_LDA(At, 0, 1); PG8_STAGE(PG8_SB(0, 0), b2, voffB); PG8_STAGE(PG8_SB(0, 1), b2 + hstepB, voffB); PG8_STAGE(PG8_SA(0, 0), a2, voffA);
;             PG8_WAIT_V(8); PG8_WAIT_L(0); PG8_BAR; PG8_MMA(1, 0, At, B0); PG8_MMA(1, 1, At, B1); PG8_BAR; PG8_SCHED;
;             PG8_LDB(B0, 1, 0); PG8_LDB(B1, 1, 1); PG8_SCHED; PG8_LDA(At, 1, 0); PG8_STAGE(PG8_SA(0, 1), a2 + hstep, voffA);
;             PG8_WAIT_V(8); PG8_WAIT_L(0); PG8_BAR; PG8_MMA(0, 0, At, B0); PG8_MMA(0, 1, At, B1); PG8_BAR; PG8_SCHED;
;             PG8_LDA(At, 1, 1); PG8_STAGE(PG8_SB(1, 0), b3, voffB); PG8_STAGE(PG8_SB(1, 1), b3 + hstepB, voffB); PG8_STAGE(PG8_SA(1, 0), a3, voffA);
;             PG8_WAIT_V(8); PG8_WAIT_L(0); PG8_BAR; PG8_MMA(1, 0, At, B0); PG8_MMA(1, 1, At, B1); PG8_BAR; PG8_SCHED;
.Lprio_2143:
	ds_read_b128 v[34:37], v202
	ds_read_b128 v[38:41], v202 offset:1024
	ds_read_b128 v[42:45], v202 offset:2048
	ds_read_b128 v[46:49], v202 offset:3072
	ds_read_b128 v[98:101], v203
	ds_read_b128 v[102:105], v203 offset:1024
	ds_read_b128 v[106:109], v203 offset:2048
	ds_read_b128 v[110:113], v203 offset:3072
	s_add_u32 s22, s20, 0xfff80080
	s_addc_u32 s23, s21, -1
	s_cmp_eq_u32 s34, 28
	s_cselect_b32 s37, s3, s23
	s_cselect_b32 s36, s13, s22
	s_cselect_b32 s23, s11, s25
	s_cselect_b32 s22, s19, s24
	s_add_i32 m0, s28, 0xc000
	ds_read_b128 v[210:213], v204
	ds_read_b128 v[214:217], v204 offset:1024
	ds_read_b128 v[218:221], v204 offset:2048
	ds_read_b128 v[222:225], v204 offset:3072
	ds_read_b128 v[226:229], v204 offset:4096
	ds_read_b128 v[230:233], v204 offset:5120
	ds_read_b128 v[234:237], v204 offset:6144
	ds_read_b128 v[238:241], v204 offset:7168
	global_load_lds_dwordx4 v174, s[20:21]
	s_add_i32 m0, s28, 0xe000
	s_nop 0
	global_load_lds_dwordx4 v172, s[20:21]
	s_waitcnt lgkmcnt(0)
	s_barrier
	s_waitcnt lgkmcnt(0)
	v_mfma_f32_16x16x32_bf16 v[158:161], v[34:37], v[210:213], 0
	v_mfma_f32_16x16x32_bf16 v[154:157], v[42:45], v[210:213], 0
	v_mfma_f32_16x16x32_bf16 v[142:145], v[34:37], v[218:221], 0
	v_mfma_f32_16x16x32_bf16 v[138:141], v[42:45], v[218:221], 0
	v_mfma_f32_16x16x32_bf16 v[126:129], v[34:37], v[226:229], 0
	v_mfma_f32_16x16x32_bf16 v[122:125], v[42:45], v[226:229], 0
	v_mfma_f32_16x16x32_bf16 v[94:97], v[34:37], v[234:237], 0
	v_mfma_f32_16x16x32_bf16 v[90:93], v[42:45], v[234:237], 0
	v_mfma_f32_16x16x32_bf16 v[158:161], v[38:41], v[214:217], v[158:161]
	v_mfma_f32_16x16x32_bf16 v[154:157], v[46:49], v[214:217], v[154:157]
	v_mfma_f32_16x16x32_bf16 v[142:145], v[38:41], v[222:225], v[142:145]
	v_mfma_f32_16x16x32_bf16 v[138:141], v[46:49], v[222:225], v[138:141]
	v_mfma_f32_16x16x32_bf16 v[126:129], v[38:41], v[230:233], v[126:129]
	v_mfma_f32_16x16x32_bf16 v[122:125], v[46:49], v[230:233], v[122:125]
	v_mfma_f32_16x16x32_bf16 v[94:97], v[38:41], v[238:241], v[94:97]
	v_mfma_f32_16x16x32_bf16 v[90:93], v[46:49], v[238:241], v[90:93]
	v_mfma_f32_16x16x32_bf16 v[150:153], v[98:101], v[210:213], 0
	v_mfma_f32_16x16x32_bf16 v[146:149], v[106:109], v[210:213], 0
	v_mfma_f32_16x16x32_bf16 v[134:137], v[98:101], v[218:221], 0
	v_mfma_f32_16x16x32_bf16 v[130:133], v[106:109], v[218:221], 0
	v_mfma_f32_16x16x32_bf16 v[118:121], v[98:101], v[226:229], 0
	v_mfma_f32_16x16x32_bf16 v[114:117], v[106:109], v[226:229], 0
	v_mfma_f32_16x16x32_bf16 v[86:89], v[98:101], v[234:237], 0
	v_mfma_f32_16x16x32_bf16 v[82:85], v[106:109], v[234:237], 0
	v_mfma_f32_16x16x32_bf16 v[150:153], v[102:105], v[214:217], v[150:153]
	v_mfma_f32_16x16x32_bf16 v[146:149], v[110:113], v[214:217], v[146:149]
	v_mfma_f32_16x16x32_bf16 v[134:137], v[102:105], v[222:225], v[134:137]
	v_mfma_f32_16x16x32_bf16 v[130:133], v[110:113], v[222:225], v[130:133]
	v_mfma_f32_16x16x32_bf16 v[118:121], v[102:105], v[230:233], v[118:121]
	v_mfma_f32_16x16x32_bf16 v[114:117], v[110:113], v[230:233], v[114:117]
	v_mfma_f32_16x16x32_bf16 v[86:89], v[102:105], v[238:241], v[86:89]
	v_mfma_f32_16x16x32_bf16 v[82:85], v[110:113], v[238:241], v[82:85]
	s_barrier
	s_add_i32 s35, s56, s27
	v_lshl_add_u64 v[182:183], s[22:23], 0, v[164:165]
	s_mov_b32 m0, s35
	ds_read_b128 v[210:213], v204 offset:16384
	ds_read_b128 v[214:217], v204 offset:17408
	ds_read_b128 v[218:221], v204 offset:18432
	ds_read_b128 v[222:225], v204 offset:19456
	ds_read_b128 v[226:229], v204 offset:20480
	ds_read_b128 v[230:233], v204 offset:21504
	ds_read_b128 v[234:237], v204 offset:22528
	ds_read_b128 v[238:241], v204 offset:23552
	global_load_lds_dwordx4 v[182:183], off
	s_add_i32 m0, s35, 0x2000
	s_add_u32 s46, s22, 0x20000
	v_lshl_add_u64 v[242:243], s[22:23], 0, v[168:169]
	s_addc_u32 s47, s23, 0
	s_add_i32 s35, s57, s27
	global_load_lds_dwordx4 v[242:243], off
	s_mov_b32 m0, s35
	v_lshl_add_u64 v[246:247], s[36:37], 0, v[166:167]
	global_load_lds_dwordx4 v164, s[46:47]
	s_add_i32 m0, s35, 0x2000
	s_nop 0
	global_load_lds_dwordx4 v168, s[46:47]
	v_lshl_add_u64 v[244:245], s[36:37], 0, v[162:163]
	s_mov_b32 m0, s28
	s_nop 0
	global_load_lds_dwordx4 v[244:245], off
	s_mov_b32 m0, s29
	s_nop 0
	global_load_lds_dwordx4 v[246:247], off
	s_waitcnt lgkmcnt(0)
	s_barrier
	s_waitcnt lgkmcnt(0)
	v_mfma_f32_16x16x32_bf16 v[78:81], v[34:37], v[210:213], 0
	v_mfma_f32_16x16x32_bf16 v[74:77], v[42:45], v[210:213], 0
	v_mfma_f32_16x16x32_bf16 v[62:65], v[34:37], v[218:221], 0
	v_mfma_f32_16x16x32_bf16 v[58:61], v[42:45], v[218:221], 0
	v_mfma_f32_16x16x32_bf16 v[30:33], v[34:37], v[226:229], 0
	v_mfma_f32_16x16x32_bf16 v[26:29], v[42:45], v[226:229], 0
	v_mfma_f32_16x16x32_bf16 v[14:17], v[34:37], v[234:237], 0
	v_mfma_f32_16x16x32_bf16 v[10:13], v[42:45], v[234:237], 0
	v_mfma_f32_16x16x32_bf16 v[78:81], v[38:41], v[214:217], v[78:81]
	v_mfma_f32_16x16x32_bf16 v[74:77], v[46:49], v[214:217], v[74:77]
	v_mfma_f32_16x16x32_bf16 v[62:65], v[38:41], v[222:225], v[62:65]
	v_mfma_f32_16x16x32_bf16 v[58:61], v[46:49], v[222:225], v[58:61]
	v_mfma_f32_16x16x32_bf16 v[30:33], v[38:41], v[230:233], v[30:33]
	v_mfma_f32_16x16x32_bf16 v[26:29], v[46:49], v[230:233], v[26:29]
	v_mfma_f32_16x16x32_bf16 v[14:17], v[38:41], v[238:241], v[14:17]
	v_mfma_f32_16x16x32_bf16 v[10:13], v[46:49], v[238:241], v[10:13]
	v_mfma_f32_16x16x32_bf16 v[22:25], v[98:101], v[226:229], 0
	v_mfma_f32_16x16x32_bf16 v[18:21], v[106:109], v[226:229], 0
	v_mfma_f32_16x16x32_bf16 v[6:9], v[98:101], v[234:237], 0
	v_mfma_f32_16x16x32_bf16 v[2:5], v[106:109], v[234:237], 0
	v_mfma_f32_16x16x32_bf16 v[34:37], v[98:101], v[210:213], 0
	v_mfma_f32_16x16x32_bf16 v[38:41], v[106:109], v[210:213], 0
	v_mfma_f32_16x16x32_bf16 v[42:45], v[98:101], v[218:221], 0
	v_mfma_f32_16x16x32_bf16 v[46:49], v[106:109], v[218:221], 0
	v_mfma_f32_16x16x32_bf16 v[22:25], v[102:105], v[230:233], v[22:25]
	v_mfma_f32_16x16x32_bf16 v[18:21], v[110:113], v[230:233], v[18:21]
	v_mfma_f32_16x16x32_bf16 v[6:9], v[102:105], v[238:241], v[6:9]
	v_mfma_f32_16x16x32_bf16 v[2:5], v[110:113], v[238:241], v[2:5]
	v_mfma_f32_16x16x32_bf16 v[34:37], v[102:105], v[214:217], v[34:37]
	v_mfma_f32_16x16x32_bf16 v[38:41], v[110:113], v[214:217], v[38:41]
	v_mfma_f32_16x16x32_bf16 v[42:45], v[102:105], v[222:225], v[42:45]
	v_mfma_f32_16x16x32_bf16 v[46:49], v[110:113], v[222:225], v[46:49]
	s_barrier
; #define PG8_STAGE(bufoff, gbase, voff) do { _Pragma("unroll") for (int _i = 0; _i < 2; ++_i) \
;         __builtin_amdgcn_global_load_lds((const unsigned*)((const char*)(gbase) + (voff)[_i]), (LAS unsigned*)(lds + (bufoff) + ldsw + _i * 8192), 16, 0, 0); } while (0)
; #define PG8_LDA(dst, b, h) do { _Pragma("unroll") for (int m = 0; m < 4; ++m) _Pragma("unroll") for (int k = 0; k < 2; ++k) dst[m][k] = *(const LAS bf16x8*)(lds + PG8_SA(b, h) + aoff + m * 2048 + k * 1024); } while (0)
; #define PG8_LDB(dst, b, h) do { _Pragma("unroll") for (int n = 0; n < 2; ++n) _Pragma("unroll") for (int k = 0; k < 2; ++k) dst[n][k] = *(const LAS bf16x8*)(lds + PG8_SB(b, h) + boff + n * 2048 + k * 1024); } while (0)
; template <class Epi, class Sched, bool ALIGN_EPI = false, bool SP2 = false>
; __device__ __forceinline__ void gemm_phase(LAS unsigned char* lds, const Gemm g, const Sched& S, const Epi& E) {
;     ...
;         for (int t = 0; t < nt; t += 2) {
;             const bool last = (t == nt - 2);
;             const char* a1 = cA + (size_t)(t + 1) * kstep;
;             const char* a2 = last ? nA : cA + (size_t)(t + 2) * kstep; const char* b2 = last ? nB : cB + (size_t)(t + 2) * kstep;
;             const char* a3 = a2 + kstep; const char* b3 = b2 + kstep;
;             if (last && has_next) S.a_ready(nxt);
;             if constexpr (SP2) {
;             PG8_LDB(B0, 0, 0); PG8_LDB(B1, 0, 1); PG8_SCHED; PG8_LDA(At, 0, 0); PG8_STAGE(PG8_SA(1, 1), a1 + hstep, voffA);
;             PG8_WAIT_V(8); PG8_WAIT_L(0); PG8_BAR; PG8_MMA(0, 0, At, B0); PG8_MMA(0, 1, At, B1); PG8_BAR; PG8_SCHED;
;             PG8_LDA(At, 0, 1); PG8_STAGE(PG8_SB(0, 0), b2, voffB); PG8_STAGE(PG8_SB(0, 1), b2 + hstepB, voffB); PG8_STAGE(PG8_SA(0, 0), a2, voffA);
;             PG8_WAIT_V(8); PG8_WAIT_L(0); PG8_BAR; PG8_MMA(1, 0, At, B0); PG8_MMA(1, 1, At, B1); PG8_BAR; PG8_SCHED;
;             PG8_LDB(B0, 1, 0); PG8_LDB(B1, 1, 1); PG8_SCHED; PG8_LDA(At, 1, 0); PG8_STAGE(PG8_SA(0, 1), a2 + hstep, voffA);
;             PG8_WAIT_V(8); PG8_WAIT_L(0); PG8_BAR; PG8_MMA(0, 0, At, B0); PG8_MMA(0, 1, At, B1); PG8_BAR; PG8_SCHED;
;             PG8_LDA(At, 1, 1); PG8_STAGE(PG8_SB(1, 0), b3, voffB); PG8_STAGE(PG8_SB(1, 1), b3 + hstepB, voffB); PG8_STAGE(PG8_SA(1, 0), a3, voffA);
;             PG8_WAIT_V(8); PG8_WAIT_L(0); PG8_BAR; PG8_MMA(1, 0, At, B0); PG8_MMA(1, 1, At, B1); PG8_BAR; PG8_SCHED;
	s_add_i32 s35, 0, 0x18000
	s_add_i32 s46, 0, 0x1c000
	v_add_u32_e32 v70, s35, v185
	v_add_u32_e32 v110, s46, v185
	ds_read_b128 v[50:53], v70
	ds_read_b128 v[54:57], v70 offset:1024
	ds_read_b128 v[66:69], v70 offset:2048
	ds_read_b128 v[70:73], v70 offset:3072
	ds_read_b128 v[98:101], v110
	ds_read_b128 v[102:105], v110 offset:1024
	ds_read_b128 v[106:109], v110 offset:2048
	ds_read_b128 v[110:113], v110 offset:3072
	s_add_u32 s36, s36, 0x80000
	s_addc_u32 s37, s37, 0
	s_mov_b32 m0, s30
	ds_read_b128 v[210:213], v204 offset:32768
	ds_read_b128 v[214:217], v204 offset:33792
	ds_read_b128 v[218:221], v204 offset:34816
	ds_read_b128 v[222:225], v204 offset:35840
	ds_read_b128 v[226:229], v204 offset:36864
	ds_read_b128 v[230:233], v204 offset:37888
	ds_read_b128 v[234:237], v204 offset:38912
	ds_read_b128 v[238:241], v204 offset:39936
	global_load_lds_dwordx4 v162, s[36:37]
	s_mov_b32 m0, s31
	s_nop 0
	global_load_lds_dwordx4 v166, s[36:37]
	s_waitcnt vmcnt(8)
	s_waitcnt lgkmcnt(0)
	s_barrier
	s_waitcnt lgkmcnt(0)
	v_mfma_f32_16x16x32_bf16 v[158:161], v[50:53], v[210:213], v[158:161]
	v_mfma_f32_16x16x32_bf16 v[154:157], v[66:69], v[210:213], v[154:157]
	v_mfma_f32_16x16x32_bf16 v[142:145], v[50:53], v[218:221], v[142:145]
	v_mfma_f32_16x16x32_bf16 v[138:141], v[66:69], v[218:221], v[138:141]
	v_mfma_f32_16x16x32_bf16 v[126:129], v[50:53], v[226:229], v[126:129]
	v_mfma_f32_16x16x32_bf16 v[122:125], v[66:69], v[226:229], v[122:125]
	v_mfma_f32_16x16x32_bf16 v[94:97], v[50:53], v[234:237], v[94:97]
	v_mfma_f32_16x16x32_bf16 v[90:93], v[66:69], v[234:237], v[90:93]
	v_mfma_f32_16x16x32_bf16 v[158:161], v[54:57], v[214:217], v[158:161]
	v_mfma_f32_16x16x32_bf16 v[154:157], v[70:73], v[214:217], v[154:157]
	v_mfma_f32_16x16x32_bf16 v[142:145], v[54:57], v[222:225], v[142:145]
	v_mfma_f32_16x16x32_bf16 v[138:141], v[70:73], v[222:225], v[138:141]
	v_mfma_f32_16x16x32_bf16 v[126:129], v[54:57], v[230:233], v[126:129]
	v_mfma_f32_16x16x32_bf16 v[122:125], v[70:73], v[230:233], v[122:125]
	v_mfma_f32_16x16x32_bf16 v[94:97], v[54:57], v[238:241], v[94:97]
	v_mfma_f32_16x16x32_bf16 v[90:93], v[70:73], v[238:241], v[90:93]
	v_mfma_f32_16x16x32_bf16 v[150:153], v[98:101], v[210:213], v[150:153]
	v_mfma_f32_16x16x32_bf16 v[146:149], v[106:109], v[210:213], v[146:149]
	v_mfma_f32_16x16x32_bf16 v[134:137], v[98:101], v[218:221], v[134:137]
	v_mfma_f32_16x16x32_bf16 v[130:133], v[106:109], v[218:221], v[130:133]
	v_mfma_f32_16x16x32_bf16 v[118:121], v[98:101], v[226:229], v[118:121]
	v_mfma_f32_16x16x32_bf16 v[114:117], v[106:109], v[226:229], v[114:117]
	v_mfma_f32_16x16x32_bf16 v[86:89], v[98:101], v[234:237], v[86:89]
	v_mfma_f32_16x16x32_bf16 v[82:85], v[106:109], v[234:237], v[82:85]
	v_mfma_f32_16x16x32_bf16 v[150:153], v[102:105], v[214:217], v[150:153]
	v_mfma_f32_16x16x32_bf16 v[146:149], v[110:113], v[214:217], v[146:149]
	v_mfma_f32_16x16x32_bf16 v[134:137], v[102:105], v[222:225], v[134:137]
	v_mfma_f32_16x16x32_bf16 v[130:133], v[110:113], v[222:225], v[130:133]
	v_mfma_f32_16x16x32_bf16 v[118:121], v[102:105], v[230:233], v[118:121]
	v_mfma_f32_16x16x32_bf16 v[114:117], v[110:113], v[230:233], v[114:117]
	v_mfma_f32_16x16x32_bf16 v[86:89], v[102:105], v[238:241], v[86:89]
	v_mfma_f32_16x16x32_bf16 v[82:85], v[110:113], v[238:241], v[82:85]
	s_barrier
	s_add_i32 s35, s35, s27
	v_lshl_add_u64 v[182:183], v[182:183], 0, s[4:5]
	s_mov_b32 m0, s35
	ds_read_b128 v[210:213], v204 offset:49152
	ds_read_b128 v[214:217], v204 offset:50176
	ds_read_b128 v[218:221], v204 offset:51200
	ds_read_b128 v[222:225], v204 offset:52224
	ds_read_b128 v[226:229], v204 offset:53248
	ds_read_b128 v[230:233], v204 offset:54272
	ds_read_b128 v[234:237], v204 offset:55296
	ds_read_b128 v[238:241], v204 offset:56320
	global_load_lds_dwordx4 v[182:183], off
	s_add_i32 m0, s35, 0x2000
	s_add_u32 s22, s22, 0x20080
	v_lshl_add_u64 v[182:183], v[242:243], 0, s[4:5]
	s_addc_u32 s23, s23, 0
	s_add_i32 s35, s46, s27
	global_load_lds_dwordx4 v[182:183], off
	s_mov_b32 m0, s35
	s_nop 0
	global_load_lds_dwordx4 v164, s[22:23]
	s_add_i32 m0, s35, 0x2000
	s_nop 0
	global_load_lds_dwordx4 v168, s[22:23]
	v_lshl_add_u64 v[182:183], v[244:245], 0, s[4:5]
	s_mov_b32 m0, s53
	s_nop 0
	global_load_lds_dwordx4 v[182:183], off
	v_lshl_add_u64 v[182:183], v[246:247], 0, s[4:5]
	s_mov_b32 m0, s54
	s_nop 0
	global_load_lds_dwordx4 v[182:183], off
	s_waitcnt vmcnt(8)
	s_waitcnt lgkmcnt(0)
	s_barrier
	s_waitcnt lgkmcnt(0)
	v_mfma_f32_16x16x32_bf16 v[78:81], v[50:53], v[210:213], v[78:81]
	v_mfma_f32_16x16x32_bf16 v[74:77], v[66:69], v[210:213], v[74:77]
	v_mfma_f32_16x16x32_bf16 v[62:65], v[50:53], v[218:221], v[62:65]
	v_mfma_f32_16x16x32_bf16 v[58:61], v[66:69], v[218:221], v[58:61]
	v_mfma_f32_16x16x32_bf16 v[30:33], v[50:53], v[226:229], v[30:33]
	v_mfma_f32_16x16x32_bf16 v[26:29], v[66:69], v[226:229], v[26:29]
	v_mfma_f32_16x16x32_bf16 v[14:17], v[50:53], v[234:237], v[14:17]
	v_mfma_f32_16x16x32_bf16 v[10:13], v[66:69], v[234:237], v[10:13]
	v_mfma_f32_16x16x32_bf16 v[78:81], v[54:57], v[214:217], v[78:81]
	v_mfma_f32_16x16x32_bf16 v[74:77], v[70:73], v[214:217], v[74:77]
	v_mfma_f32_16x16x32_bf16 v[62:65], v[54:57], v[222:225], v[62:65]
	v_mfma_f32_16x16x32_bf16 v[58:61], v[70:73], v[222:225], v[58:61]
	v_mfma_f32_16x16x32_bf16 v[30:33], v[54:57], v[230:233], v[30:33]
	v_mfma_f32_16x16x32_bf16 v[26:29], v[70:73], v[230:233], v[26:29]
	v_mfma_f32_16x16x32_bf16 v[14:17], v[54:57], v[238:241], v[14:17]
	v_mfma_f32_16x16x32_bf16 v[10:13], v[70:73], v[238:241], v[10:13]
	v_mfma_f32_16x16x32_bf16 v[34:37], v[98:101], v[210:213], v[34:37]
	v_mfma_f32_16x16x32_bf16 v[70:73], v[102:105], v[214:217], v[34:37]
	v_mfma_f32_16x16x32_bf16 v[34:37], v[106:109], v[210:213], v[38:41]
	v_mfma_f32_16x16x32_bf16 v[66:69], v[110:113], v[214:217], v[34:37]
	v_mfma_f32_16x16x32_bf16 v[34:37], v[98:101], v[218:221], v[42:45]
	v_mfma_f32_16x16x32_bf16 v[54:57], v[102:105], v[222:225], v[34:37]
	v_mfma_f32_16x16x32_bf16 v[34:37], v[106:109], v[218:221], v[46:49]
	v_mfma_f32_16x16x32_bf16 v[22:25], v[98:101], v[226:229], v[22:25]
	v_mfma_f32_16x16x32_bf16 v[18:21], v[106:109], v[226:229], v[18:21]
	v_mfma_f32_16x16x32_bf16 v[6:9], v[98:101], v[234:237], v[6:9]
	v_mfma_f32_16x16x32_bf16 v[2:5], v[106:109], v[234:237], v[2:5]
	v_mfma_f32_16x16x32_bf16 v[50:53], v[110:113], v[222:225], v[34:37]
	v_mfma_f32_16x16x32_bf16 v[22:25], v[102:105], v[230:233], v[22:25]
	v_mfma_f32_16x16x32_bf16 v[18:21], v[110:113], v[230:233], v[18:21]
	v_mfma_f32_16x16x32_bf16 v[6:9], v[102:105], v[238:241], v[6:9]
	v_mfma_f32_16x16x32_bf16 v[2:5], v[110:113], v[238:241], v[2:5]
	s_barrier
	s_add_i32 s34, s34, 2
	s_add_u32 s24, s24, 0x100
	s_addc_u32 s25, s25, 0
	s_add_u32 s20, s20, 0x100
	s_addc_u32 s21, s21, 0
	s_cmp_lt_u32 s34, 30
; #define PG8_STAGE(bufoff, gbase, voff) do { _Pragma("unroll") for (int _i = 0; _i < 2; ++_i) \
;         __builtin_amdgcn_global_load_lds((const unsigned*)((const char*)(gbase) + (voff)[_i]), (LAS unsigned*)(lds + (bufoff) + ldsw + _i * 8192), 16, 0, 0); } while (0)
; #define PG8_LDA(dst, b, h) do { _Pragma("unroll") for (int m = 0; m < 4; ++m) _Pragma("unroll") for (int k = 0; k < 2; ++k) dst[m][k] = *(const LAS bf16x8*)(lds + PG8_SA(b, h) + aoff + m * 2048 + k * 1024); } while (0)
; #define PG8_LDB(dst, b, h) do { _Pragma("unroll") for (int n = 0; n < 2; ++n) _Pragma("unroll") for (int k = 0; k < 2; ++k) dst[n][k] = *(const LAS bf16x8*)(lds + PG8_SB(b, h) + boff + n * 2048 + k * 1024); } while (0)
; template <class Epi, class Sched, bool ALIGN_EPI = false, bool SP2 = false>
; __device__ __forceinline__ void gemm_phase(LAS unsigned char* lds, const Gemm g, const Sched& S, const Epi& E) {
;     ...
;         for (int t = 0; t < nt; t += 2) {
;             const bool last = (t == nt - 2);
;             const char* a1 = cA + (size_t)(t + 1) * kstep;
;             const char* a2 = last ? nA : cA + (size_t)(t + 2) * kstep; const char* b2 = last ? nB : cB + (size_t)(t + 2) * kstep;
;             const char* a3 = a2 + kstep; const char* b3 = b2 + kstep;
;             if (last && has_next) S.a_ready(nxt);
;             if constexpr (SP2) {
;             PG8_LDB(B0, 0, 0); PG8_LDB(B1, 0, 1); PG8_SCHED; PG8_LDA(At, 0, 0); PG8_STAGE(PG8_SA(1, 1), a1 + hstep, voffA);
;             PG8_WAIT_V(8); PG8_WAIT_L(0); PG8_BAR; PG8_MMA(0, 0, At, B0); PG8_MMA(0, 1, At, B1); PG8_BAR; PG8_SCHED;
;             PG8_LDA(At, 0, 1); PG8_STAGE(PG8_SB(0, 0), b2, voffB); PG8_STAGE(PG8_SB(0, 1), b2 + hstepB, voffB); PG8_STAGE(PG8_SA(0, 0), a2, voffA);
;             PG8_WAIT_V(8); PG8_WAIT_L(0); PG8_BAR; PG8_MMA(1, 0, At, B0); PG8_MMA(1, 1, At, B1); PG8_BAR; PG8_SCHED;
;             PG8_LDB(B0, 1, 0); PG8_LDB(B1, 1, 1); PG8_SCHED; PG8_LDA(At, 1, 0); PG8_STAGE(PG8_SA(0, 1), a2 + hstep, voffA);
;             PG8_WAIT_V(8); PG8_WAIT_L(0); PG8_BAR; PG8_MMA(0, 0, At, B0); PG8_MMA(0, 1, At, B1); PG8_BAR; PG8_SCHED;
;             PG8_LDA(At, 1, 1); PG8_STAGE(PG8_SB(1, 0), b3, voffB); PG8_STAGE(PG8_SB(1, 1), b3 + hstepB, voffB); PG8_STAGE(PG8_SA(1, 0), a3, voffA);
;             PG8_WAIT_V(8); PG8_WAIT_L(0); PG8_BAR; PG8_MMA(1, 0, At, B0); PG8_MMA(1, 1, At, B1); PG8_BAR; PG8_SCHED;
.LBB0_2143:
	ds_read_b128 v[34:37], v202
	ds_read_b128 v[38:41], v202 offset:1024
	ds_read_b128 v[42:45], v202 offset:2048
	ds_read_b128 v[46:49], v202 offset:3072
	ds_read_b128 v[98:101], v203
	ds_read_b128 v[102:105], v203 offset:1024
	ds_read_b128 v[106:109], v203 offset:2048
	ds_read_b128 v[110:113], v203 offset:3072
	s_add_u32 s22, s20, 0xfff80080
	s_addc_u32 s23, s21, -1
	s_cmp_eq_u32 s34, 28
	s_cselect_b32 s37, s3, s23
	s_cselect_b32 s36, s13, s22
	s_cselect_b32 s23, s11, s25
	s_cselect_b32 s22, s19, s24
	s_add_i32 m0, s28, 0xc000
	ds_read_b128 v[210:213], v204
	ds_read_b128 v[214:217], v204 offset:1024
	ds_read_b128 v[218:221], v204 offset:2048
	ds_read_b128 v[222:225], v204 offset:3072
	ds_read_b128 v[226:229], v204 offset:4096
	ds_read_b128 v[230:233], v204 offset:5120
	ds_read_b128 v[234:237], v204 offset:6144
	ds_read_b128 v[238:241], v204 offset:7168
	global_load_lds_dwordx4 v174, s[20:21]
	s_add_i32 m0, s28, 0xe000
	s_nop 0
	global_load_lds_dwordx4 v172, s[20:21]
	s_waitcnt vmcnt(8)
	s_waitcnt lgkmcnt(0)
	s_barrier
	s_waitcnt lgkmcnt(0)
	v_mfma_f32_16x16x32_bf16 v[158:161], v[34:37], v[210:213], v[158:161]
	v_mfma_f32_16x16x32_bf16 v[154:157], v[42:45], v[210:213], v[154:157]
	v_mfma_f32_16x16x32_bf16 v[142:145], v[34:37], v[218:221], v[142:145]
	v_mfma_f32_16x16x32_bf16 v[138:141], v[42:45], v[218:221], v[138:141]
	v_mfma_f32_16x16x32_bf16 v[126:129], v[34:37], v[226:229], v[126:129]
	v_mfma_f32_16x16x32_bf16 v[122:125], v[42:45], v[226:229], v[122:125]
	v_mfma_f32_16x16x32_bf16 v[94:97], v[34:37], v[234:237], v[94:97]
	v_mfma_f32_16x16x32_bf16 v[90:93], v[42:45], v[234:237], v[90:93]
	v_mfma_f32_16x16x32_bf16 v[158:161], v[38:41], v[214:217], v[158:161]
	v_mfma_f32_16x16x32_bf16 v[154:157], v[46:49], v[214:217], v[154:157]
	v_mfma_f32_16x16x32_bf16 v[142:145], v[38:41], v[222:225], v[142:145]
	v_mfma_f32_16x16x32_bf16 v[138:141], v[46:49], v[222:225], v[138:141]
	v_mfma_f32_16x16x32_bf16 v[126:129], v[38:41], v[230:233], v[126:129]
	v_mfma_f32_16x16x32_bf16 v[122:125], v[46:49], v[230:233], v[122:125]
	v_mfma_f32_16x16x32_bf16 v[94:97], v[38:41], v[238:241], v[94:97]
	v_mfma_f32_16x16x32_bf16 v[90:93], v[46:49], v[238:241], v[90:93]
	v_mfma_f32_16x16x32_bf16 v[150:153], v[98:101], v[210:213], v[150:153]
	v_mfma_f32_16x16x32_bf16 v[146:149], v[106:109], v[210:213], v[146:149]
	v_mfma_f32_16x16x32_bf16 v[134:137], v[98:101], v[218:221], v[134:137]
	v_mfma_f32_16x16x32_bf16 v[130:133], v[106:109], v[218:221], v[130:133]
	v_mfma_f32_16x16x32_bf16 v[118:121], v[98:101], v[226:229], v[118:121]
	v_mfma_f32_16x16x32_bf16 v[114:117], v[106:109], v[226:229], v[114:117]
	v_mfma_f32_16x16x32_bf16 v[86:89], v[98:101], v[234:237], v[86:89]
	v_mfma_f32_16x16x32_bf16 v[82:85], v[106:109], v[234:237], v[82:85]
	v_mfma_f32_16x16x32_bf16 v[150:153], v[102:105], v[214:217], v[150:153]
	v_mfma_f32_16x16x32_bf16 v[146:149], v[110:113], v[214:217], v[146:149]
	v_mfma_f32_16x16x32_bf16 v[134:137], v[102:105], v[222:225], v[134:137]
	v_mfma_f32_16x16x32_bf16 v[130:133], v[110:113], v[222:225], v[130:133]
	v_mfma_f32_16x16x32_bf16 v[118:121], v[102:105], v[230:233], v[118:121]
	v_mfma_f32_16x16x32_bf16 v[114:117], v[110:113], v[230:233], v[114:117]
	v_mfma_f32_16x16x32_bf16 v[86:89], v[102:105], v[238:241], v[86:89]
	v_mfma_f32_16x16x32_bf16 v[82:85], v[110:113], v[238:241], v[82:85]
	s_barrier
	s_add_i32 s35, s56, s27
	v_lshl_add_u64 v[182:183], s[22:23], 0, v[164:165]
	s_mov_b32 m0, s35
	ds_read_b128 v[210:213], v204 offset:16384
	ds_read_b128 v[214:217], v204 offset:17408
	ds_read_b128 v[218:221], v204 offset:18432
	ds_read_b128 v[222:225], v204 offset:19456
	ds_read_b128 v[226:229], v204 offset:20480
	ds_read_b128 v[230:233], v204 offset:21504
	ds_read_b128 v[234:237], v204 offset:22528
	ds_read_b128 v[238:241], v204 offset:23552
	global_load_lds_dwordx4 v[182:183], off
	s_add_i32 m0, s35, 0x2000
	s_add_u32 s46, s22, 0x20000
	v_lshl_add_u64 v[242:243], s[22:23], 0, v[168:169]
	s_addc_u32 s47, s23, 0
	s_add_i32 s35, s57, s27
	global_load_lds_dwordx4 v[242:243], off
	s_mov_b32 m0, s35
	v_lshl_add_u64 v[246:247], s[36:37], 0, v[166:167]
	global_load_lds_dwordx4 v164, s[46:47]
	s_add_i32 m0, s35, 0x2000
	s_nop 0
	global_load_lds_dwordx4 v168, s[46:47]
	v_lshl_add_u64 v[244:245], s[36:37], 0, v[162:163]
	s_mov_b32 m0, s28
	s_nop 0
	global_load_lds_dwordx4 v[244:245], off
	s_mov_b32 m0, s29
	s_nop 0
	global_load_lds_dwordx4 v[246:247], off
	s_waitcnt vmcnt(8)
	s_waitcnt lgkmcnt(0)
	s_barrier
	s_waitcnt lgkmcnt(0)
	v_mfma_f32_16x16x32_bf16 v[78:81], v[34:37], v[210:213], v[78:81]
	v_mfma_f32_16x16x32_bf16 v[74:77], v[42:45], v[210:213], v[74:77]
	v_mfma_f32_16x16x32_bf16 v[62:65], v[34:37], v[218:221], v[62:65]
	v_mfma_f32_16x16x32_bf16 v[58:61], v[42:45], v[218:221], v[58:61]
	v_mfma_f32_16x16x32_bf16 v[30:33], v[34:37], v[226:229], v[30:33]
	v_mfma_f32_16x16x32_bf16 v[26:29], v[42:45], v[226:229], v[26:29]
	v_mfma_f32_16x16x32_bf16 v[14:17], v[34:37], v[234:237], v[14:17]
	v_mfma_f32_16x16x32_bf16 v[10:13], v[42:45], v[234:237], v[10:13]
	v_mfma_f32_16x16x32_bf16 v[78:81], v[38:41], v[214:217], v[78:81]
	v_mfma_f32_16x16x32_bf16 v[74:77], v[46:49], v[214:217], v[74:77]
	v_mfma_f32_16x16x32_bf16 v[62:65], v[38:41], v[222:225], v[62:65]
	v_mfma_f32_16x16x32_bf16 v[58:61], v[46:49], v[222:225], v[58:61]
	v_mfma_f32_16x16x32_bf16 v[30:33], v[38:41], v[230:233], v[30:33]
	v_mfma_f32_16x16x32_bf16 v[26:29], v[46:49], v[230:233], v[26:29]
	v_mfma_f32_16x16x32_bf16 v[14:17], v[38:41], v[238:241], v[14:17]
	v_mfma_f32_16x16x32_bf16 v[10:13], v[46:49], v[238:241], v[10:13]
	v_mfma_f32_16x16x32_bf16 v[22:25], v[98:101], v[226:229], v[22:25]
	v_mfma_f32_16x16x32_bf16 v[18:21], v[106:109], v[226:229], v[18:21]
	v_mfma_f32_16x16x32_bf16 v[6:9], v[98:101], v[234:237], v[6:9]
	v_mfma_f32_16x16x32_bf16 v[2:5], v[106:109], v[234:237], v[2:5]
	v_mfma_f32_16x16x32_bf16 v[34:37], v[98:101], v[210:213], v[70:73]
	v_mfma_f32_16x16x32_bf16 v[38:41], v[106:109], v[210:213], v[66:69]
	v_mfma_f32_16x16x32_bf16 v[42:45], v[98:101], v[218:221], v[54:57]
	v_mfma_f32_16x16x32_bf16 v[46:49], v[106:109], v[218:221], v[50:53]
	v_mfma_f32_16x16x32_bf16 v[22:25], v[102:105], v[230:233], v[22:25]
	v_mfma_f32_16x16x32_bf16 v[18:21], v[110:113], v[230:233], v[18:21]
	v_mfma_f32_16x16x32_bf16 v[6:9], v[102:105], v[238:241], v[6:9]
	v_mfma_f32_16x16x32_bf16 v[2:5], v[110:113], v[238:241], v[2:5]
	v_mfma_f32_16x16x32_bf16 v[34:37], v[102:105], v[214:217], v[34:37]
	v_mfma_f32_16x16x32_bf16 v[38:41], v[110:113], v[214:217], v[38:41]
	v_mfma_f32_16x16x32_bf16 v[42:45], v[102:105], v[222:225], v[42:45]
	v_mfma_f32_16x16x32_bf16 v[46:49], v[110:113], v[222:225], v[46:49]
	s_barrier
; #define PG8_STAGE(bufoff, gbase, voff) do { _Pragma("unroll") for (int _i = 0; _i < 2; ++_i) \
;         __builtin_amdgcn_global_load_lds((const unsigned*)((const char*)(gbase) + (voff)[_i]), (LAS unsigned*)(lds + (bufoff) + ldsw + _i * 8192), 16, 0, 0); } while (0)
; #define PG8_LDA(dst, b, h) do { _Pragma("unroll") for (int m = 0; m < 4; ++m) _Pragma("unroll") for (int k = 0; k < 2; ++k) dst[m][k] = *(const LAS bf16x8*)(lds + PG8_SA(b, h) + aoff + m * 2048 + k * 1024); } while (0)
; #define PG8_BAR __builtin_amdgcn_s_barrier()
; template <class Epi, class Sched, bool ALIGN_EPI = false, bool SP2 = false>
; __device__ __forceinline__ void gemm_phase(LAS unsigned char* lds, const Gemm g, const Sched& S, const Epi& E) {
;     ...
;         for (int t = 0; t < nt; t += 2) {
;             const bool last = (t == nt - 2);
;             const char* a1 = cA + (size_t)(t + 1) * kstep;
;             const char* a2 = last ? nA : cA + (size_t)(t + 2) * kstep; const char* b2 = last ? nB : cB + (size_t)(t + 2) * kstep;
;             const char* a3 = a2 + kstep; const char* b3 = b2 + kstep;
;             if (last && has_next) S.a_ready(nxt);
;             if constexpr (SP2) {
;             PG8_LDB(B0, 0, 0); PG8_LDB(B1, 0, 1); PG8_SCHED; PG8_LDA(At, 0, 0); PG8_STAGE(PG8_SA(1, 1), a1 + hstep, voffA);
;             PG8_WAIT_V(8); PG8_WAIT_L(0); PG8_BAR; PG8_MMA(0, 0, At, B0); PG8_MMA(0, 1, At, B1); PG8_BAR; PG8_SCHED;
;             PG8_LDA(At, 0, 1); PG8_STAGE(PG8_SB(0, 0), b2, voffB); PG8_STAGE(PG8_SB(0, 1), b2 + hstepB, voffB); PG8_STAGE(PG8_SA(0, 0), a2, voffA);
;             PG8_WAIT_V(8); PG8_WAIT_L(0); PG8_BAR; PG8_MMA(1, 0, At, B0); PG8_MMA(1, 1, At, B1); PG8_BAR; PG8_SCHED;
;             PG8_LDB(B0, 1, 0); PG8_LDB(B1, 1, 1); PG8_SCHED; PG8_LDA(At, 1, 0); PG8_STAGE(PG8_SA(0, 1), a2 + hstep, voffA);
;             PG8_WAIT_V(8); PG8_WAIT_L(0); PG8_BAR; PG8_MMA(0, 0, At, B0); PG8_MMA(0, 1, At, B1); PG8_BAR; PG8_SCHED;
;             PG8_LDA(At, 1, 1); PG8_STAGE(PG8_SB(1, 0), b3, voffB); PG8_STAGE(PG8_SB(1, 1), b3 + hstepB, voffB); PG8_STAGE(PG8_SA(1, 0), a3, voffA);
;             PG8_WAIT_V(8); PG8_WAIT_L(0); PG8_BAR; PG8_MMA(1, 0, At, B0); PG8_MMA(1, 1, At, B1); PG8_BAR; PG8_SCHED;
;     ...
;         if constexpr (ALIGN_EPI) { if (wr == 0) PG8_BAR; }
;         if constexpr (!Epi::AFTER_DRAIN) { E(acc, cur, wr, wc, fr, fq); S.done(cur); }
;         if (!has_next) break;
	s_add_i32 s35, 0, 0x18000
	s_add_i32 s46, 0, 0x1c000
	v_add_u32_e32 v70, s35, v185
	v_add_u32_e32 v110, s46, v185
	ds_read_b128 v[50:53], v70
	ds_read_b128 v[54:57], v70 offset:1024
	ds_read_b128 v[66:69], v70 offset:2048
	ds_read_b128 v[70:73], v70 offset:3072
	ds_read_b128 v[98:101], v110
	ds_read_b128 v[102:105], v110 offset:1024
	ds_read_b128 v[106:109], v110 offset:2048
	ds_read_b128 v[110:113], v110 offset:3072
	s_add_u32 s36, s36, 0x80000
	s_addc_u32 s37, s37, 0
	s_mov_b32 m0, s30
	ds_read_b128 v[210:213], v204 offset:32768
	ds_read_b128 v[214:217], v204 offset:33792
	ds_read_b128 v[218:221], v204 offset:34816
	ds_read_b128 v[222:225], v204 offset:35840
	ds_read_b128 v[226:229], v204 offset:36864
	ds_read_b128 v[230:233], v204 offset:37888
	ds_read_b128 v[234:237], v204 offset:38912
	ds_read_b128 v[238:241], v204 offset:39936
	global_load_lds_dwordx4 v162, s[36:37]
	s_mov_b32 m0, s31
	s_nop 0
	global_load_lds_dwordx4 v166, s[36:37]
	s_waitcnt vmcnt(8)
	s_waitcnt lgkmcnt(0)
	s_barrier
	s_waitcnt lgkmcnt(0)
	v_mfma_f32_16x16x32_bf16 v[158:161], v[50:53], v[210:213], v[158:161]
	v_mfma_f32_16x16x32_bf16 v[154:157], v[66:69], v[210:213], v[154:157]
	v_mfma_f32_16x16x32_bf16 v[142:145], v[50:53], v[218:221], v[142:145]
	v_mfma_f32_16x16x32_bf16 v[138:141], v[66:69], v[218:221], v[138:141]
	v_mfma_f32_16x16x32_bf16 v[126:129], v[50:53], v[226:229], v[126:129]
	v_mfma_f32_16x16x32_bf16 v[122:125], v[66:69], v[226:229], v[122:125]
	v_mfma_f32_16x16x32_bf16 v[94:97], v[50:53], v[234:237], v[94:97]
	v_mfma_f32_16x16x32_bf16 v[90:93], v[66:69], v[234:237], v[90:93]
	v_mfma_f32_16x16x32_bf16 v[158:161], v[54:57], v[214:217], v[158:161]
	v_mfma_f32_16x16x32_bf16 v[154:157], v[70:73], v[214:217], v[154:157]
	v_mfma_f32_16x16x32_bf16 v[142:145], v[54:57], v[222:225], v[142:145]
	v_mfma_f32_16x16x32_bf16 v[138:141], v[70:73], v[222:225], v[138:141]
	v_mfma_f32_16x16x32_bf16 v[126:129], v[54:57], v[230:233], v[126:129]
	v_mfma_f32_16x16x32_bf16 v[122:125], v[70:73], v[230:233], v[122:125]
	v_mfma_f32_16x16x32_bf16 v[94:97], v[54:57], v[238:241], v[94:97]
	v_mfma_f32_16x16x32_bf16 v[90:93], v[70:73], v[238:241], v[90:93]
	v_mfma_f32_16x16x32_bf16 v[150:153], v[98:101], v[210:213], v[150:153]
	v_mfma_f32_16x16x32_bf16 v[146:149], v[106:109], v[210:213], v[146:149]
	v_mfma_f32_16x16x32_bf16 v[134:137], v[98:101], v[218:221], v[134:137]
	v_mfma_f32_16x16x32_bf16 v[130:133], v[106:109], v[218:221], v[130:133]
	v_mfma_f32_16x16x32_bf16 v[118:121], v[98:101], v[226:229], v[118:121]
	v_mfma_f32_16x16x32_bf16 v[114:117], v[106:109], v[226:229], v[114:117]
	v_mfma_f32_16x16x32_bf16 v[86:89], v[98:101], v[234:237], v[86:89]
	v_mfma_f32_16x16x32_bf16 v[82:85], v[106:109], v[234:237], v[82:85]
	v_mfma_f32_16x16x32_bf16 v[150:153], v[102:105], v[214:217], v[150:153]
	v_mfma_f32_16x16x32_bf16 v[146:149], v[110:113], v[214:217], v[146:149]
	v_mfma_f32_16x16x32_bf16 v[134:137], v[102:105], v[222:225], v[134:137]
	v_mfma_f32_16x16x32_bf16 v[130:133], v[110:113], v[222:225], v[130:133]
	v_mfma_f32_16x16x32_bf16 v[118:121], v[102:105], v[230:233], v[118:121]
	v_mfma_f32_16x16x32_bf16 v[114:117], v[110:113], v[230:233], v[114:117]
	v_mfma_f32_16x16x32_bf16 v[86:89], v[102:105], v[238:241], v[86:89]
	v_mfma_f32_16x16x32_bf16 v[82:85], v[110:113], v[238:241], v[82:85]
	s_barrier
	s_add_i32 s35, s35, s27
	v_lshl_add_u64 v[182:183], v[182:183], 0, s[4:5]
	s_mov_b32 m0, s35
	ds_read_b128 v[210:213], v204 offset:49152
	ds_read_b128 v[214:217], v204 offset:50176
	ds_read_b128 v[218:221], v204 offset:51200
	ds_read_b128 v[222:225], v204 offset:52224
	ds_read_b128 v[226:229], v204 offset:53248
	ds_read_b128 v[230:233], v204 offset:54272
	ds_read_b128 v[234:237], v204 offset:55296
	ds_read_b128 v[238:241], v204 offset:56320
	global_load_lds_dwordx4 v[182:183], off
	s_add_i32 m0, s35, 0x2000
	s_add_u32 s22, s22, 0x20080
	v_lshl_add_u64 v[182:183], v[242:243], 0, s[4:5]
	s_addc_u32 s23, s23, 0
	s_add_i32 s35, s46, s27
	global_load_lds_dwordx4 v[182:183], off
	s_mov_b32 m0, s35
	s_nop 0
	global_load_lds_dwordx4 v164, s[22:23]
	s_add_i32 m0, s35, 0x2000
	s_nop 0
	global_load_lds_dwordx4 v168, s[22:23]
	v_lshl_add_u64 v[182:183], v[244:245], 0, s[4:5]
	s_mov_b32 m0, s53
	s_nop 0
	global_load_lds_dwordx4 v[182:183], off
	v_lshl_add_u64 v[182:183], v[246:247], 0, s[4:5]
	s_mov_b32 m0, s54
	s_nop 0
	global_load_lds_dwordx4 v[182:183], off
	s_waitcnt vmcnt(8)
	s_waitcnt lgkmcnt(0)
	s_barrier
	s_waitcnt lgkmcnt(0)
	v_mfma_f32_16x16x32_bf16 v[78:81], v[50:53], v[210:213], v[78:81]
	v_mfma_f32_16x16x32_bf16 v[74:77], v[66:69], v[210:213], v[74:77]
	v_mfma_f32_16x16x32_bf16 v[62:65], v[50:53], v[218:221], v[62:65]
	v_mfma_f32_16x16x32_bf16 v[58:61], v[66:69], v[218:221], v[58:61]
	v_mfma_f32_16x16x32_bf16 v[30:33], v[50:53], v[226:229], v[30:33]
	v_mfma_f32_16x16x32_bf16 v[26:29], v[66:69], v[226:229], v[26:29]
	v_mfma_f32_16x16x32_bf16 v[14:17], v[50:53], v[234:237], v[14:17]
	v_mfma_f32_16x16x32_bf16 v[10:13], v[66:69], v[234:237], v[10:13]
	v_mfma_f32_16x16x32_bf16 v[78:81], v[54:57], v[214:217], v[78:81]
	v_mfma_f32_16x16x32_bf16 v[74:77], v[70:73], v[214:217], v[74:77]
	v_mfma_f32_16x16x32_bf16 v[62:65], v[54:57], v[222:225], v[62:65]
	v_mfma_f32_16x16x32_bf16 v[58:61], v[70:73], v[222:225], v[58:61]
	v_mfma_f32_16x16x32_bf16 v[30:33], v[54:57], v[230:233], v[30:33]
	v_mfma_f32_16x16x32_bf16 v[26:29], v[70:73], v[230:233], v[26:29]
	v_mfma_f32_16x16x32_bf16 v[14:17], v[54:57], v[238:241], v[14:17]
	v_mfma_f32_16x16x32_bf16 v[10:13], v[70:73], v[238:241], v[10:13]
	v_mfma_f32_16x16x32_bf16 v[34:37], v[98:101], v[210:213], v[34:37]
	v_mfma_f32_16x16x32_bf16 v[70:73], v[102:105], v[214:217], v[34:37]
	v_mfma_f32_16x16x32_bf16 v[34:37], v[106:109], v[210:213], v[38:41]
	v_mfma_f32_16x16x32_bf16 v[66:69], v[110:113], v[214:217], v[34:37]
	v_mfma_f32_16x16x32_bf16 v[34:37], v[98:101], v[218:221], v[42:45]
	v_mfma_f32_16x16x32_bf16 v[54:57], v[102:105], v[222:225], v[34:37]
	v_mfma_f32_16x16x32_bf16 v[34:37], v[106:109], v[218:221], v[46:49]
	v_mfma_f32_16x16x32_bf16 v[22:25], v[98:101], v[226:229], v[22:25]
	v_mfma_f32_16x16x32_bf16 v[18:21], v[106:109], v[226:229], v[18:21]
	v_mfma_f32_16x16x32_bf16 v[6:9], v[98:101], v[234:237], v[6:9]
	v_mfma_f32_16x16x32_bf16 v[2:5], v[106:109], v[234:237], v[2:5]
	v_mfma_f32_16x16x32_bf16 v[50:53], v[110:113], v[222:225], v[34:37]
	v_mfma_f32_16x16x32_bf16 v[22:25], v[102:105], v[230:233], v[22:25]
	v_mfma_f32_16x16x32_bf16 v[18:21], v[110:113], v[230:233], v[18:21]
	v_mfma_f32_16x16x32_bf16 v[6:9], v[102:105], v[238:241], v[6:9]
	v_mfma_f32_16x16x32_bf16 v[2:5], v[110:113], v[238:241], v[2:5]
	s_barrier
	s_add_i32 s34, s34, 2
	s_add_u32 s24, s24, 0x100
	s_addc_u32 s25, s25, 0
	s_add_u32 s20, s20, 0x100
	s_addc_u32 s21, s21, 0
	s_cmp_lt_u32 s34, 30
	s_cbranch_scc1 .LBB0_2143
	s_setprio 0
	s_andn2_b64 vcc, exec, s[8:9]
	s_cbranch_vccnz .LBB0_2146
	s_barrier

; #define PG8_STAGE(bufoff, gbase, voff) do { _Pragma("unroll") for (int _i = 0; _i < 2; ++_i) \
;         __builtin_amdgcn_global_load_lds((const unsigned*)((const char*)(gbase) + (voff)[_i]), (LAS unsigned*)(lds + (bufoff) + ldsw + _i * 8192), 16, 0, 0); } while (0)
; #define PG8_LDA(dst, b, h) do { _Pragma("unroll") for (int m = 0; m < 4; ++m) _Pragma("unroll") for (int k = 0; k < 2; ++k) dst[m][k] = *(const LAS bf16x8*)(lds + PG8_SA(b, h) + aoff + m * 2048 + k * 1024); } while (0)
; #define PG8_LDB(dst, b, h) do { _Pragma("unroll") for (int n = 0; n < 2; ++n) _Pragma("unroll") for (int k = 0; k < 2; ++k) dst[n][k] = *(const LAS bf16x8*)(lds + PG8_SB(b, h) + boff + n * 2048 + k * 1024); } while (0)
; template <class Epi, class Sched, bool ALIGN_EPI = false, bool SP2 = false>
; __device__ __forceinline__ void gemm_phase(LAS unsigned char* lds, const Gemm g, const Sched& S, const Epi& E) {
;     ...
;         for (int t = 0; t < nt; t += 2) {
;             const bool last = (t == nt - 2);
;             const char* a1 = cA + (size_t)(t + 1) * kstep;
;             const char* a2 = last ? nA : cA + (size_t)(t + 2) * kstep; const char* b2 = last ? nB : cB + (size_t)(t + 2) * kstep;
;             const char* a3 = a2 + kstep; const char* b3 = b2 + kstep;
;             if (last && has_next) S.a_ready(nxt);
;             if constexpr (SP2) {
;             PG8_LDB(B0, 0, 0); PG8_LDB(B1, 0, 1); PG8_SCHED; PG8_LDA(At, 0, 0); PG8_STAGE(PG8_SA(1, 1), a1 + hstep, voffA);
;             PG8_WAIT_V(8); PG8_WAIT_L(0); PG8_BAR; PG8_MMA(0, 0, At, B0); PG8_MMA(0, 1, At, B1); PG8_BAR; PG8_SCHED;
;             PG8_LDA(At, 0, 1); PG8_STAGE(PG8_SB(0, 0), b2, voffB); PG8_STAGE(PG8_SB(0, 1), b2 + hstepB, voffB); PG8_STAGE(PG8_SA(0, 0), a2, voffA);
;             PG8_WAIT_V(8); PG8_WAIT_L(0); PG8_BAR; PG8_MMA(1, 0, At, B0); PG8_MMA(1, 1, At, B1); PG8_BAR; PG8_SCHED;
;             PG8_LDB(B0, 1, 0); PG8_LDB(B1, 1, 1); PG8_SCHED; PG8_LDA(At, 1, 0); PG8_STAGE(PG8_SA(0, 1), a2 + hstep, voffA);
;             PG8_WAIT_V(8); PG8_WAIT_L(0); PG8_BAR; PG8_MMA(0, 0, At, B0); PG8_MMA(0, 1, At, B1); PG8_BAR; PG8_SCHED;
;             PG8_LDA(At, 1, 1); PG8_STAGE(PG8_SB(1, 0), b3, voffB); PG8_STAGE(PG8_SB(1, 1), b3 + hstepB, voffB); PG8_STAGE(PG8_SA(1, 0), a3, voffA);
;             PG8_WAIT_V(8); PG8_WAIT_L(0); PG8_BAR; PG8_MMA(1, 0, At, B0); PG8_MMA(1, 1, At, B1); PG8_BAR; PG8_SCHED;
.Lprio_2766:
	ds_read_b128 v[50:53], v196
	ds_read_b128 v[54:57], v196 offset:1024
	ds_read_b128 v[138:141], v196 offset:2048
	ds_read_b128 v[142:145], v196 offset:3072
	ds_read_b128 v[146:149], v197
	ds_read_b128 v[150:153], v197 offset:1024
	ds_read_b128 v[174:177], v197 offset:2048
	ds_read_b128 v[178:181], v197 offset:3072
	s_add_u32 s24, s22, 0xfff80080
	s_addc_u32 s25, s23, -1
	s_cmp_eq_u32 s55, 28
	s_cselect_b32 s35, s3, s25
	s_cselect_b32 s34, s15, s24
	s_cselect_b32 s25, s13, s54
	s_cselect_b32 s24, s21, s53
	s_add_i32 m0, s28, 0xc000
	ds_read_b128 v[182:185], v198
	ds_read_b128 v[186:189], v198 offset:1024
	ds_read_b128 v[202:205], v198 offset:2048
	ds_read_b128 v[206:209], v198 offset:3072
	ds_read_b128 v[210:213], v198 offset:4096
	ds_read_b128 v[214:217], v198 offset:5120
	ds_read_b128 v[218:221], v198 offset:6144
	ds_read_b128 v[222:225], v198 offset:7168
	global_load_lds_dwordx4 v168, s[22:23]
	s_add_i32 m0, s28, 0xe000
	s_nop 0
	global_load_lds_dwordx4 v166, s[22:23]
	s_waitcnt lgkmcnt(0)
	s_barrier
	s_waitcnt lgkmcnt(0)
	v_mfma_f32_16x16x32_bf16 v[134:137], v[50:53], v[182:185], 0
	v_mfma_f32_16x16x32_bf16 v[130:133], v[138:141], v[182:185], 0
	v_mfma_f32_16x16x32_bf16 v[118:121], v[50:53], v[202:205], 0
	v_mfma_f32_16x16x32_bf16 v[114:117], v[138:141], v[202:205], 0
	v_mfma_f32_16x16x32_bf16 v[102:105], v[50:53], v[210:213], 0
	v_mfma_f32_16x16x32_bf16 v[98:101], v[138:141], v[210:213], 0
	v_mfma_f32_16x16x32_bf16 v[86:89], v[50:53], v[218:221], 0
	v_mfma_f32_16x16x32_bf16 v[82:85], v[138:141], v[218:221], 0
	v_mfma_f32_16x16x32_bf16 v[134:137], v[54:57], v[186:189], v[134:137]
	v_mfma_f32_16x16x32_bf16 v[130:133], v[142:145], v[186:189], v[130:133]
	v_mfma_f32_16x16x32_bf16 v[118:121], v[54:57], v[206:209], v[118:121]
	v_mfma_f32_16x16x32_bf16 v[114:117], v[142:145], v[206:209], v[114:117]
	v_mfma_f32_16x16x32_bf16 v[102:105], v[54:57], v[214:217], v[102:105]
	v_mfma_f32_16x16x32_bf16 v[98:101], v[142:145], v[214:217], v[98:101]
	v_mfma_f32_16x16x32_bf16 v[86:89], v[54:57], v[222:225], v[86:89]
	v_mfma_f32_16x16x32_bf16 v[82:85], v[142:145], v[222:225], v[82:85]
	v_mfma_f32_16x16x32_bf16 v[126:129], v[146:149], v[182:185], 0
	v_mfma_f32_16x16x32_bf16 v[122:125], v[174:177], v[182:185], 0
	v_mfma_f32_16x16x32_bf16 v[110:113], v[146:149], v[202:205], 0
	v_mfma_f32_16x16x32_bf16 v[106:109], v[174:177], v[202:205], 0
	v_mfma_f32_16x16x32_bf16 v[94:97], v[146:149], v[210:213], 0
	v_mfma_f32_16x16x32_bf16 v[90:93], v[174:177], v[210:213], 0
	v_mfma_f32_16x16x32_bf16 v[78:81], v[146:149], v[218:221], 0
	v_mfma_f32_16x16x32_bf16 v[74:77], v[174:177], v[218:221], 0
	v_mfma_f32_16x16x32_bf16 v[126:129], v[150:153], v[186:189], v[126:129]
	v_mfma_f32_16x16x32_bf16 v[122:125], v[178:181], v[186:189], v[122:125]
	v_mfma_f32_16x16x32_bf16 v[110:113], v[150:153], v[206:209], v[110:113]
	v_mfma_f32_16x16x32_bf16 v[106:109], v[178:181], v[206:209], v[106:109]
	v_mfma_f32_16x16x32_bf16 v[94:97], v[150:153], v[214:217], v[94:97]
	v_mfma_f32_16x16x32_bf16 v[90:93], v[178:181], v[214:217], v[90:93]
	v_mfma_f32_16x16x32_bf16 v[78:81], v[150:153], v[222:225], v[78:81]
	v_mfma_f32_16x16x32_bf16 v[74:77], v[178:181], v[222:225], v[74:77]
	s_barrier
	s_add_i32 s56, s51, s27
	v_lshl_add_u64 v[190:191], s[24:25], 0, v[156:157]
	s_mov_b32 m0, s56
	ds_read_b128 v[182:185], v198 offset:16384
	ds_read_b128 v[186:189], v198 offset:17408
	ds_read_b128 v[202:205], v198 offset:18432
	ds_read_b128 v[206:209], v198 offset:19456
	ds_read_b128 v[210:213], v198 offset:20480
	ds_read_b128 v[214:217], v198 offset:21504
	ds_read_b128 v[218:221], v198 offset:22528
	ds_read_b128 v[222:225], v198 offset:23552
	global_load_lds_dwordx4 v[190:191], off
	s_add_i32 m0, s56, 0x2000
	s_add_u32 s56, s24, 0x20000
	v_lshl_add_u64 v[226:227], s[24:25], 0, v[160:161]
	s_addc_u32 s57, s25, 0
	s_add_i32 s58, s52, s27
	global_load_lds_dwordx4 v[226:227], off
	s_mov_b32 m0, s58
	v_lshl_add_u64 v[230:231], s[34:35], 0, v[158:159]
	global_load_lds_dwordx4 v156, s[56:57]
	s_add_i32 m0, s58, 0x2000
	s_nop 0
	global_load_lds_dwordx4 v160, s[56:57]
	v_lshl_add_u64 v[228:229], s[34:35], 0, v[154:155]
	s_mov_b32 m0, s28
	s_nop 0
	global_load_lds_dwordx4 v[228:229], off
	s_mov_b32 m0, s29
	s_nop 0
	global_load_lds_dwordx4 v[230:231], off
	s_waitcnt lgkmcnt(0)
	s_barrier
	s_waitcnt lgkmcnt(0)
	v_mfma_f32_16x16x32_bf16 v[70:73], v[50:53], v[182:185], 0
	v_mfma_f32_16x16x32_bf16 v[66:69], v[138:141], v[182:185], 0
	v_mfma_f32_16x16x32_bf16 v[46:49], v[50:53], v[202:205], 0
	v_mfma_f32_16x16x32_bf16 v[42:45], v[138:141], v[202:205], 0
	v_mfma_f32_16x16x32_bf16 v[30:33], v[50:53], v[210:213], 0
	v_mfma_f32_16x16x32_bf16 v[26:29], v[138:141], v[210:213], 0
	v_mfma_f32_16x16x32_bf16 v[14:17], v[50:53], v[218:221], 0
	v_mfma_f32_16x16x32_bf16 v[10:13], v[138:141], v[218:221], 0
	v_mfma_f32_16x16x32_bf16 v[70:73], v[54:57], v[186:189], v[70:73]
	v_mfma_f32_16x16x32_bf16 v[66:69], v[142:145], v[186:189], v[66:69]
	v_mfma_f32_16x16x32_bf16 v[46:49], v[54:57], v[206:209], v[46:49]
	v_mfma_f32_16x16x32_bf16 v[42:45], v[142:145], v[206:209], v[42:45]
	v_mfma_f32_16x16x32_bf16 v[30:33], v[54:57], v[214:217], v[30:33]
	v_mfma_f32_16x16x32_bf16 v[26:29], v[142:145], v[214:217], v[26:29]
	v_mfma_f32_16x16x32_bf16 v[14:17], v[54:57], v[222:225], v[14:17]
	v_mfma_f32_16x16x32_bf16 v[10:13], v[142:145], v[222:225], v[10:13]
	v_mfma_f32_16x16x32_bf16 v[38:41], v[146:149], v[202:205], 0
	v_mfma_f32_16x16x32_bf16 v[34:37], v[174:177], v[202:205], 0
	v_mfma_f32_16x16x32_bf16 v[22:25], v[146:149], v[210:213], 0
	v_mfma_f32_16x16x32_bf16 v[18:21], v[174:177], v[210:213], 0
	v_mfma_f32_16x16x32_bf16 v[6:9], v[146:149], v[218:221], 0
	v_mfma_f32_16x16x32_bf16 v[2:5], v[174:177], v[218:221], 0
	v_mfma_f32_16x16x32_bf16 v[50:53], v[146:149], v[182:185], 0
	v_mfma_f32_16x16x32_bf16 v[54:57], v[174:177], v[182:185], 0
	v_mfma_f32_16x16x32_bf16 v[38:41], v[150:153], v[206:209], v[38:41]
	v_mfma_f32_16x16x32_bf16 v[34:37], v[178:181], v[206:209], v[34:37]
	v_mfma_f32_16x16x32_bf16 v[22:25], v[150:153], v[214:217], v[22:25]
	v_mfma_f32_16x16x32_bf16 v[18:21], v[178:181], v[214:217], v[18:21]
	v_mfma_f32_16x16x32_bf16 v[6:9], v[150:153], v[222:225], v[6:9]
	v_mfma_f32_16x16x32_bf16 v[2:5], v[178:181], v[222:225], v[2:5]
	v_mfma_f32_16x16x32_bf16 v[50:53], v[150:153], v[186:189], v[50:53]
	v_mfma_f32_16x16x32_bf16 v[54:57], v[178:181], v[186:189], v[54:57]
	s_barrier
; #define PG8_STAGE(bufoff, gbase, voff) do { _Pragma("unroll") for (int _i = 0; _i < 2; ++_i) \
;         __builtin_amdgcn_global_load_lds((const unsigned*)((const char*)(gbase) + (voff)[_i]), (LAS unsigned*)(lds + (bufoff) + ldsw + _i * 8192), 16, 0, 0); } while (0)
; #define PG8_LDA(dst, b, h) do { _Pragma("unroll") for (int m = 0; m < 4; ++m) _Pragma("unroll") for (int k = 0; k < 2; ++k) dst[m][k] = *(const LAS bf16x8*)(lds + PG8_SA(b, h) + aoff + m * 2048 + k * 1024); } while (0)
; #define PG8_LDB(dst, b, h) do { _Pragma("unroll") for (int n = 0; n < 2; ++n) _Pragma("unroll") for (int k = 0; k < 2; ++k) dst[n][k] = *(const LAS bf16x8*)(lds + PG8_SB(b, h) + boff + n * 2048 + k * 1024); } while (0)
; #define PG8_MMA(ai, bj, At, Bt) do { __builtin_amdgcn_s_setprio(1); _Pragma("unroll") for (int m = 0; m < 4; ++m) _Pragma("unroll") for (int n = 0; n < 2; ++n) _Pragma("unroll") for (int k = 0; k < 2; ++k) \
;         acc[ai][bj][m][n] = __builtin_amdgcn_mfma_f32_16x16x32_bf16(Bt[n][k], At[m][k], acc[ai][bj][m][n], 0, 0, 0); __builtin_amdgcn_s_setprio(0); } while (0)
; #define PG8_WAIT_V(n) asm volatile("s_waitcnt vmcnt(" #n ")" ::: "memory")
; #define PG8_WAIT_L(n) asm volatile("s_waitcnt lgkmcnt(" #n ")" ::: "memory")
; #define PG8_BAR __builtin_amdgcn_s_barrier()
; #define PG8_SCHED __builtin_amdgcn_sched_barrier(0)
; template <class Epi, class Sched, bool ALIGN_EPI = false, bool SP2 = false>
; __device__ __forceinline__ void gemm_phase(LAS unsigned char* lds, const Gemm g, const Sched& S, const Epi& E) {
;     ...
;             PG8_LDB(B0, 1, 0); PG8_LDB(B1, 1, 1); PG8_SCHED; PG8_LDA(At, 1, 0); PG8_STAGE(PG8_SA(0, 1), a2 + hstep, voffA);
;             PG8_WAIT_V(8); PG8_WAIT_L(0); PG8_BAR; PG8_MMA(0, 0, At, B0); PG8_MMA(0, 1, At, B1); PG8_BAR; PG8_SCHED;
;             PG8_LDA(At, 1, 1); PG8_STAGE(PG8_SB(1, 0), b3, voffB); PG8_STAGE(PG8_SB(1, 1), b3 + hstepB, voffB); PG8_STAGE(PG8_SA(1, 0), a3, voffA);
;             PG8_WAIT_V(8); PG8_WAIT_L(0); PG8_BAR; PG8_MMA(1, 0, At, B0); PG8_MMA(1, 1, At, B1); PG8_BAR; PG8_SCHED;
	s_add_i32 s56, 0, 0x18000
	s_add_i32 s57, 0, 0x1c000
	v_add_u32_e32 v142, s56, v1
	v_add_u32_e32 v162, s57, v1
	ds_read_b128 v[58:61], v142
	ds_read_b128 v[62:65], v142 offset:1024
	ds_read_b128 v[138:141], v142 offset:2048
	ds_read_b128 v[142:145], v142 offset:3072
	ds_read_b128 v[146:149], v162
	ds_read_b128 v[150:153], v162 offset:1024
	ds_read_b128 v[174:177], v162 offset:2048
	ds_read_b128 v[178:181], v162 offset:3072
	s_add_u32 s34, s34, 0x80000
	s_addc_u32 s35, s35, 0
	s_mov_b32 m0, s30
	ds_read_b128 v[182:185], v198 offset:32768
	ds_read_b128 v[186:189], v198 offset:33792
	ds_read_b128 v[202:205], v198 offset:34816
	ds_read_b128 v[206:209], v198 offset:35840
	ds_read_b128 v[210:213], v198 offset:36864
	ds_read_b128 v[214:217], v198 offset:37888
	ds_read_b128 v[218:221], v198 offset:38912
	ds_read_b128 v[222:225], v198 offset:39936
	global_load_lds_dwordx4 v154, s[34:35]
	s_mov_b32 m0, s31
	s_nop 0
	global_load_lds_dwordx4 v158, s[34:35]
	s_waitcnt vmcnt(8)
	s_waitcnt lgkmcnt(0)
	s_barrier
	s_waitcnt lgkmcnt(0)
	v_mfma_f32_16x16x32_bf16 v[134:137], v[58:61], v[182:185], v[134:137]
	v_mfma_f32_16x16x32_bf16 v[130:133], v[138:141], v[182:185], v[130:133]
	v_mfma_f32_16x16x32_bf16 v[118:121], v[58:61], v[202:205], v[118:121]
	v_mfma_f32_16x16x32_bf16 v[114:117], v[138:141], v[202:205], v[114:117]
	v_mfma_f32_16x16x32_bf16 v[102:105], v[58:61], v[210:213], v[102:105]
	v_mfma_f32_16x16x32_bf16 v[98:101], v[138:141], v[210:213], v[98:101]
	v_mfma_f32_16x16x32_bf16 v[86:89], v[58:61], v[218:221], v[86:89]
	v_mfma_f32_16x16x32_bf16 v[82:85], v[138:141], v[218:221], v[82:85]
	v_mfma_f32_16x16x32_bf16 v[134:137], v[62:65], v[186:189], v[134:137]
	v_mfma_f32_16x16x32_bf16 v[130:133], v[142:145], v[186:189], v[130:133]
	v_mfma_f32_16x16x32_bf16 v[118:121], v[62:65], v[206:209], v[118:121]
	v_mfma_f32_16x16x32_bf16 v[114:117], v[142:145], v[206:209], v[114:117]
	v_mfma_f32_16x16x32_bf16 v[102:105], v[62:65], v[214:217], v[102:105]
	v_mfma_f32_16x16x32_bf16 v[98:101], v[142:145], v[214:217], v[98:101]
	v_mfma_f32_16x16x32_bf16 v[86:89], v[62:65], v[222:225], v[86:89]
	v_mfma_f32_16x16x32_bf16 v[82:85], v[142:145], v[222:225], v[82:85]
	v_mfma_f32_16x16x32_bf16 v[126:129], v[146:149], v[182:185], v[126:129]
	v_mfma_f32_16x16x32_bf16 v[122:125], v[174:177], v[182:185], v[122:125]
	v_mfma_f32_16x16x32_bf16 v[110:113], v[146:149], v[202:205], v[110:113]
	v_mfma_f32_16x16x32_bf16 v[106:109], v[174:177], v[202:205], v[106:109]
	v_mfma_f32_16x16x32_bf16 v[94:97], v[146:149], v[210:213], v[94:97]
	v_mfma_f32_16x16x32_bf16 v[90:93], v[174:177], v[210:213], v[90:93]
	v_mfma_f32_16x16x32_bf16 v[78:81], v[146:149], v[218:221], v[78:81]
	v_mfma_f32_16x16x32_bf16 v[74:77], v[174:177], v[218:221], v[74:77]
	v_mfma_f32_16x16x32_bf16 v[126:129], v[150:153], v[186:189], v[126:129]
	v_mfma_f32_16x16x32_bf16 v[122:125], v[178:181], v[186:189], v[122:125]
	v_mfma_f32_16x16x32_bf16 v[110:113], v[150:153], v[206:209], v[110:113]
	v_mfma_f32_16x16x32_bf16 v[106:109], v[178:181], v[206:209], v[106:109]
	v_mfma_f32_16x16x32_bf16 v[94:97], v[150:153], v[214:217], v[94:97]
	v_mfma_f32_16x16x32_bf16 v[90:93], v[178:181], v[214:217], v[90:93]
	v_mfma_f32_16x16x32_bf16 v[78:81], v[150:153], v[222:225], v[78:81]
	v_mfma_f32_16x16x32_bf16 v[74:77], v[178:181], v[222:225], v[74:77]
	s_barrier
	s_add_i32 s34, s56, s27
	v_lshl_add_u64 v[190:191], v[190:191], 0, s[8:9]
	s_mov_b32 m0, s34
	ds_read_b128 v[182:185], v198 offset:49152
	ds_read_b128 v[186:189], v198 offset:50176
	ds_read_b128 v[202:205], v198 offset:51200
	ds_read_b128 v[206:209], v198 offset:52224
	ds_read_b128 v[210:213], v198 offset:53248
	ds_read_b128 v[214:217], v198 offset:54272
	ds_read_b128 v[218:221], v198 offset:55296
	ds_read_b128 v[222:225], v198 offset:56320
	global_load_lds_dwordx4 v[190:191], off
	s_add_i32 m0, s34, 0x2000
	s_add_u32 s24, s24, 0x20080
	v_lshl_add_u64 v[190:191], v[226:227], 0, s[8:9]
	s_addc_u32 s25, s25, 0
	s_add_i32 s34, s57, s27
	global_load_lds_dwordx4 v[190:191], off
	s_mov_b32 m0, s34
	s_nop 0
	global_load_lds_dwordx4 v156, s[24:25]
	s_add_i32 m0, s34, 0x2000
	s_nop 0
	global_load_lds_dwordx4 v160, s[24:25]
	v_lshl_add_u64 v[190:191], v[228:229], 0, s[8:9]
	s_mov_b32 m0, s48
	s_nop 0
	global_load_lds_dwordx4 v[190:191], off
	v_lshl_add_u64 v[190:191], v[230:231], 0, s[8:9]
	s_mov_b32 m0, s49
	s_nop 0
	global_load_lds_dwordx4 v[190:191], off
	s_waitcnt vmcnt(8)
	s_waitcnt lgkmcnt(0)
	s_barrier
	s_waitcnt lgkmcnt(0)
	v_mfma_f32_16x16x32_bf16 v[70:73], v[58:61], v[182:185], v[70:73]
	v_mfma_f32_16x16x32_bf16 v[66:69], v[138:141], v[182:185], v[66:69]
	v_mfma_f32_16x16x32_bf16 v[46:49], v[58:61], v[202:205], v[46:49]
	v_mfma_f32_16x16x32_bf16 v[42:45], v[138:141], v[202:205], v[42:45]
	v_mfma_f32_16x16x32_bf16 v[30:33], v[58:61], v[210:213], v[30:33]
	v_mfma_f32_16x16x32_bf16 v[26:29], v[138:141], v[210:213], v[26:29]
	v_mfma_f32_16x16x32_bf16 v[14:17], v[58:61], v[218:221], v[14:17]
	v_mfma_f32_16x16x32_bf16 v[10:13], v[138:141], v[218:221], v[10:13]
	v_mfma_f32_16x16x32_bf16 v[70:73], v[62:65], v[186:189], v[70:73]
	v_mfma_f32_16x16x32_bf16 v[66:69], v[142:145], v[186:189], v[66:69]
	v_mfma_f32_16x16x32_bf16 v[46:49], v[62:65], v[206:209], v[46:49]
	v_mfma_f32_16x16x32_bf16 v[42:45], v[142:145], v[206:209], v[42:45]
	v_mfma_f32_16x16x32_bf16 v[30:33], v[62:65], v[214:217], v[30:33]
	v_mfma_f32_16x16x32_bf16 v[26:29], v[142:145], v[214:217], v[26:29]
	v_mfma_f32_16x16x32_bf16 v[14:17], v[62:65], v[222:225], v[14:17]
	v_mfma_f32_16x16x32_bf16 v[10:13], v[142:145], v[222:225], v[10:13]
	v_mfma_f32_16x16x32_bf16 v[50:53], v[146:149], v[182:185], v[50:53]
	v_mfma_f32_16x16x32_bf16 v[62:65], v[150:153], v[186:189], v[50:53]
	v_mfma_f32_16x16x32_bf16 v[50:53], v[174:177], v[182:185], v[54:57]
	v_mfma_f32_16x16x32_bf16 v[38:41], v[146:149], v[202:205], v[38:41]
	v_mfma_f32_16x16x32_bf16 v[34:37], v[174:177], v[202:205], v[34:37]
	v_mfma_f32_16x16x32_bf16 v[22:25], v[146:149], v[210:213], v[22:25]
	v_mfma_f32_16x16x32_bf16 v[18:21], v[174:177], v[210:213], v[18:21]
	v_mfma_f32_16x16x32_bf16 v[6:9], v[146:149], v[218:221], v[6:9]
	v_mfma_f32_16x16x32_bf16 v[2:5], v[174:177], v[218:221], v[2:5]
	v_mfma_f32_16x16x32_bf16 v[58:61], v[178:181], v[186:189], v[50:53]
	v_mfma_f32_16x16x32_bf16 v[38:41], v[150:153], v[206:209], v[38:41]
	v_mfma_f32_16x16x32_bf16 v[34:37], v[178:181], v[206:209], v[34:37]
	v_mfma_f32_16x16x32_bf16 v[22:25], v[150:153], v[214:217], v[22:25]
	v_mfma_f32_16x16x32_bf16 v[18:21], v[178:181], v[214:217], v[18:21]
	v_mfma_f32_16x16x32_bf16 v[6:9], v[150:153], v[222:225], v[6:9]
	v_mfma_f32_16x16x32_bf16 v[2:5], v[178:181], v[222:225], v[2:5]
	s_barrier
	s_add_i32 s55, s55, 2
	s_add_u32 s53, s53, 0x100
	s_addc_u32 s54, s54, 0
	s_add_u32 s22, s22, 0x100
	s_addc_u32 s23, s23, 0
	s_cmp_lt_u32 s55, 30
; #define PG8_STAGE(bufoff, gbase, voff) do { _Pragma("unroll") for (int _i = 0; _i < 2; ++_i) \
;         __builtin_amdgcn_global_load_lds((const unsigned*)((const char*)(gbase) + (voff)[_i]), (LAS unsigned*)(lds + (bufoff) + ldsw + _i * 8192), 16, 0, 0); } while (0)
; #define PG8_LDA(dst, b, h) do { _Pragma("unroll") for (int m = 0; m < 4; ++m) _Pragma("unroll") for (int k = 0; k < 2; ++k) dst[m][k] = *(const LAS bf16x8*)(lds + PG8_SA(b, h) + aoff + m * 2048 + k * 1024); } while (0)
; #define PG8_LDB(dst, b, h) do { _Pragma("unroll") for (int n = 0; n < 2; ++n) _Pragma("unroll") for (int k = 0; k < 2; ++k) dst[n][k] = *(const LAS bf16x8*)(lds + PG8_SB(b, h) + boff + n * 2048 + k * 1024); } while (0)
; #define PG8_MMA(ai, bj, At, Bt) do { __builtin_amdgcn_s_setprio(1); _Pragma("unroll") for (int m = 0; m < 4; ++m) _Pragma("unroll") for (int n = 0; n < 2; ++n) _Pragma("unroll") for (int k = 0; k < 2; ++k) \
;         acc[ai][bj][m][n] = __builtin_amdgcn_mfma_f32_16x16x32_bf16(Bt[n][k], At[m][k], acc[ai][bj][m][n], 0, 0, 0); __builtin_amdgcn_s_setprio(0); } while (0)
; #define PG8_WAIT_V(n) asm volatile("s_waitcnt vmcnt(" #n ")" ::: "memory")
; #define PG8_WAIT_L(n) asm volatile("s_waitcnt lgkmcnt(" #n ")" ::: "memory")
; #define PG8_BAR __builtin_amdgcn_s_barrier()
; template <class Epi, class Sched, bool ALIGN_EPI = false, bool SP2 = false>
; __device__ __forceinline__ void gemm_phase(LAS unsigned char* lds, const Gemm g, const Sched& S, const Epi& E) {
;     ...
;             const bool last = (t == nt - 2);
;             const char* a1 = cA + (size_t)(t + 1) * kstep;
;             const char* a2 = last ? nA : cA + (size_t)(t + 2) * kstep; const char* b2 = last ? nB : cB + (size_t)(t + 2) * kstep;
;             const char* a3 = a2 + kstep; const char* b3 = b2 + kstep;
;             if (last && has_next) S.a_ready(nxt);
;             if constexpr (SP2) {
;             PG8_LDB(B0, 0, 0); PG8_LDB(B1, 0, 1); PG8_SCHED; PG8_LDA(At, 0, 0); PG8_STAGE(PG8_SA(1, 1), a1 + hstep, voffA);
;             PG8_WAIT_V(8); PG8_WAIT_L(0); PG8_BAR; PG8_MMA(0, 0, At, B0); PG8_MMA(0, 1, At, B1); PG8_BAR; PG8_SCHED;
;             PG8_LDA(At, 0, 1); PG8_STAGE(PG8_SB(0, 0), b2, voffB); PG8_STAGE(PG8_SB(0, 1), b2 + hstepB, voffB); PG8_STAGE(PG8_SA(0, 0), a2, voffA);
;             PG8_WAIT_V(8); PG8_WAIT_L(0); PG8_BAR; PG8_MMA(1, 0, At, B0); PG8_MMA(1, 1, At, B1); PG8_BAR; PG8_SCHED;
.LBB0_2766:
	ds_read_b128 v[50:53], v196
	ds_read_b128 v[54:57], v196 offset:1024
	ds_read_b128 v[138:141], v196 offset:2048
	ds_read_b128 v[142:145], v196 offset:3072
	ds_read_b128 v[146:149], v197
	ds_read_b128 v[150:153], v197 offset:1024
	ds_read_b128 v[174:177], v197 offset:2048
	ds_read_b128 v[178:181], v197 offset:3072
	s_add_u32 s24, s22, 0xfff80080
	s_addc_u32 s25, s23, -1
	s_cmp_eq_u32 s55, 28
	s_cselect_b32 s35, s3, s25
	s_cselect_b32 s34, s15, s24
	s_cselect_b32 s25, s13, s54
	s_cselect_b32 s24, s21, s53
	s_add_i32 m0, s28, 0xc000
	ds_read_b128 v[182:185], v198
	ds_read_b128 v[186:189], v198 offset:1024
	ds_read_b128 v[202:205], v198 offset:2048
	ds_read_b128 v[206:209], v198 offset:3072
	ds_read_b128 v[210:213], v198 offset:4096
	ds_read_b128 v[214:217], v198 offset:5120
	ds_read_b128 v[218:221], v198 offset:6144
	ds_read_b128 v[222:225], v198 offset:7168
	global_load_lds_dwordx4 v168, s[22:23]
	s_add_i32 m0, s28, 0xe000
	s_nop 0
	global_load_lds_dwordx4 v166, s[22:23]
	s_waitcnt vmcnt(8)
	s_waitcnt lgkmcnt(0)
	s_barrier
	s_waitcnt lgkmcnt(0)
	v_mfma_f32_16x16x32_bf16 v[134:137], v[50:53], v[182:185], v[134:137]
	v_mfma_f32_16x16x32_bf16 v[130:133], v[138:141], v[182:185], v[130:133]
	v_mfma_f32_16x16x32_bf16 v[118:121], v[50:53], v[202:205], v[118:121]
	v_mfma_f32_16x16x32_bf16 v[114:117], v[138:141], v[202:205], v[114:117]
	v_mfma_f32_16x16x32_bf16 v[102:105], v[50:53], v[210:213], v[102:105]
	v_mfma_f32_16x16x32_bf16 v[98:101], v[138:141], v[210:213], v[98:101]
	v_mfma_f32_16x16x32_bf16 v[86:89], v[50:53], v[218:221], v[86:89]
	v_mfma_f32_16x16x32_bf16 v[82:85], v[138:141], v[218:221], v[82:85]
	v_mfma_f32_16x16x32_bf16 v[134:137], v[54:57], v[186:189], v[134:137]
	v_mfma_f32_16x16x32_bf16 v[130:133], v[142:145], v[186:189], v[130:133]
	v_mfma_f32_16x16x32_bf16 v[118:121], v[54:57], v[206:209], v[118:121]
	v_mfma_f32_16x16x32_bf16 v[114:117], v[142:145], v[206:209], v[114:117]
	v_mfma_f32_16x16x32_bf16 v[102:105], v[54:57], v[214:217], v[102:105]
	v_mfma_f32_16x16x32_bf16 v[98:101], v[142:145], v[214:217], v[98:101]
	v_mfma_f32_16x16x32_bf16 v[86:89], v[54:57], v[222:225], v[86:89]
	v_mfma_f32_16x16x32_bf16 v[82:85], v[142:145], v[222:225], v[82:85]
	v_mfma_f32_16x16x32_bf16 v[126:129], v[146:149], v[182:185], v[126:129]
	v_mfma_f32_16x16x32_bf16 v[122:125], v[174:177], v[182:185], v[122:125]
	v_mfma_f32_16x16x32_bf16 v[110:113], v[146:149], v[202:205], v[110:113]
	v_mfma_f32_16x16x32_bf16 v[106:109], v[174:177], v[202:205], v[106:109]
	v_mfma_f32_16x16x32_bf16 v[94:97], v[146:149], v[210:213], v[94:97]
	v_mfma_f32_16x16x32_bf16 v[90:93], v[174:177], v[210:213], v[90:93]
	v_mfma_f32_16x16x32_bf16 v[78:81], v[146:149], v[218:221], v[78:81]
	v_mfma_f32_16x16x32_bf16 v[74:77], v[174:177], v[218:221], v[74:77]
	v_mfma_f32_16x16x32_bf16 v[126:129], v[150:153], v[186:189], v[126:129]
	v_mfma_f32_16x16x32_bf16 v[122:125], v[178:181], v[186:189], v[122:125]
	v_mfma_f32_16x16x32_bf16 v[110:113], v[150:153], v[206:209], v[110:113]
	v_mfma_f32_16x16x32_bf16 v[106:109], v[178:181], v[206:209], v[106:109]
	v_mfma_f32_16x16x32_bf16 v[94:97], v[150:153], v[214:217], v[94:97]
	v_mfma_f32_16x16x32_bf16 v[90:93], v[178:181], v[214:217], v[90:93]
	v_mfma_f32_16x16x32_bf16 v[78:81], v[150:153], v[222:225], v[78:81]
	v_mfma_f32_16x16x32_bf16 v[74:77], v[178:181], v[222:225], v[74:77]
	s_barrier
	s_add_i32 s56, s51, s27
	v_lshl_add_u64 v[190:191], s[24:25], 0, v[156:157]
	s_mov_b32 m0, s56
	ds_read_b128 v[182:185], v198 offset:16384
	ds_read_b128 v[186:189], v198 offset:17408
	ds_read_b128 v[202:205], v198 offset:18432
	ds_read_b128 v[206:209], v198 offset:19456
	ds_read_b128 v[210:213], v198 offset:20480
	ds_read_b128 v[214:217], v198 offset:21504
	ds_read_b128 v[218:221], v198 offset:22528
	ds_read_b128 v[222:225], v198 offset:23552
	global_load_lds_dwordx4 v[190:191], off
	s_add_i32 m0, s56, 0x2000
	s_add_u32 s56, s24, 0x20000
	v_lshl_add_u64 v[226:227], s[24:25], 0, v[160:161]
	s_addc_u32 s57, s25, 0
	s_add_i32 s58, s52, s27
	global_load_lds_dwordx4 v[226:227], off
	s_mov_b32 m0, s58
	v_lshl_add_u64 v[230:231], s[34:35], 0, v[158:159]
	global_load_lds_dwordx4 v156, s[56:57]
	s_add_i32 m0, s58, 0x2000
	s_nop 0
	global_load_lds_dwordx4 v160, s[56:57]
	v_lshl_add_u64 v[228:229], s[34:35], 0, v[154:155]
	s_mov_b32 m0, s28
	s_nop 0
	global_load_lds_dwordx4 v[228:229], off
	s_mov_b32 m0, s29
	s_nop 0
	global_load_lds_dwordx4 v[230:231], off
	s_waitcnt vmcnt(8)
	s_waitcnt lgkmcnt(0)
	s_barrier
	s_waitcnt lgkmcnt(0)
	v_mfma_f32_16x16x32_bf16 v[70:73], v[50:53], v[182:185], v[70:73]
	v_mfma_f32_16x16x32_bf16 v[66:69], v[138:141], v[182:185], v[66:69]
	v_mfma_f32_16x16x32_bf16 v[46:49], v[50:53], v[202:205], v[46:49]
	v_mfma_f32_16x16x32_bf16 v[42:45], v[138:141], v[202:205], v[42:45]
	v_mfma_f32_16x16x32_bf16 v[30:33], v[50:53], v[210:213], v[30:33]
	v_mfma_f32_16x16x32_bf16 v[26:29], v[138:141], v[210:213], v[26:29]
	v_mfma_f32_16x16x32_bf16 v[14:17], v[50:53], v[218:221], v[14:17]
	v_mfma_f32_16x16x32_bf16 v[10:13], v[138:141], v[218:221], v[10:13]
	v_mfma_f32_16x16x32_bf16 v[70:73], v[54:57], v[186:189], v[70:73]
	v_mfma_f32_16x16x32_bf16 v[66:69], v[142:145], v[186:189], v[66:69]
	v_mfma_f32_16x16x32_bf16 v[46:49], v[54:57], v[206:209], v[46:49]
	v_mfma_f32_16x16x32_bf16 v[42:45], v[142:145], v[206:209], v[42:45]
	v_mfma_f32_16x16x32_bf16 v[30:33], v[54:57], v[214:217], v[30:33]
	v_mfma_f32_16x16x32_bf16 v[26:29], v[142:145], v[214:217], v[26:29]
	v_mfma_f32_16x16x32_bf16 v[14:17], v[54:57], v[222:225], v[14:17]
	v_mfma_f32_16x16x32_bf16 v[10:13], v[142:145], v[222:225], v[10:13]
	v_mfma_f32_16x16x32_bf16 v[38:41], v[146:149], v[202:205], v[38:41]
	v_mfma_f32_16x16x32_bf16 v[34:37], v[174:177], v[202:205], v[34:37]
	v_mfma_f32_16x16x32_bf16 v[22:25], v[146:149], v[210:213], v[22:25]
	v_mfma_f32_16x16x32_bf16 v[18:21], v[174:177], v[210:213], v[18:21]
	v_mfma_f32_16x16x32_bf16 v[6:9], v[146:149], v[218:221], v[6:9]
	v_mfma_f32_16x16x32_bf16 v[2:5], v[174:177], v[218:221], v[2:5]
	v_mfma_f32_16x16x32_bf16 v[50:53], v[146:149], v[182:185], v[62:65]
	v_mfma_f32_16x16x32_bf16 v[54:57], v[174:177], v[182:185], v[58:61]
	v_mfma_f32_16x16x32_bf16 v[38:41], v[150:153], v[206:209], v[38:41]
	v_mfma_f32_16x16x32_bf16 v[34:37], v[178:181], v[206:209], v[34:37]
	v_mfma_f32_16x16x32_bf16 v[22:25], v[150:153], v[214:217], v[22:25]
	v_mfma_f32_16x16x32_bf16 v[18:21], v[178:181], v[214:217], v[18:21]
	v_mfma_f32_16x16x32_bf16 v[6:9], v[150:153], v[222:225], v[6:9]
	v_mfma_f32_16x16x32_bf16 v[2:5], v[178:181], v[222:225], v[2:5]
	v_mfma_f32_16x16x32_bf16 v[50:53], v[150:153], v[186:189], v[50:53]
	v_mfma_f32_16x16x32_bf16 v[54:57], v[178:181], v[186:189], v[54:57]
	s_barrier
; #define PG8_STAGE(bufoff, gbase, voff) do { _Pragma("unroll") for (int _i = 0; _i < 2; ++_i) \
;         __builtin_amdgcn_global_load_lds((const unsigned*)((const char*)(gbase) + (voff)[_i]), (LAS unsigned*)(lds + (bufoff) + ldsw + _i * 8192), 16, 0, 0); } while (0)
; #define PG8_LDA(dst, b, h) do { _Pragma("unroll") for (int m = 0; m < 4; ++m) _Pragma("unroll") for (int k = 0; k < 2; ++k) dst[m][k] = *(const LAS bf16x8*)(lds + PG8_SA(b, h) + aoff + m * 2048 + k * 1024); } while (0)
; #define PG8_LDB(dst, b, h) do { _Pragma("unroll") for (int n = 0; n < 2; ++n) _Pragma("unroll") for (int k = 0; k < 2; ++k) dst[n][k] = *(const LAS bf16x8*)(lds + PG8_SB(b, h) + boff + n * 2048 + k * 1024); } while (0)
; #define PG8_MMA(ai, bj, At, Bt) do { __builtin_amdgcn_s_setprio(1); _Pragma("unroll") for (int m = 0; m < 4; ++m) _Pragma("unroll") for (int n = 0; n < 2; ++n) _Pragma("unroll") for (int k = 0; k < 2; ++k) \
;         acc[ai][bj][m][n] = __builtin_amdgcn_mfma_f32_16x16x32_bf16(Bt[n][k], At[m][k], acc[ai][bj][m][n], 0, 0, 0); __builtin_amdgcn_s_setprio(0); } while (0)
; #define PG8_WAIT_V(n) asm volatile("s_waitcnt vmcnt(" #n ")" ::: "memory")
; #define PG8_WAIT_L(n) asm volatile("s_waitcnt lgkmcnt(" #n ")" ::: "memory")
; #define PG8_BAR __builtin_amdgcn_s_barrier()
; #define PG8_SCHED __builtin_amdgcn_sched_barrier(0)
; template <class Epi, class Sched, bool ALIGN_EPI = false, bool SP2 = false>
; __device__ __forceinline__ void gemm_phase(LAS unsigned char* lds, const Gemm g, const Sched& S, const Epi& E) {
;     ...
;             PG8_LDB(B0, 1, 0); PG8_LDB(B1, 1, 1); PG8_SCHED; PG8_LDA(At, 1, 0); PG8_STAGE(PG8_SA(0, 1), a2 + hstep, voffA);
;             PG8_WAIT_V(8); PG8_WAIT_L(0); PG8_BAR; PG8_MMA(0, 0, At, B0); PG8_MMA(0, 1, At, B1); PG8_BAR; PG8_SCHED;
;             PG8_LDA(At, 1, 1); PG8_STAGE(PG8_SB(1, 0), b3, voffB); PG8_STAGE(PG8_SB(1, 1), b3 + hstepB, voffB); PG8_STAGE(PG8_SA(1, 0), a3, voffA);
;             PG8_WAIT_V(8); PG8_WAIT_L(0); PG8_BAR; PG8_MMA(1, 0, At, B0); PG8_MMA(1, 1, At, B1); PG8_BAR; PG8_SCHED;
	s_add_i32 s56, 0, 0x18000
	s_add_i32 s57, 0, 0x1c000
	v_add_u32_e32 v142, s56, v1
	v_add_u32_e32 v162, s57, v1
	ds_read_b128 v[58:61], v142
	ds_read_b128 v[62:65], v142 offset:1024
	ds_read_b128 v[138:141], v142 offset:2048
	ds_read_b128 v[142:145], v142 offset:3072
	ds_read_b128 v[146:149], v162
	ds_read_b128 v[150:153], v162 offset:1024
	ds_read_b128 v[174:177], v162 offset:2048
	ds_read_b128 v[178:181], v162 offset:3072
	s_add_u32 s34, s34, 0x80000
	s_addc_u32 s35, s35, 0
	s_mov_b32 m0, s30
	ds_read_b128 v[182:185], v198 offset:32768
	ds_read_b128 v[186:189], v198 offset:33792
	ds_read_b128 v[202:205], v198 offset:34816
	ds_read_b128 v[206:209], v198 offset:35840
	ds_read_b128 v[210:213], v198 offset:36864
	ds_read_b128 v[214:217], v198 offset:37888
	ds_read_b128 v[218:221], v198 offset:38912
	ds_read_b128 v[222:225], v198 offset:39936
	global_load_lds_dwordx4 v154, s[34:35]
	s_mov_b32 m0, s31
	s_nop 0
	global_load_lds_dwordx4 v158, s[34:35]
	s_waitcnt vmcnt(8)
	s_waitcnt lgkmcnt(0)
	s_barrier
	s_waitcnt lgkmcnt(0)
	v_mfma_f32_16x16x32_bf16 v[134:137], v[58:61], v[182:185], v[134:137]
	v_mfma_f32_16x16x32_bf16 v[130:133], v[138:141], v[182:185], v[130:133]
	v_mfma_f32_16x16x32_bf16 v[118:121], v[58:61], v[202:205], v[118:121]
	v_mfma_f32_16x16x32_bf16 v[114:117], v[138:141], v[202:205], v[114:117]
	v_mfma_f32_16x16x32_bf16 v[102:105], v[58:61], v[210:213], v[102:105]
	v_mfma_f32_16x16x32_bf16 v[98:101], v[138:141], v[210:213], v[98:101]
	v_mfma_f32_16x16x32_bf16 v[86:89], v[58:61], v[218:221], v[86:89]
	v_mfma_f32_16x16x32_bf16 v[82:85], v[138:141], v[218:221], v[82:85]
	v_mfma_f32_16x16x32_bf16 v[134:137], v[62:65], v[186:189], v[134:137]
	v_mfma_f32_16x16x32_bf16 v[130:133], v[142:145], v[186:189], v[130:133]
	v_mfma_f32_16x16x32_bf16 v[118:121], v[62:65], v[206:209], v[118:121]
	v_mfma_f32_16x16x32_bf16 v[114:117], v[142:145], v[206:209], v[114:117]
	v_mfma_f32_16x16x32_bf16 v[102:105], v[62:65], v[214:217], v[102:105]
	v_mfma_f32_16x16x32_bf16 v[98:101], v[142:145], v[214:217], v[98:101]
	v_mfma_f32_16x16x32_bf16 v[86:89], v[62:65], v[222:225], v[86:89]
	v_mfma_f32_16x16x32_bf16 v[82:85], v[142:145], v[222:225], v[82:85]
	v_mfma_f32_16x16x32_bf16 v[126:129], v[146:149], v[182:185], v[126:129]
	v_mfma_f32_16x16x32_bf16 v[122:125], v[174:177], v[182:185], v[122:125]
	v_mfma_f32_16x16x32_bf16 v[110:113], v[146:149], v[202:205], v[110:113]
	v_mfma_f32_16x16x32_bf16 v[106:109], v[174:177], v[202:205], v[106:109]
	v_mfma_f32_16x16x32_bf16 v[94:97], v[146:149], v[210:213], v[94:97]
	v_mfma_f32_16x16x32_bf16 v[90:93], v[174:177], v[210:213], v[90:93]
	v_mfma_f32_16x16x32_bf16 v[78:81], v[146:149], v[218:221], v[78:81]
	v_mfma_f32_16x16x32_bf16 v[74:77], v[174:177], v[218:221], v[74:77]
	v_mfma_f32_16x16x32_bf16 v[126:129], v[150:153], v[186:189], v[126:129]
	v_mfma_f32_16x16x32_bf16 v[122:125], v[178:181], v[186:189], v[122:125]
	v_mfma_f32_16x16x32_bf16 v[110:113], v[150:153], v[206:209], v[110:113]
	v_mfma_f32_16x16x32_bf16 v[106:109], v[178:181], v[206:209], v[106:109]
	v_mfma_f32_16x16x32_bf16 v[94:97], v[150:153], v[214:217], v[94:97]
	v_mfma_f32_16x16x32_bf16 v[90:93], v[178:181], v[214:217], v[90:93]
	v_mfma_f32_16x16x32_bf16 v[78:81], v[150:153], v[222:225], v[78:81]
	v_mfma_f32_16x16x32_bf16 v[74:77], v[178:181], v[222:225], v[74:77]
	s_barrier
	s_add_i32 s34, s56, s27
	v_lshl_add_u64 v[190:191], v[190:191], 0, s[8:9]
	s_mov_b32 m0, s34
	ds_read_b128 v[182:185], v198 offset:49152
	ds_read_b128 v[186:189], v198 offset:50176
	ds_read_b128 v[202:205], v198 offset:51200
	ds_read_b128 v[206:209], v198 offset:52224
	ds_read_b128 v[210:213], v198 offset:53248
	ds_read_b128 v[214:217], v198 offset:54272
	ds_read_b128 v[218:221], v198 offset:55296
	ds_read_b128 v[222:225], v198 offset:56320
	global_load_lds_dwordx4 v[190:191], off
	s_add_i32 m0, s34, 0x2000
	s_add_u32 s24, s24, 0x20080
	v_lshl_add_u64 v[190:191], v[226:227], 0, s[8:9]
	s_addc_u32 s25, s25, 0
	s_add_i32 s34, s57, s27
	global_load_lds_dwordx4 v[190:191], off
	s_mov_b32 m0, s34
	s_nop 0
	global_load_lds_dwordx4 v156, s[24:25]
	s_add_i32 m0, s34, 0x2000
	s_nop 0
	global_load_lds_dwordx4 v160, s[24:25]
	v_lshl_add_u64 v[190:191], v[228:229], 0, s[8:9]
	s_mov_b32 m0, s48
	s_nop 0
	global_load_lds_dwordx4 v[190:191], off
	v_lshl_add_u64 v[190:191], v[230:231], 0, s[8:9]
	s_mov_b32 m0, s49
	s_nop 0
	global_load_lds_dwordx4 v[190:191], off
	s_waitcnt vmcnt(8)
	s_waitcnt lgkmcnt(0)
	s_barrier
	s_waitcnt lgkmcnt(0)
	v_mfma_f32_16x16x32_bf16 v[70:73], v[58:61], v[182:185], v[70:73]
	v_mfma_f32_16x16x32_bf16 v[66:69], v[138:141], v[182:185], v[66:69]
	v_mfma_f32_16x16x32_bf16 v[46:49], v[58:61], v[202:205], v[46:49]
	v_mfma_f32_16x16x32_bf16 v[42:45], v[138:141], v[202:205], v[42:45]
	v_mfma_f32_16x16x32_bf16 v[30:33], v[58:61], v[210:213], v[30:33]
	v_mfma_f32_16x16x32_bf16 v[26:29], v[138:141], v[210:213], v[26:29]
	v_mfma_f32_16x16x32_bf16 v[14:17], v[58:61], v[218:221], v[14:17]
	v_mfma_f32_16x16x32_bf16 v[10:13], v[138:141], v[218:221], v[10:13]
	v_mfma_f32_16x16x32_bf16 v[70:73], v[62:65], v[186:189], v[70:73]
	v_mfma_f32_16x16x32_bf16 v[66:69], v[142:145], v[186:189], v[66:69]
	v_mfma_f32_16x16x32_bf16 v[46:49], v[62:65], v[206:209], v[46:49]
	v_mfma_f32_16x16x32_bf16 v[42:45], v[142:145], v[206:209], v[42:45]
	v_mfma_f32_16x16x32_bf16 v[30:33], v[62:65], v[214:217], v[30:33]
	v_mfma_f32_16x16x32_bf16 v[26:29], v[142:145], v[214:217], v[26:29]
	v_mfma_f32_16x16x32_bf16 v[14:17], v[62:65], v[222:225], v[14:17]
	v_mfma_f32_16x16x32_bf16 v[10:13], v[142:145], v[222:225], v[10:13]
	v_mfma_f32_16x16x32_bf16 v[50:53], v[146:149], v[182:185], v[50:53]
	v_mfma_f32_16x16x32_bf16 v[62:65], v[150:153], v[186:189], v[50:53]
	v_mfma_f32_16x16x32_bf16 v[50:53], v[174:177], v[182:185], v[54:57]
	v_mfma_f32_16x16x32_bf16 v[38:41], v[146:149], v[202:205], v[38:41]
	v_mfma_f32_16x16x32_bf16 v[34:37], v[174:177], v[202:205], v[34:37]
	v_mfma_f32_16x16x32_bf16 v[22:25], v[146:149], v[210:213], v[22:25]
	v_mfma_f32_16x16x32_bf16 v[18:21], v[174:177], v[210:213], v[18:21]
	v_mfma_f32_16x16x32_bf16 v[6:9], v[146:149], v[218:221], v[6:9]
	v_mfma_f32_16x16x32_bf16 v[2:5], v[174:177], v[218:221], v[2:5]
	v_mfma_f32_16x16x32_bf16 v[58:61], v[178:181], v[186:189], v[50:53]
	v_mfma_f32_16x16x32_bf16 v[38:41], v[150:153], v[206:209], v[38:41]
	v_mfma_f32_16x16x32_bf16 v[34:37], v[178:181], v[206:209], v[34:37]
	v_mfma_f32_16x16x32_bf16 v[22:25], v[150:153], v[214:217], v[22:25]
	v_mfma_f32_16x16x32_bf16 v[18:21], v[178:181], v[214:217], v[18:21]
	v_mfma_f32_16x16x32_bf16 v[6:9], v[150:153], v[222:225], v[6:9]
	v_mfma_f32_16x16x32_bf16 v[2:5], v[178:181], v[222:225], v[2:5]
	s_barrier
	s_add_i32 s55, s55, 2
	s_add_u32 s53, s53, 0x100
	s_addc_u32 s54, s54, 0
	s_add_u32 s22, s22, 0x100
	s_addc_u32 s23, s23, 0
	s_cmp_lt_u32 s55, 30
	s_cbranch_scc1 .LBB0_2766
	s_setprio 0
	s_andn2_b64 vcc, exec, s[10:11]
	s_cbranch_vccnz .LBB0_2769
	s_barrier

; #define PG8_STAGE(bufoff, gbase, voff) do { _Pragma("unroll") for (int _i = 0; _i < 2; ++_i) \
;         __builtin_amdgcn_global_load_lds((const unsigned*)((const char*)(gbase) + (voff)[_i]), (LAS unsigned*)(lds + (bufoff) + ldsw + _i * 8192), 16, 0, 0); } while (0)
; #define PG8_LDA(dst, b, h) do { _Pragma("unroll") for (int m = 0; m < 4; ++m) _Pragma("unroll") for (int k = 0; k < 2; ++k) dst[m][k] = *(const LAS bf16x8*)(lds + PG8_SA(b, h) + aoff + m * 2048 + k * 1024); } while (0)
; #define PG8_LDB(dst, b, h) do { _Pragma("unroll") for (int n = 0; n < 2; ++n) _Pragma("unroll") for (int k = 0; k < 2; ++k) dst[n][k] = *(const LAS bf16x8*)(lds + PG8_SB(b, h) + boff + n * 2048 + k * 1024); } while (0)
; #define PG8_MMA(ai, bj, At, Bt) do { __builtin_amdgcn_s_setprio(1); _Pragma("unroll") for (int m = 0; m < 4; ++m) _Pragma("unroll") for (int n = 0; n < 2; ++n) _Pragma("unroll") for (int k = 0; k < 2; ++k) \
;         acc[ai][bj][m][n] = __builtin_amdgcn_mfma_f32_16x16x32_bf16(Bt[n][k], At[m][k], acc[ai][bj][m][n], 0, 0, 0); __builtin_amdgcn_s_setprio(0); } while (0)
; #define PG8_WAIT_V(n) asm volatile("s_waitcnt vmcnt(" #n ")" ::: "memory")
; #define PG8_WAIT_L(n) asm volatile("s_waitcnt lgkmcnt(" #n ")" ::: "memory")
; #define PG8_BAR __builtin_amdgcn_s_barrier()
; template <class Epi, class Sched, bool ALIGN_EPI = false, bool SP2 = false>
; __device__ __forceinline__ void gemm_phase(LAS unsigned char* lds, const Gemm g, const Sched& S, const Epi& E) {
;     ...
;             const bool last = (t == nt - 2);
;             const char* a1 = cA + (size_t)(t + 1) * kstep;
;             const char* a2 = last ? nA : cA + (size_t)(t + 2) * kstep; const char* b2 = last ? nB : cB + (size_t)(t + 2) * kstep;
;             const char* a3 = a2 + kstep; const char* b3 = b2 + kstep;
;             if (last && has_next) S.a_ready(nxt);
;             if constexpr (SP2) {
;             PG8_LDB(B0, 0, 0); PG8_LDB(B1, 0, 1); PG8_SCHED; PG8_LDA(At, 0, 0); PG8_STAGE(PG8_SA(1, 1), a1 + hstep, voffA);
;             PG8_WAIT_V(8); PG8_WAIT_L(0); PG8_BAR; PG8_MMA(0, 0, At, B0); PG8_MMA(0, 1, At, B1); PG8_BAR; PG8_SCHED;
;             PG8_LDA(At, 0, 1); PG8_STAGE(PG8_SB(0, 0), b2, voffB); PG8_STAGE(PG8_SB(0, 1), b2 + hstepB, voffB); PG8_STAGE(PG8_SA(0, 0), a2, voffA);
;             PG8_WAIT_V(8); PG8_WAIT_L(0); PG8_BAR; PG8_MMA(1, 0, At, B0); PG8_MMA(1, 1, At, B1); PG8_BAR; PG8_SCHED;
.Lprio_2916:
	ds_read_b128 v[66:69], v173
	ds_read_b128 v[70:73], v173 offset:1024
	ds_read_b128 v[74:77], v173 offset:2048
	ds_read_b128 v[78:81], v173 offset:3072
	ds_read_b128 v[162:165], v174
	ds_read_b128 v[180:183], v174 offset:1024
	ds_read_b128 v[184:187], v174 offset:2048
	ds_read_b128 v[188:191], v174 offset:3072
	s_add_u32 s20, s18, 0xfff80080
	s_addc_u32 s21, s19, -1
	s_cmp_eq_u32 s50, 28
	s_cselect_b32 s23, s13, s21
	s_cselect_b32 s22, s46, s20
	s_cselect_b32 s21, s11, s49
	s_cselect_b32 s20, s47, s48
	s_add_i32 m0, s28, 0xc000
	ds_read_b128 v[192:195], v175
	ds_read_b128 v[196:199], v175 offset:1024
	ds_read_b128 v[200:203], v175 offset:2048
	ds_read_b128 v[204:207], v175 offset:3072
	ds_read_b128 v[208:211], v175 offset:4096
	ds_read_b128 v[212:215], v175 offset:5120
	ds_read_b128 v[216:219], v175 offset:6144
	ds_read_b128 v[220:223], v175 offset:7168
	global_load_lds_dwordx4 v156, s[18:19]
	s_add_i32 m0, s28, 0xe000
	s_nop 0
	global_load_lds_dwordx4 v154, s[18:19]
	s_waitcnt lgkmcnt(0)
	s_barrier
	s_waitcnt lgkmcnt(0)
	v_mfma_f32_16x16x32_bf16 v[142:145], v[66:69], v[192:195], 0
	v_mfma_f32_16x16x32_bf16 v[138:141], v[74:77], v[192:195], 0
	v_mfma_f32_16x16x32_bf16 v[126:129], v[66:69], v[200:203], 0
	v_mfma_f32_16x16x32_bf16 v[122:125], v[74:77], v[200:203], 0
	v_mfma_f32_16x16x32_bf16 v[110:113], v[66:69], v[208:211], 0
	v_mfma_f32_16x16x32_bf16 v[106:109], v[74:77], v[208:211], 0
	v_mfma_f32_16x16x32_bf16 v[94:97], v[66:69], v[216:219], 0
	v_mfma_f32_16x16x32_bf16 v[90:93], v[74:77], v[216:219], 0
	v_mfma_f32_16x16x32_bf16 v[142:145], v[70:73], v[196:199], v[142:145]
	v_mfma_f32_16x16x32_bf16 v[138:141], v[78:81], v[196:199], v[138:141]
	v_mfma_f32_16x16x32_bf16 v[126:129], v[70:73], v[204:207], v[126:129]
	v_mfma_f32_16x16x32_bf16 v[122:125], v[78:81], v[204:207], v[122:125]
	v_mfma_f32_16x16x32_bf16 v[110:113], v[70:73], v[212:215], v[110:113]
	v_mfma_f32_16x16x32_bf16 v[106:109], v[78:81], v[212:215], v[106:109]
	v_mfma_f32_16x16x32_bf16 v[94:97], v[70:73], v[220:223], v[94:97]
	v_mfma_f32_16x16x32_bf16 v[90:93], v[78:81], v[220:223], v[90:93]
	v_mfma_f32_16x16x32_bf16 v[134:137], v[162:165], v[192:195], 0
	v_mfma_f32_16x16x32_bf16 v[130:133], v[184:187], v[192:195], 0
	v_mfma_f32_16x16x32_bf16 v[118:121], v[162:165], v[200:203], 0
	v_mfma_f32_16x16x32_bf16 v[114:117], v[184:187], v[200:203], 0
	v_mfma_f32_16x16x32_bf16 v[102:105], v[162:165], v[208:211], 0
	v_mfma_f32_16x16x32_bf16 v[98:101], v[184:187], v[208:211], 0
	v_mfma_f32_16x16x32_bf16 v[86:89], v[162:165], v[216:219], 0
	v_mfma_f32_16x16x32_bf16 v[82:85], v[184:187], v[216:219], 0
	v_mfma_f32_16x16x32_bf16 v[134:137], v[180:183], v[196:199], v[134:137]
	v_mfma_f32_16x16x32_bf16 v[130:133], v[188:191], v[196:199], v[130:133]
	v_mfma_f32_16x16x32_bf16 v[118:121], v[180:183], v[204:207], v[118:121]
	v_mfma_f32_16x16x32_bf16 v[114:117], v[188:191], v[204:207], v[114:117]
	v_mfma_f32_16x16x32_bf16 v[102:105], v[180:183], v[212:215], v[102:105]
	v_mfma_f32_16x16x32_bf16 v[98:101], v[188:191], v[212:215], v[98:101]
	v_mfma_f32_16x16x32_bf16 v[86:89], v[180:183], v[220:223], v[86:89]
	v_mfma_f32_16x16x32_bf16 v[82:85], v[188:191], v[220:223], v[82:85]
	s_barrier
	s_add_i32 s51, s41, s25
	v_lshl_add_u64 v[166:167], s[20:21], 0, v[150:151]
	s_mov_b32 m0, s51
	ds_read_b128 v[192:195], v175 offset:16384
	ds_read_b128 v[196:199], v175 offset:17408
	ds_read_b128 v[200:203], v175 offset:18432
	ds_read_b128 v[204:207], v175 offset:19456
	ds_read_b128 v[208:211], v175 offset:20480
	ds_read_b128 v[212:215], v175 offset:21504
	ds_read_b128 v[216:219], v175 offset:22528
	ds_read_b128 v[220:223], v175 offset:23552
	global_load_lds_dwordx4 v[166:167], off
	s_add_i32 m0, s51, 0x2000
	s_add_u32 s52, s20, 0x80000
	v_lshl_add_u64 v[224:225], s[20:21], 0, v[146:147]
	s_addc_u32 s53, s21, 0
	s_add_i32 s51, s42, s25
	global_load_lds_dwordx4 v[224:225], off
	s_mov_b32 m0, s51
	v_lshl_add_u64 v[228:229], s[22:23], 0, v[148:149]
	global_load_lds_dwordx4 v150, s[52:53]
	s_add_i32 m0, s51, 0x2000
	s_nop 0
	global_load_lds_dwordx4 v146, s[52:53]
	v_lshl_add_u64 v[226:227], s[22:23], 0, v[152:153]
	s_mov_b32 m0, s28
	s_nop 0
	global_load_lds_dwordx4 v[226:227], off
	s_mov_b32 m0, s29
	s_nop 0
	global_load_lds_dwordx4 v[228:229], off
	s_waitcnt lgkmcnt(0)
	s_barrier
	s_waitcnt lgkmcnt(0)
	v_mfma_f32_16x16x32_bf16 v[62:65], v[66:69], v[192:195], 0
	v_mfma_f32_16x16x32_bf16 v[58:61], v[74:77], v[192:195], 0
	v_mfma_f32_16x16x32_bf16 v[46:49], v[66:69], v[200:203], 0
	v_mfma_f32_16x16x32_bf16 v[42:45], v[74:77], v[200:203], 0
	v_mfma_f32_16x16x32_bf16 v[30:33], v[66:69], v[208:211], 0
	v_mfma_f32_16x16x32_bf16 v[26:29], v[74:77], v[208:211], 0
	v_mfma_f32_16x16x32_bf16 v[14:17], v[66:69], v[216:219], 0
	v_mfma_f32_16x16x32_bf16 v[10:13], v[74:77], v[216:219], 0
	v_mfma_f32_16x16x32_bf16 v[62:65], v[70:73], v[196:199], v[62:65]
	v_mfma_f32_16x16x32_bf16 v[58:61], v[78:81], v[196:199], v[58:61]
	v_mfma_f32_16x16x32_bf16 v[46:49], v[70:73], v[204:207], v[46:49]
	v_mfma_f32_16x16x32_bf16 v[42:45], v[78:81], v[204:207], v[42:45]
	v_mfma_f32_16x16x32_bf16 v[30:33], v[70:73], v[212:215], v[30:33]
	v_mfma_f32_16x16x32_bf16 v[26:29], v[78:81], v[212:215], v[26:29]
	v_mfma_f32_16x16x32_bf16 v[14:17], v[70:73], v[220:223], v[14:17]
	v_mfma_f32_16x16x32_bf16 v[10:13], v[78:81], v[220:223], v[10:13]
	v_mfma_f32_16x16x32_bf16 v[54:57], v[162:165], v[192:195], 0
	v_mfma_f32_16x16x32_bf16 v[50:53], v[184:187], v[192:195], 0
	v_mfma_f32_16x16x32_bf16 v[38:41], v[162:165], v[200:203], 0
	v_mfma_f32_16x16x32_bf16 v[34:37], v[184:187], v[200:203], 0
	v_mfma_f32_16x16x32_bf16 v[22:25], v[162:165], v[208:211], 0
	v_mfma_f32_16x16x32_bf16 v[18:21], v[184:187], v[208:211], 0
	v_mfma_f32_16x16x32_bf16 v[6:9], v[162:165], v[216:219], 0
	v_mfma_f32_16x16x32_bf16 v[2:5], v[184:187], v[216:219], 0
	v_mfma_f32_16x16x32_bf16 v[54:57], v[180:183], v[196:199], v[54:57]
	v_mfma_f32_16x16x32_bf16 v[50:53], v[188:191], v[196:199], v[50:53]
	v_mfma_f32_16x16x32_bf16 v[38:41], v[180:183], v[204:207], v[38:41]
	v_mfma_f32_16x16x32_bf16 v[34:37], v[188:191], v[204:207], v[34:37]
	v_mfma_f32_16x16x32_bf16 v[22:25], v[180:183], v[212:215], v[22:25]
	v_mfma_f32_16x16x32_bf16 v[18:21], v[188:191], v[212:215], v[18:21]
	v_mfma_f32_16x16x32_bf16 v[6:9], v[180:183], v[220:223], v[6:9]
	v_mfma_f32_16x16x32_bf16 v[2:5], v[188:191], v[220:223], v[2:5]
	s_barrier
; #define PG8_STAGE(bufoff, gbase, voff) do { _Pragma("unroll") for (int _i = 0; _i < 2; ++_i) \
;         __builtin_amdgcn_global_load_lds((const unsigned*)((const char*)(gbase) + (voff)[_i]), (LAS unsigned*)(lds + (bufoff) + ldsw + _i * 8192), 16, 0, 0); } while (0)
; #define PG8_LDA(dst, b, h) do { _Pragma("unroll") for (int m = 0; m < 4; ++m) _Pragma("unroll") for (int k = 0; k < 2; ++k) dst[m][k] = *(const LAS bf16x8*)(lds + PG8_SA(b, h) + aoff + m * 2048 + k * 1024); } while (0)
; #define PG8_LDB(dst, b, h) do { _Pragma("unroll") for (int n = 0; n < 2; ++n) _Pragma("unroll") for (int k = 0; k < 2; ++k) dst[n][k] = *(const LAS bf16x8*)(lds + PG8_SB(b, h) + boff + n * 2048 + k * 1024); } while (0)
; #define PG8_MMA(ai, bj, At, Bt) do { __builtin_amdgcn_s_setprio(1); _Pragma("unroll") for (int m = 0; m < 4; ++m) _Pragma("unroll") for (int n = 0; n < 2; ++n) _Pragma("unroll") for (int k = 0; k < 2; ++k) \
;         acc[ai][bj][m][n] = __builtin_amdgcn_mfma_f32_16x16x32_bf16(Bt[n][k], At[m][k], acc[ai][bj][m][n], 0, 0, 0); __builtin_amdgcn_s_setprio(0); } while (0)
; #define PG8_WAIT_V(n) asm volatile("s_waitcnt vmcnt(" #n ")" ::: "memory")
; #define PG8_WAIT_L(n) asm volatile("s_waitcnt lgkmcnt(" #n ")" ::: "memory")
; #define PG8_BAR __builtin_amdgcn_s_barrier()
; #define PG8_SCHED __builtin_amdgcn_sched_barrier(0)
; template <class Epi, class Sched, bool ALIGN_EPI = false, bool SP2 = false>
; __device__ __forceinline__ void gemm_phase(LAS unsigned char* lds, const Gemm g, const Sched& S, const Epi& E) {
;     ...
;             PG8_LDB(B0, 1, 0); PG8_LDB(B1, 1, 1); PG8_SCHED; PG8_LDA(At, 1, 0); PG8_STAGE(PG8_SA(0, 1), a2 + hstep, voffA);
;             PG8_WAIT_V(8); PG8_WAIT_L(0); PG8_BAR; PG8_MMA(0, 0, At, B0); PG8_MMA(0, 1, At, B1); PG8_BAR; PG8_SCHED;
;             PG8_LDA(At, 1, 1); PG8_STAGE(PG8_SB(1, 0), b3, voffB); PG8_STAGE(PG8_SB(1, 1), b3 + hstepB, voffB); PG8_STAGE(PG8_SA(1, 0), a3, voffA);
;             PG8_WAIT_V(8); PG8_WAIT_L(0); PG8_BAR; PG8_MMA(1, 0, At, B0); PG8_MMA(1, 1, At, B1); PG8_BAR; PG8_SCHED;
	s_add_i32 s51, 0, 0x18000
	s_add_i32 s52, 0, 0x1c000
	v_add_u32_e32 v78, s51, v169
	v_add_u32_e32 v168, s52, v169
	ds_read_b128 v[66:69], v78
	ds_read_b128 v[70:73], v78 offset:1024
	ds_read_b128 v[74:77], v78 offset:2048
	ds_read_b128 v[78:81], v78 offset:3072
	ds_read_b128 v[162:165], v168
	ds_read_b128 v[180:183], v168 offset:1024
	ds_read_b128 v[184:187], v168 offset:2048
	ds_read_b128 v[188:191], v168 offset:3072
	s_add_u32 s22, s22, 0x80000
	s_addc_u32 s23, s23, 0
	s_mov_b32 m0, s30
	ds_read_b128 v[192:195], v175 offset:32768
	ds_read_b128 v[196:199], v175 offset:33792
	ds_read_b128 v[200:203], v175 offset:34816
	ds_read_b128 v[204:207], v175 offset:35840
	ds_read_b128 v[208:211], v175 offset:36864
	ds_read_b128 v[212:215], v175 offset:37888
	ds_read_b128 v[216:219], v175 offset:38912
	ds_read_b128 v[220:223], v175 offset:39936
	global_load_lds_dwordx4 v152, s[22:23]
	s_mov_b32 m0, s31
	s_nop 0
	global_load_lds_dwordx4 v148, s[22:23]
	s_waitcnt vmcnt(8)
	s_waitcnt lgkmcnt(0)
	s_barrier
	s_waitcnt lgkmcnt(0)
	v_mfma_f32_16x16x32_bf16 v[142:145], v[66:69], v[192:195], v[142:145]
	v_mfma_f32_16x16x32_bf16 v[138:141], v[74:77], v[192:195], v[138:141]
	v_mfma_f32_16x16x32_bf16 v[126:129], v[66:69], v[200:203], v[126:129]
	v_mfma_f32_16x16x32_bf16 v[122:125], v[74:77], v[200:203], v[122:125]
	v_mfma_f32_16x16x32_bf16 v[110:113], v[66:69], v[208:211], v[110:113]
	v_mfma_f32_16x16x32_bf16 v[106:109], v[74:77], v[208:211], v[106:109]
	v_mfma_f32_16x16x32_bf16 v[94:97], v[66:69], v[216:219], v[94:97]
	v_mfma_f32_16x16x32_bf16 v[90:93], v[74:77], v[216:219], v[90:93]
	v_mfma_f32_16x16x32_bf16 v[142:145], v[70:73], v[196:199], v[142:145]
	v_mfma_f32_16x16x32_bf16 v[138:141], v[78:81], v[196:199], v[138:141]
	v_mfma_f32_16x16x32_bf16 v[126:129], v[70:73], v[204:207], v[126:129]
	v_mfma_f32_16x16x32_bf16 v[122:125], v[78:81], v[204:207], v[122:125]
	v_mfma_f32_16x16x32_bf16 v[110:113], v[70:73], v[212:215], v[110:113]
	v_mfma_f32_16x16x32_bf16 v[106:109], v[78:81], v[212:215], v[106:109]
	v_mfma_f32_16x16x32_bf16 v[94:97], v[70:73], v[220:223], v[94:97]
	v_mfma_f32_16x16x32_bf16 v[90:93], v[78:81], v[220:223], v[90:93]
	v_mfma_f32_16x16x32_bf16 v[134:137], v[162:165], v[192:195], v[134:137]
	v_mfma_f32_16x16x32_bf16 v[130:133], v[184:187], v[192:195], v[130:133]
	v_mfma_f32_16x16x32_bf16 v[118:121], v[162:165], v[200:203], v[118:121]
	v_mfma_f32_16x16x32_bf16 v[114:117], v[184:187], v[200:203], v[114:117]
	v_mfma_f32_16x16x32_bf16 v[102:105], v[162:165], v[208:211], v[102:105]
	v_mfma_f32_16x16x32_bf16 v[98:101], v[184:187], v[208:211], v[98:101]
	v_mfma_f32_16x16x32_bf16 v[86:89], v[162:165], v[216:219], v[86:89]
	v_mfma_f32_16x16x32_bf16 v[82:85], v[184:187], v[216:219], v[82:85]
	v_mfma_f32_16x16x32_bf16 v[134:137], v[180:183], v[196:199], v[134:137]
	v_mfma_f32_16x16x32_bf16 v[130:133], v[188:191], v[196:199], v[130:133]
	v_mfma_f32_16x16x32_bf16 v[118:121], v[180:183], v[204:207], v[118:121]
	v_mfma_f32_16x16x32_bf16 v[114:117], v[188:191], v[204:207], v[114:117]
	v_mfma_f32_16x16x32_bf16 v[102:105], v[180:183], v[212:215], v[102:105]
	v_mfma_f32_16x16x32_bf16 v[98:101], v[188:191], v[212:215], v[98:101]
	v_mfma_f32_16x16x32_bf16 v[86:89], v[180:183], v[220:223], v[86:89]
	v_mfma_f32_16x16x32_bf16 v[82:85], v[188:191], v[220:223], v[82:85]
	s_barrier
	s_add_i32 s22, s51, s25
	v_lshl_add_u64 v[166:167], v[166:167], 0, s[6:7]
	s_mov_b32 m0, s22
	ds_read_b128 v[192:195], v175 offset:49152
	ds_read_b128 v[196:199], v175 offset:50176
	ds_read_b128 v[200:203], v175 offset:51200
	ds_read_b128 v[204:207], v175 offset:52224
	ds_read_b128 v[208:211], v175 offset:53248
	ds_read_b128 v[212:215], v175 offset:54272
	ds_read_b128 v[216:219], v175 offset:55296
	ds_read_b128 v[220:223], v175 offset:56320
	global_load_lds_dwordx4 v[166:167], off
	s_add_i32 m0, s22, 0x2000
	s_add_u32 s20, s20, 0x80080
	v_lshl_add_u64 v[166:167], v[224:225], 0, s[6:7]
	s_addc_u32 s21, s21, 0
	s_add_i32 s22, s52, s25
	global_load_lds_dwordx4 v[166:167], off
	s_mov_b32 m0, s22
	s_nop 0
	global_load_lds_dwordx4 v150, s[20:21]
	s_add_i32 m0, s22, 0x2000
	s_nop 0
	global_load_lds_dwordx4 v146, s[20:21]
	v_lshl_add_u64 v[166:167], v[226:227], 0, s[6:7]
	s_mov_b32 m0, s39
	s_nop 0
	global_load_lds_dwordx4 v[166:167], off
	v_lshl_add_u64 v[166:167], v[228:229], 0, s[6:7]
	s_mov_b32 m0, s40
	s_nop 0
	global_load_lds_dwordx4 v[166:167], off
	s_waitcnt vmcnt(8)
	s_waitcnt lgkmcnt(0)
	s_barrier
	s_waitcnt lgkmcnt(0)
	v_mfma_f32_16x16x32_bf16 v[62:65], v[66:69], v[192:195], v[62:65]
	v_mfma_f32_16x16x32_bf16 v[58:61], v[74:77], v[192:195], v[58:61]
	v_mfma_f32_16x16x32_bf16 v[46:49], v[66:69], v[200:203], v[46:49]
	v_mfma_f32_16x16x32_bf16 v[42:45], v[74:77], v[200:203], v[42:45]
	v_mfma_f32_16x16x32_bf16 v[30:33], v[66:69], v[208:211], v[30:33]
	v_mfma_f32_16x16x32_bf16 v[26:29], v[74:77], v[208:211], v[26:29]
	v_mfma_f32_16x16x32_bf16 v[14:17], v[66:69], v[216:219], v[14:17]
	v_mfma_f32_16x16x32_bf16 v[10:13], v[74:77], v[216:219], v[10:13]
	v_mfma_f32_16x16x32_bf16 v[62:65], v[70:73], v[196:199], v[62:65]
	v_mfma_f32_16x16x32_bf16 v[58:61], v[78:81], v[196:199], v[58:61]
	v_mfma_f32_16x16x32_bf16 v[46:49], v[70:73], v[204:207], v[46:49]
	v_mfma_f32_16x16x32_bf16 v[42:45], v[78:81], v[204:207], v[42:45]
	v_mfma_f32_16x16x32_bf16 v[30:33], v[70:73], v[212:215], v[30:33]
	v_mfma_f32_16x16x32_bf16 v[26:29], v[78:81], v[212:215], v[26:29]
	v_mfma_f32_16x16x32_bf16 v[14:17], v[70:73], v[220:223], v[14:17]
	v_mfma_f32_16x16x32_bf16 v[10:13], v[78:81], v[220:223], v[10:13]
	v_mfma_f32_16x16x32_bf16 v[54:57], v[162:165], v[192:195], v[54:57]
	v_mfma_f32_16x16x32_bf16 v[50:53], v[184:187], v[192:195], v[50:53]
	v_mfma_f32_16x16x32_bf16 v[38:41], v[162:165], v[200:203], v[38:41]
	v_mfma_f32_16x16x32_bf16 v[34:37], v[184:187], v[200:203], v[34:37]
	v_mfma_f32_16x16x32_bf16 v[22:25], v[162:165], v[208:211], v[22:25]
	v_mfma_f32_16x16x32_bf16 v[18:21], v[184:187], v[208:211], v[18:21]
	v_mfma_f32_16x16x32_bf16 v[6:9], v[162:165], v[216:219], v[6:9]
	v_mfma_f32_16x16x32_bf16 v[2:5], v[184:187], v[216:219], v[2:5]
	v_mfma_f32_16x16x32_bf16 v[54:57], v[180:183], v[196:199], v[54:57]
	v_mfma_f32_16x16x32_bf16 v[50:53], v[188:191], v[196:199], v[50:53]
	v_mfma_f32_16x16x32_bf16 v[38:41], v[180:183], v[204:207], v[38:41]
	v_mfma_f32_16x16x32_bf16 v[34:37], v[188:191], v[204:207], v[34:37]
	v_mfma_f32_16x16x32_bf16 v[22:25], v[180:183], v[212:215], v[22:25]
	v_mfma_f32_16x16x32_bf16 v[18:21], v[188:191], v[212:215], v[18:21]
	v_mfma_f32_16x16x32_bf16 v[6:9], v[180:183], v[220:223], v[6:9]
	v_mfma_f32_16x16x32_bf16 v[2:5], v[188:191], v[220:223], v[2:5]
	s_barrier
	s_add_i32 s50, s50, 2
	s_add_u32 s48, s48, 0x100
	s_addc_u32 s49, s49, 0
	s_add_u32 s18, s18, 0x100
	s_addc_u32 s19, s19, 0
	s_cmp_lt_u32 s50, 30
; #define PG8_STAGE(bufoff, gbase, voff) do { _Pragma("unroll") for (int _i = 0; _i < 2; ++_i) \
;         __builtin_amdgcn_global_load_lds((const unsigned*)((const char*)(gbase) + (voff)[_i]), (LAS unsigned*)(lds + (bufoff) + ldsw + _i * 8192), 16, 0, 0); } while (0)
; #define PG8_LDA(dst, b, h) do { _Pragma("unroll") for (int m = 0; m < 4; ++m) _Pragma("unroll") for (int k = 0; k < 2; ++k) dst[m][k] = *(const LAS bf16x8*)(lds + PG8_SA(b, h) + aoff + m * 2048 + k * 1024); } while (0)
; #define PG8_LDB(dst, b, h) do { _Pragma("unroll") for (int n = 0; n < 2; ++n) _Pragma("unroll") for (int k = 0; k < 2; ++k) dst[n][k] = *(const LAS bf16x8*)(lds + PG8_SB(b, h) + boff + n * 2048 + k * 1024); } while (0)
; #define PG8_MMA(ai, bj, At, Bt) do { __builtin_amdgcn_s_setprio(1); _Pragma("unroll") for (int m = 0; m < 4; ++m) _Pragma("unroll") for (int n = 0; n < 2; ++n) _Pragma("unroll") for (int k = 0; k < 2; ++k) \
;         acc[ai][bj][m][n] = __builtin_amdgcn_mfma_f32_16x16x32_bf16(Bt[n][k], At[m][k], acc[ai][bj][m][n], 0, 0, 0); __builtin_amdgcn_s_setprio(0); } while (0)
; #define PG8_WAIT_V(n) asm volatile("s_waitcnt vmcnt(" #n ")" ::: "memory")
; #define PG8_WAIT_L(n) asm volatile("s_waitcnt lgkmcnt(" #n ")" ::: "memory")
; #define PG8_BAR __builtin_amdgcn_s_barrier()
; template <class Epi, class Sched, bool ALIGN_EPI = false, bool SP2 = false>
; __device__ __forceinline__ void gemm_phase(LAS unsigned char* lds, const Gemm g, const Sched& S, const Epi& E) {
;     ...
;             const bool last = (t == nt - 2);
;             const char* a1 = cA + (size_t)(t + 1) * kstep;
;             const char* a2 = last ? nA : cA + (size_t)(t + 2) * kstep; const char* b2 = last ? nB : cB + (size_t)(t + 2) * kstep;
;             const char* a3 = a2 + kstep; const char* b3 = b2 + kstep;
;             if (last && has_next) S.a_ready(nxt);
;             if constexpr (SP2) {
;             PG8_LDB(B0, 0, 0); PG8_LDB(B1, 0, 1); PG8_SCHED; PG8_LDA(At, 0, 0); PG8_STAGE(PG8_SA(1, 1), a1 + hstep, voffA);
;             PG8_WAIT_V(8); PG8_WAIT_L(0); PG8_BAR; PG8_MMA(0, 0, At, B0); PG8_MMA(0, 1, At, B1); PG8_BAR; PG8_SCHED;
;             PG8_LDA(At, 0, 1); PG8_STAGE(PG8_SB(0, 0), b2, voffB); PG8_STAGE(PG8_SB(0, 1), b2 + hstepB, voffB); PG8_STAGE(PG8_SA(0, 0), a2, voffA);
;             PG8_WAIT_V(8); PG8_WAIT_L(0); PG8_BAR; PG8_MMA(1, 0, At, B0); PG8_MMA(1, 1, At, B1); PG8_BAR; PG8_SCHED;
.LBB0_2916:
	ds_read_b128 v[66:69], v173
	ds_read_b128 v[70:73], v173 offset:1024
	ds_read_b128 v[74:77], v173 offset:2048
	ds_read_b128 v[78:81], v173 offset:3072
	ds_read_b128 v[162:165], v174
	ds_read_b128 v[180:183], v174 offset:1024
	ds_read_b128 v[184:187], v174 offset:2048
	ds_read_b128 v[188:191], v174 offset:3072
	s_add_u32 s20, s18, 0xfff80080
	s_addc_u32 s21, s19, -1
	s_cmp_eq_u32 s50, 28
	s_cselect_b32 s23, s13, s21
	s_cselect_b32 s22, s46, s20
	s_cselect_b32 s21, s11, s49
	s_cselect_b32 s20, s47, s48
	s_add_i32 m0, s28, 0xc000
	ds_read_b128 v[192:195], v175
	ds_read_b128 v[196:199], v175 offset:1024
	ds_read_b128 v[200:203], v175 offset:2048
	ds_read_b128 v[204:207], v175 offset:3072
	ds_read_b128 v[208:211], v175 offset:4096
	ds_read_b128 v[212:215], v175 offset:5120
	ds_read_b128 v[216:219], v175 offset:6144
	ds_read_b128 v[220:223], v175 offset:7168
	global_load_lds_dwordx4 v156, s[18:19]
	s_add_i32 m0, s28, 0xe000
	s_nop 0
	global_load_lds_dwordx4 v154, s[18:19]
	s_waitcnt vmcnt(8)
	s_waitcnt lgkmcnt(0)
	s_barrier
	s_waitcnt lgkmcnt(0)
	v_mfma_f32_16x16x32_bf16 v[142:145], v[66:69], v[192:195], v[142:145]
	v_mfma_f32_16x16x32_bf16 v[138:141], v[74:77], v[192:195], v[138:141]
	v_mfma_f32_16x16x32_bf16 v[126:129], v[66:69], v[200:203], v[126:129]
	v_mfma_f32_16x16x32_bf16 v[122:125], v[74:77], v[200:203], v[122:125]
	v_mfma_f32_16x16x32_bf16 v[110:113], v[66:69], v[208:211], v[110:113]
	v_mfma_f32_16x16x32_bf16 v[106:109], v[74:77], v[208:211], v[106:109]
	v_mfma_f32_16x16x32_bf16 v[94:97], v[66:69], v[216:219], v[94:97]
	v_mfma_f32_16x16x32_bf16 v[90:93], v[74:77], v[216:219], v[90:93]
	v_mfma_f32_16x16x32_bf16 v[142:145], v[70:73], v[196:199], v[142:145]
	v_mfma_f32_16x16x32_bf16 v[138:141], v[78:81], v[196:199], v[138:141]
	v_mfma_f32_16x16x32_bf16 v[126:129], v[70:73], v[204:207], v[126:129]
	v_mfma_f32_16x16x32_bf16 v[122:125], v[78:81], v[204:207], v[122:125]
	v_mfma_f32_16x16x32_bf16 v[110:113], v[70:73], v[212:215], v[110:113]
	v_mfma_f32_16x16x32_bf16 v[106:109], v[78:81], v[212:215], v[106:109]
	v_mfma_f32_16x16x32_bf16 v[94:97], v[70:73], v[220:223], v[94:97]
	v_mfma_f32_16x16x32_bf16 v[90:93], v[78:81], v[220:223], v[90:93]
	v_mfma_f32_16x16x32_bf16 v[134:137], v[162:165], v[192:195], v[134:137]
	v_mfma_f32_16x16x32_bf16 v[130:133], v[184:187], v[192:195], v[130:133]
	v_mfma_f32_16x16x32_bf16 v[118:121], v[162:165], v[200:203], v[118:121]
	v_mfma_f32_16x16x32_bf16 v[114:117], v[184:187], v[200:203], v[114:117]
	v_mfma_f32_16x16x32_bf16 v[102:105], v[162:165], v[208:211], v[102:105]
	v_mfma_f32_16x16x32_bf16 v[98:101], v[184:187], v[208:211], v[98:101]
	v_mfma_f32_16x16x32_bf16 v[86:89], v[162:165], v[216:219], v[86:89]
	v_mfma_f32_16x16x32_bf16 v[82:85], v[184:187], v[216:219], v[82:85]
	v_mfma_f32_16x16x32_bf16 v[134:137], v[180:183], v[196:199], v[134:137]
	v_mfma_f32_16x16x32_bf16 v[130:133], v[188:191], v[196:199], v[130:133]
	v_mfma_f32_16x16x32_bf16 v[118:121], v[180:183], v[204:207], v[118:121]
	v_mfma_f32_16x16x32_bf16 v[114:117], v[188:191], v[204:207], v[114:117]
	v_mfma_f32_16x16x32_bf16 v[102:105], v[180:183], v[212:215], v[102:105]
	v_mfma_f32_16x16x32_bf16 v[98:101], v[188:191], v[212:215], v[98:101]
	v_mfma_f32_16x16x32_bf16 v[86:89], v[180:183], v[220:223], v[86:89]
	v_mfma_f32_16x16x32_bf16 v[82:85], v[188:191], v[220:223], v[82:85]
	s_barrier
	s_add_i32 s51, s41, s25
	v_lshl_add_u64 v[166:167], s[20:21], 0, v[150:151]
	s_mov_b32 m0, s51
	ds_read_b128 v[192:195], v175 offset:16384
	ds_read_b128 v[196:199], v175 offset:17408
	ds_read_b128 v[200:203], v175 offset:18432
	ds_read_b128 v[204:207], v175 offset:19456
	ds_read_b128 v[208:211], v175 offset:20480
	ds_read_b128 v[212:215], v175 offset:21504
	ds_read_b128 v[216:219], v175 offset:22528
	ds_read_b128 v[220:223], v175 offset:23552
	global_load_lds_dwordx4 v[166:167], off
	s_add_i32 m0, s51, 0x2000
	s_add_u32 s52, s20, 0x80000
	v_lshl_add_u64 v[224:225], s[20:21], 0, v[146:147]
	s_addc_u32 s53, s21, 0
	s_add_i32 s51, s42, s25
	global_load_lds_dwordx4 v[224:225], off
	s_mov_b32 m0, s51
	v_lshl_add_u64 v[228:229], s[22:23], 0, v[148:149]
	global_load_lds_dwordx4 v150, s[52:53]
	s_add_i32 m0, s51, 0x2000
	s_nop 0
	global_load_lds_dwordx4 v146, s[52:53]
	v_lshl_add_u64 v[226:227], s[22:23], 0, v[152:153]
	s_mov_b32 m0, s28
	s_nop 0
	global_load_lds_dwordx4 v[226:227], off
	s_mov_b32 m0, s29
	s_nop 0
	global_load_lds_dwordx4 v[228:229], off
	s_waitcnt vmcnt(8)
	s_waitcnt lgkmcnt(0)
	s_barrier
	s_waitcnt lgkmcnt(0)
	v_mfma_f32_16x16x32_bf16 v[62:65], v[66:69], v[192:195], v[62:65]
	v_mfma_f32_16x16x32_bf16 v[58:61], v[74:77], v[192:195], v[58:61]
	v_mfma_f32_16x16x32_bf16 v[46:49], v[66:69], v[200:203], v[46:49]
	v_mfma_f32_16x16x32_bf16 v[42:45], v[74:77], v[200:203], v[42:45]
	v_mfma_f32_16x16x32_bf16 v[30:33], v[66:69], v[208:211], v[30:33]
	v_mfma_f32_16x16x32_bf16 v[26:29], v[74:77], v[208:211], v[26:29]
	v_mfma_f32_16x16x32_bf16 v[14:17], v[66:69], v[216:219], v[14:17]
	v_mfma_f32_16x16x32_bf16 v[10:13], v[74:77], v[216:219], v[10:13]
	v_mfma_f32_16x16x32_bf16 v[62:65], v[70:73], v[196:199], v[62:65]
	v_mfma_f32_16x16x32_bf16 v[58:61], v[78:81], v[196:199], v[58:61]
	v_mfma_f32_16x16x32_bf16 v[46:49], v[70:73], v[204:207], v[46:49]
	v_mfma_f32_16x16x32_bf16 v[42:45], v[78:81], v[204:207], v[42:45]
	v_mfma_f32_16x16x32_bf16 v[30:33], v[70:73], v[212:215], v[30:33]
	v_mfma_f32_16x16x32_bf16 v[26:29], v[78:81], v[212:215], v[26:29]
	v_mfma_f32_16x16x32_bf16 v[14:17], v[70:73], v[220:223], v[14:17]
	v_mfma_f32_16x16x32_bf16 v[10:13], v[78:81], v[220:223], v[10:13]
	v_mfma_f32_16x16x32_bf16 v[54:57], v[162:165], v[192:195], v[54:57]
	v_mfma_f32_16x16x32_bf16 v[50:53], v[184:187], v[192:195], v[50:53]
	v_mfma_f32_16x16x32_bf16 v[38:41], v[162:165], v[200:203], v[38:41]
	v_mfma_f32_16x16x32_bf16 v[34:37], v[184:187], v[200:203], v[34:37]
	v_mfma_f32_16x16x32_bf16 v[22:25], v[162:165], v[208:211], v[22:25]
	v_mfma_f32_16x16x32_bf16 v[18:21], v[184:187], v[208:211], v[18:21]
	v_mfma_f32_16x16x32_bf16 v[6:9], v[162:165], v[216:219], v[6:9]
	v_mfma_f32_16x16x32_bf16 v[2:5], v[184:187], v[216:219], v[2:5]
	v_mfma_f32_16x16x32_bf16 v[54:57], v[180:183], v[196:199], v[54:57]
	v_mfma_f32_16x16x32_bf16 v[50:53], v[188:191], v[196:199], v[50:53]
	v_mfma_f32_16x16x32_bf16 v[38:41], v[180:183], v[204:207], v[38:41]
	v_mfma_f32_16x16x32_bf16 v[34:37], v[188:191], v[204:207], v[34:37]
	v_mfma_f32_16x16x32_bf16 v[22:25], v[180:183], v[212:215], v[22:25]
	v_mfma_f32_16x16x32_bf16 v[18:21], v[188:191], v[212:215], v[18:21]
	v_mfma_f32_16x16x32_bf16 v[6:9], v[180:183], v[220:223], v[6:9]
	v_mfma_f32_16x16x32_bf16 v[2:5], v[188:191], v[220:223], v[2:5]
	s_barrier
; #define PG8_STAGE(bufoff, gbase, voff) do { _Pragma("unroll") for (int _i = 0; _i < 2; ++_i) \
;         __builtin_amdgcn_global_load_lds((const unsigned*)((const char*)(gbase) + (voff)[_i]), (LAS unsigned*)(lds + (bufoff) + ldsw + _i * 8192), 16, 0, 0); } while (0)
; #define PG8_LDA(dst, b, h) do { _Pragma("unroll") for (int m = 0; m < 4; ++m) _Pragma("unroll") for (int k = 0; k < 2; ++k) dst[m][k] = *(const LAS bf16x8*)(lds + PG8_SA(b, h) + aoff + m * 2048 + k * 1024); } while (0)
; #define PG8_LDB(dst, b, h) do { _Pragma("unroll") for (int n = 0; n < 2; ++n) _Pragma("unroll") for (int k = 0; k < 2; ++k) dst[n][k] = *(const LAS bf16x8*)(lds + PG8_SB(b, h) + boff + n * 2048 + k * 1024); } while (0)
; #define PG8_MMA(ai, bj, At, Bt) do { __builtin_amdgcn_s_setprio(1); _Pragma("unroll") for (int m = 0; m < 4; ++m) _Pragma("unroll") for (int n = 0; n < 2; ++n) _Pragma("unroll") for (int k = 0; k < 2; ++k) \
;         acc[ai][bj][m][n] = __builtin_amdgcn_mfma_f32_16x16x32_bf16(Bt[n][k], At[m][k], acc[ai][bj][m][n], 0, 0, 0); __builtin_amdgcn_s_setprio(0); } while (0)
; #define PG8_WAIT_V(n) asm volatile("s_waitcnt vmcnt(" #n ")" ::: "memory")
; #define PG8_WAIT_L(n) asm volatile("s_waitcnt lgkmcnt(" #n ")" ::: "memory")
; #define PG8_BAR __builtin_amdgcn_s_barrier()
; #define PG8_SCHED __builtin_amdgcn_sched_barrier(0)
; template <class Epi, class Sched, bool ALIGN_EPI = false, bool SP2 = false>
; __device__ __forceinline__ void gemm_phase(LAS unsigned char* lds, const Gemm g, const Sched& S, const Epi& E) {
;     ...
;             PG8_LDB(B0, 1, 0); PG8_LDB(B1, 1, 1); PG8_SCHED; PG8_LDA(At, 1, 0); PG8_STAGE(PG8_SA(0, 1), a2 + hstep, voffA);
;             PG8_WAIT_V(8); PG8_WAIT_L(0); PG8_BAR; PG8_MMA(0, 0, At, B0); PG8_MMA(0, 1, At, B1); PG8_BAR; PG8_SCHED;
;             PG8_LDA(At, 1, 1); PG8_STAGE(PG8_SB(1, 0), b3, voffB); PG8_STAGE(PG8_SB(1, 1), b3 + hstepB, voffB); PG8_STAGE(PG8_SA(1, 0), a3, voffA);
;             PG8_WAIT_V(8); PG8_WAIT_L(0); PG8_BAR; PG8_MMA(1, 0, At, B0); PG8_MMA(1, 1, At, B1); PG8_BAR; PG8_SCHED;
	s_add_i32 s51, 0, 0x18000
	s_add_i32 s52, 0, 0x1c000
	v_add_u32_e32 v78, s51, v169
	v_add_u32_e32 v168, s52, v169
	ds_read_b128 v[66:69], v78
	ds_read_b128 v[70:73], v78 offset:1024
	ds_read_b128 v[74:77], v78 offset:2048
	ds_read_b128 v[78:81], v78 offset:3072
	ds_read_b128 v[162:165], v168
	ds_read_b128 v[180:183], v168 offset:1024
	ds_read_b128 v[184:187], v168 offset:2048
	ds_read_b128 v[188:191], v168 offset:3072
	s_add_u32 s22, s22, 0x80000
	s_addc_u32 s23, s23, 0
	s_mov_b32 m0, s30
	ds_read_b128 v[192:195], v175 offset:32768
	ds_read_b128 v[196:199], v175 offset:33792
	ds_read_b128 v[200:203], v175 offset:34816
	ds_read_b128 v[204:207], v175 offset:35840
	ds_read_b128 v[208:211], v175 offset:36864
	ds_read_b128 v[212:215], v175 offset:37888
	ds_read_b128 v[216:219], v175 offset:38912
	ds_read_b128 v[220:223], v175 offset:39936
	global_load_lds_dwordx4 v152, s[22:23]
	s_mov_b32 m0, s31
	s_nop 0
	global_load_lds_dwordx4 v148, s[22:23]
	s_waitcnt vmcnt(8)
	s_waitcnt lgkmcnt(0)
	s_barrier
	s_waitcnt lgkmcnt(0)
	v_mfma_f32_16x16x32_bf16 v[142:145], v[66:69], v[192:195], v[142:145]
	v_mfma_f32_16x16x32_bf16 v[138:141], v[74:77], v[192:195], v[138:141]
	v_mfma_f32_16x16x32_bf16 v[126:129], v[66:69], v[200:203], v[126:129]
	v_mfma_f32_16x16x32_bf16 v[122:125], v[74:77], v[200:203], v[122:125]
	v_mfma_f32_16x16x32_bf16 v[110:113], v[66:69], v[208:211], v[110:113]
	v_mfma_f32_16x16x32_bf16 v[106:109], v[74:77], v[208:211], v[106:109]
	v_mfma_f32_16x16x32_bf16 v[94:97], v[66:69], v[216:219], v[94:97]
	v_mfma_f32_16x16x32_bf16 v[90:93], v[74:77], v[216:219], v[90:93]
	v_mfma_f32_16x16x32_bf16 v[142:145], v[70:73], v[196:199], v[142:145]
	v_mfma_f32_16x16x32_bf16 v[138:141], v[78:81], v[196:199], v[138:141]
	v_mfma_f32_16x16x32_bf16 v[126:129], v[70:73], v[204:207], v[126:129]
	v_mfma_f32_16x16x32_bf16 v[122:125], v[78:81], v[204:207], v[122:125]
	v_mfma_f32_16x16x32_bf16 v[110:113], v[70:73], v[212:215], v[110:113]
	v_mfma_f32_16x16x32_bf16 v[106:109], v[78:81], v[212:215], v[106:109]
	v_mfma_f32_16x16x32_bf16 v[94:97], v[70:73], v[220:223], v[94:97]
	v_mfma_f32_16x16x32_bf16 v[90:93], v[78:81], v[220:223], v[90:93]
	v_mfma_f32_16x16x32_bf16 v[134:137], v[162:165], v[192:195], v[134:137]
	v_mfma_f32_16x16x32_bf16 v[130:133], v[184:187], v[192:195], v[130:133]
	v_mfma_f32_16x16x32_bf16 v[118:121], v[162:165], v[200:203], v[118:121]
	v_mfma_f32_16x16x32_bf16 v[114:117], v[184:187], v[200:203], v[114:117]
	v_mfma_f32_16x16x32_bf16 v[102:105], v[162:165], v[208:211], v[102:105]
	v_mfma_f32_16x16x32_bf16 v[98:101], v[184:187], v[208:211], v[98:101]
	v_mfma_f32_16x16x32_bf16 v[86:89], v[162:165], v[216:219], v[86:89]
	v_mfma_f32_16x16x32_bf16 v[82:85], v[184:187], v[216:219], v[82:85]
	v_mfma_f32_16x16x32_bf16 v[134:137], v[180:183], v[196:199], v[134:137]
	v_mfma_f32_16x16x32_bf16 v[130:133], v[188:191], v[196:199], v[130:133]
	v_mfma_f32_16x16x32_bf16 v[118:121], v[180:183], v[204:207], v[118:121]
	v_mfma_f32_16x16x32_bf16 v[114:117], v[188:191], v[204:207], v[114:117]
	v_mfma_f32_16x16x32_bf16 v[102:105], v[180:183], v[212:215], v[102:105]
	v_mfma_f32_16x16x32_bf16 v[98:101], v[188:191], v[212:215], v[98:101]
	v_mfma_f32_16x16x32_bf16 v[86:89], v[180:183], v[220:223], v[86:89]
	v_mfma_f32_16x16x32_bf16 v[82:85], v[188:191], v[220:223], v[82:85]
	s_barrier
	s_add_i32 s22, s51, s25
	v_lshl_add_u64 v[166:167], v[166:167], 0, s[6:7]
	s_mov_b32 m0, s22
	ds_read_b128 v[192:195], v175 offset:49152
	ds_read_b128 v[196:199], v175 offset:50176
	ds_read_b128 v[200:203], v175 offset:51200
	ds_read_b128 v[204:207], v175 offset:52224
	ds_read_b128 v[208:211], v175 offset:53248
	ds_read_b128 v[212:215], v175 offset:54272
	ds_read_b128 v[216:219], v175 offset:55296
	ds_read_b128 v[220:223], v175 offset:56320
	global_load_lds_dwordx4 v[166:167], off
	s_add_i32 m0, s22, 0x2000
	s_add_u32 s20, s20, 0x80080
	v_lshl_add_u64 v[166:167], v[224:225], 0, s[6:7]
	s_addc_u32 s21, s21, 0
	s_add_i32 s22, s52, s25
	global_load_lds_dwordx4 v[166:167], off
	s_mov_b32 m0, s22
	s_nop 0
	global_load_lds_dwordx4 v150, s[20:21]
	s_add_i32 m0, s22, 0x2000
	s_nop 0
	global_load_lds_dwordx4 v146, s[20:21]
	v_lshl_add_u64 v[166:167], v[226:227], 0, s[6:7]
	s_mov_b32 m0, s39
	s_nop 0
	global_load_lds_dwordx4 v[166:167], off
	v_lshl_add_u64 v[166:167], v[228:229], 0, s[6:7]
	s_mov_b32 m0, s40
	s_nop 0
	global_load_lds_dwordx4 v[166:167], off
	s_waitcnt vmcnt(8)
	s_waitcnt lgkmcnt(0)
	s_barrier
	s_waitcnt lgkmcnt(0)
	v_mfma_f32_16x16x32_bf16 v[62:65], v[66:69], v[192:195], v[62:65]
	v_mfma_f32_16x16x32_bf16 v[58:61], v[74:77], v[192:195], v[58:61]
	v_mfma_f32_16x16x32_bf16 v[46:49], v[66:69], v[200:203], v[46:49]
	v_mfma_f32_16x16x32_bf16 v[42:45], v[74:77], v[200:203], v[42:45]
	v_mfma_f32_16x16x32_bf16 v[30:33], v[66:69], v[208:211], v[30:33]
	v_mfma_f32_16x16x32_bf16 v[26:29], v[74:77], v[208:211], v[26:29]
	v_mfma_f32_16x16x32_bf16 v[14:17], v[66:69], v[216:219], v[14:17]
	v_mfma_f32_16x16x32_bf16 v[10:13], v[74:77], v[216:219], v[10:13]
	v_mfma_f32_16x16x32_bf16 v[62:65], v[70:73], v[196:199], v[62:65]
	v_mfma_f32_16x16x32_bf16 v[58:61], v[78:81], v[196:199], v[58:61]
	v_mfma_f32_16x16x32_bf16 v[46:49], v[70:73], v[204:207], v[46:49]
	v_mfma_f32_16x16x32_bf16 v[42:45], v[78:81], v[204:207], v[42:45]
	v_mfma_f32_16x16x32_bf16 v[30:33], v[70:73], v[212:215], v[30:33]
	v_mfma_f32_16x16x32_bf16 v[26:29], v[78:81], v[212:215], v[26:29]
	v_mfma_f32_16x16x32_bf16 v[14:17], v[70:73], v[220:223], v[14:17]
	v_mfma_f32_16x16x32_bf16 v[10:13], v[78:81], v[220:223], v[10:13]
	v_mfma_f32_16x16x32_bf16 v[54:57], v[162:165], v[192:195], v[54:57]
	v_mfma_f32_16x16x32_bf16 v[50:53], v[184:187], v[192:195], v[50:53]
	v_mfma_f32_16x16x32_bf16 v[38:41], v[162:165], v[200:203], v[38:41]
	v_mfma_f32_16x16x32_bf16 v[34:37], v[184:187], v[200:203], v[34:37]
	v_mfma_f32_16x16x32_bf16 v[22:25], v[162:165], v[208:211], v[22:25]
	v_mfma_f32_16x16x32_bf16 v[18:21], v[184:187], v[208:211], v[18:21]
	v_mfma_f32_16x16x32_bf16 v[6:9], v[162:165], v[216:219], v[6:9]
	v_mfma_f32_16x16x32_bf16 v[2:5], v[184:187], v[216:219], v[2:5]
	v_mfma_f32_16x16x32_bf16 v[54:57], v[180:183], v[196:199], v[54:57]
	v_mfma_f32_16x16x32_bf16 v[50:53], v[188:191], v[196:199], v[50:53]
	v_mfma_f32_16x16x32_bf16 v[38:41], v[180:183], v[204:207], v[38:41]
	v_mfma_f32_16x16x32_bf16 v[34:37], v[188:191], v[204:207], v[34:37]
	v_mfma_f32_16x16x32_bf16 v[22:25], v[180:183], v[212:215], v[22:25]
	v_mfma_f32_16x16x32_bf16 v[18:21], v[188:191], v[212:215], v[18:21]
	v_mfma_f32_16x16x32_bf16 v[6:9], v[180:183], v[220:223], v[6:9]
	v_mfma_f32_16x16x32_bf16 v[2:5], v[188:191], v[220:223], v[2:5]
	s_barrier
	s_add_i32 s50, s50, 2
	s_add_u32 s48, s48, 0x100
	s_addc_u32 s49, s49, 0
	s_add_u32 s18, s18, 0x100
	s_addc_u32 s19, s19, 0
	s_cmp_lt_u32 s50, 30
	s_cbranch_scc1 .LBB0_2916
	s_setprio 0
	s_andn2_b64 vcc, exec, s[8:9]
	s_cbranch_vccnz .LBB0_2919
	s_barrier

; #define PG8_STAGE(bufoff, gbase, voff) do { _Pragma("unroll") for (int _i = 0; _i < 2; ++_i) \
;         __builtin_amdgcn_global_load_lds((const unsigned*)((const char*)(gbase) + (voff)[_i]), (LAS unsigned*)(lds + (bufoff) + ldsw + _i * 8192), 16, 0, 0); } while (0)
; #define PG8_LDA(dst, b, h) do { _Pragma("unroll") for (int m = 0; m < 4; ++m) _Pragma("unroll") for (int k = 0; k < 2; ++k) dst[m][k] = *(const LAS bf16x8*)(lds + PG8_SA(b, h) + aoff + m * 2048 + k * 1024); } while (0)
; #define PG8_LDB(dst, b, h) do { _Pragma("unroll") for (int n = 0; n < 2; ++n) _Pragma("unroll") for (int k = 0; k < 2; ++k) dst[n][k] = *(const LAS bf16x8*)(lds + PG8_SB(b, h) + boff + n * 2048 + k * 1024); } while (0)
; #define PG8_MMA(ai, bj, At, Bt) do { __builtin_amdgcn_s_setprio(1); _Pragma("unroll") for (int m = 0; m < 4; ++m) _Pragma("unroll") for (int n = 0; n < 2; ++n) _Pragma("unroll") for (int k = 0; k < 2; ++k) \
;         acc[ai][bj][m][n] = __builtin_amdgcn_mfma_f32_16x16x32_bf16(Bt[n][k], At[m][k], acc[ai][bj][m][n], 0, 0, 0); __builtin_amdgcn_s_setprio(0); } while (0)
; #define PG8_WAIT_V(n) asm volatile("s_waitcnt vmcnt(" #n ")" ::: "memory")
; #define PG8_WAIT_L(n) asm volatile("s_waitcnt lgkmcnt(" #n ")" ::: "memory")
; #define PG8_BAR __builtin_amdgcn_s_barrier()
; template <class Epi, class Sched, bool ALIGN_EPI = false, bool SP2 = false>
; __device__ __forceinline__ void gemm_phase(LAS unsigned char* lds, const Gemm g, const Sched& S, const Epi& E) {
;     ...
;             const bool last = (t == nt - 2);
;             const char* a1 = cA + (size_t)(t + 1) * kstep;
;             const char* a2 = last ? nA : cA + (size_t)(t + 2) * kstep; const char* b2 = last ? nB : cB + (size_t)(t + 2) * kstep;
;             const char* a3 = a2 + kstep; const char* b3 = b2 + kstep;
;             if (last && has_next) S.a_ready(nxt);
;             if constexpr (SP2) {
;             PG8_LDB(B0, 0, 0); PG8_LDB(B1, 0, 1); PG8_SCHED; PG8_LDA(At, 0, 0); PG8_STAGE(PG8_SA(1, 1), a1 + hstep, voffA);
;             PG8_WAIT_V(8); PG8_WAIT_L(0); PG8_BAR; PG8_MMA(0, 0, At, B0); PG8_MMA(0, 1, At, B1); PG8_BAR; PG8_SCHED;
;             PG8_LDA(At, 0, 1); PG8_STAGE(PG8_SB(0, 0), b2, voffB); PG8_STAGE(PG8_SB(0, 1), b2 + hstepB, voffB); PG8_STAGE(PG8_SA(0, 0), a2, voffA);
;             PG8_WAIT_V(8); PG8_WAIT_L(0); PG8_BAR; PG8_MMA(1, 0, At, B0); PG8_MMA(1, 1, At, B1); PG8_BAR; PG8_SCHED;
.Lprio_3002:
	ds_read_b128 v[152:155], v147
	ds_read_b128 v[156:159], v147 offset:1024
	ds_read_b128 v[160:163], v147 offset:2048
	ds_read_b128 v[164:167], v147 offset:3072
	ds_read_b128 v[168:171], v148
	ds_read_b128 v[172:175], v148 offset:1024
	ds_read_b128 v[176:179], v148 offset:2048
	ds_read_b128 v[180:183], v148 offset:3072
	s_add_u32 s16, s14, 0x100
	s_addc_u32 s17, s15, 0
	s_cmpk_eq_i32 s40, 0x54
	s_cselect_b32 s21, s11, s17
	s_cselect_b32 s20, s10, s16
	s_cselect_b32 s19, s3, s39
	s_cselect_b32 s18, s2, s13
	v_lshl_add_u64 v[216:217], s[14:15], 0, v[138:139]
	s_add_i32 m0, s24, 0xc000
	ds_read_b128 v[184:187], v149
	ds_read_b128 v[188:191], v149 offset:1024
	ds_read_b128 v[192:195], v149 offset:2048
	ds_read_b128 v[196:199], v149 offset:3072
	ds_read_b128 v[200:203], v149 offset:4096
	ds_read_b128 v[204:207], v149 offset:5120
	ds_read_b128 v[208:211], v149 offset:6144
	ds_read_b128 v[212:215], v149 offset:7168
	global_load_lds_dwordx4 v[216:217], off
	v_lshl_add_u64 v[216:217], s[14:15], 0, v[136:137]
	s_add_i32 m0, s24, 0xe000
	s_nop 0
	global_load_lds_dwordx4 v[216:217], off
	s_waitcnt lgkmcnt(0)
	s_barrier
	s_waitcnt lgkmcnt(0)
	v_mfma_f32_16x16x32_bf16 v[124:127], v[152:155], v[184:187], 0
	v_mfma_f32_16x16x32_bf16 v[120:123], v[160:163], v[184:187], 0
	v_mfma_f32_16x16x32_bf16 v[112:115], v[152:155], v[192:195], 0
	v_mfma_f32_16x16x32_bf16 v[104:107], v[160:163], v[192:195], 0
	v_mfma_f32_16x16x32_bf16 v[92:95], v[152:155], v[200:203], 0
	v_mfma_f32_16x16x32_bf16 v[88:91], v[160:163], v[200:203], 0
	v_mfma_f32_16x16x32_bf16 v[76:79], v[152:155], v[208:211], 0
	v_mfma_f32_16x16x32_bf16 v[72:75], v[160:163], v[208:211], 0
	v_mfma_f32_16x16x32_bf16 v[124:127], v[156:159], v[188:191], v[124:127]
	v_mfma_f32_16x16x32_bf16 v[120:123], v[164:167], v[188:191], v[120:123]
	v_mfma_f32_16x16x32_bf16 v[112:115], v[156:159], v[196:199], v[112:115]
	v_mfma_f32_16x16x32_bf16 v[104:107], v[164:167], v[196:199], v[104:107]
	v_mfma_f32_16x16x32_bf16 v[92:95], v[156:159], v[204:207], v[92:95]
	v_mfma_f32_16x16x32_bf16 v[88:91], v[164:167], v[204:207], v[88:91]
	v_mfma_f32_16x16x32_bf16 v[76:79], v[156:159], v[212:215], v[76:79]
	v_mfma_f32_16x16x32_bf16 v[72:75], v[164:167], v[212:215], v[72:75]
	v_mfma_f32_16x16x32_bf16 v[116:119], v[168:171], v[184:187], 0
	v_mfma_f32_16x16x32_bf16 v[108:111], v[176:179], v[184:187], 0
	v_mfma_f32_16x16x32_bf16 v[100:103], v[168:171], v[192:195], 0
	v_mfma_f32_16x16x32_bf16 v[96:99], v[176:179], v[192:195], 0
	v_mfma_f32_16x16x32_bf16 v[84:87], v[168:171], v[200:203], 0
	v_mfma_f32_16x16x32_bf16 v[80:83], v[176:179], v[200:203], 0
	v_mfma_f32_16x16x32_bf16 v[68:71], v[168:171], v[208:211], 0
	v_mfma_f32_16x16x32_bf16 v[64:67], v[176:179], v[208:211], 0
	v_mfma_f32_16x16x32_bf16 v[116:119], v[172:175], v[188:191], v[116:119]
	v_mfma_f32_16x16x32_bf16 v[108:111], v[180:183], v[188:191], v[108:111]
	v_mfma_f32_16x16x32_bf16 v[100:103], v[172:175], v[196:199], v[100:103]
	v_mfma_f32_16x16x32_bf16 v[96:99], v[180:183], v[196:199], v[96:99]
	v_mfma_f32_16x16x32_bf16 v[84:87], v[172:175], v[204:207], v[84:87]
	v_mfma_f32_16x16x32_bf16 v[80:83], v[180:183], v[204:207], v[80:83]
	v_mfma_f32_16x16x32_bf16 v[68:71], v[172:175], v[212:215], v[68:71]
	v_mfma_f32_16x16x32_bf16 v[64:67], v[180:183], v[212:215], v[64:67]
	s_barrier
	s_add_i32 s14, s34, s23
	v_lshl_add_u64 v[216:217], s[18:19], 0, v[130:131]
	s_mov_b32 m0, s14
	ds_read_b128 v[184:187], v149 offset:16384
	ds_read_b128 v[188:191], v149 offset:17408
	ds_read_b128 v[192:195], v149 offset:18432
	ds_read_b128 v[196:199], v149 offset:19456
	ds_read_b128 v[200:203], v149 offset:20480
	ds_read_b128 v[204:207], v149 offset:21504
	ds_read_b128 v[208:211], v149 offset:22528
	ds_read_b128 v[212:215], v149 offset:23552
	global_load_lds_dwordx4 v[216:217], off
	s_add_i32 m0, s14, 0x2000
	s_add_u32 s14, s18, 0x58000
	v_lshl_add_u64 v[218:219], s[18:19], 0, v[134:135]
	s_addc_u32 s15, s19, 0
	s_add_i32 s41, s35, s23
	global_load_lds_dwordx4 v[218:219], off
	s_mov_b32 m0, s41
	v_lshl_add_u64 v[222:223], s[20:21], 0, v[132:133]
	global_load_lds_dwordx4 v130, s[14:15]
	s_add_i32 m0, s41, 0x2000
	s_nop 0
	global_load_lds_dwordx4 v134, s[14:15]
	v_lshl_add_u64 v[220:221], s[20:21], 0, v[128:129]
	s_mov_b32 m0, s24
	s_nop 0
	global_load_lds_dwordx4 v[220:221], off
	s_mov_b32 m0, s25
	s_nop 0
	global_load_lds_dwordx4 v[222:223], off
	s_waitcnt lgkmcnt(0)
	s_barrier
	s_waitcnt lgkmcnt(0)
	v_mfma_f32_16x16x32_bf16 v[60:63], v[152:155], v[184:187], 0
	v_mfma_f32_16x16x32_bf16 v[56:59], v[160:163], v[184:187], 0
	v_mfma_f32_16x16x32_bf16 v[44:47], v[152:155], v[192:195], 0
	v_mfma_f32_16x16x32_bf16 v[40:43], v[160:163], v[192:195], 0
	v_mfma_f32_16x16x32_bf16 v[28:31], v[152:155], v[200:203], 0
	v_mfma_f32_16x16x32_bf16 v[24:27], v[160:163], v[200:203], 0
	v_mfma_f32_16x16x32_bf16 v[12:15], v[152:155], v[208:211], 0
	v_mfma_f32_16x16x32_bf16 v[8:11], v[160:163], v[208:211], 0
	v_mfma_f32_16x16x32_bf16 v[60:63], v[156:159], v[188:191], v[60:63]
	v_mfma_f32_16x16x32_bf16 v[56:59], v[164:167], v[188:191], v[56:59]
	v_mfma_f32_16x16x32_bf16 v[44:47], v[156:159], v[196:199], v[44:47]
	v_mfma_f32_16x16x32_bf16 v[40:43], v[164:167], v[196:199], v[40:43]
	v_mfma_f32_16x16x32_bf16 v[28:31], v[156:159], v[204:207], v[28:31]
	v_mfma_f32_16x16x32_bf16 v[24:27], v[164:167], v[204:207], v[24:27]
	v_mfma_f32_16x16x32_bf16 v[12:15], v[156:159], v[212:215], v[12:15]
	v_mfma_f32_16x16x32_bf16 v[8:11], v[164:167], v[212:215], v[8:11]
	v_mfma_f32_16x16x32_bf16 v[52:55], v[168:171], v[184:187], 0
	v_mfma_f32_16x16x32_bf16 v[48:51], v[176:179], v[184:187], 0
	v_mfma_f32_16x16x32_bf16 v[36:39], v[168:171], v[192:195], 0
	v_mfma_f32_16x16x32_bf16 v[32:35], v[176:179], v[192:195], 0
	v_mfma_f32_16x16x32_bf16 v[20:23], v[168:171], v[200:203], 0
	v_mfma_f32_16x16x32_bf16 v[16:19], v[176:179], v[200:203], 0
	v_mfma_f32_16x16x32_bf16 v[4:7], v[168:171], v[208:211], 0
	v_mfma_f32_16x16x32_bf16 v[0:3], v[176:179], v[208:211], 0
	v_mfma_f32_16x16x32_bf16 v[52:55], v[172:175], v[188:191], v[52:55]
	v_mfma_f32_16x16x32_bf16 v[48:51], v[180:183], v[188:191], v[48:51]
	v_mfma_f32_16x16x32_bf16 v[36:39], v[172:175], v[196:199], v[36:39]
	v_mfma_f32_16x16x32_bf16 v[32:35], v[180:183], v[196:199], v[32:35]
	v_mfma_f32_16x16x32_bf16 v[20:23], v[172:175], v[204:207], v[20:23]
	v_mfma_f32_16x16x32_bf16 v[16:19], v[180:183], v[204:207], v[16:19]
	v_mfma_f32_16x16x32_bf16 v[4:7], v[172:175], v[212:215], v[4:7]
	v_mfma_f32_16x16x32_bf16 v[0:3], v[180:183], v[212:215], v[0:3]
	s_barrier
; #define PG8_STAGE(bufoff, gbase, voff) do { _Pragma("unroll") for (int _i = 0; _i < 2; ++_i) \
;         __builtin_amdgcn_global_load_lds((const unsigned*)((const char*)(gbase) + (voff)[_i]), (LAS unsigned*)(lds + (bufoff) + ldsw + _i * 8192), 16, 0, 0); } while (0)
; #define PG8_LDA(dst, b, h) do { _Pragma("unroll") for (int m = 0; m < 4; ++m) _Pragma("unroll") for (int k = 0; k < 2; ++k) dst[m][k] = *(const LAS bf16x8*)(lds + PG8_SA(b, h) + aoff + m * 2048 + k * 1024); } while (0)
; #define PG8_LDB(dst, b, h) do { _Pragma("unroll") for (int n = 0; n < 2; ++n) _Pragma("unroll") for (int k = 0; k < 2; ++k) dst[n][k] = *(const LAS bf16x8*)(lds + PG8_SB(b, h) + boff + n * 2048 + k * 1024); } while (0)
; #define PG8_MMA(ai, bj, At, Bt) do { __builtin_amdgcn_s_setprio(1); _Pragma("unroll") for (int m = 0; m < 4; ++m) _Pragma("unroll") for (int n = 0; n < 2; ++n) _Pragma("unroll") for (int k = 0; k < 2; ++k) \
;         acc[ai][bj][m][n] = __builtin_amdgcn_mfma_f32_16x16x32_bf16(Bt[n][k], At[m][k], acc[ai][bj][m][n], 0, 0, 0); __builtin_amdgcn_s_setprio(0); } while (0)
; #define PG8_WAIT_V(n) asm volatile("s_waitcnt vmcnt(" #n ")" ::: "memory")
; #define PG8_WAIT_L(n) asm volatile("s_waitcnt lgkmcnt(" #n ")" ::: "memory")
; #define PG8_BAR __builtin_amdgcn_s_barrier()
; #define PG8_SCHED __builtin_amdgcn_sched_barrier(0)
; template <class Epi, class Sched, bool ALIGN_EPI = false, bool SP2 = false>
; __device__ __forceinline__ void gemm_phase(LAS unsigned char* lds, const Gemm g, const Sched& S, const Epi& E) {
;     ...
;             PG8_LDB(B0, 1, 0); PG8_LDB(B1, 1, 1); PG8_SCHED; PG8_LDA(At, 1, 0); PG8_STAGE(PG8_SA(0, 1), a2 + hstep, voffA);
;             PG8_WAIT_V(8); PG8_WAIT_L(0); PG8_BAR; PG8_MMA(0, 0, At, B0); PG8_MMA(0, 1, At, B1); PG8_BAR; PG8_SCHED;
;             PG8_LDA(At, 1, 1); PG8_STAGE(PG8_SB(1, 0), b3, voffB); PG8_STAGE(PG8_SB(1, 1), b3 + hstepB, voffB); PG8_STAGE(PG8_SA(1, 0), a3, voffA);
;             PG8_WAIT_V(8); PG8_WAIT_L(0); PG8_BAR; PG8_MMA(1, 0, At, B0); PG8_MMA(1, 1, At, B1); PG8_BAR; PG8_SCHED;
	s_add_i32 s41, 0, 0x18000
	s_add_i32 s42, 0, 0x1c000
	v_add_u32_e32 v164, s41, v144
	v_add_u32_e32 v180, s42, v144
	ds_read_b128 v[152:155], v164
	ds_read_b128 v[156:159], v164 offset:1024
	ds_read_b128 v[160:163], v164 offset:2048
	ds_read_b128 v[164:167], v164 offset:3072
	ds_read_b128 v[168:171], v180
	ds_read_b128 v[172:175], v180 offset:1024
	ds_read_b128 v[176:179], v180 offset:2048
	ds_read_b128 v[180:183], v180 offset:3072
	s_add_u32 s14, s20, 0x160000
	s_addc_u32 s15, s21, 0
	s_mov_b32 m0, s26
	ds_read_b128 v[184:187], v149 offset:32768
	ds_read_b128 v[188:191], v149 offset:33792
	ds_read_b128 v[192:195], v149 offset:34816
	ds_read_b128 v[196:199], v149 offset:35840
	ds_read_b128 v[200:203], v149 offset:36864
	ds_read_b128 v[204:207], v149 offset:37888
	ds_read_b128 v[208:211], v149 offset:38912
	ds_read_b128 v[212:215], v149 offset:39936
	global_load_lds_dwordx4 v128, s[14:15]
	s_mov_b32 m0, s27
	s_nop 0
	global_load_lds_dwordx4 v132, s[14:15]
	s_waitcnt vmcnt(8)
	s_waitcnt lgkmcnt(0)
	s_barrier
	s_waitcnt lgkmcnt(0)
	v_mfma_f32_16x16x32_bf16 v[124:127], v[152:155], v[184:187], v[124:127]
	v_mfma_f32_16x16x32_bf16 v[120:123], v[160:163], v[184:187], v[120:123]
	v_mfma_f32_16x16x32_bf16 v[112:115], v[152:155], v[192:195], v[112:115]
	v_mfma_f32_16x16x32_bf16 v[104:107], v[160:163], v[192:195], v[104:107]
	v_mfma_f32_16x16x32_bf16 v[92:95], v[152:155], v[200:203], v[92:95]
	v_mfma_f32_16x16x32_bf16 v[88:91], v[160:163], v[200:203], v[88:91]
	v_mfma_f32_16x16x32_bf16 v[76:79], v[152:155], v[208:211], v[76:79]
	v_mfma_f32_16x16x32_bf16 v[72:75], v[160:163], v[208:211], v[72:75]
	v_mfma_f32_16x16x32_bf16 v[124:127], v[156:159], v[188:191], v[124:127]
	v_mfma_f32_16x16x32_bf16 v[120:123], v[164:167], v[188:191], v[120:123]
	v_mfma_f32_16x16x32_bf16 v[112:115], v[156:159], v[196:199], v[112:115]
	v_mfma_f32_16x16x32_bf16 v[104:107], v[164:167], v[196:199], v[104:107]
	v_mfma_f32_16x16x32_bf16 v[92:95], v[156:159], v[204:207], v[92:95]
	v_mfma_f32_16x16x32_bf16 v[88:91], v[164:167], v[204:207], v[88:91]
	v_mfma_f32_16x16x32_bf16 v[76:79], v[156:159], v[212:215], v[76:79]
	v_mfma_f32_16x16x32_bf16 v[72:75], v[164:167], v[212:215], v[72:75]
	v_mfma_f32_16x16x32_bf16 v[116:119], v[168:171], v[184:187], v[116:119]
	v_mfma_f32_16x16x32_bf16 v[108:111], v[176:179], v[184:187], v[108:111]
	v_mfma_f32_16x16x32_bf16 v[100:103], v[168:171], v[192:195], v[100:103]
	v_mfma_f32_16x16x32_bf16 v[96:99], v[176:179], v[192:195], v[96:99]
	v_mfma_f32_16x16x32_bf16 v[84:87], v[168:171], v[200:203], v[84:87]
	v_mfma_f32_16x16x32_bf16 v[80:83], v[176:179], v[200:203], v[80:83]
	v_mfma_f32_16x16x32_bf16 v[68:71], v[168:171], v[208:211], v[68:71]
	v_mfma_f32_16x16x32_bf16 v[64:67], v[176:179], v[208:211], v[64:67]
	v_mfma_f32_16x16x32_bf16 v[116:119], v[172:175], v[188:191], v[116:119]
	v_mfma_f32_16x16x32_bf16 v[108:111], v[180:183], v[188:191], v[108:111]
	v_mfma_f32_16x16x32_bf16 v[100:103], v[172:175], v[196:199], v[100:103]
	v_mfma_f32_16x16x32_bf16 v[96:99], v[180:183], v[196:199], v[96:99]
	v_mfma_f32_16x16x32_bf16 v[84:87], v[172:175], v[204:207], v[84:87]
	v_mfma_f32_16x16x32_bf16 v[80:83], v[180:183], v[204:207], v[80:83]
	v_mfma_f32_16x16x32_bf16 v[68:71], v[172:175], v[212:215], v[68:71]
	v_mfma_f32_16x16x32_bf16 v[64:67], v[180:183], v[212:215], v[64:67]
	s_barrier
	s_add_i32 s14, s41, s23
	v_lshl_add_u64 v[216:217], v[216:217], 0, s[6:7]
	s_mov_b32 m0, s14
	ds_read_b128 v[184:187], v149 offset:49152
	ds_read_b128 v[188:191], v149 offset:50176
	ds_read_b128 v[192:195], v149 offset:51200
	ds_read_b128 v[196:199], v149 offset:52224
	ds_read_b128 v[200:203], v149 offset:53248
	ds_read_b128 v[204:207], v149 offset:54272
	ds_read_b128 v[208:211], v149 offset:55296
	ds_read_b128 v[212:215], v149 offset:56320
	global_load_lds_dwordx4 v[216:217], off
	s_add_i32 m0, s14, 0x2000
	s_add_u32 s14, s18, 0x58080
	v_lshl_add_u64 v[216:217], v[218:219], 0, s[6:7]
	s_addc_u32 s15, s19, 0
	s_add_i32 s18, s42, s23
	global_load_lds_dwordx4 v[216:217], off
	s_mov_b32 m0, s18
	s_nop 0
	global_load_lds_dwordx4 v130, s[14:15]
	s_add_i32 m0, s18, 0x2000
	s_nop 0
	global_load_lds_dwordx4 v134, s[14:15]
	v_lshl_add_u64 v[216:217], v[220:221], 0, s[6:7]
	s_mov_b32 m0, s31
	s_nop 0
	global_load_lds_dwordx4 v[216:217], off
	v_lshl_add_u64 v[216:217], v[222:223], 0, s[6:7]
	s_mov_b32 m0, s33
	s_nop 0
	global_load_lds_dwordx4 v[216:217], off
	s_waitcnt vmcnt(8)
	s_waitcnt lgkmcnt(0)
	s_barrier
	s_waitcnt lgkmcnt(0)
	v_mfma_f32_16x16x32_bf16 v[60:63], v[152:155], v[184:187], v[60:63]
	v_mfma_f32_16x16x32_bf16 v[56:59], v[160:163], v[184:187], v[56:59]
	v_mfma_f32_16x16x32_bf16 v[44:47], v[152:155], v[192:195], v[44:47]
	v_mfma_f32_16x16x32_bf16 v[40:43], v[160:163], v[192:195], v[40:43]
	v_mfma_f32_16x16x32_bf16 v[28:31], v[152:155], v[200:203], v[28:31]
	v_mfma_f32_16x16x32_bf16 v[24:27], v[160:163], v[200:203], v[24:27]
	v_mfma_f32_16x16x32_bf16 v[12:15], v[152:155], v[208:211], v[12:15]
	v_mfma_f32_16x16x32_bf16 v[8:11], v[160:163], v[208:211], v[8:11]
	v_mfma_f32_16x16x32_bf16 v[60:63], v[156:159], v[188:191], v[60:63]
	v_mfma_f32_16x16x32_bf16 v[56:59], v[164:167], v[188:191], v[56:59]
	v_mfma_f32_16x16x32_bf16 v[44:47], v[156:159], v[196:199], v[44:47]
	v_mfma_f32_16x16x32_bf16 v[40:43], v[164:167], v[196:199], v[40:43]
	v_mfma_f32_16x16x32_bf16 v[28:31], v[156:159], v[204:207], v[28:31]
	v_mfma_f32_16x16x32_bf16 v[24:27], v[164:167], v[204:207], v[24:27]
	v_mfma_f32_16x16x32_bf16 v[12:15], v[156:159], v[212:215], v[12:15]
	v_mfma_f32_16x16x32_bf16 v[8:11], v[164:167], v[212:215], v[8:11]
	v_mfma_f32_16x16x32_bf16 v[52:55], v[168:171], v[184:187], v[52:55]
	v_mfma_f32_16x16x32_bf16 v[48:51], v[176:179], v[184:187], v[48:51]
	v_mfma_f32_16x16x32_bf16 v[36:39], v[168:171], v[192:195], v[36:39]
	v_mfma_f32_16x16x32_bf16 v[32:35], v[176:179], v[192:195], v[32:35]
	v_mfma_f32_16x16x32_bf16 v[20:23], v[168:171], v[200:203], v[20:23]
	v_mfma_f32_16x16x32_bf16 v[16:19], v[176:179], v[200:203], v[16:19]
	v_mfma_f32_16x16x32_bf16 v[4:7], v[168:171], v[208:211], v[4:7]
	v_mfma_f32_16x16x32_bf16 v[0:3], v[176:179], v[208:211], v[0:3]
	v_mfma_f32_16x16x32_bf16 v[52:55], v[172:175], v[188:191], v[52:55]
	v_mfma_f32_16x16x32_bf16 v[48:51], v[180:183], v[188:191], v[48:51]
	v_mfma_f32_16x16x32_bf16 v[36:39], v[172:175], v[196:199], v[36:39]
	v_mfma_f32_16x16x32_bf16 v[32:35], v[180:183], v[196:199], v[32:35]
	v_mfma_f32_16x16x32_bf16 v[20:23], v[172:175], v[204:207], v[20:23]
	v_mfma_f32_16x16x32_bf16 v[16:19], v[180:183], v[204:207], v[16:19]
	v_mfma_f32_16x16x32_bf16 v[4:7], v[172:175], v[212:215], v[4:7]
	v_mfma_f32_16x16x32_bf16 v[0:3], v[180:183], v[212:215], v[0:3]
	s_barrier
	s_add_i32 s40, s40, 2
	s_add_u32 s13, s13, 0x100
	s_addc_u32 s39, s39, 0
	s_cmpk_lt_u32 s40, 0x56
	s_mov_b64 s[14:15], s[16:17]
; #define PG8_STAGE(bufoff, gbase, voff) do { _Pragma("unroll") for (int _i = 0; _i < 2; ++_i) \
;         __builtin_amdgcn_global_load_lds((const unsigned*)((const char*)(gbase) + (voff)[_i]), (LAS unsigned*)(lds + (bufoff) + ldsw + _i * 8192), 16, 0, 0); } while (0)
; #define PG8_LDA(dst, b, h) do { _Pragma("unroll") for (int m = 0; m < 4; ++m) _Pragma("unroll") for (int k = 0; k < 2; ++k) dst[m][k] = *(const LAS bf16x8*)(lds + PG8_SA(b, h) + aoff + m * 2048 + k * 1024); } while (0)
; #define PG8_LDB(dst, b, h) do { _Pragma("unroll") for (int n = 0; n < 2; ++n) _Pragma("unroll") for (int k = 0; k < 2; ++k) dst[n][k] = *(const LAS bf16x8*)(lds + PG8_SB(b, h) + boff + n * 2048 + k * 1024); } while (0)
; #define PG8_MMA(ai, bj, At, Bt) do { __builtin_amdgcn_s_setprio(1); _Pragma("unroll") for (int m = 0; m < 4; ++m) _Pragma("unroll") for (int n = 0; n < 2; ++n) _Pragma("unroll") for (int k = 0; k < 2; ++k) \
;         acc[ai][bj][m][n] = __builtin_amdgcn_mfma_f32_16x16x32_bf16(Bt[n][k], At[m][k], acc[ai][bj][m][n], 0, 0, 0); __builtin_amdgcn_s_setprio(0); } while (0)
; #define PG8_WAIT_V(n) asm volatile("s_waitcnt vmcnt(" #n ")" ::: "memory")
; #define PG8_WAIT_L(n) asm volatile("s_waitcnt lgkmcnt(" #n ")" ::: "memory")
; #define PG8_BAR __builtin_amdgcn_s_barrier()
; #define PG8_SCHED __builtin_amdgcn_sched_barrier(0)
; template <class Epi, class Sched, bool ALIGN_EPI = false, bool SP2 = false>
; __device__ __forceinline__ void gemm_phase(LAS unsigned char* lds, const Gemm g, const Sched& S, const Epi& E) {
;     ...
;             const bool last = (t == nt - 2);
;             const char* a1 = cA + (size_t)(t + 1) * kstep;
;             const char* a2 = last ? nA : cA + (size_t)(t + 2) * kstep; const char* b2 = last ? nB : cB + (size_t)(t + 2) * kstep;
;             const char* a3 = a2 + kstep; const char* b3 = b2 + kstep;
;             if (last && has_next) S.a_ready(nxt);
;             if constexpr (SP2) {
;             PG8_LDB(B0, 0, 0); PG8_LDB(B1, 0, 1); PG8_SCHED; PG8_LDA(At, 0, 0); PG8_STAGE(PG8_SA(1, 1), a1 + hstep, voffA);
;             PG8_WAIT_V(8); PG8_WAIT_L(0); PG8_BAR; PG8_MMA(0, 0, At, B0); PG8_MMA(0, 1, At, B1); PG8_BAR; PG8_SCHED;
;             PG8_LDA(At, 0, 1); PG8_STAGE(PG8_SB(0, 0), b2, voffB); PG8_STAGE(PG8_SB(0, 1), b2 + hstepB, voffB); PG8_STAGE(PG8_SA(0, 0), a2, voffA);
.LBB0_3002:
	ds_read_b128 v[152:155], v147
	ds_read_b128 v[156:159], v147 offset:1024
	ds_read_b128 v[160:163], v147 offset:2048
	ds_read_b128 v[164:167], v147 offset:3072
	ds_read_b128 v[168:171], v148
	ds_read_b128 v[172:175], v148 offset:1024
	ds_read_b128 v[176:179], v148 offset:2048
	ds_read_b128 v[180:183], v148 offset:3072
	s_add_u32 s16, s14, 0x100
	s_addc_u32 s17, s15, 0
	s_cmpk_eq_i32 s40, 0x54
	s_cselect_b32 s21, s11, s17
	s_cselect_b32 s20, s10, s16
	s_cselect_b32 s19, s3, s39
	s_cselect_b32 s18, s2, s13
	v_lshl_add_u64 v[216:217], s[14:15], 0, v[138:139]
	s_add_i32 m0, s24, 0xc000
	ds_read_b128 v[184:187], v149
	ds_read_b128 v[188:191], v149 offset:1024
	ds_read_b128 v[192:195], v149 offset:2048
	ds_read_b128 v[196:199], v149 offset:3072
	ds_read_b128 v[200:203], v149 offset:4096
	ds_read_b128 v[204:207], v149 offset:5120
	ds_read_b128 v[208:211], v149 offset:6144
	ds_read_b128 v[212:215], v149 offset:7168
	global_load_lds_dwordx4 v[216:217], off
	v_lshl_add_u64 v[216:217], s[14:15], 0, v[136:137]
	s_add_i32 m0, s24, 0xe000
	s_nop 0
	global_load_lds_dwordx4 v[216:217], off
	s_waitcnt vmcnt(8)
	s_waitcnt lgkmcnt(0)
	s_barrier
	s_waitcnt lgkmcnt(0)
	v_mfma_f32_16x16x32_bf16 v[124:127], v[152:155], v[184:187], v[124:127]
	v_mfma_f32_16x16x32_bf16 v[120:123], v[160:163], v[184:187], v[120:123]
	v_mfma_f32_16x16x32_bf16 v[112:115], v[152:155], v[192:195], v[112:115]
	v_mfma_f32_16x16x32_bf16 v[104:107], v[160:163], v[192:195], v[104:107]
	v_mfma_f32_16x16x32_bf16 v[92:95], v[152:155], v[200:203], v[92:95]
	v_mfma_f32_16x16x32_bf16 v[88:91], v[160:163], v[200:203], v[88:91]
	v_mfma_f32_16x16x32_bf16 v[76:79], v[152:155], v[208:211], v[76:79]
	v_mfma_f32_16x16x32_bf16 v[72:75], v[160:163], v[208:211], v[72:75]
	v_mfma_f32_16x16x32_bf16 v[124:127], v[156:159], v[188:191], v[124:127]
	v_mfma_f32_16x16x32_bf16 v[120:123], v[164:167], v[188:191], v[120:123]
	v_mfma_f32_16x16x32_bf16 v[112:115], v[156:159], v[196:199], v[112:115]
	v_mfma_f32_16x16x32_bf16 v[104:107], v[164:167], v[196:199], v[104:107]
	v_mfma_f32_16x16x32_bf16 v[92:95], v[156:159], v[204:207], v[92:95]
	v_mfma_f32_16x16x32_bf16 v[88:91], v[164:167], v[204:207], v[88:91]
	v_mfma_f32_16x16x32_bf16 v[76:79], v[156:159], v[212:215], v[76:79]
	v_mfma_f32_16x16x32_bf16 v[72:75], v[164:167], v[212:215], v[72:75]
	v_mfma_f32_16x16x32_bf16 v[116:119], v[168:171], v[184:187], v[116:119]
	v_mfma_f32_16x16x32_bf16 v[108:111], v[176:179], v[184:187], v[108:111]
	v_mfma_f32_16x16x32_bf16 v[100:103], v[168:171], v[192:195], v[100:103]
	v_mfma_f32_16x16x32_bf16 v[96:99], v[176:179], v[192:195], v[96:99]
	v_mfma_f32_16x16x32_bf16 v[84:87], v[168:171], v[200:203], v[84:87]
	v_mfma_f32_16x16x32_bf16 v[80:83], v[176:179], v[200:203], v[80:83]
	v_mfma_f32_16x16x32_bf16 v[68:71], v[168:171], v[208:211], v[68:71]
	v_mfma_f32_16x16x32_bf16 v[64:67], v[176:179], v[208:211], v[64:67]
	v_mfma_f32_16x16x32_bf16 v[116:119], v[172:175], v[188:191], v[116:119]
	v_mfma_f32_16x16x32_bf16 v[108:111], v[180:183], v[188:191], v[108:111]
	v_mfma_f32_16x16x32_bf16 v[100:103], v[172:175], v[196:199], v[100:103]
	v_mfma_f32_16x16x32_bf16 v[96:99], v[180:183], v[196:199], v[96:99]
	v_mfma_f32_16x16x32_bf16 v[84:87], v[172:175], v[204:207], v[84:87]
	v_mfma_f32_16x16x32_bf16 v[80:83], v[180:183], v[204:207], v[80:83]
	v_mfma_f32_16x16x32_bf16 v[68:71], v[172:175], v[212:215], v[68:71]
	v_mfma_f32_16x16x32_bf16 v[64:67], v[180:183], v[212:215], v[64:67]
	s_barrier
	s_add_i32 s14, s34, s23
	v_lshl_add_u64 v[216:217], s[18:19], 0, v[130:131]
	s_mov_b32 m0, s14
	ds_read_b128 v[184:187], v149 offset:16384
	ds_read_b128 v[188:191], v149 offset:17408
	ds_read_b128 v[192:195], v149 offset:18432
	ds_read_b128 v[196:199], v149 offset:19456
	ds_read_b128 v[200:203], v149 offset:20480
	ds_read_b128 v[204:207], v149 offset:21504
	ds_read_b128 v[208:211], v149 offset:22528
	ds_read_b128 v[212:215], v149 offset:23552
	global_load_lds_dwordx4 v[216:217], off
	s_add_i32 m0, s14, 0x2000
	s_add_u32 s14, s18, 0x58000
	v_lshl_add_u64 v[218:219], s[18:19], 0, v[134:135]
	s_addc_u32 s15, s19, 0
	s_add_i32 s41, s35, s23
	global_load_lds_dwordx4 v[218:219], off
	s_mov_b32 m0, s41
	v_lshl_add_u64 v[222:223], s[20:21], 0, v[132:133]
	global_load_lds_dwordx4 v130, s[14:15]
	s_add_i32 m0, s41, 0x2000
	s_nop 0
	global_load_lds_dwordx4 v134, s[14:15]
	v_lshl_add_u64 v[220:221], s[20:21], 0, v[128:129]
	s_mov_b32 m0, s24
	s_nop 0
	global_load_lds_dwordx4 v[220:221], off
	s_mov_b32 m0, s25
	s_nop 0
	global_load_lds_dwordx4 v[222:223], off
	s_waitcnt vmcnt(8)
	s_waitcnt lgkmcnt(0)
	s_barrier
; #define PG8_STAGE(bufoff, gbase, voff) do { _Pragma("unroll") for (int _i = 0; _i < 2; ++_i) \
;         __builtin_amdgcn_global_load_lds((const unsigned*)((const char*)(gbase) + (voff)[_i]), (LAS unsigned*)(lds + (bufoff) + ldsw + _i * 8192), 16, 0, 0); } while (0)
; #define PG8_LDA(dst, b, h) do { _Pragma("unroll") for (int m = 0; m < 4; ++m) _Pragma("unroll") for (int k = 0; k < 2; ++k) dst[m][k] = *(const LAS bf16x8*)(lds + PG8_SA(b, h) + aoff + m * 2048 + k * 1024); } while (0)
; #define PG8_LDB(dst, b, h) do { _Pragma("unroll") for (int n = 0; n < 2; ++n) _Pragma("unroll") for (int k = 0; k < 2; ++k) dst[n][k] = *(const LAS bf16x8*)(lds + PG8_SB(b, h) + boff + n * 2048 + k * 1024); } while (0)
; #define PG8_MMA(ai, bj, At, Bt) do { __builtin_amdgcn_s_setprio(1); _Pragma("unroll") for (int m = 0; m < 4; ++m) _Pragma("unroll") for (int n = 0; n < 2; ++n) _Pragma("unroll") for (int k = 0; k < 2; ++k) \
;         acc[ai][bj][m][n] = __builtin_amdgcn_mfma_f32_16x16x32_bf16(Bt[n][k], At[m][k], acc[ai][bj][m][n], 0, 0, 0); __builtin_amdgcn_s_setprio(0); } while (0)
; #define PG8_WAIT_V(n) asm volatile("s_waitcnt vmcnt(" #n ")" ::: "memory")
; #define PG8_WAIT_L(n) asm volatile("s_waitcnt lgkmcnt(" #n ")" ::: "memory")
; #define PG8_BAR __builtin_amdgcn_s_barrier()
; #define PG8_SCHED __builtin_amdgcn_sched_barrier(0)
; template <class Epi, class Sched, bool ALIGN_EPI = false, bool SP2 = false>
; __device__ __forceinline__ void gemm_phase(LAS unsigned char* lds, const Gemm g, const Sched& S, const Epi& E) {
;     ...
;             PG8_WAIT_V(8); PG8_WAIT_L(0); PG8_BAR; PG8_MMA(1, 0, At, B0); PG8_MMA(1, 1, At, B1); PG8_BAR; PG8_SCHED;
;             PG8_LDB(B0, 1, 0); PG8_LDB(B1, 1, 1); PG8_SCHED; PG8_LDA(At, 1, 0); PG8_STAGE(PG8_SA(0, 1), a2 + hstep, voffA);
;             PG8_WAIT_V(8); PG8_WAIT_L(0); PG8_BAR; PG8_MMA(0, 0, At, B0); PG8_MMA(0, 1, At, B1); PG8_BAR; PG8_SCHED;
	s_waitcnt lgkmcnt(0)
	v_mfma_f32_16x16x32_bf16 v[60:63], v[152:155], v[184:187], v[60:63]
	v_mfma_f32_16x16x32_bf16 v[56:59], v[160:163], v[184:187], v[56:59]
	v_mfma_f32_16x16x32_bf16 v[44:47], v[152:155], v[192:195], v[44:47]
	v_mfma_f32_16x16x32_bf16 v[40:43], v[160:163], v[192:195], v[40:43]
	v_mfma_f32_16x16x32_bf16 v[28:31], v[152:155], v[200:203], v[28:31]
	v_mfma_f32_16x16x32_bf16 v[24:27], v[160:163], v[200:203], v[24:27]
	v_mfma_f32_16x16x32_bf16 v[12:15], v[152:155], v[208:211], v[12:15]
	v_mfma_f32_16x16x32_bf16 v[8:11], v[160:163], v[208:211], v[8:11]
	v_mfma_f32_16x16x32_bf16 v[60:63], v[156:159], v[188:191], v[60:63]
	v_mfma_f32_16x16x32_bf16 v[56:59], v[164:167], v[188:191], v[56:59]
	v_mfma_f32_16x16x32_bf16 v[44:47], v[156:159], v[196:199], v[44:47]
	v_mfma_f32_16x16x32_bf16 v[40:43], v[164:167], v[196:199], v[40:43]
	v_mfma_f32_16x16x32_bf16 v[28:31], v[156:159], v[204:207], v[28:31]
	v_mfma_f32_16x16x32_bf16 v[24:27], v[164:167], v[204:207], v[24:27]
	v_mfma_f32_16x16x32_bf16 v[12:15], v[156:159], v[212:215], v[12:15]
	v_mfma_f32_16x16x32_bf16 v[8:11], v[164:167], v[212:215], v[8:11]
	v_mfma_f32_16x16x32_bf16 v[52:55], v[168:171], v[184:187], v[52:55]
	v_mfma_f32_16x16x32_bf16 v[48:51], v[176:179], v[184:187], v[48:51]
	v_mfma_f32_16x16x32_bf16 v[36:39], v[168:171], v[192:195], v[36:39]
	v_mfma_f32_16x16x32_bf16 v[32:35], v[176:179], v[192:195], v[32:35]
	v_mfma_f32_16x16x32_bf16 v[20:23], v[168:171], v[200:203], v[20:23]
	v_mfma_f32_16x16x32_bf16 v[16:19], v[176:179], v[200:203], v[16:19]
	v_mfma_f32_16x16x32_bf16 v[4:7], v[168:171], v[208:211], v[4:7]
	v_mfma_f32_16x16x32_bf16 v[0:3], v[176:179], v[208:211], v[0:3]
	v_mfma_f32_16x16x32_bf16 v[52:55], v[172:175], v[188:191], v[52:55]
	v_mfma_f32_16x16x32_bf16 v[48:51], v[180:183], v[188:191], v[48:51]
	v_mfma_f32_16x16x32_bf16 v[36:39], v[172:175], v[196:199], v[36:39]
	v_mfma_f32_16x16x32_bf16 v[32:35], v[180:183], v[196:199], v[32:35]
	v_mfma_f32_16x16x32_bf16 v[20:23], v[172:175], v[204:207], v[20:23]
	v_mfma_f32_16x16x32_bf16 v[16:19], v[180:183], v[204:207], v[16:19]
	v_mfma_f32_16x16x32_bf16 v[4:7], v[172:175], v[212:215], v[4:7]
	v_mfma_f32_16x16x32_bf16 v[0:3], v[180:183], v[212:215], v[0:3]
	s_barrier
	s_add_i32 s41, 0, 0x18000
	s_add_i32 s42, 0, 0x1c000
	v_add_u32_e32 v164, s41, v144
	v_add_u32_e32 v180, s42, v144
	ds_read_b128 v[152:155], v164
	ds_read_b128 v[156:159], v164 offset:1024
	ds_read_b128 v[160:163], v164 offset:2048
	ds_read_b128 v[164:167], v164 offset:3072
	ds_read_b128 v[168:171], v180
	ds_read_b128 v[172:175], v180 offset:1024
	ds_read_b128 v[176:179], v180 offset:2048
	ds_read_b128 v[180:183], v180 offset:3072
	s_add_u32 s14, s20, 0x160000
	s_addc_u32 s15, s21, 0
	s_mov_b32 m0, s26
	ds_read_b128 v[184:187], v149 offset:32768
	ds_read_b128 v[188:191], v149 offset:33792
	ds_read_b128 v[192:195], v149 offset:34816
	ds_read_b128 v[196:199], v149 offset:35840
	ds_read_b128 v[200:203], v149 offset:36864
	ds_read_b128 v[204:207], v149 offset:37888
	ds_read_b128 v[208:211], v149 offset:38912
	ds_read_b128 v[212:215], v149 offset:39936
	global_load_lds_dwordx4 v128, s[14:15]
	s_mov_b32 m0, s27
	s_nop 0
	global_load_lds_dwordx4 v132, s[14:15]
	s_waitcnt vmcnt(8)
	s_waitcnt lgkmcnt(0)
	s_barrier
	s_waitcnt lgkmcnt(0)
	v_mfma_f32_16x16x32_bf16 v[124:127], v[152:155], v[184:187], v[124:127]
	v_mfma_f32_16x16x32_bf16 v[120:123], v[160:163], v[184:187], v[120:123]
	v_mfma_f32_16x16x32_bf16 v[112:115], v[152:155], v[192:195], v[112:115]
	v_mfma_f32_16x16x32_bf16 v[104:107], v[160:163], v[192:195], v[104:107]
	v_mfma_f32_16x16x32_bf16 v[92:95], v[152:155], v[200:203], v[92:95]
	v_mfma_f32_16x16x32_bf16 v[88:91], v[160:163], v[200:203], v[88:91]
	v_mfma_f32_16x16x32_bf16 v[76:79], v[152:155], v[208:211], v[76:79]
	v_mfma_f32_16x16x32_bf16 v[72:75], v[160:163], v[208:211], v[72:75]
	v_mfma_f32_16x16x32_bf16 v[124:127], v[156:159], v[188:191], v[124:127]
	v_mfma_f32_16x16x32_bf16 v[120:123], v[164:167], v[188:191], v[120:123]
	v_mfma_f32_16x16x32_bf16 v[112:115], v[156:159], v[196:199], v[112:115]
	v_mfma_f32_16x16x32_bf16 v[104:107], v[164:167], v[196:199], v[104:107]
	v_mfma_f32_16x16x32_bf16 v[92:95], v[156:159], v[204:207], v[92:95]
	v_mfma_f32_16x16x32_bf16 v[88:91], v[164:167], v[204:207], v[88:91]
	v_mfma_f32_16x16x32_bf16 v[76:79], v[156:159], v[212:215], v[76:79]
	v_mfma_f32_16x16x32_bf16 v[72:75], v[164:167], v[212:215], v[72:75]
	v_mfma_f32_16x16x32_bf16 v[116:119], v[168:171], v[184:187], v[116:119]
	v_mfma_f32_16x16x32_bf16 v[108:111], v[176:179], v[184:187], v[108:111]
	v_mfma_f32_16x16x32_bf16 v[100:103], v[168:171], v[192:195], v[100:103]
	v_mfma_f32_16x16x32_bf16 v[96:99], v[176:179], v[192:195], v[96:99]
	v_mfma_f32_16x16x32_bf16 v[84:87], v[168:171], v[200:203], v[84:87]
	v_mfma_f32_16x16x32_bf16 v[80:83], v[176:179], v[200:203], v[80:83]
	v_mfma_f32_16x16x32_bf16 v[68:71], v[168:171], v[208:211], v[68:71]
	v_mfma_f32_16x16x32_bf16 v[64:67], v[176:179], v[208:211], v[64:67]
	v_mfma_f32_16x16x32_bf16 v[116:119], v[172:175], v[188:191], v[116:119]
	v_mfma_f32_16x16x32_bf16 v[108:111], v[180:183], v[188:191], v[108:111]
	v_mfma_f32_16x16x32_bf16 v[100:103], v[172:175], v[196:199], v[100:103]
	v_mfma_f32_16x16x32_bf16 v[96:99], v[180:183], v[196:199], v[96:99]
	v_mfma_f32_16x16x32_bf16 v[84:87], v[172:175], v[204:207], v[84:87]
	v_mfma_f32_16x16x32_bf16 v[80:83], v[180:183], v[204:207], v[80:83]
	v_mfma_f32_16x16x32_bf16 v[68:71], v[172:175], v[212:215], v[68:71]
	v_mfma_f32_16x16x32_bf16 v[64:67], v[180:183], v[212:215], v[64:67]
	s_barrier
; #define PG8_STAGE(bufoff, gbase, voff) do { _Pragma("unroll") for (int _i = 0; _i < 2; ++_i) \
;         __builtin_amdgcn_global_load_lds((const unsigned*)((const char*)(gbase) + (voff)[_i]), (LAS unsigned*)(lds + (bufoff) + ldsw + _i * 8192), 16, 0, 0); } while (0)
; #define PG8_LDA(dst, b, h) do { _Pragma("unroll") for (int m = 0; m < 4; ++m) _Pragma("unroll") for (int k = 0; k < 2; ++k) dst[m][k] = *(const LAS bf16x8*)(lds + PG8_SA(b, h) + aoff + m * 2048 + k * 1024); } while (0)
; #define PG8_MMA(ai, bj, At, Bt) do { __builtin_amdgcn_s_setprio(1); _Pragma("unroll") for (int m = 0; m < 4; ++m) _Pragma("unroll") for (int n = 0; n < 2; ++n) _Pragma("unroll") for (int k = 0; k < 2; ++k) \
;         acc[ai][bj][m][n] = __builtin_amdgcn_mfma_f32_16x16x32_bf16(Bt[n][k], At[m][k], acc[ai][bj][m][n], 0, 0, 0); __builtin_amdgcn_s_setprio(0); } while (0)
; #define PG8_WAIT_V(n) asm volatile("s_waitcnt vmcnt(" #n ")" ::: "memory")
; #define PG8_WAIT_L(n) asm volatile("s_waitcnt lgkmcnt(" #n ")" ::: "memory")
; #define PG8_BAR __builtin_amdgcn_s_barrier()
; #define PG8_SCHED __builtin_amdgcn_sched_barrier(0)
; template <class Epi, class Sched, bool ALIGN_EPI = false, bool SP2 = false>
; __device__ __forceinline__ void gemm_phase(LAS unsigned char* lds, const Gemm g, const Sched& S, const Epi& E) {
;     ...
;             PG8_LDA(At, 1, 1); PG8_STAGE(PG8_SB(1, 0), b3, voffB); PG8_STAGE(PG8_SB(1, 1), b3 + hstepB, voffB); PG8_STAGE(PG8_SA(1, 0), a3, voffA);
;             PG8_WAIT_V(8); PG8_WAIT_L(0); PG8_BAR; PG8_MMA(1, 0, At, B0); PG8_MMA(1, 1, At, B1); PG8_BAR; PG8_SCHED;
	s_add_i32 s14, s41, s23
	v_lshl_add_u64 v[216:217], v[216:217], 0, s[6:7]
	s_mov_b32 m0, s14
	ds_read_b128 v[184:187], v149 offset:49152
	ds_read_b128 v[188:191], v149 offset:50176
	ds_read_b128 v[192:195], v149 offset:51200
	ds_read_b128 v[196:199], v149 offset:52224
	ds_read_b128 v[200:203], v149 offset:53248
	ds_read_b128 v[204:207], v149 offset:54272
	ds_read_b128 v[208:211], v149 offset:55296
	ds_read_b128 v[212:215], v149 offset:56320
	global_load_lds_dwordx4 v[216:217], off
	s_add_i32 m0, s14, 0x2000
	s_add_u32 s14, s18, 0x58080
	v_lshl_add_u64 v[216:217], v[218:219], 0, s[6:7]
	s_addc_u32 s15, s19, 0
	s_add_i32 s18, s42, s23
	global_load_lds_dwordx4 v[216:217], off
	s_mov_b32 m0, s18
	s_nop 0
	global_load_lds_dwordx4 v130, s[14:15]
	s_add_i32 m0, s18, 0x2000
	s_nop 0
	global_load_lds_dwordx4 v134, s[14:15]
	v_lshl_add_u64 v[216:217], v[220:221], 0, s[6:7]
	s_mov_b32 m0, s31
	s_nop 0
	global_load_lds_dwordx4 v[216:217], off
	v_lshl_add_u64 v[216:217], v[222:223], 0, s[6:7]
	s_mov_b32 m0, s33
	s_nop 0
	global_load_lds_dwordx4 v[216:217], off
	s_waitcnt vmcnt(8)
	s_waitcnt lgkmcnt(0)
	s_barrier
	s_waitcnt lgkmcnt(0)
	v_mfma_f32_16x16x32_bf16 v[60:63], v[152:155], v[184:187], v[60:63]
	v_mfma_f32_16x16x32_bf16 v[56:59], v[160:163], v[184:187], v[56:59]
	v_mfma_f32_16x16x32_bf16 v[44:47], v[152:155], v[192:195], v[44:47]
	v_mfma_f32_16x16x32_bf16 v[40:43], v[160:163], v[192:195], v[40:43]
	v_mfma_f32_16x16x32_bf16 v[28:31], v[152:155], v[200:203], v[28:31]
	v_mfma_f32_16x16x32_bf16 v[24:27], v[160:163], v[200:203], v[24:27]
	v_mfma_f32_16x16x32_bf16 v[12:15], v[152:155], v[208:211], v[12:15]
	v_mfma_f32_16x16x32_bf16 v[8:11], v[160:163], v[208:211], v[8:11]
	v_mfma_f32_16x16x32_bf16 v[60:63], v[156:159], v[188:191], v[60:63]
	v_mfma_f32_16x16x32_bf16 v[56:59], v[164:167], v[188:191], v[56:59]
	v_mfma_f32_16x16x32_bf16 v[44:47], v[156:159], v[196:199], v[44:47]
	v_mfma_f32_16x16x32_bf16 v[40:43], v[164:167], v[196:199], v[40:43]
	v_mfma_f32_16x16x32_bf16 v[28:31], v[156:159], v[204:207], v[28:31]
	v_mfma_f32_16x16x32_bf16 v[24:27], v[164:167], v[204:207], v[24:27]
	v_mfma_f32_16x16x32_bf16 v[12:15], v[156:159], v[212:215], v[12:15]
	v_mfma_f32_16x16x32_bf16 v[8:11], v[164:167], v[212:215], v[8:11]
	v_mfma_f32_16x16x32_bf16 v[52:55], v[168:171], v[184:187], v[52:55]
	v_mfma_f32_16x16x32_bf16 v[48:51], v[176:179], v[184:187], v[48:51]
	v_mfma_f32_16x16x32_bf16 v[36:39], v[168:171], v[192:195], v[36:39]
	v_mfma_f32_16x16x32_bf16 v[32:35], v[176:179], v[192:195], v[32:35]
	v_mfma_f32_16x16x32_bf16 v[20:23], v[168:171], v[200:203], v[20:23]
	v_mfma_f32_16x16x32_bf16 v[16:19], v[176:179], v[200:203], v[16:19]
	v_mfma_f32_16x16x32_bf16 v[4:7], v[168:171], v[208:211], v[4:7]
	v_mfma_f32_16x16x32_bf16 v[0:3], v[176:179], v[208:211], v[0:3]
	v_mfma_f32_16x16x32_bf16 v[52:55], v[172:175], v[188:191], v[52:55]
	v_mfma_f32_16x16x32_bf16 v[48:51], v[180:183], v[188:191], v[48:51]
	v_mfma_f32_16x16x32_bf16 v[36:39], v[172:175], v[196:199], v[36:39]
	v_mfma_f32_16x16x32_bf16 v[32:35], v[180:183], v[196:199], v[32:35]
	v_mfma_f32_16x16x32_bf16 v[20:23], v[172:175], v[204:207], v[20:23]
	v_mfma_f32_16x16x32_bf16 v[16:19], v[180:183], v[204:207], v[16:19]
	v_mfma_f32_16x16x32_bf16 v[4:7], v[172:175], v[212:215], v[4:7]
	v_mfma_f32_16x16x32_bf16 v[0:3], v[180:183], v[212:215], v[0:3]
	s_barrier
	s_add_i32 s40, s40, 2
	s_add_u32 s13, s13, 0x100
	s_addc_u32 s39, s39, 0
	s_cmpk_lt_u32 s40, 0x56
	s_mov_b64 s[14:15], s[16:17]
	s_cbranch_scc1 .LBB0_3002
	s_setprio 0
	s_andn2_b64 vcc, exec, s[8:9]
	s_cbranch_vccnz .LBB0_3005
	s_barrier
